# on top of v8: weight-conversion flat loads/stores as global ops; PV waits trimmed to two counted lgkmcnt per block
# speedup vs baseline: 1.0196x; 1.0065x over previous
; #define LAS __attribute__((address_space(3)))
; __device__ __forceinline__ ItemPos item_load(const XItem* tab, int it, int lane, f32x4 (&v)[16], float (&gv)[16]) {
;     int e = 0;
; #pragma unroll 1
;     for (int q = 1; q < 20; ++q) if (it >= tab[q].start) e = q;
;     const XItem x = tab[e]; const int item = it - x.start;
;     const int nblk = x.N >> 6, kb = item / nblk, nb = item - kb * nblk, k0 = kb << 6, n0 = nb << 6;
;     const int lr = lane >> 4, lc = (lane & 15) * 4;
;     const float* W = x.src + (size_t)(k0 + lr) * x.N + n0 + lc; const size_t rstep = (size_t)4 * x.N;
; #pragma unroll
;     for (int i = 0; i < 16; ++i) v[i] = __builtin_nontemporal_load((const f32x4*)(W + i * rstep));
; #pragma unroll
;     for (int i = 0; i < 16; ++i) gv[i] = x.g ? x.g[k0 + 4 * i + lr] : 1.0f;
; __device__ __forceinline__ void convert_range(unsigned char* lds, int lo, int hi, int w, int nworkers, int wave, int lane) {
;     const XItem* tab = (const XItem*)(lds + 8 * 16640);
;     LAS float* scr = (LAS float*)((LAS unsigned char*)lds + wave * 16640);
;     int it = lo + w; if (it >= hi) return;
;     f32x4 v[16]; float gv[16]; ItemPos p = item_load(tab, it, lane, v, gv);
.LBB0_23:
	v_mov_b32_e32 v3, s0
	ds_read_b32 v3, v3
	v_mov_b32_e32 v4, s1
	s_add_i32 s1, s1, 1
	s_add_i32 s0, s0, 40
	s_cmp_eq_u32 s1, 20
	s_waitcnt lgkmcnt(0)
	v_cmp_lt_i32_e32 vcc, s12, v3
	s_nop 1
	v_cndmask_b32_e32 v2, v4, v2, vcc
	s_cbranch_scc0 .LBB0_23
	v_mul_lo_u32 v2, v2, 40
	v_add_u32_e32 v2, 0, v2
	v_add_u32_e32 v10, 0x20800, v2
	ds_read2_b64 v[2:5], v10 offset0:3 offset1:4
	ds_read2_b64 v[6:9], v10 offset1:1
	ds_read_b64 v[74:75], v10 offset:16
	v_ashrrev_i32_e32 v77, 4, v100
	v_lshlrev_b32_e32 v11, 2, v100
	v_mov_b32_e32 v79, 0
	s_waitcnt lgkmcnt(2)
	v_readfirstlane_b32 s2, v3
	s_ashr_i32 s0, s2, 6
	s_abs_i32 s1, s0
	v_cvt_f32_u32_e32 v3, s1
	s_sub_i32 s6, 0, s1
	v_readfirstlane_b32 s3, v5
	s_sub_i32 s3, s12, s3
	v_rcp_iflag_f32_e32 v3, v3
	s_abs_i32 s5, s3
	s_xor_b32 s4, s3, s0
	s_ashr_i32 s4, s4, 31
	v_mul_f32_e32 v3, 0x4f7ffffe, v3
	v_cvt_u32_f32_e32 v3, v3
	v_and_b32_e32 v5, 60, v11
	v_lshlrev_b32_e32 v78, 2, v5
	v_readfirstlane_b32 s7, v3
	s_mul_i32 s6, s6, s7
	s_mul_hi_u32 s6, s7, s6
	s_add_i32 s7, s7, s6
	s_mul_hi_u32 s6, s5, s7
	s_mul_i32 s7, s6, s1
	s_sub_i32 s5, s5, s7
	s_add_i32 s14, s6, 1
	s_sub_i32 s7, s5, s1
	s_cmp_ge_u32 s5, s1
	s_cselect_b32 s6, s14, s6
	s_cselect_b32 s5, s7, s5
	s_add_i32 s7, s6, 1
	s_cmp_ge_u32 s5, s1
	s_cselect_b32 s1, s7, s6
	s_xor_b32 s1, s1, s4
	s_sub_i32 s1, s1, s4
	s_mul_i32 s0, s1, s0
	s_lshl_b32 s18, s1, 6
	s_sub_i32 s14, s3, s0
	v_add_u32_e32 v80, s18, v77
	s_lshl_b32 s0, s14, 6
	v_mad_i64_i32 v[10:11], s[4:5], v80, s2, 0
	s_waitcnt lgkmcnt(1)
	v_lshl_add_u64 v[6:7], v[10:11], 2, v[6:7]
	s_ashr_i32 s1, s0, 31
	s_ashr_i32 s3, s2, 31
	v_lshl_add_u64 v[6:7], s[0:1], 2, v[6:7]
	v_lshl_add_u64 v[6:7], v[6:7], 0, v[78:79]
	s_lshl_b64 s[2:3], s[2:3], 4
	v_lshl_add_u64 v[18:19], v[6:7], 0, s[2:3]
	global_load_dwordx4 v[10:13], v[6:7], off nt
	global_load_dwordx4 v[14:17], v[18:19], off nt
	v_lshl_add_u64 v[6:7], v[18:19], 0, s[2:3]
	v_lshl_add_u64 v[26:27], v[6:7], 0, s[2:3]
	global_load_dwordx4 v[18:21], v[6:7], off nt
	global_load_dwordx4 v[22:25], v[26:27], off nt
	v_lshl_add_u64 v[6:7], v[26:27], 0, s[2:3]
	v_lshl_add_u64 v[34:35], v[6:7], 0, s[2:3]
	global_load_dwordx4 v[26:29], v[6:7], off nt
	global_load_dwordx4 v[30:33], v[34:35], off nt
	v_lshl_add_u64 v[6:7], v[34:35], 0, s[2:3]
	v_lshl_add_u64 v[42:43], v[6:7], 0, s[2:3]
	global_load_dwordx4 v[34:37], v[6:7], off nt
	global_load_dwordx4 v[38:41], v[42:43], off nt
	v_lshl_add_u64 v[6:7], v[42:43], 0, s[2:3]
	global_load_dwordx4 v[42:45], v[6:7], off nt
	v_lshl_add_u64 v[6:7], v[6:7], 0, s[2:3]
	global_load_dwordx4 v[46:49], v[6:7], off nt
	v_lshl_add_u64 v[6:7], v[6:7], 0, s[2:3]
	v_lshl_add_u64 v[54:55], v[6:7], 0, s[2:3]
	global_load_dwordx4 v[50:53], v[6:7], off nt
	v_lshl_add_u64 v[6:7], v[54:55], 0, s[2:3]
	v_lshl_add_u64 v[62:63], v[6:7], 0, s[2:3]
	global_load_dwordx4 v[58:61], v[6:7], off nt
	v_lshl_add_u64 v[6:7], v[62:63], 0, s[2:3]
	global_load_dwordx4 v[54:57], v[54:55], off nt
	v_lshl_add_u64 v[82:83], v[6:7], 0, s[2:3]
	global_load_dwordx4 v[62:65], v[62:63], off nt
	s_nop 0
	global_load_dwordx4 v[66:69], v[6:7], off nt
	global_load_dwordx4 v[70:73], v[82:83], off nt
	v_ashrrev_i32_e32 v81, 31, v80
	s_waitcnt lgkmcnt(0)
	v_cmp_ne_u64_e64 s[6:7], 0, v[74:75]
	v_lshl_add_u64 v[6:7], v[80:81], 2, v[74:75]
	s_and_b64 vcc, exec, s[6:7]
	s_cbranch_vccnz .LBB0_25
	s_getpc_b64 s[98:99]

; __device__ __forceinline__ ItemPos item_load(const XItem* tab, int it, int lane, f32x4 (&v)[16], float (&gv)[16]) {
;     ...
;     for (int i = 0; i < 16; ++i) gv[i] = x.g ? x.g[k0 + 4 * i + lr] : 1.0f;
.LBB0_25:
	global_load_dword v80, v[6:7], off
	global_load_dword v81, v[6:7], off offset:16
	v_cndmask_b32_e64 v3, 0, 1, s[6:7]
	v_cmp_ne_u32_e64 s[4:5], 1, v3
	s_andn2_b64 vcc, exec, s[6:7]
	s_cbranch_vccz .LBB0_26
	s_getpc_b64 s[98:99]

; __device__ __forceinline__ ItemPos item_load(const XItem* tab, int it, int lane, f32x4 (&v)[16], float (&gv)[16]) {
;     ...
;     for (int i = 0; i < 16; ++i) gv[i] = x.g ? x.g[k0 + 4 * i + lr] : 1.0f;
.LBB0_26:
	global_load_dword v82, v[6:7], off offset:32
	global_load_dword v83, v[6:7], off offset:48
	s_cbranch_execnz .LBB0_28

; __device__ __forceinline__ ItemPos item_load(const XItem* tab, int it, int lane, f32x4 (&v)[16], float (&gv)[16]) {
;     ...
;     for (int i = 0; i < 16; ++i) gv[i] = x.g ? x.g[k0 + 4 * i + lr] : 1.0f;
.LBB0_29:
	global_load_dword v86, v[6:7], off offset:64
	global_load_dword v87, v[6:7], off offset:80
	s_cbranch_execnz .LBB0_31

; __device__ __forceinline__ ItemPos item_load(const XItem* tab, int it, int lane, f32x4 (&v)[16], float (&gv)[16]) {
;     ...
;     for (int i = 0; i < 16; ++i) gv[i] = x.g ? x.g[k0 + 4 * i + lr] : 1.0f;
.LBB0_32:
	global_load_dword v88, v[6:7], off offset:96
	global_load_dword v89, v[6:7], off offset:112
	s_cbranch_execnz .LBB0_34

; __device__ __forceinline__ ItemPos item_load(const XItem* tab, int it, int lane, f32x4 (&v)[16], float (&gv)[16]) {
;     ...
;     for (int i = 0; i < 16; ++i) gv[i] = x.g ? x.g[k0 + 4 * i + lr] : 1.0f;
.LBB0_35:
	global_load_dword v90, v[6:7], off offset:128
	global_load_dword v91, v[6:7], off offset:144
	s_cbranch_execnz .LBB0_37

; __device__ __forceinline__ ItemPos item_load(const XItem* tab, int it, int lane, f32x4 (&v)[16], float (&gv)[16]) {
;     ...
;     for (int i = 0; i < 16; ++i) gv[i] = x.g ? x.g[k0 + 4 * i + lr] : 1.0f;
.LBB0_38:
	global_load_dword v92, v[6:7], off offset:160
	global_load_dword v93, v[6:7], off offset:176
	s_cbranch_execnz .LBB0_40

; __device__ __forceinline__ ItemPos item_load(const XItem* tab, int it, int lane, f32x4 (&v)[16], float (&gv)[16]) {
;     ...
;     for (int i = 0; i < 16; ++i) gv[i] = x.g ? x.g[k0 + 4 * i + lr] : 1.0f;
.LBB0_41:
	global_load_dword v94, v[6:7], off offset:192
	global_load_dword v95, v[6:7], off offset:208
	s_cbranch_execnz .LBB0_43

; __device__ __forceinline__ ItemPos item_load(const XItem* tab, int it, int lane, f32x4 (&v)[16], float (&gv)[16]) {
;     ...
;     for (int i = 0; i < 16; ++i) gv[i] = x.g ? x.g[k0 + 4 * i + lr] : 1.0f;
.LBB0_44:
	global_load_dword v96, v[6:7], off offset:224
	global_load_dword v97, v[6:7], off offset:240
	s_cbranch_execnz .LBB0_46

; __device__ __forceinline__ ItemPos item_load(const XItem* tab, int it, int lane, f32x4 (&v)[16], float (&gv)[16]) {
;     int e = 0;
; #pragma unroll 1
;     for (int q = 1; q < 20; ++q) if (it >= tab[q].start) e = q;
;     const XItem x = tab[e]; const int item = it - x.start;
;     const int nblk = x.N >> 6, kb = item / nblk, nb = item - kb * nblk, k0 = kb << 6, n0 = nb << 6;
;     const int lr = lane >> 4, lc = (lane & 15) * 4;
;     const float* W = x.src + (size_t)(k0 + lr) * x.N + n0 + lc; const size_t rstep = (size_t)4 * x.N;
; #pragma unroll
;     for (int i = 0; i < 16; ++i) v[i] = __builtin_nontemporal_load((const f32x4*)(W + i * rstep));
; #pragma unroll
;     for (int i = 0; i < 16; ++i) gv[i] = x.g ? x.g[k0 + 4 * i + lr] : 1.0f;
; __device__ __forceinline__ void convert_range(unsigned char* lds, int lo, int hi, int w, int nworkers, int wave, int lane) {
;     ...
;     for (;;) {
;         item_to_lds(v, gv, p.scaled, scr, lane);
;         const int nx = it + nworkers; const bool more = nx < hi; ItemPos pn = p;
;         if (more) pn = item_load(tab, nx, lane, v, gv);
.LBB0_52:
	v_mov_b32_e32 v5, s1
	ds_read_b32 v5, v5
	v_mov_b32_e32 v6, s0
	s_add_i32 s0, s0, 1
	s_add_i32 s1, s1, 40
	s_cmp_eq_u32 s0, 20
	s_waitcnt lgkmcnt(0)
	v_cmp_lt_i32_e32 vcc, s27, v5
	s_nop 1
	v_cndmask_b32_e32 v4, v6, v4, vcc
	s_cbranch_scc0 .LBB0_52
	v_mul_lo_u32 v4, v4, 40
	v_add_u32_e32 v4, 0, v4
	v_add_u32_e32 v10, 0x20800, v4
	ds_read2_b64 v[4:7], v10 offset0:3 offset1:4
	ds_read2_b64 v[72:75], v10 offset1:1
	ds_read_b64 v[80:81], v10 offset:16
	s_waitcnt lgkmcnt(2)
	v_readfirstlane_b32 s4, v5
	s_ashr_i32 s0, s4, 6
	s_abs_i32 s1, s0
	v_cvt_f32_u32_e32 v5, s1
	v_readfirstlane_b32 s5, v7
	s_sub_i32 s6, s27, s5
	s_xor_b32 s5, s6, s0
	v_rcp_iflag_f32_e32 v5, v5
	s_ashr_i32 s19, s5, 31
	s_sub_i32 s5, 0, s1
	s_abs_i32 s7, s6
	v_mul_f32_e32 v5, 0x4f7ffffe, v5
	v_cvt_u32_f32_e32 v5, v5
	s_nop 0
	v_readfirstlane_b32 s28, v5
	s_mul_i32 s5, s5, s28
	s_mul_hi_u32 s5, s28, s5
	s_add_i32 s28, s28, s5
	s_mul_hi_u32 s5, s7, s28
	s_mul_i32 s28, s5, s1
	s_sub_i32 s7, s7, s28
	s_add_i32 s29, s5, 1
	s_sub_i32 s28, s7, s1
	s_cmp_ge_u32 s7, s1
	s_cselect_b32 s5, s29, s5
	s_cselect_b32 s7, s28, s7
	s_add_i32 s28, s5, 1
	s_cmp_ge_u32 s7, s1
	s_cselect_b32 s1, s28, s5
	s_xor_b32 s1, s1, s19
	s_sub_i32 s1, s1, s19
	s_mul_i32 s0, s1, s0
	s_lshl_b32 s28, s1, 6
	s_sub_i32 s19, s6, s0
	v_add_u32_e32 v82, s28, v77
	s_lshl_b32 s0, s19, 6
	v_mad_i64_i32 v[10:11], s[6:7], v82, s4, 0
	s_waitcnt lgkmcnt(1)
	v_lshl_add_u64 v[10:11], v[10:11], 2, v[72:73]
	s_ashr_i32 s1, s0, 31
	s_ashr_i32 s5, s4, 31
	v_lshl_add_u64 v[10:11], s[0:1], 2, v[10:11]
	v_lshl_add_u64 v[18:19], v[10:11], 0, v[78:79]
	s_lshl_b64 s[4:5], s[4:5], 4
	v_lshl_add_u64 v[20:21], v[18:19], 0, s[4:5]
	v_lshl_add_u64 v[26:27], v[20:21], 0, s[4:5]
	v_lshl_add_u64 v[28:29], v[26:27], 0, s[4:5]
	v_lshl_add_u64 v[34:35], v[28:29], 0, s[4:5]
	v_lshl_add_u64 v[36:37], v[34:35], 0, s[4:5]
	v_lshl_add_u64 v[42:43], v[36:37], 0, s[4:5]
	v_lshl_add_u64 v[44:45], v[42:43], 0, s[4:5]
	v_lshl_add_u64 v[46:47], v[44:45], 0, s[4:5]
	v_lshl_add_u64 v[50:51], v[46:47], 0, s[4:5]
	v_lshl_add_u64 v[54:55], v[50:51], 0, s[4:5]
	v_lshl_add_u64 v[58:59], v[54:55], 0, s[4:5]
	v_lshl_add_u64 v[62:63], v[58:59], 0, s[4:5]
	v_lshl_add_u64 v[66:67], v[62:63], 0, s[4:5]
	v_lshl_add_u64 v[70:71], v[66:67], 0, s[4:5]
	global_load_dwordx4 v[10:13], v[18:19], off nt
	global_load_dwordx4 v[14:17], v[20:21], off nt
	s_nop 0
	global_load_dwordx4 v[18:21], v[26:27], off nt
	global_load_dwordx4 v[22:25], v[28:29], off nt
	s_nop 0
	global_load_dwordx4 v[26:29], v[34:35], off nt
	global_load_dwordx4 v[30:33], v[36:37], off nt
	s_nop 0
	global_load_dwordx4 v[34:37], v[42:43], off nt
	global_load_dwordx4 v[38:41], v[44:45], off nt
	v_ashrrev_i32_e32 v83, 31, v82
	global_load_dwordx4 v[42:45], v[46:47], off nt
	s_waitcnt lgkmcnt(0)
	v_cmp_ne_u64_e64 s[6:7], 0, v[80:81]
	global_load_dwordx4 v[46:49], v[50:51], off nt
	s_and_b64 vcc, exec, s[6:7]
	global_load_dwordx4 v[50:53], v[54:55], off nt
	v_lshl_add_u64 v[98:99], v[82:83], 2, v[80:81]
	global_load_dwordx4 v[54:57], v[58:59], off nt
	s_nop 0
	global_load_dwordx4 v[58:61], v[62:63], off nt
	s_nop 0
	global_load_dwordx4 v[62:65], v[66:67], off nt
	s_nop 0
	global_load_dwordx4 v[66:69], v[70:71], off nt
	v_lshl_add_u64 v[70:71], v[70:71], 0, s[4:5]
	global_load_dwordx4 v[70:73], v[70:71], off nt
	s_cbranch_vccz .LBB0_80
	global_load_dword v80, v[98:99], off
	global_load_dword v81, v[98:99], off offset:16
	s_cbranch_execnz .LBB0_56

; __device__ __forceinline__ ItemPos item_load(const XItem* tab, int it, int lane, f32x4 (&v)[16], float (&gv)[16]) {
;     ...
;     for (int i = 0; i < 16; ++i) gv[i] = x.g ? x.g[k0 + 4 * i + lr] : 1.0f;
.LBB0_56:
	v_cndmask_b32_e64 v5, 0, 1, s[6:7]
	v_cmp_ne_u32_e64 s[4:5], 1, v5
	s_andn2_b64 vcc, exec, s[6:7]
	s_cbranch_vccnz .LBB0_81
	global_load_dword v82, v[98:99], off offset:32
	global_load_dword v83, v[98:99], off offset:48
	s_cbranch_execnz .LBB0_59

; __device__ __forceinline__ ItemPos item_load(const XItem* tab, int it, int lane, f32x4 (&v)[16], float (&gv)[16]) {
;     ...
;     for (int i = 0; i < 16; ++i) gv[i] = x.g ? x.g[k0 + 4 * i + lr] : 1.0f;
.LBB0_59:
	s_and_b64 vcc, exec, s[4:5]
	s_cbranch_vccnz .LBB0_82
	global_load_dword v86, v[98:99], off offset:64
	global_load_dword v87, v[98:99], off offset:80
	s_cbranch_execnz .LBB0_62

; __device__ __forceinline__ ItemPos item_load(const XItem* tab, int it, int lane, f32x4 (&v)[16], float (&gv)[16]) {
;     ...
;     for (int i = 0; i < 16; ++i) gv[i] = x.g ? x.g[k0 + 4 * i + lr] : 1.0f;
.LBB0_62:
	s_and_b64 vcc, exec, s[4:5]
	s_cbranch_vccnz .LBB0_83
	global_load_dword v88, v[98:99], off offset:96
	global_load_dword v89, v[98:99], off offset:112
	s_cbranch_execnz .LBB0_65

; __device__ __forceinline__ ItemPos item_load(const XItem* tab, int it, int lane, f32x4 (&v)[16], float (&gv)[16]) {
;     ...
;     for (int i = 0; i < 16; ++i) gv[i] = x.g ? x.g[k0 + 4 * i + lr] : 1.0f;
.LBB0_65:
	s_and_b64 vcc, exec, s[4:5]
	s_cbranch_vccnz .LBB0_84
	global_load_dword v90, v[98:99], off offset:128
	global_load_dword v91, v[98:99], off offset:144
	s_cbranch_execnz .LBB0_68

; __device__ __forceinline__ ItemPos item_load(const XItem* tab, int it, int lane, f32x4 (&v)[16], float (&gv)[16]) {
;     ...
;     for (int i = 0; i < 16; ++i) gv[i] = x.g ? x.g[k0 + 4 * i + lr] : 1.0f;
.LBB0_68:
	s_and_b64 vcc, exec, s[4:5]
	s_cbranch_vccnz .LBB0_85
	global_load_dword v92, v[98:99], off offset:160
	global_load_dword v93, v[98:99], off offset:176
	s_cbranch_execnz .LBB0_71

; __device__ __forceinline__ ItemPos item_load(const XItem* tab, int it, int lane, f32x4 (&v)[16], float (&gv)[16]) {
;     ...
;     for (int i = 0; i < 16; ++i) gv[i] = x.g ? x.g[k0 + 4 * i + lr] : 1.0f;
.LBB0_71:
	s_and_b64 vcc, exec, s[4:5]
	s_cbranch_vccnz .LBB0_86
	global_load_dword v94, v[98:99], off offset:192
	global_load_dword v95, v[98:99], off offset:208
	s_cbranch_execnz .LBB0_74

; __device__ __forceinline__ ItemPos item_load(const XItem* tab, int it, int lane, f32x4 (&v)[16], float (&gv)[16]) {
;     ...
;     for (int i = 0; i < 16; ++i) gv[i] = x.g ? x.g[k0 + 4 * i + lr] : 1.0f;
.LBB0_74:
	s_and_b64 vcc, exec, s[4:5]
	s_cbranch_vccnz .LBB0_87
	global_load_dword v96, v[98:99], off offset:224
	global_load_dword v97, v[98:99], off offset:240
	s_cbranch_execnz .LBB0_77

; #define LAS __attribute__((address_space(3)))
; __device__ __forceinline__ unsigned pk2(float lo, float hi) { return f2bf(lo) | (f2bf(hi) << 16); }
; __device__ __forceinline__ void item_store(const ItemPos p, LAS float* scr, int lane) {
;     const int c = lane & 7;
; #pragma unroll
;     for (int j = 0; j < 8; ++j) { const int n = (lane >> 3) + 8 * j; const LAS float* s = scr + (8 * c) * 65 + n;
;         u32x4 o; o.x = pk2(s[0 * 65], s[1 * 65]); o.y = pk2(s[2 * 65], s[3 * 65]); o.z = pk2(s[4 * 65], s[5 * 65]); o.w = pk2(s[6 * 65], s[7 * 65]);
;         __builtin_nontemporal_store(o, (u32x4*)(p.WT + (size_t)(p.rb + n) * p.K + p.k0 + 8 * c)); }
;     asm volatile("s_waitcnt lgkmcnt(0)" ::: "memory");
; }
.LBB0_78:
	s_ashr_i32 s19, s18, 31
	s_lshl_b64 s[0:1], s[18:19], 1
	v_lshl_add_u64 v[6:7], v[8:9], 0, s[0:1]
	v_mov_b32_e32 v85, v79
	v_lshl_add_u64 v[6:7], v[6:7], 0, v[84:85]
	ds_read_b32 v85, v102
	ds_read_b32 v98, v102 offset:260
	ds_read_b32 v99, v102 offset:520
	ds_read_b32 v131, v102 offset:780
	ds_read_b32 v132, v102 offset:1040
	ds_read_b32 v133, v102 offset:1300
	ds_read_b32 v134, v102 offset:1560
	ds_read_b32 v135, v102 offset:1820
	s_waitcnt lgkmcnt(0)
	v_bfe_u32 v130, v85, 16, 1
	v_add3_u32 v85, v85, v130, s24
	v_bfe_u32 v130, v98, 16, 1
	v_lshrrev_b32_e32 v85, 16, v85
	v_add3_u32 v98, v98, v130, s24
	v_and_or_b32 v130, v98, s25, v85
	v_bfe_u32 v85, v99, 16, 1
	v_add3_u32 v85, v99, v85, s24
	v_bfe_u32 v98, v131, 16, 1
	v_lshrrev_b32_e32 v85, 16, v85
	v_add3_u32 v98, v131, v98, s24
	v_and_or_b32 v131, v98, s25, v85
	v_bfe_u32 v85, v132, 16, 1
	v_add3_u32 v85, v132, v85, s24
	v_bfe_u32 v98, v133, 16, 1
	v_lshrrev_b32_e32 v85, 16, v85
	v_add3_u32 v98, v133, v98, s24
	v_and_or_b32 v132, v98, s25, v85
	v_bfe_u32 v85, v134, 16, 1
	v_add3_u32 v85, v134, v85, s24
	v_bfe_u32 v98, v135, 16, 1
	v_lshrrev_b32_e32 v85, 16, v85
	v_add3_u32 v98, v135, v98, s24
	v_and_or_b32 v133, v98, s25, v85
	v_add_u32_e32 v85, v3, v101
	v_mad_i64_i32 v[98:99], s[0:1], v85, v2, 0
	v_lshl_add_u64 v[98:99], v[98:99], 1, v[6:7]
	global_store_dwordx4 v[98:99], v[130:133], off nt
	ds_read_b32 v98, v102 offset:32
	ds_read_b32 v99, v102 offset:292
	ds_read_b32 v131, v102 offset:552
	ds_read_b32 v132, v102 offset:812
	ds_read_b32 v133, v102 offset:1072
	ds_read_b32 v134, v102 offset:1332
	ds_read_b32 v135, v102 offset:1592
	ds_read_b32 v136, v102 offset:1852
	s_waitcnt lgkmcnt(0)
	v_bfe_u32 v130, v98, 16, 1
	v_add3_u32 v98, v98, v130, s24
	v_bfe_u32 v130, v99, 16, 1
	v_lshrrev_b32_e32 v98, 16, v98
	v_add3_u32 v99, v99, v130, s24
	v_and_or_b32 v130, v99, s25, v98
	v_bfe_u32 v98, v131, 16, 1
	v_add3_u32 v98, v131, v98, s24
	v_bfe_u32 v99, v132, 16, 1
	v_lshrrev_b32_e32 v98, 16, v98
	v_add3_u32 v99, v132, v99, s24
	v_and_or_b32 v131, v99, s25, v98
	v_bfe_u32 v98, v133, 16, 1
	v_add3_u32 v98, v133, v98, s24
	v_bfe_u32 v99, v134, 16, 1
	v_lshrrev_b32_e32 v98, 16, v98
	v_add3_u32 v99, v134, v99, s24
	v_and_or_b32 v132, v99, s25, v98
	v_bfe_u32 v98, v135, 16, 1
	v_add3_u32 v98, v135, v98, s24
	v_bfe_u32 v99, v136, 16, 1
	v_lshrrev_b32_e32 v98, 16, v98
	v_add3_u32 v99, v136, v99, s24
	v_and_or_b32 v133, v99, s25, v98
	v_add_u32_e32 v98, 8, v85
	v_mad_i64_i32 v[98:99], s[0:1], v98, v2, 0
	v_lshl_add_u64 v[98:99], v[98:99], 1, v[6:7]
	global_store_dwordx4 v[98:99], v[130:133], off nt
	ds_read_b32 v98, v102 offset:64
	ds_read_b32 v99, v102 offset:324
	ds_read_b32 v131, v102 offset:584
	ds_read_b32 v132, v102 offset:844
	ds_read_b32 v133, v102 offset:1104
	ds_read_b32 v134, v102 offset:1364
	ds_read_b32 v135, v102 offset:1624
	ds_read_b32 v136, v102 offset:1884
	s_waitcnt lgkmcnt(0)
	v_bfe_u32 v130, v98, 16, 1
	v_add3_u32 v98, v98, v130, s24
	v_bfe_u32 v130, v99, 16, 1
	v_lshrrev_b32_e32 v98, 16, v98
	v_add3_u32 v99, v99, v130, s24
	v_and_or_b32 v130, v99, s25, v98
	v_bfe_u32 v98, v131, 16, 1
	v_add3_u32 v98, v131, v98, s24
	v_bfe_u32 v99, v132, 16, 1
	v_lshrrev_b32_e32 v98, 16, v98
	v_add3_u32 v99, v132, v99, s24
	v_and_or_b32 v131, v99, s25, v98
	v_bfe_u32 v98, v133, 16, 1
	v_add3_u32 v98, v133, v98, s24
	v_bfe_u32 v99, v134, 16, 1
	v_lshrrev_b32_e32 v98, 16, v98
	v_add3_u32 v99, v134, v99, s24
	v_and_or_b32 v132, v99, s25, v98
	v_bfe_u32 v98, v135, 16, 1
	v_add3_u32 v98, v135, v98, s24
	v_bfe_u32 v99, v136, 16, 1
	v_lshrrev_b32_e32 v98, 16, v98
	v_add3_u32 v99, v136, v99, s24
	v_and_or_b32 v133, v99, s25, v98
	v_add_u32_e32 v98, 16, v85
	v_mad_i64_i32 v[98:99], s[0:1], v98, v2, 0
	v_lshl_add_u64 v[98:99], v[98:99], 1, v[6:7]
	global_store_dwordx4 v[98:99], v[130:133], off nt
	ds_read_b32 v98, v102 offset:96
	ds_read_b32 v99, v102 offset:356
	ds_read_b32 v131, v102 offset:616
	ds_read_b32 v132, v102 offset:876
	ds_read_b32 v133, v102 offset:1136
	ds_read_b32 v134, v102 offset:1396
	ds_read_b32 v135, v102 offset:1656
	ds_read_b32 v136, v102 offset:1916
	s_waitcnt lgkmcnt(0)
	v_bfe_u32 v130, v98, 16, 1
	v_add3_u32 v98, v98, v130, s24
	v_bfe_u32 v130, v99, 16, 1
	v_lshrrev_b32_e32 v98, 16, v98
	v_add3_u32 v99, v99, v130, s24
	v_and_or_b32 v130, v99, s25, v98
	v_bfe_u32 v98, v131, 16, 1
	v_add3_u32 v98, v131, v98, s24
	v_bfe_u32 v99, v132, 16, 1
	v_lshrrev_b32_e32 v98, 16, v98
	v_add3_u32 v99, v132, v99, s24
	v_and_or_b32 v131, v99, s25, v98
	v_bfe_u32 v98, v133, 16, 1
	v_add3_u32 v98, v133, v98, s24
	v_bfe_u32 v99, v134, 16, 1
	v_lshrrev_b32_e32 v98, 16, v98
	v_add3_u32 v99, v134, v99, s24
	v_and_or_b32 v132, v99, s25, v98
	v_bfe_u32 v98, v135, 16, 1
	v_add3_u32 v98, v135, v98, s24
	v_bfe_u32 v99, v136, 16, 1
	v_lshrrev_b32_e32 v98, 16, v98
	v_add3_u32 v99, v136, v99, s24
	v_and_or_b32 v133, v99, s25, v98
	v_add_u32_e32 v98, 24, v85
	v_mad_i64_i32 v[98:99], s[0:1], v98, v2, 0
	v_lshl_add_u64 v[98:99], v[98:99], 1, v[6:7]
	global_store_dwordx4 v[98:99], v[130:133], off nt
	ds_read_b32 v98, v102 offset:128
	ds_read_b32 v99, v102 offset:388
	ds_read_b32 v131, v102 offset:648
	ds_read_b32 v132, v102 offset:908
	ds_read_b32 v133, v102 offset:1168
	ds_read_b32 v134, v102 offset:1428
	ds_read_b32 v135, v102 offset:1688
	ds_read_b32 v136, v102 offset:1948
	s_waitcnt lgkmcnt(0)
; #define LAS __attribute__((address_space(3)))
; __device__ __forceinline__ unsigned pk2(float lo, float hi) { return f2bf(lo) | (f2bf(hi) << 16); }
; __device__ __forceinline__ void item_store(const ItemPos p, LAS float* scr, int lane) {
;     const int c = lane & 7;
; #pragma unroll
;     for (int j = 0; j < 8; ++j) { const int n = (lane >> 3) + 8 * j; const LAS float* s = scr + (8 * c) * 65 + n;
;         u32x4 o; o.x = pk2(s[0 * 65], s[1 * 65]); o.y = pk2(s[2 * 65], s[3 * 65]); o.z = pk2(s[4 * 65], s[5 * 65]); o.w = pk2(s[6 * 65], s[7 * 65]);
;         __builtin_nontemporal_store(o, (u32x4*)(p.WT + (size_t)(p.rb + n) * p.K + p.k0 + 8 * c)); }
;     asm volatile("s_waitcnt lgkmcnt(0)" ::: "memory");
; }
; __device__ __forceinline__ void convert_range(unsigned char* lds, int lo, int hi, int w, int nworkers, int wave, int lane) {
;     ...
;     for (;;) {
;         item_to_lds(v, gv, p.scaled, scr, lane);
;         const int nx = it + nworkers; const bool more = nx < hi; ItemPos pn = p;
;         if (more) pn = item_load(tab, nx, lane, v, gv);
;         item_store(p, scr, lane);
;         if (!more) break;
;         it = nx; p = pn;
;     }
	v_bfe_u32 v130, v98, 16, 1
	v_add3_u32 v98, v98, v130, s24
	v_bfe_u32 v130, v99, 16, 1
	v_lshrrev_b32_e32 v98, 16, v98
	v_add3_u32 v99, v99, v130, s24
	v_and_or_b32 v130, v99, s25, v98
	v_bfe_u32 v98, v131, 16, 1
	v_add3_u32 v98, v131, v98, s24
	v_bfe_u32 v99, v132, 16, 1
	v_lshrrev_b32_e32 v98, 16, v98
	v_add3_u32 v99, v132, v99, s24
	v_and_or_b32 v131, v99, s25, v98
	v_bfe_u32 v98, v133, 16, 1
	v_add3_u32 v98, v133, v98, s24
	v_bfe_u32 v99, v134, 16, 1
	v_lshrrev_b32_e32 v98, 16, v98
	v_add3_u32 v99, v134, v99, s24
	v_and_or_b32 v132, v99, s25, v98
	v_bfe_u32 v98, v135, 16, 1
	v_add3_u32 v98, v135, v98, s24
	v_bfe_u32 v99, v136, 16, 1
	v_lshrrev_b32_e32 v98, 16, v98
	v_add3_u32 v99, v136, v99, s24
	v_and_or_b32 v133, v99, s25, v98
	v_add_u32_e32 v98, 32, v85
	v_mad_i64_i32 v[98:99], s[0:1], v98, v2, 0
	v_lshl_add_u64 v[98:99], v[98:99], 1, v[6:7]
	global_store_dwordx4 v[98:99], v[130:133], off nt
	ds_read_b32 v98, v102 offset:160
	ds_read_b32 v99, v102 offset:420
	ds_read_b32 v131, v102 offset:680
	ds_read_b32 v132, v102 offset:940
	ds_read_b32 v133, v102 offset:1200
	ds_read_b32 v134, v102 offset:1460
	ds_read_b32 v135, v102 offset:1720
	ds_read_b32 v136, v102 offset:1980
	s_waitcnt lgkmcnt(0)
	v_bfe_u32 v130, v98, 16, 1
	v_add3_u32 v98, v98, v130, s24
	v_bfe_u32 v130, v99, 16, 1
	v_lshrrev_b32_e32 v98, 16, v98
	v_add3_u32 v99, v99, v130, s24
	v_and_or_b32 v130, v99, s25, v98
	v_bfe_u32 v98, v131, 16, 1
	v_add3_u32 v98, v131, v98, s24
	v_bfe_u32 v99, v132, 16, 1
	v_lshrrev_b32_e32 v98, 16, v98
	v_add3_u32 v99, v132, v99, s24
	v_and_or_b32 v131, v99, s25, v98
	v_bfe_u32 v98, v133, 16, 1
	v_add3_u32 v98, v133, v98, s24
	v_bfe_u32 v99, v134, 16, 1
	v_lshrrev_b32_e32 v98, 16, v98
	v_add3_u32 v99, v134, v99, s24
	v_and_or_b32 v132, v99, s25, v98
	v_bfe_u32 v98, v135, 16, 1
	v_add3_u32 v98, v135, v98, s24
	v_bfe_u32 v99, v136, 16, 1
	v_lshrrev_b32_e32 v98, 16, v98
	v_add3_u32 v99, v136, v99, s24
	v_and_or_b32 v133, v99, s25, v98
	v_add_u32_e32 v98, 40, v85
	v_mad_i64_i32 v[98:99], s[0:1], v98, v2, 0
	v_lshl_add_u64 v[98:99], v[98:99], 1, v[6:7]
	global_store_dwordx4 v[98:99], v[130:133], off nt
	ds_read_b32 v98, v102 offset:192
	ds_read_b32 v99, v102 offset:452
	ds_read_b32 v131, v102 offset:712
	ds_read_b32 v132, v102 offset:972
	ds_read_b32 v133, v102 offset:1232
	ds_read_b32 v134, v102 offset:1492
	ds_read_b32 v135, v102 offset:1752
	ds_read_b32 v136, v102 offset:2012
	s_waitcnt lgkmcnt(0)
	v_bfe_u32 v130, v98, 16, 1
	v_add3_u32 v98, v98, v130, s24
	v_bfe_u32 v130, v99, 16, 1
	v_lshrrev_b32_e32 v98, 16, v98
	v_add3_u32 v99, v99, v130, s24
	v_and_or_b32 v130, v99, s25, v98
	v_bfe_u32 v98, v131, 16, 1
	v_add3_u32 v98, v131, v98, s24
	v_bfe_u32 v99, v132, 16, 1
	v_lshrrev_b32_e32 v98, 16, v98
	v_add3_u32 v99, v132, v99, s24
	v_and_or_b32 v131, v99, s25, v98
	v_bfe_u32 v98, v133, 16, 1
	v_add3_u32 v98, v133, v98, s24
	v_bfe_u32 v99, v134, 16, 1
	v_lshrrev_b32_e32 v98, 16, v98
	v_add3_u32 v99, v134, v99, s24
	v_and_or_b32 v132, v99, s25, v98
	v_bfe_u32 v98, v135, 16, 1
	v_add3_u32 v98, v135, v98, s24
	v_bfe_u32 v99, v136, 16, 1
	v_lshrrev_b32_e32 v98, 16, v98
	v_add3_u32 v99, v136, v99, s24
	v_and_or_b32 v133, v99, s25, v98
	v_add_u32_e32 v98, 48, v85
	v_mad_i64_i32 v[98:99], s[0:1], v98, v2, 0
	v_lshl_add_u64 v[98:99], v[98:99], 1, v[6:7]
	global_store_dwordx4 v[98:99], v[130:133], off nt
	ds_read_b32 v98, v102 offset:224
	ds_read_b32 v99, v102 offset:484
	ds_read_b32 v131, v102 offset:744
	ds_read_b32 v132, v102 offset:1004
	ds_read_b32 v133, v102 offset:1264
	ds_read_b32 v134, v102 offset:1524
	ds_read_b32 v135, v102 offset:1784
	ds_read_b32 v136, v102 offset:2044
	s_waitcnt lgkmcnt(0)
	v_bfe_u32 v130, v98, 16, 1
	v_add3_u32 v98, v98, v130, s24
	v_bfe_u32 v130, v99, 16, 1
	v_lshrrev_b32_e32 v98, 16, v98
	v_add3_u32 v99, v99, v130, s24
	v_and_or_b32 v130, v99, s25, v98
	v_bfe_u32 v98, v131, 16, 1
	v_add3_u32 v98, v131, v98, s24
	v_bfe_u32 v99, v132, 16, 1
	v_lshrrev_b32_e32 v98, 16, v98
	v_add3_u32 v99, v132, v99, s24
	v_and_or_b32 v131, v99, s25, v98
	v_bfe_u32 v98, v133, 16, 1
	v_add3_u32 v98, v133, v98, s24
	v_bfe_u32 v99, v134, 16, 1
	v_lshrrev_b32_e32 v98, 16, v98
	v_add3_u32 v99, v134, v99, s24
	v_and_or_b32 v132, v99, s25, v98
	v_bfe_u32 v98, v135, 16, 1
	v_add3_u32 v98, v135, v98, s24
	v_bfe_u32 v99, v136, 16, 1
	v_lshrrev_b32_e32 v98, 16, v98
	v_add3_u32 v99, v136, v99, s24
	v_add_u32_e32 v85, 56, v85
	v_and_or_b32 v133, v99, s25, v98
	v_mad_i64_i32 v[98:99], s[0:1], v85, v2, 0
	v_lshl_add_u64 v[6:7], v[98:99], 1, v[6:7]
	global_store_dwordx4 v[6:7], v[130:133], off nt
	s_waitcnt lgkmcnt(0)
	s_andn2_b64 vcc, exec, s[14:15]
	s_cbranch_vccnz .LBB0_47
	v_mov_b64_e32 v[8:9], v[74:75]
	v_mov_b32_e32 v2, v4
	v_mov_b32_e32 v3, v5
	s_mov_b32 s18, s28
	s_mov_b32 s26, s27
	s_branch .LBB0_47

; __device__ __forceinline__ ItemPos item_load(const XItem* tab, int it, int lane, f32x4 (&v)[16], float (&gv)[16]) {
;     int e = 0;
; #pragma unroll 1
;     for (int q = 1; q < 20; ++q) if (it >= tab[q].start) e = q;
;     const XItem x = tab[e]; const int item = it - x.start;
;     const int nblk = x.N >> 6, kb = item / nblk, nb = item - kb * nblk, k0 = kb << 6, n0 = nb << 6;
;     const int lr = lane >> 4, lc = (lane & 15) * 4;
;     const float* W = x.src + (size_t)(k0 + lr) * x.N + n0 + lc; const size_t rstep = (size_t)4 * x.N;
; #pragma unroll
;     for (int i = 0; i < 16; ++i) v[i] = __builtin_nontemporal_load((const f32x4*)(W + i * rstep));
; #pragma unroll
;     for (int i = 0; i < 16; ++i) gv[i] = x.g ? x.g[k0 + 4 * i + lr] : 1.0f;
.LBB0_92:
	v_mov_b32_e32 v3, s0
	ds_read_b32 v3, v3
	v_mov_b32_e32 v4, s1
	s_add_i32 s1, s1, 1
	s_add_i32 s0, s0, 40
	s_cmp_eq_u32 s1, 20
	s_waitcnt lgkmcnt(0)
	v_cmp_lt_i32_e32 vcc, s20, v3
	s_nop 1
	v_cndmask_b32_e32 v2, v4, v2, vcc
	s_cbranch_scc0 .LBB0_92
	v_mul_lo_u32 v2, v2, 40
	v_add_u32_e32 v2, 0, v2
	s_waitcnt vmcnt(0)
	v_add_u32_e32 v10, 0x20800, v2
	ds_read2_b64 v[2:5], v10 offset0:3 offset1:4
	ds_read2_b64 v[6:9], v10 offset1:1
	ds_read_b64 v[74:75], v10 offset:16
	v_ashrrev_i32_e32 v77, 4, v100
	v_lshlrev_b32_e32 v11, 2, v100
	v_mov_b32_e32 v79, 0
	s_waitcnt lgkmcnt(2)
	v_readfirstlane_b32 s2, v3
	s_ashr_i32 s0, s2, 6
	s_abs_i32 s1, s0
	v_cvt_f32_u32_e32 v3, s1
	s_sub_i32 s6, 0, s1
	v_readfirstlane_b32 s3, v5
	s_sub_i32 s3, s20, s3
	v_rcp_iflag_f32_e32 v3, v3
	s_abs_i32 s5, s3
	s_xor_b32 s4, s3, s0
	s_ashr_i32 s4, s4, 31
	v_mul_f32_e32 v3, 0x4f7ffffe, v3
	v_cvt_u32_f32_e32 v3, v3
	v_and_b32_e32 v5, 60, v11
	v_lshlrev_b32_e32 v78, 2, v5
	v_readfirstlane_b32 s7, v3
	s_mul_i32 s6, s6, s7
	s_mul_hi_u32 s6, s7, s6
	s_add_i32 s7, s7, s6
	s_mul_hi_u32 s6, s5, s7
	s_mul_i32 s7, s6, s1
	s_sub_i32 s5, s5, s7
	s_add_i32 s14, s6, 1
	s_sub_i32 s7, s5, s1
	s_cmp_ge_u32 s5, s1
	s_cselect_b32 s6, s14, s6
	s_cselect_b32 s5, s7, s5
	s_add_i32 s7, s6, 1
	s_cmp_ge_u32 s5, s1
	s_cselect_b32 s1, s7, s6
	s_xor_b32 s1, s1, s4
	s_sub_i32 s1, s1, s4
	s_mul_i32 s0, s1, s0
	s_lshl_b32 s18, s1, 6
	s_sub_i32 s14, s3, s0
	v_add_u32_e32 v80, s18, v77
	s_lshl_b32 s0, s14, 6
	v_mad_i64_i32 v[10:11], s[4:5], v80, s2, 0
	s_waitcnt lgkmcnt(1)
	v_lshl_add_u64 v[6:7], v[10:11], 2, v[6:7]
	s_ashr_i32 s1, s0, 31
	s_ashr_i32 s3, s2, 31
	v_lshl_add_u64 v[6:7], s[0:1], 2, v[6:7]
	v_lshl_add_u64 v[6:7], v[6:7], 0, v[78:79]
	s_lshl_b64 s[2:3], s[2:3], 4
	v_lshl_add_u64 v[18:19], v[6:7], 0, s[2:3]
	global_load_dwordx4 v[10:13], v[6:7], off nt
	global_load_dwordx4 v[14:17], v[18:19], off nt
	v_lshl_add_u64 v[6:7], v[18:19], 0, s[2:3]
	v_lshl_add_u64 v[26:27], v[6:7], 0, s[2:3]
	global_load_dwordx4 v[18:21], v[6:7], off nt
	global_load_dwordx4 v[22:25], v[26:27], off nt
	v_lshl_add_u64 v[6:7], v[26:27], 0, s[2:3]
	v_lshl_add_u64 v[34:35], v[6:7], 0, s[2:3]
	global_load_dwordx4 v[26:29], v[6:7], off nt
	global_load_dwordx4 v[30:33], v[34:35], off nt
	v_lshl_add_u64 v[6:7], v[34:35], 0, s[2:3]
	v_lshl_add_u64 v[42:43], v[6:7], 0, s[2:3]
	global_load_dwordx4 v[34:37], v[6:7], off nt
	global_load_dwordx4 v[38:41], v[42:43], off nt
	v_lshl_add_u64 v[6:7], v[42:43], 0, s[2:3]
	global_load_dwordx4 v[42:45], v[6:7], off nt
	v_lshl_add_u64 v[6:7], v[6:7], 0, s[2:3]
	global_load_dwordx4 v[46:49], v[6:7], off nt
	v_lshl_add_u64 v[6:7], v[6:7], 0, s[2:3]
	global_load_dwordx4 v[50:53], v[6:7], off nt
	v_lshl_add_u64 v[6:7], v[6:7], 0, s[2:3]
	global_load_dwordx4 v[54:57], v[6:7], off nt
	v_lshl_add_u64 v[6:7], v[6:7], 0, s[2:3]
	global_load_dwordx4 v[58:61], v[6:7], off nt
	v_lshl_add_u64 v[6:7], v[6:7], 0, s[2:3]
	global_load_dwordx4 v[62:65], v[6:7], off nt
	v_lshl_add_u64 v[6:7], v[6:7], 0, s[2:3]
	global_load_dwordx4 v[66:69], v[6:7], off nt
	v_lshl_add_u64 v[6:7], v[6:7], 0, s[2:3]
	global_load_dwordx4 v[70:73], v[6:7], off nt
	v_ashrrev_i32_e32 v81, 31, v80
	s_waitcnt lgkmcnt(0)
	v_cmp_ne_u64_e64 s[6:7], 0, v[74:75]
	s_and_b64 vcc, exec, s[6:7]
	v_lshl_add_u64 v[6:7], v[80:81], 2, v[74:75]
	s_cbranch_vccnz .LBB0_94
	s_getpc_b64 s[98:99]

; #define LAS __attribute__((address_space(3)))
; __device__ __forceinline__ unsigned f2bf(float f) { unsigned u = __builtin_bit_cast(unsigned, f); return (u + 0x7fffu + ((u >> 16) & 1u)) >> 16; }
; __device__ __forceinline__ unsigned pk2(float lo, float hi) { return f2bf(lo) | (f2bf(hi) << 16); }
; __device__ __forceinline__ void item_store(const ItemPos p, LAS float* scr, int lane) {
;     const int c = lane & 7;
; #pragma unroll
;     for (int j = 0; j < 8; ++j) { const int n = (lane >> 3) + 8 * j; const LAS float* s = scr + (8 * c) * 65 + n;
;         u32x4 o; o.x = pk2(s[0 * 65], s[1 * 65]); o.y = pk2(s[2 * 65], s[3 * 65]); o.z = pk2(s[4 * 65], s[5 * 65]); o.w = pk2(s[6 * 65], s[7 * 65]);
;         __builtin_nontemporal_store(o, (u32x4*)(p.WT + (size_t)(p.rb + n) * p.K + p.k0 + 8 * c)); }
;     asm volatile("s_waitcnt lgkmcnt(0)" ::: "memory");
; }
.LBB0_147:
	s_ashr_i32 s19, s18, 31
	s_lshl_b64 s[0:1], s[18:19], 1
	v_lshl_add_u64 v[6:7], v[8:9], 0, s[0:1]
	v_mov_b32_e32 v85, v79
	v_lshl_add_u64 v[6:7], v[6:7], 0, v[84:85]
	ds_read_b32 v85, v102
	ds_read_b32 v98, v102 offset:260
	ds_read_b32 v99, v102 offset:520
	ds_read_b32 v131, v102 offset:780
	ds_read_b32 v132, v102 offset:1040
	ds_read_b32 v133, v102 offset:1300
	ds_read_b32 v134, v102 offset:1560
	ds_read_b32 v135, v102 offset:1820
	s_waitcnt lgkmcnt(0)
	v_bfe_u32 v130, v85, 16, 1
	v_add3_u32 v85, v85, v130, s25
	v_bfe_u32 v130, v98, 16, 1
	v_lshrrev_b32_e32 v85, 16, v85
	v_add3_u32 v98, v98, v130, s25
	v_and_or_b32 v130, v98, s26, v85
	v_bfe_u32 v85, v99, 16, 1
	v_add3_u32 v85, v99, v85, s25
	v_bfe_u32 v98, v131, 16, 1
	v_lshrrev_b32_e32 v85, 16, v85
	v_add3_u32 v98, v131, v98, s25
	v_and_or_b32 v131, v98, s26, v85
	v_bfe_u32 v85, v132, 16, 1
	v_add3_u32 v85, v132, v85, s25
	v_bfe_u32 v98, v133, 16, 1
	v_lshrrev_b32_e32 v85, 16, v85
	v_add3_u32 v98, v133, v98, s25
	v_and_or_b32 v132, v98, s26, v85
	v_bfe_u32 v85, v134, 16, 1
	v_add3_u32 v85, v134, v85, s25
	v_bfe_u32 v98, v135, 16, 1
	v_lshrrev_b32_e32 v85, 16, v85
	v_add3_u32 v98, v135, v98, s25
	v_and_or_b32 v133, v98, s26, v85
	v_add_u32_e32 v85, v3, v101
	v_mad_i64_i32 v[98:99], s[0:1], v85, v2, 0
	v_lshl_add_u64 v[98:99], v[98:99], 1, v[6:7]
	global_store_dwordx4 v[98:99], v[130:133], off nt
	ds_read_b32 v98, v102 offset:32
	ds_read_b32 v99, v102 offset:292
	ds_read_b32 v131, v102 offset:552
	ds_read_b32 v132, v102 offset:812
	ds_read_b32 v133, v102 offset:1072
	ds_read_b32 v134, v102 offset:1332
	ds_read_b32 v135, v102 offset:1592
	ds_read_b32 v136, v102 offset:1852
	s_waitcnt lgkmcnt(0)
	v_bfe_u32 v130, v98, 16, 1
	v_add3_u32 v98, v98, v130, s25
	v_bfe_u32 v130, v99, 16, 1
	v_lshrrev_b32_e32 v98, 16, v98
	v_add3_u32 v99, v99, v130, s25
	v_and_or_b32 v130, v99, s26, v98
	v_bfe_u32 v98, v131, 16, 1
	v_add3_u32 v98, v131, v98, s25
	v_bfe_u32 v99, v132, 16, 1
	v_lshrrev_b32_e32 v98, 16, v98
	v_add3_u32 v99, v132, v99, s25
	v_and_or_b32 v131, v99, s26, v98
	v_bfe_u32 v98, v133, 16, 1
	v_add3_u32 v98, v133, v98, s25
	v_bfe_u32 v99, v134, 16, 1
	v_lshrrev_b32_e32 v98, 16, v98
	v_add3_u32 v99, v134, v99, s25
	v_and_or_b32 v132, v99, s26, v98
	v_bfe_u32 v98, v135, 16, 1
	v_add3_u32 v98, v135, v98, s25
	v_bfe_u32 v99, v136, 16, 1
	v_lshrrev_b32_e32 v98, 16, v98
	v_add3_u32 v99, v136, v99, s25
	v_and_or_b32 v133, v99, s26, v98
	v_add_u32_e32 v98, 8, v85
	v_mad_i64_i32 v[98:99], s[0:1], v98, v2, 0
	v_lshl_add_u64 v[98:99], v[98:99], 1, v[6:7]
	global_store_dwordx4 v[98:99], v[130:133], off nt
	ds_read_b32 v98, v102 offset:64
	ds_read_b32 v99, v102 offset:324
	ds_read_b32 v131, v102 offset:584
	ds_read_b32 v132, v102 offset:844
	ds_read_b32 v133, v102 offset:1104
	ds_read_b32 v134, v102 offset:1364
	ds_read_b32 v135, v102 offset:1624
	ds_read_b32 v136, v102 offset:1884
	s_waitcnt lgkmcnt(0)
	v_bfe_u32 v130, v98, 16, 1
	v_add3_u32 v98, v98, v130, s25
	v_bfe_u32 v130, v99, 16, 1
	v_lshrrev_b32_e32 v98, 16, v98
	v_add3_u32 v99, v99, v130, s25
	v_and_or_b32 v130, v99, s26, v98
	v_bfe_u32 v98, v131, 16, 1
	v_add3_u32 v98, v131, v98, s25
	v_bfe_u32 v99, v132, 16, 1
	v_lshrrev_b32_e32 v98, 16, v98
	v_add3_u32 v99, v132, v99, s25
	v_and_or_b32 v131, v99, s26, v98
	v_bfe_u32 v98, v133, 16, 1
	v_add3_u32 v98, v133, v98, s25
	v_bfe_u32 v99, v134, 16, 1
	v_lshrrev_b32_e32 v98, 16, v98
	v_add3_u32 v99, v134, v99, s25
	v_and_or_b32 v132, v99, s26, v98
	v_bfe_u32 v98, v135, 16, 1
	v_add3_u32 v98, v135, v98, s25
	v_bfe_u32 v99, v136, 16, 1
	v_lshrrev_b32_e32 v98, 16, v98
	v_add3_u32 v99, v136, v99, s25
	v_and_or_b32 v133, v99, s26, v98
	v_add_u32_e32 v98, 16, v85
	v_mad_i64_i32 v[98:99], s[0:1], v98, v2, 0
	v_lshl_add_u64 v[98:99], v[98:99], 1, v[6:7]
	global_store_dwordx4 v[98:99], v[130:133], off nt
	ds_read_b32 v98, v102 offset:96
	ds_read_b32 v99, v102 offset:356
	ds_read_b32 v131, v102 offset:616
	ds_read_b32 v132, v102 offset:876
	ds_read_b32 v133, v102 offset:1136
	ds_read_b32 v134, v102 offset:1396
	ds_read_b32 v135, v102 offset:1656
	ds_read_b32 v136, v102 offset:1916
	s_waitcnt lgkmcnt(0)
	v_bfe_u32 v130, v98, 16, 1
	v_add3_u32 v98, v98, v130, s25
	v_bfe_u32 v130, v99, 16, 1
	v_lshrrev_b32_e32 v98, 16, v98
	v_add3_u32 v99, v99, v130, s25
	v_and_or_b32 v130, v99, s26, v98
	v_bfe_u32 v98, v131, 16, 1
	v_add3_u32 v98, v131, v98, s25
	v_bfe_u32 v99, v132, 16, 1
	v_lshrrev_b32_e32 v98, 16, v98
	v_add3_u32 v99, v132, v99, s25
	v_and_or_b32 v131, v99, s26, v98
	v_bfe_u32 v98, v133, 16, 1
	v_add3_u32 v98, v133, v98, s25
	v_bfe_u32 v99, v134, 16, 1
	v_lshrrev_b32_e32 v98, 16, v98
	v_add3_u32 v99, v134, v99, s25
	v_and_or_b32 v132, v99, s26, v98
	v_bfe_u32 v98, v135, 16, 1
	v_add3_u32 v98, v135, v98, s25
	v_bfe_u32 v99, v136, 16, 1
	v_lshrrev_b32_e32 v98, 16, v98
	v_add3_u32 v99, v136, v99, s25
	v_and_or_b32 v133, v99, s26, v98
	v_add_u32_e32 v98, 24, v85
	v_mad_i64_i32 v[98:99], s[0:1], v98, v2, 0
	v_lshl_add_u64 v[98:99], v[98:99], 1, v[6:7]
	global_store_dwordx4 v[98:99], v[130:133], off nt
	ds_read_b32 v98, v102 offset:128
	ds_read_b32 v99, v102 offset:388
	ds_read_b32 v131, v102 offset:648
	ds_read_b32 v132, v102 offset:908
	ds_read_b32 v133, v102 offset:1168
	ds_read_b32 v134, v102 offset:1428
	ds_read_b32 v135, v102 offset:1688
	ds_read_b32 v136, v102 offset:1948
	s_waitcnt lgkmcnt(0)
; #define LAS __attribute__((address_space(3)))
; __device__ __forceinline__ unsigned pk2(float lo, float hi) { return f2bf(lo) | (f2bf(hi) << 16); }
; __device__ __forceinline__ void item_store(const ItemPos p, LAS float* scr, int lane) {
;     const int c = lane & 7;
; #pragma unroll
;     for (int j = 0; j < 8; ++j) { const int n = (lane >> 3) + 8 * j; const LAS float* s = scr + (8 * c) * 65 + n;
;         u32x4 o; o.x = pk2(s[0 * 65], s[1 * 65]); o.y = pk2(s[2 * 65], s[3 * 65]); o.z = pk2(s[4 * 65], s[5 * 65]); o.w = pk2(s[6 * 65], s[7 * 65]);
;         __builtin_nontemporal_store(o, (u32x4*)(p.WT + (size_t)(p.rb + n) * p.K + p.k0 + 8 * c)); }
;     asm volatile("s_waitcnt lgkmcnt(0)" ::: "memory");
; }
; __device__ __forceinline__ void convert_range(unsigned char* lds, int lo, int hi, int w, int nworkers, int wave, int lane) {
;     ...
;         const int nx = it + nworkers; const bool more = nx < hi; ItemPos pn = p;
;         if (more) pn = item_load(tab, nx, lane, v, gv);
;         item_store(p, scr, lane);
;         if (!more) break;
;         it = nx; p = pn;
	v_bfe_u32 v130, v98, 16, 1
	v_add3_u32 v98, v98, v130, s25
	v_bfe_u32 v130, v99, 16, 1
	v_lshrrev_b32_e32 v98, 16, v98
	v_add3_u32 v99, v99, v130, s25
	v_and_or_b32 v130, v99, s26, v98
	v_bfe_u32 v98, v131, 16, 1
	v_add3_u32 v98, v131, v98, s25
	v_bfe_u32 v99, v132, 16, 1
	v_lshrrev_b32_e32 v98, 16, v98
	v_add3_u32 v99, v132, v99, s25
	v_and_or_b32 v131, v99, s26, v98
	v_bfe_u32 v98, v133, 16, 1
	v_add3_u32 v98, v133, v98, s25
	v_bfe_u32 v99, v134, 16, 1
	v_lshrrev_b32_e32 v98, 16, v98
	v_add3_u32 v99, v134, v99, s25
	v_and_or_b32 v132, v99, s26, v98
	v_bfe_u32 v98, v135, 16, 1
	v_add3_u32 v98, v135, v98, s25
	v_bfe_u32 v99, v136, 16, 1
	v_lshrrev_b32_e32 v98, 16, v98
	v_add3_u32 v99, v136, v99, s25
	v_and_or_b32 v133, v99, s26, v98
	v_add_u32_e32 v98, 32, v85
	v_mad_i64_i32 v[98:99], s[0:1], v98, v2, 0
	v_lshl_add_u64 v[98:99], v[98:99], 1, v[6:7]
	global_store_dwordx4 v[98:99], v[130:133], off nt
	ds_read_b32 v98, v102 offset:160
	ds_read_b32 v99, v102 offset:420
	ds_read_b32 v131, v102 offset:680
	ds_read_b32 v132, v102 offset:940
	ds_read_b32 v133, v102 offset:1200
	ds_read_b32 v134, v102 offset:1460
	ds_read_b32 v135, v102 offset:1720
	ds_read_b32 v136, v102 offset:1980
	s_waitcnt lgkmcnt(0)
	v_bfe_u32 v130, v98, 16, 1
	v_add3_u32 v98, v98, v130, s25
	v_bfe_u32 v130, v99, 16, 1
	v_lshrrev_b32_e32 v98, 16, v98
	v_add3_u32 v99, v99, v130, s25
	v_and_or_b32 v130, v99, s26, v98
	v_bfe_u32 v98, v131, 16, 1
	v_add3_u32 v98, v131, v98, s25
	v_bfe_u32 v99, v132, 16, 1
	v_lshrrev_b32_e32 v98, 16, v98
	v_add3_u32 v99, v132, v99, s25
	v_and_or_b32 v131, v99, s26, v98
	v_bfe_u32 v98, v133, 16, 1
	v_add3_u32 v98, v133, v98, s25
	v_bfe_u32 v99, v134, 16, 1
	v_lshrrev_b32_e32 v98, 16, v98
	v_add3_u32 v99, v134, v99, s25
	v_and_or_b32 v132, v99, s26, v98
	v_bfe_u32 v98, v135, 16, 1
	v_add3_u32 v98, v135, v98, s25
	v_bfe_u32 v99, v136, 16, 1
	v_lshrrev_b32_e32 v98, 16, v98
	v_add3_u32 v99, v136, v99, s25
	v_and_or_b32 v133, v99, s26, v98
	v_add_u32_e32 v98, 40, v85
	v_mad_i64_i32 v[98:99], s[0:1], v98, v2, 0
	v_lshl_add_u64 v[98:99], v[98:99], 1, v[6:7]
	global_store_dwordx4 v[98:99], v[130:133], off nt
	ds_read_b32 v98, v102 offset:192
	ds_read_b32 v99, v102 offset:452
	ds_read_b32 v131, v102 offset:712
	ds_read_b32 v132, v102 offset:972
	ds_read_b32 v133, v102 offset:1232
	ds_read_b32 v134, v102 offset:1492
	ds_read_b32 v135, v102 offset:1752
	ds_read_b32 v136, v102 offset:2012
	s_waitcnt lgkmcnt(0)
	v_bfe_u32 v130, v98, 16, 1
	v_add3_u32 v98, v98, v130, s25
	v_bfe_u32 v130, v99, 16, 1
	v_lshrrev_b32_e32 v98, 16, v98
	v_add3_u32 v99, v99, v130, s25
	v_and_or_b32 v130, v99, s26, v98
	v_bfe_u32 v98, v131, 16, 1
	v_add3_u32 v98, v131, v98, s25
	v_bfe_u32 v99, v132, 16, 1
	v_lshrrev_b32_e32 v98, 16, v98
	v_add3_u32 v99, v132, v99, s25
	v_and_or_b32 v131, v99, s26, v98
	v_bfe_u32 v98, v133, 16, 1
	v_add3_u32 v98, v133, v98, s25
	v_bfe_u32 v99, v134, 16, 1
	v_lshrrev_b32_e32 v98, 16, v98
	v_add3_u32 v99, v134, v99, s25
	v_and_or_b32 v132, v99, s26, v98
	v_bfe_u32 v98, v135, 16, 1
	v_add3_u32 v98, v135, v98, s25
	v_bfe_u32 v99, v136, 16, 1
	v_lshrrev_b32_e32 v98, 16, v98
	v_add3_u32 v99, v136, v99, s25
	v_and_or_b32 v133, v99, s26, v98
	v_add_u32_e32 v98, 48, v85
	v_mad_i64_i32 v[98:99], s[0:1], v98, v2, 0
	v_lshl_add_u64 v[98:99], v[98:99], 1, v[6:7]
	global_store_dwordx4 v[98:99], v[130:133], off nt
	ds_read_b32 v98, v102 offset:224
	ds_read_b32 v99, v102 offset:484
	ds_read_b32 v131, v102 offset:744
	ds_read_b32 v132, v102 offset:1004
	ds_read_b32 v133, v102 offset:1264
	ds_read_b32 v134, v102 offset:1524
	ds_read_b32 v135, v102 offset:1784
	ds_read_b32 v136, v102 offset:2044
	s_waitcnt lgkmcnt(0)
	v_bfe_u32 v130, v98, 16, 1
	v_add3_u32 v98, v98, v130, s25
	v_bfe_u32 v130, v99, 16, 1
	v_lshrrev_b32_e32 v98, 16, v98
	v_add3_u32 v99, v99, v130, s25
	v_and_or_b32 v130, v99, s26, v98
	v_bfe_u32 v98, v131, 16, 1
	v_add3_u32 v98, v131, v98, s25
	v_bfe_u32 v99, v132, 16, 1
	v_lshrrev_b32_e32 v98, 16, v98
	v_add3_u32 v99, v132, v99, s25
	v_and_or_b32 v131, v99, s26, v98
	v_bfe_u32 v98, v133, 16, 1
	v_add3_u32 v98, v133, v98, s25
	v_bfe_u32 v99, v134, 16, 1
	v_lshrrev_b32_e32 v98, 16, v98
	v_add3_u32 v99, v134, v99, s25
	v_and_or_b32 v132, v99, s26, v98
	v_bfe_u32 v98, v135, 16, 1
	v_add3_u32 v98, v135, v98, s25
	v_bfe_u32 v99, v136, 16, 1
	v_lshrrev_b32_e32 v98, 16, v98
	v_add3_u32 v99, v136, v99, s25
	v_add_u32_e32 v85, 56, v85
	v_and_or_b32 v133, v99, s26, v98
	v_mad_i64_i32 v[98:99], s[0:1], v85, v2, 0
	v_lshl_add_u64 v[6:7], v[98:99], 1, v[6:7]
	global_store_dwordx4 v[6:7], v[130:133], off nt
	s_waitcnt lgkmcnt(0)
	s_andn2_b64 vcc, exec, s[14:15]
	s_cbranch_vccnz .LBB0_116
	v_mov_b64_e32 v[8:9], v[74:75]
	v_mov_b32_e32 v2, v4
	v_mov_b32_e32 v3, v5
	s_mov_b32 s18, s28
	s_mov_b32 s20, s27
	s_branch .LBB0_116

; __device__ __forceinline__ ItemPos item_load(const XItem* tab, int it, int lane, f32x4 (&v)[16], float (&gv)[16]) {
;     int e = 0;
; #pragma unroll 1
;     for (int q = 1; q < 20; ++q) if (it >= tab[q].start) e = q;
;     const XItem x = tab[e]; const int item = it - x.start;
;     const int nblk = x.N >> 6, kb = item / nblk, nb = item - kb * nblk, k0 = kb << 6, n0 = nb << 6;
;     const int lr = lane >> 4, lc = (lane & 15) * 4;
;     const float* W = x.src + (size_t)(k0 + lr) * x.N + n0 + lc; const size_t rstep = (size_t)4 * x.N;
; #pragma unroll
;     for (int i = 0; i < 16; ++i) v[i] = __builtin_nontemporal_load((const f32x4*)(W + i * rstep));
; #pragma unroll
;     for (int i = 0; i < 16; ++i) gv[i] = x.g ? x.g[k0 + 4 * i + lr] : 1.0f;
;     ItemPos p; p.scaled = (x.g != nullptr); p.WT = x.dst; p.K = x.K; p.k0 = k0; p.rb = (x.mode == 0) ? n0 : ((n0 >> 7) * 256 + (x.mode - 1) * 128 + (n0 & 127));
;     return p;
.LBB0_161:
	v_mov_b32_e32 v3, s0
	ds_read_b32 v3, v3
	v_mov_b32_e32 v4, s1
	s_add_i32 s1, s1, 1
	s_add_i32 s0, s0, 40
	s_cmp_eq_u32 s1, 20
	s_waitcnt lgkmcnt(0)
	v_cmp_lt_i32_e32 vcc, s23, v3
	s_nop 1
	v_cndmask_b32_e32 v2, v4, v2, vcc
	s_cbranch_scc0 .LBB0_161
	v_mul_lo_u32 v2, v2, 40
	v_add_u32_e32 v2, 0, v2
	s_waitcnt vmcnt(0)
	v_add_u32_e32 v10, 0x20800, v2
	ds_read2_b64 v[2:5], v10 offset0:3 offset1:4
	ds_read2_b64 v[6:9], v10 offset1:1
	ds_read_b64 v[74:75], v10 offset:16
	v_ashrrev_i32_e32 v77, 4, v100
	v_lshlrev_b32_e32 v11, 2, v100
	v_mov_b32_e32 v79, 0
	s_waitcnt lgkmcnt(2)
	v_readfirstlane_b32 s2, v3
	s_ashr_i32 s0, s2, 6
	s_abs_i32 s1, s0
	v_cvt_f32_u32_e32 v3, s1
	s_sub_i32 s6, 0, s1
	v_readfirstlane_b32 s3, v5
	s_sub_i32 s3, s23, s3
	v_rcp_iflag_f32_e32 v3, v3
	s_abs_i32 s5, s3
	s_xor_b32 s4, s3, s0
	s_ashr_i32 s4, s4, 31
	v_mul_f32_e32 v3, 0x4f7ffffe, v3
	v_cvt_u32_f32_e32 v3, v3
	v_and_b32_e32 v5, 60, v11
	v_lshlrev_b32_e32 v78, 2, v5
	v_readfirstlane_b32 s7, v3
	s_mul_i32 s6, s6, s7
	s_mul_hi_u32 s6, s7, s6
	s_add_i32 s7, s7, s6
	s_mul_hi_u32 s6, s5, s7
	s_mul_i32 s7, s6, s1
	s_sub_i32 s5, s5, s7
	s_add_i32 s14, s6, 1
	s_sub_i32 s7, s5, s1
	s_cmp_ge_u32 s5, s1
	s_cselect_b32 s6, s14, s6
	s_cselect_b32 s5, s7, s5
	s_add_i32 s7, s6, 1
	s_cmp_ge_u32 s5, s1
	s_cselect_b32 s1, s7, s6
	s_xor_b32 s1, s1, s4
	s_sub_i32 s1, s1, s4
	s_mul_i32 s0, s1, s0
	s_lshl_b32 s20, s1, 6
	s_sub_i32 s14, s3, s0
	v_add_u32_e32 v80, s20, v77
	s_lshl_b32 s0, s14, 6
	v_mad_i64_i32 v[10:11], s[4:5], v80, s2, 0
	s_waitcnt lgkmcnt(1)
	v_lshl_add_u64 v[6:7], v[10:11], 2, v[6:7]
	s_ashr_i32 s1, s0, 31
	s_ashr_i32 s3, s2, 31
	v_lshl_add_u64 v[6:7], s[0:1], 2, v[6:7]
	v_lshl_add_u64 v[6:7], v[6:7], 0, v[78:79]
	s_lshl_b64 s[2:3], s[2:3], 4
	v_lshl_add_u64 v[18:19], v[6:7], 0, s[2:3]
	global_load_dwordx4 v[10:13], v[6:7], off nt
	global_load_dwordx4 v[14:17], v[18:19], off nt
	v_lshl_add_u64 v[6:7], v[18:19], 0, s[2:3]
	v_lshl_add_u64 v[26:27], v[6:7], 0, s[2:3]
	global_load_dwordx4 v[18:21], v[6:7], off nt
	global_load_dwordx4 v[22:25], v[26:27], off nt
	v_lshl_add_u64 v[6:7], v[26:27], 0, s[2:3]
	v_lshl_add_u64 v[34:35], v[6:7], 0, s[2:3]
	global_load_dwordx4 v[26:29], v[6:7], off nt
	global_load_dwordx4 v[30:33], v[34:35], off nt
	v_lshl_add_u64 v[6:7], v[34:35], 0, s[2:3]
	v_lshl_add_u64 v[42:43], v[6:7], 0, s[2:3]
	global_load_dwordx4 v[34:37], v[6:7], off nt
	global_load_dwordx4 v[38:41], v[42:43], off nt
	v_lshl_add_u64 v[6:7], v[42:43], 0, s[2:3]
	global_load_dwordx4 v[42:45], v[6:7], off nt
	v_lshl_add_u64 v[6:7], v[6:7], 0, s[2:3]
	global_load_dwordx4 v[46:49], v[6:7], off nt
	v_lshl_add_u64 v[6:7], v[6:7], 0, s[2:3]
	global_load_dwordx4 v[50:53], v[6:7], off nt
	v_lshl_add_u64 v[6:7], v[6:7], 0, s[2:3]
	global_load_dwordx4 v[54:57], v[6:7], off nt
	v_lshl_add_u64 v[6:7], v[6:7], 0, s[2:3]
	global_load_dwordx4 v[58:61], v[6:7], off nt
	v_lshl_add_u64 v[6:7], v[6:7], 0, s[2:3]
	global_load_dwordx4 v[62:65], v[6:7], off nt
	v_lshl_add_u64 v[6:7], v[6:7], 0, s[2:3]
	global_load_dwordx4 v[66:69], v[6:7], off nt
	v_lshl_add_u64 v[6:7], v[6:7], 0, s[2:3]
	global_load_dwordx4 v[70:73], v[6:7], off nt
	v_ashrrev_i32_e32 v81, 31, v80
	s_waitcnt lgkmcnt(0)
	v_cmp_ne_u64_e64 s[6:7], 0, v[74:75]
	s_and_b64 vcc, exec, s[6:7]
	v_lshl_add_u64 v[6:7], v[80:81], 2, v[74:75]
	s_cbranch_vccnz .LBB0_163
	s_getpc_b64 s[98:99]

; __device__ __forceinline__ ItemPos item_load(const XItem* tab, int it, int lane, f32x4 (&v)[16], float (&gv)[16]) {
;     int e = 0;
; #pragma unroll 1
;     for (int q = 1; q < 20; ++q) if (it >= tab[q].start) e = q;
;     const XItem x = tab[e]; const int item = it - x.start;
;     const int nblk = x.N >> 6, kb = item / nblk, nb = item - kb * nblk, k0 = kb << 6, n0 = nb << 6;
;     const int lr = lane >> 4, lc = (lane & 15) * 4;
;     const float* W = x.src + (size_t)(k0 + lr) * x.N + n0 + lc; const size_t rstep = (size_t)4 * x.N;
; #pragma unroll
;     for (int i = 0; i < 16; ++i) v[i] = __builtin_nontemporal_load((const f32x4*)(W + i * rstep));
; #pragma unroll
;     for (int i = 0; i < 16; ++i) gv[i] = x.g ? x.g[k0 + 4 * i + lr] : 1.0f;
;     ItemPos p; p.scaled = (x.g != nullptr); p.WT = x.dst; p.K = x.K; p.k0 = k0; p.rb = (x.mode == 0) ? n0 : ((n0 >> 7) * 256 + (x.mode - 1) * 128 + (n0 & 127));
;     return p;
.LBB0_190:
	v_mov_b32_e32 v5, s1
	ds_read_b32 v5, v5
	v_mov_b32_e32 v6, s0
	s_add_i32 s0, s0, 1
	s_add_i32 s1, s1, 40
	s_cmp_eq_u32 s0, 20
	s_waitcnt lgkmcnt(0)
	v_cmp_lt_i32_e32 vcc, s29, v5
	s_nop 1
	v_cndmask_b32_e32 v4, v6, v4, vcc
	s_cbranch_scc0 .LBB0_190
	v_mul_lo_u32 v4, v4, 40
	v_add_u32_e32 v4, 0, v4
	v_add_u32_e32 v10, 0x20800, v4
	ds_read2_b64 v[4:7], v10 offset0:3 offset1:4
	ds_read2_b64 v[72:75], v10 offset1:1
	ds_read_b64 v[80:81], v10 offset:16
	s_waitcnt lgkmcnt(2)
	v_readfirstlane_b32 s4, v5
	s_ashr_i32 s0, s4, 6
	s_abs_i32 s1, s0
	v_cvt_f32_u32_e32 v5, s1
	v_readfirstlane_b32 s5, v7
	s_sub_i32 s6, s29, s5
	s_xor_b32 s5, s6, s0
	v_rcp_iflag_f32_e32 v5, v5
	s_ashr_i32 s21, s5, 31
	s_sub_i32 s5, 0, s1
	s_abs_i32 s7, s6
	v_mul_f32_e32 v5, 0x4f7ffffe, v5
	v_cvt_u32_f32_e32 v5, v5
	s_nop 0
	v_readfirstlane_b32 s30, v5
	s_mul_i32 s5, s5, s30
	s_mul_hi_u32 s5, s30, s5
	s_add_i32 s30, s30, s5
	s_mul_hi_u32 s5, s7, s30
	s_mul_i32 s30, s5, s1
	s_sub_i32 s7, s7, s30
	s_add_i32 s31, s5, 1
	s_sub_i32 s30, s7, s1
	s_cmp_ge_u32 s7, s1
	s_cselect_b32 s5, s31, s5
	s_cselect_b32 s7, s30, s7
	s_add_i32 s30, s5, 1
	s_cmp_ge_u32 s7, s1
	s_cselect_b32 s1, s30, s5
	s_xor_b32 s1, s1, s21
	s_sub_i32 s1, s1, s21
	s_mul_i32 s0, s1, s0
	s_lshl_b32 s30, s1, 6
	s_sub_i32 s21, s6, s0
	v_add_u32_e32 v82, s30, v77
	s_lshl_b32 s0, s21, 6
	v_mad_i64_i32 v[10:11], s[6:7], v82, s4, 0
	s_waitcnt lgkmcnt(1)
	v_lshl_add_u64 v[10:11], v[10:11], 2, v[72:73]
	s_ashr_i32 s1, s0, 31
	s_ashr_i32 s5, s4, 31
	v_lshl_add_u64 v[10:11], s[0:1], 2, v[10:11]
	v_lshl_add_u64 v[18:19], v[10:11], 0, v[78:79]
	s_lshl_b64 s[4:5], s[4:5], 4
	v_lshl_add_u64 v[20:21], v[18:19], 0, s[4:5]
	v_lshl_add_u64 v[26:27], v[20:21], 0, s[4:5]
	v_lshl_add_u64 v[28:29], v[26:27], 0, s[4:5]
	v_lshl_add_u64 v[34:35], v[28:29], 0, s[4:5]
	v_lshl_add_u64 v[36:37], v[34:35], 0, s[4:5]
	v_lshl_add_u64 v[42:43], v[36:37], 0, s[4:5]
	v_lshl_add_u64 v[44:45], v[42:43], 0, s[4:5]
	v_lshl_add_u64 v[46:47], v[44:45], 0, s[4:5]
	v_lshl_add_u64 v[50:51], v[46:47], 0, s[4:5]
	v_lshl_add_u64 v[54:55], v[50:51], 0, s[4:5]
	v_lshl_add_u64 v[58:59], v[54:55], 0, s[4:5]
	v_lshl_add_u64 v[62:63], v[58:59], 0, s[4:5]
	v_lshl_add_u64 v[66:67], v[62:63], 0, s[4:5]
	v_lshl_add_u64 v[70:71], v[66:67], 0, s[4:5]
	global_load_dwordx4 v[10:13], v[18:19], off nt
	global_load_dwordx4 v[14:17], v[20:21], off nt
	s_nop 0
	global_load_dwordx4 v[18:21], v[26:27], off nt
	global_load_dwordx4 v[22:25], v[28:29], off nt
	s_nop 0
	global_load_dwordx4 v[26:29], v[34:35], off nt
	global_load_dwordx4 v[30:33], v[36:37], off nt
	s_nop 0
	global_load_dwordx4 v[34:37], v[42:43], off nt
	global_load_dwordx4 v[38:41], v[44:45], off nt
	v_ashrrev_i32_e32 v83, 31, v82
	global_load_dwordx4 v[42:45], v[46:47], off nt
	s_waitcnt lgkmcnt(0)
	v_cmp_ne_u64_e64 s[6:7], 0, v[80:81]
	global_load_dwordx4 v[46:49], v[50:51], off nt
	s_and_b64 vcc, exec, s[6:7]
	global_load_dwordx4 v[50:53], v[54:55], off nt
	v_lshl_add_u64 v[98:99], v[82:83], 2, v[80:81]
	global_load_dwordx4 v[54:57], v[58:59], off nt
	s_nop 0
	global_load_dwordx4 v[58:61], v[62:63], off nt
	s_nop 0
	global_load_dwordx4 v[62:65], v[66:67], off nt
	s_nop 0
	global_load_dwordx4 v[66:69], v[70:71], off nt
	v_lshl_add_u64 v[70:71], v[70:71], 0, s[4:5]
	global_load_dwordx4 v[70:73], v[70:71], off nt
	s_cbranch_vccz .LBB0_218
	global_load_dword v80, v[98:99], off
	global_load_dword v81, v[98:99], off offset:16
	s_cbranch_execnz .LBB0_194

; #define LAS __attribute__((address_space(3)))
; __device__ __forceinline__ unsigned f2bf(float f) { unsigned u = __builtin_bit_cast(unsigned, f); return (u + 0x7fffu + ((u >> 16) & 1u)) >> 16; }
; __device__ __forceinline__ unsigned pk2(float lo, float hi) { return f2bf(lo) | (f2bf(hi) << 16); }
; __device__ __forceinline__ void item_store(const ItemPos p, LAS float* scr, int lane) {
;     const int c = lane & 7;
; #pragma unroll
;     for (int j = 0; j < 8; ++j) { const int n = (lane >> 3) + 8 * j; const LAS float* s = scr + (8 * c) * 65 + n;
;         u32x4 o; o.x = pk2(s[0 * 65], s[1 * 65]); o.y = pk2(s[2 * 65], s[3 * 65]); o.z = pk2(s[4 * 65], s[5 * 65]); o.w = pk2(s[6 * 65], s[7 * 65]);
;         __builtin_nontemporal_store(o, (u32x4*)(p.WT + (size_t)(p.rb + n) * p.K + p.k0 + 8 * c)); }
;     asm volatile("s_waitcnt lgkmcnt(0)" ::: "memory");
; }
.LBB0_216:
	s_ashr_i32 s21, s20, 31
	s_lshl_b64 s[0:1], s[20:21], 1
	v_lshl_add_u64 v[6:7], v[8:9], 0, s[0:1]
	v_mov_b32_e32 v85, v79
	v_lshl_add_u64 v[6:7], v[6:7], 0, v[84:85]
	ds_read_b32 v85, v102
	ds_read_b32 v98, v102 offset:260
	ds_read_b32 v99, v102 offset:520
	ds_read_b32 v131, v102 offset:780
	ds_read_b32 v132, v102 offset:1040
	ds_read_b32 v133, v102 offset:1300
	ds_read_b32 v134, v102 offset:1560
	ds_read_b32 v135, v102 offset:1820
	s_waitcnt lgkmcnt(0)
	v_bfe_u32 v130, v85, 16, 1
	v_add3_u32 v85, v85, v130, s27
	v_bfe_u32 v130, v98, 16, 1
	v_lshrrev_b32_e32 v85, 16, v85
	v_add3_u32 v98, v98, v130, s27
	v_and_or_b32 v130, v98, s28, v85
	v_bfe_u32 v85, v99, 16, 1
	v_add3_u32 v85, v99, v85, s27
	v_bfe_u32 v98, v131, 16, 1
	v_lshrrev_b32_e32 v85, 16, v85
	v_add3_u32 v98, v131, v98, s27
	v_and_or_b32 v131, v98, s28, v85
	v_bfe_u32 v85, v132, 16, 1
	v_add3_u32 v85, v132, v85, s27
	v_bfe_u32 v98, v133, 16, 1
	v_lshrrev_b32_e32 v85, 16, v85
	v_add3_u32 v98, v133, v98, s27
	v_and_or_b32 v132, v98, s28, v85
	v_bfe_u32 v85, v134, 16, 1
	v_add3_u32 v85, v134, v85, s27
	v_bfe_u32 v98, v135, 16, 1
	v_lshrrev_b32_e32 v85, 16, v85
	v_add3_u32 v98, v135, v98, s27
	v_and_or_b32 v133, v98, s28, v85
	v_add_u32_e32 v85, v3, v101
	v_mad_i64_i32 v[98:99], s[0:1], v85, v2, 0
	v_lshl_add_u64 v[98:99], v[98:99], 1, v[6:7]
	global_store_dwordx4 v[98:99], v[130:133], off nt
	ds_read_b32 v98, v102 offset:32
	ds_read_b32 v99, v102 offset:292
	ds_read_b32 v131, v102 offset:552
	ds_read_b32 v132, v102 offset:812
	ds_read_b32 v133, v102 offset:1072
	ds_read_b32 v134, v102 offset:1332
	ds_read_b32 v135, v102 offset:1592
	ds_read_b32 v136, v102 offset:1852
	s_waitcnt lgkmcnt(0)
	v_bfe_u32 v130, v98, 16, 1
	v_add3_u32 v98, v98, v130, s27
	v_bfe_u32 v130, v99, 16, 1
	v_lshrrev_b32_e32 v98, 16, v98
	v_add3_u32 v99, v99, v130, s27
	v_and_or_b32 v130, v99, s28, v98
	v_bfe_u32 v98, v131, 16, 1
	v_add3_u32 v98, v131, v98, s27
	v_bfe_u32 v99, v132, 16, 1
	v_lshrrev_b32_e32 v98, 16, v98
	v_add3_u32 v99, v132, v99, s27
	v_and_or_b32 v131, v99, s28, v98
	v_bfe_u32 v98, v133, 16, 1
	v_add3_u32 v98, v133, v98, s27
	v_bfe_u32 v99, v134, 16, 1
	v_lshrrev_b32_e32 v98, 16, v98
	v_add3_u32 v99, v134, v99, s27
	v_and_or_b32 v132, v99, s28, v98
	v_bfe_u32 v98, v135, 16, 1
	v_add3_u32 v98, v135, v98, s27
	v_bfe_u32 v99, v136, 16, 1
	v_lshrrev_b32_e32 v98, 16, v98
	v_add3_u32 v99, v136, v99, s27
	v_and_or_b32 v133, v99, s28, v98
	v_add_u32_e32 v98, 8, v85
	v_mad_i64_i32 v[98:99], s[0:1], v98, v2, 0
	v_lshl_add_u64 v[98:99], v[98:99], 1, v[6:7]
	global_store_dwordx4 v[98:99], v[130:133], off nt
	ds_read_b32 v98, v102 offset:64
	ds_read_b32 v99, v102 offset:324
	ds_read_b32 v131, v102 offset:584
	ds_read_b32 v132, v102 offset:844
	ds_read_b32 v133, v102 offset:1104
	ds_read_b32 v134, v102 offset:1364
	ds_read_b32 v135, v102 offset:1624
	ds_read_b32 v136, v102 offset:1884
	s_waitcnt lgkmcnt(0)
	v_bfe_u32 v130, v98, 16, 1
	v_add3_u32 v98, v98, v130, s27
	v_bfe_u32 v130, v99, 16, 1
	v_lshrrev_b32_e32 v98, 16, v98
	v_add3_u32 v99, v99, v130, s27
	v_and_or_b32 v130, v99, s28, v98
	v_bfe_u32 v98, v131, 16, 1
	v_add3_u32 v98, v131, v98, s27
	v_bfe_u32 v99, v132, 16, 1
	v_lshrrev_b32_e32 v98, 16, v98
	v_add3_u32 v99, v132, v99, s27
	v_and_or_b32 v131, v99, s28, v98
	v_bfe_u32 v98, v133, 16, 1
	v_add3_u32 v98, v133, v98, s27
	v_bfe_u32 v99, v134, 16, 1
	v_lshrrev_b32_e32 v98, 16, v98
	v_add3_u32 v99, v134, v99, s27
	v_and_or_b32 v132, v99, s28, v98
	v_bfe_u32 v98, v135, 16, 1
	v_add3_u32 v98, v135, v98, s27
	v_bfe_u32 v99, v136, 16, 1
	v_lshrrev_b32_e32 v98, 16, v98
	v_add3_u32 v99, v136, v99, s27
	v_and_or_b32 v133, v99, s28, v98
	v_add_u32_e32 v98, 16, v85
	v_mad_i64_i32 v[98:99], s[0:1], v98, v2, 0
	v_lshl_add_u64 v[98:99], v[98:99], 1, v[6:7]
	global_store_dwordx4 v[98:99], v[130:133], off nt
	ds_read_b32 v98, v102 offset:96
	ds_read_b32 v99, v102 offset:356
	ds_read_b32 v131, v102 offset:616
	ds_read_b32 v132, v102 offset:876
	ds_read_b32 v133, v102 offset:1136
	ds_read_b32 v134, v102 offset:1396
	ds_read_b32 v135, v102 offset:1656
	ds_read_b32 v136, v102 offset:1916
	s_waitcnt lgkmcnt(0)
	v_bfe_u32 v130, v98, 16, 1
	v_add3_u32 v98, v98, v130, s27
	v_bfe_u32 v130, v99, 16, 1
	v_lshrrev_b32_e32 v98, 16, v98
	v_add3_u32 v99, v99, v130, s27
	v_and_or_b32 v130, v99, s28, v98
	v_bfe_u32 v98, v131, 16, 1
	v_add3_u32 v98, v131, v98, s27
	v_bfe_u32 v99, v132, 16, 1
	v_lshrrev_b32_e32 v98, 16, v98
	v_add3_u32 v99, v132, v99, s27
	v_and_or_b32 v131, v99, s28, v98
	v_bfe_u32 v98, v133, 16, 1
	v_add3_u32 v98, v133, v98, s27
	v_bfe_u32 v99, v134, 16, 1
	v_lshrrev_b32_e32 v98, 16, v98
	v_add3_u32 v99, v134, v99, s27
	v_and_or_b32 v132, v99, s28, v98
	v_bfe_u32 v98, v135, 16, 1
	v_add3_u32 v98, v135, v98, s27
	v_bfe_u32 v99, v136, 16, 1
	v_lshrrev_b32_e32 v98, 16, v98
	v_add3_u32 v99, v136, v99, s27
	v_and_or_b32 v133, v99, s28, v98
	v_add_u32_e32 v98, 24, v85
	v_mad_i64_i32 v[98:99], s[0:1], v98, v2, 0
	v_lshl_add_u64 v[98:99], v[98:99], 1, v[6:7]
	global_store_dwordx4 v[98:99], v[130:133], off nt
	ds_read_b32 v98, v102 offset:128
	ds_read_b32 v99, v102 offset:388
	ds_read_b32 v131, v102 offset:648
	ds_read_b32 v132, v102 offset:908
	ds_read_b32 v133, v102 offset:1168
	ds_read_b32 v134, v102 offset:1428
	ds_read_b32 v135, v102 offset:1688
	ds_read_b32 v136, v102 offset:1948
	s_waitcnt lgkmcnt(0)
; #define LAS __attribute__((address_space(3)))
; __device__ __forceinline__ unsigned pk2(float lo, float hi) { return f2bf(lo) | (f2bf(hi) << 16); }
; __device__ __forceinline__ void item_store(const ItemPos p, LAS float* scr, int lane) {
;     const int c = lane & 7;
; #pragma unroll
;     for (int j = 0; j < 8; ++j) { const int n = (lane >> 3) + 8 * j; const LAS float* s = scr + (8 * c) * 65 + n;
;         u32x4 o; o.x = pk2(s[0 * 65], s[1 * 65]); o.y = pk2(s[2 * 65], s[3 * 65]); o.z = pk2(s[4 * 65], s[5 * 65]); o.w = pk2(s[6 * 65], s[7 * 65]);
;         __builtin_nontemporal_store(o, (u32x4*)(p.WT + (size_t)(p.rb + n) * p.K + p.k0 + 8 * c)); }
;     asm volatile("s_waitcnt lgkmcnt(0)" ::: "memory");
; }
; __device__ __forceinline__ void convert_range(unsigned char* lds, int lo, int hi, int w, int nworkers, int wave, int lane) {
;     ...
;         const int nx = it + nworkers; const bool more = nx < hi; ItemPos pn = p;
;         if (more) pn = item_load(tab, nx, lane, v, gv);
;         item_store(p, scr, lane);
;         if (!more) break;
;         it = nx; p = pn;
	v_bfe_u32 v130, v98, 16, 1
	v_add3_u32 v98, v98, v130, s27
	v_bfe_u32 v130, v99, 16, 1
	v_lshrrev_b32_e32 v98, 16, v98
	v_add3_u32 v99, v99, v130, s27
	v_and_or_b32 v130, v99, s28, v98
	v_bfe_u32 v98, v131, 16, 1
	v_add3_u32 v98, v131, v98, s27
	v_bfe_u32 v99, v132, 16, 1
	v_lshrrev_b32_e32 v98, 16, v98
	v_add3_u32 v99, v132, v99, s27
	v_and_or_b32 v131, v99, s28, v98
	v_bfe_u32 v98, v133, 16, 1
	v_add3_u32 v98, v133, v98, s27
	v_bfe_u32 v99, v134, 16, 1
	v_lshrrev_b32_e32 v98, 16, v98
	v_add3_u32 v99, v134, v99, s27
	v_and_or_b32 v132, v99, s28, v98
	v_bfe_u32 v98, v135, 16, 1
	v_add3_u32 v98, v135, v98, s27
	v_bfe_u32 v99, v136, 16, 1
	v_lshrrev_b32_e32 v98, 16, v98
	v_add3_u32 v99, v136, v99, s27
	v_and_or_b32 v133, v99, s28, v98
	v_add_u32_e32 v98, 32, v85
	v_mad_i64_i32 v[98:99], s[0:1], v98, v2, 0
	v_lshl_add_u64 v[98:99], v[98:99], 1, v[6:7]
	global_store_dwordx4 v[98:99], v[130:133], off nt
	ds_read_b32 v98, v102 offset:160
	ds_read_b32 v99, v102 offset:420
	ds_read_b32 v131, v102 offset:680
	ds_read_b32 v132, v102 offset:940
	ds_read_b32 v133, v102 offset:1200
	ds_read_b32 v134, v102 offset:1460
	ds_read_b32 v135, v102 offset:1720
	ds_read_b32 v136, v102 offset:1980
	s_waitcnt lgkmcnt(0)
	v_bfe_u32 v130, v98, 16, 1
	v_add3_u32 v98, v98, v130, s27
	v_bfe_u32 v130, v99, 16, 1
	v_lshrrev_b32_e32 v98, 16, v98
	v_add3_u32 v99, v99, v130, s27
	v_and_or_b32 v130, v99, s28, v98
	v_bfe_u32 v98, v131, 16, 1
	v_add3_u32 v98, v131, v98, s27
	v_bfe_u32 v99, v132, 16, 1
	v_lshrrev_b32_e32 v98, 16, v98
	v_add3_u32 v99, v132, v99, s27
	v_and_or_b32 v131, v99, s28, v98
	v_bfe_u32 v98, v133, 16, 1
	v_add3_u32 v98, v133, v98, s27
	v_bfe_u32 v99, v134, 16, 1
	v_lshrrev_b32_e32 v98, 16, v98
	v_add3_u32 v99, v134, v99, s27
	v_and_or_b32 v132, v99, s28, v98
	v_bfe_u32 v98, v135, 16, 1
	v_add3_u32 v98, v135, v98, s27
	v_bfe_u32 v99, v136, 16, 1
	v_lshrrev_b32_e32 v98, 16, v98
	v_add3_u32 v99, v136, v99, s27
	v_and_or_b32 v133, v99, s28, v98
	v_add_u32_e32 v98, 40, v85
	v_mad_i64_i32 v[98:99], s[0:1], v98, v2, 0
	v_lshl_add_u64 v[98:99], v[98:99], 1, v[6:7]
	global_store_dwordx4 v[98:99], v[130:133], off nt
	ds_read_b32 v98, v102 offset:192
	ds_read_b32 v99, v102 offset:452
	ds_read_b32 v131, v102 offset:712
	ds_read_b32 v132, v102 offset:972
	ds_read_b32 v133, v102 offset:1232
	ds_read_b32 v134, v102 offset:1492
	ds_read_b32 v135, v102 offset:1752
	ds_read_b32 v136, v102 offset:2012
	s_waitcnt lgkmcnt(0)
	v_bfe_u32 v130, v98, 16, 1
	v_add3_u32 v98, v98, v130, s27
	v_bfe_u32 v130, v99, 16, 1
	v_lshrrev_b32_e32 v98, 16, v98
	v_add3_u32 v99, v99, v130, s27
	v_and_or_b32 v130, v99, s28, v98
	v_bfe_u32 v98, v131, 16, 1
	v_add3_u32 v98, v131, v98, s27
	v_bfe_u32 v99, v132, 16, 1
	v_lshrrev_b32_e32 v98, 16, v98
	v_add3_u32 v99, v132, v99, s27
	v_and_or_b32 v131, v99, s28, v98
	v_bfe_u32 v98, v133, 16, 1
	v_add3_u32 v98, v133, v98, s27
	v_bfe_u32 v99, v134, 16, 1
	v_lshrrev_b32_e32 v98, 16, v98
	v_add3_u32 v99, v134, v99, s27
	v_and_or_b32 v132, v99, s28, v98
	v_bfe_u32 v98, v135, 16, 1
	v_add3_u32 v98, v135, v98, s27
	v_bfe_u32 v99, v136, 16, 1
	v_lshrrev_b32_e32 v98, 16, v98
	v_add3_u32 v99, v136, v99, s27
	v_and_or_b32 v133, v99, s28, v98
	v_add_u32_e32 v98, 48, v85
	v_mad_i64_i32 v[98:99], s[0:1], v98, v2, 0
	v_lshl_add_u64 v[98:99], v[98:99], 1, v[6:7]
	global_store_dwordx4 v[98:99], v[130:133], off nt
	ds_read_b32 v98, v102 offset:224
	ds_read_b32 v99, v102 offset:484
	ds_read_b32 v131, v102 offset:744
	ds_read_b32 v132, v102 offset:1004
	ds_read_b32 v133, v102 offset:1264
	ds_read_b32 v134, v102 offset:1524
	ds_read_b32 v135, v102 offset:1784
	ds_read_b32 v136, v102 offset:2044
	s_waitcnt lgkmcnt(0)
	v_bfe_u32 v130, v98, 16, 1
	v_add3_u32 v98, v98, v130, s27
	v_bfe_u32 v130, v99, 16, 1
	v_lshrrev_b32_e32 v98, 16, v98
	v_add3_u32 v99, v99, v130, s27
	v_and_or_b32 v130, v99, s28, v98
	v_bfe_u32 v98, v131, 16, 1
	v_add3_u32 v98, v131, v98, s27
	v_bfe_u32 v99, v132, 16, 1
	v_lshrrev_b32_e32 v98, 16, v98
	v_add3_u32 v99, v132, v99, s27
	v_and_or_b32 v131, v99, s28, v98
	v_bfe_u32 v98, v133, 16, 1
	v_add3_u32 v98, v133, v98, s27
	v_bfe_u32 v99, v134, 16, 1
	v_lshrrev_b32_e32 v98, 16, v98
	v_add3_u32 v99, v134, v99, s27
	v_and_or_b32 v132, v99, s28, v98
	v_bfe_u32 v98, v135, 16, 1
	v_add3_u32 v98, v135, v98, s27
	v_bfe_u32 v99, v136, 16, 1
	v_lshrrev_b32_e32 v98, 16, v98
	v_add3_u32 v99, v136, v99, s27
	v_add_u32_e32 v85, 56, v85
	v_and_or_b32 v133, v99, s28, v98
	v_mad_i64_i32 v[98:99], s[0:1], v85, v2, 0
	v_lshl_add_u64 v[6:7], v[98:99], 1, v[6:7]
	global_store_dwordx4 v[6:7], v[130:133], off nt
	s_waitcnt lgkmcnt(0)
	s_andn2_b64 vcc, exec, s[14:15]
	s_cbranch_vccnz .LBB0_185
	v_mov_b64_e32 v[8:9], v[74:75]
	v_mov_b32_e32 v2, v4
	v_mov_b32_e32 v3, v5
	s_mov_b32 s20, s30
	s_mov_b32 s23, s29
	s_branch .LBB0_185

; __device__ __forceinline__ ItemPos item_load(const XItem* tab, int it, int lane, f32x4 (&v)[16], float (&gv)[16]) {
;     int e = 0;
; #pragma unroll 1
;     for (int q = 1; q < 20; ++q) if (it >= tab[q].start) e = q;
;     const XItem x = tab[e]; const int item = it - x.start;
;     const int nblk = x.N >> 6, kb = item / nblk, nb = item - kb * nblk, k0 = kb << 6, n0 = nb << 6;
;     const int lr = lane >> 4, lc = (lane & 15) * 4;
;     const float* W = x.src + (size_t)(k0 + lr) * x.N + n0 + lc; const size_t rstep = (size_t)4 * x.N;
; #pragma unroll
;     for (int i = 0; i < 16; ++i) v[i] = __builtin_nontemporal_load((const f32x4*)(W + i * rstep));
; #pragma unroll
;     for (int i = 0; i < 16; ++i) gv[i] = x.g ? x.g[k0 + 4 * i + lr] : 1.0f;
;     ItemPos p; p.scaled = (x.g != nullptr); p.WT = x.dst; p.K = x.K; p.k0 = k0; p.rb = (x.mode == 0) ? n0 : ((n0 >> 7) * 256 + (x.mode - 1) * 128 + (n0 & 127));
;     return p;
.LBB0_259:
	v_mov_b32_e32 v5, s1
	ds_read_b32 v5, v5
	v_mov_b32_e32 v6, s0
	s_add_i32 s0, s0, 1
	s_add_i32 s1, s1, 40
	s_cmp_eq_u32 s0, 20
	s_waitcnt lgkmcnt(0)
	v_cmp_lt_i32_e32 vcc, s26, v5
	s_nop 1
	v_cndmask_b32_e32 v4, v6, v4, vcc
	s_cbranch_scc0 .LBB0_259
	v_mul_lo_u32 v4, v4, 40
	v_add_u32_e32 v4, 0, v4
	v_add_u32_e32 v10, 0x20800, v4
	ds_read2_b64 v[4:7], v10 offset0:3 offset1:4
	ds_read2_b64 v[72:75], v10 offset1:1
	ds_read_b64 v[80:81], v10 offset:16
	s_waitcnt lgkmcnt(2)
	v_readfirstlane_b32 s4, v5
	s_ashr_i32 s0, s4, 6
	s_abs_i32 s1, s0
	v_cvt_f32_u32_e32 v5, s1
	v_readfirstlane_b32 s5, v7
	s_sub_i32 s6, s26, s5
	s_xor_b32 s5, s6, s0
	v_rcp_iflag_f32_e32 v5, v5
	s_ashr_i32 s19, s5, 31
	s_sub_i32 s5, 0, s1
	s_abs_i32 s7, s6
	v_mul_f32_e32 v5, 0x4f7ffffe, v5
	v_cvt_u32_f32_e32 v5, v5
	s_nop 0
	v_readfirstlane_b32 s27, v5
	s_mul_i32 s5, s5, s27
	s_mul_hi_u32 s5, s27, s5
	s_add_i32 s27, s27, s5
	s_mul_hi_u32 s5, s7, s27
	s_mul_i32 s27, s5, s1
	s_sub_i32 s7, s7, s27
	s_add_i32 s28, s5, 1
	s_sub_i32 s27, s7, s1
	s_cmp_ge_u32 s7, s1
	s_cselect_b32 s5, s28, s5
	s_cselect_b32 s7, s27, s7
	s_add_i32 s27, s5, 1
	s_cmp_ge_u32 s7, s1
	s_cselect_b32 s1, s27, s5
	s_xor_b32 s1, s1, s19
	s_sub_i32 s1, s1, s19
	s_mul_i32 s0, s1, s0
	s_lshl_b32 s27, s1, 6
	s_sub_i32 s19, s6, s0
	v_add_u32_e32 v82, s27, v77
	s_lshl_b32 s0, s19, 6
	v_mad_i64_i32 v[10:11], s[6:7], v82, s4, 0
	s_waitcnt lgkmcnt(1)
	v_lshl_add_u64 v[10:11], v[10:11], 2, v[72:73]
	s_ashr_i32 s1, s0, 31
	s_ashr_i32 s5, s4, 31
	v_lshl_add_u64 v[10:11], s[0:1], 2, v[10:11]
	v_lshl_add_u64 v[18:19], v[10:11], 0, v[78:79]
	s_lshl_b64 s[4:5], s[4:5], 4
	v_lshl_add_u64 v[20:21], v[18:19], 0, s[4:5]
	v_lshl_add_u64 v[26:27], v[20:21], 0, s[4:5]
	v_lshl_add_u64 v[28:29], v[26:27], 0, s[4:5]
	v_lshl_add_u64 v[34:35], v[28:29], 0, s[4:5]
	v_lshl_add_u64 v[36:37], v[34:35], 0, s[4:5]
	v_lshl_add_u64 v[42:43], v[36:37], 0, s[4:5]
	v_lshl_add_u64 v[44:45], v[42:43], 0, s[4:5]
	v_lshl_add_u64 v[46:47], v[44:45], 0, s[4:5]
	v_lshl_add_u64 v[50:51], v[46:47], 0, s[4:5]
	v_lshl_add_u64 v[54:55], v[50:51], 0, s[4:5]
	v_lshl_add_u64 v[58:59], v[54:55], 0, s[4:5]
	v_lshl_add_u64 v[62:63], v[58:59], 0, s[4:5]
	v_lshl_add_u64 v[66:67], v[62:63], 0, s[4:5]
	v_lshl_add_u64 v[70:71], v[66:67], 0, s[4:5]
	global_load_dwordx4 v[10:13], v[18:19], off nt
	global_load_dwordx4 v[14:17], v[20:21], off nt
	s_nop 0
	global_load_dwordx4 v[18:21], v[26:27], off nt
	global_load_dwordx4 v[22:25], v[28:29], off nt
	s_nop 0
	global_load_dwordx4 v[26:29], v[34:35], off nt
	global_load_dwordx4 v[30:33], v[36:37], off nt
	s_nop 0
	global_load_dwordx4 v[34:37], v[42:43], off nt
	global_load_dwordx4 v[38:41], v[44:45], off nt
	v_ashrrev_i32_e32 v83, 31, v82
	global_load_dwordx4 v[42:45], v[46:47], off nt
	s_waitcnt lgkmcnt(0)
	v_cmp_ne_u64_e64 s[6:7], 0, v[80:81]
	global_load_dwordx4 v[46:49], v[50:51], off nt
	s_and_b64 vcc, exec, s[6:7]
	global_load_dwordx4 v[50:53], v[54:55], off nt
	v_lshl_add_u64 v[98:99], v[82:83], 2, v[80:81]
	global_load_dwordx4 v[54:57], v[58:59], off nt
	s_nop 0
	global_load_dwordx4 v[58:61], v[62:63], off nt
	s_nop 0
	global_load_dwordx4 v[62:65], v[66:67], off nt
	s_nop 0
	global_load_dwordx4 v[66:69], v[70:71], off nt
	v_lshl_add_u64 v[70:71], v[70:71], 0, s[4:5]
	global_load_dwordx4 v[70:73], v[70:71], off nt
	s_cbranch_vccz .LBB0_287
	global_load_dword v80, v[98:99], off
	global_load_dword v81, v[98:99], off offset:16
	s_cbranch_execnz .LBB0_263

; #define LAS __attribute__((address_space(3)))
; __device__ __forceinline__ unsigned f2bf(float f) { unsigned u = __builtin_bit_cast(unsigned, f); return (u + 0x7fffu + ((u >> 16) & 1u)) >> 16; }
; __device__ __forceinline__ unsigned pk2(float lo, float hi) { return f2bf(lo) | (f2bf(hi) << 16); }
; __device__ __forceinline__ void item_store(const ItemPos p, LAS float* scr, int lane) {
;     const int c = lane & 7;
; #pragma unroll
;     for (int j = 0; j < 8; ++j) { const int n = (lane >> 3) + 8 * j; const LAS float* s = scr + (8 * c) * 65 + n;
;         u32x4 o; o.x = pk2(s[0 * 65], s[1 * 65]); o.y = pk2(s[2 * 65], s[3 * 65]); o.z = pk2(s[4 * 65], s[5 * 65]); o.w = pk2(s[6 * 65], s[7 * 65]);
;         __builtin_nontemporal_store(o, (u32x4*)(p.WT + (size_t)(p.rb + n) * p.K + p.k0 + 8 * c)); }
;     asm volatile("s_waitcnt lgkmcnt(0)" ::: "memory");
; }
.LBB0_285:
	s_ashr_i32 s19, s18, 31
	s_lshl_b64 s[0:1], s[18:19], 1
	v_lshl_add_u64 v[6:7], v[8:9], 0, s[0:1]
	v_mov_b32_e32 v85, v79
	v_lshl_add_u64 v[6:7], v[6:7], 0, v[84:85]
	ds_read_b32 v85, v102
	ds_read_b32 v98, v102 offset:260
	ds_read_b32 v99, v102 offset:520
	ds_read_b32 v131, v102 offset:780
	ds_read_b32 v132, v102 offset:1040
	ds_read_b32 v133, v102 offset:1300
	ds_read_b32 v134, v102 offset:1560
	ds_read_b32 v135, v102 offset:1820
	s_waitcnt lgkmcnt(0)
	v_bfe_u32 v130, v85, 16, 1
	v_add3_u32 v85, v85, v130, s24
	v_bfe_u32 v130, v98, 16, 1
	v_lshrrev_b32_e32 v85, 16, v85
	v_add3_u32 v98, v98, v130, s24
	v_and_or_b32 v130, v98, s25, v85
	v_bfe_u32 v85, v99, 16, 1
	v_add3_u32 v85, v99, v85, s24
	v_bfe_u32 v98, v131, 16, 1
	v_lshrrev_b32_e32 v85, 16, v85
	v_add3_u32 v98, v131, v98, s24
	v_and_or_b32 v131, v98, s25, v85
	v_bfe_u32 v85, v132, 16, 1
	v_add3_u32 v85, v132, v85, s24
	v_bfe_u32 v98, v133, 16, 1
	v_lshrrev_b32_e32 v85, 16, v85
	v_add3_u32 v98, v133, v98, s24
	v_and_or_b32 v132, v98, s25, v85
	v_bfe_u32 v85, v134, 16, 1
	v_add3_u32 v85, v134, v85, s24
	v_bfe_u32 v98, v135, 16, 1
	v_lshrrev_b32_e32 v85, 16, v85
	v_add3_u32 v98, v135, v98, s24
	v_and_or_b32 v133, v98, s25, v85
	v_add_u32_e32 v85, v3, v101
	v_mad_i64_i32 v[98:99], s[0:1], v85, v2, 0
	v_lshl_add_u64 v[98:99], v[98:99], 1, v[6:7]
	global_store_dwordx4 v[98:99], v[130:133], off nt
	ds_read_b32 v98, v102 offset:32
	ds_read_b32 v99, v102 offset:292
	ds_read_b32 v131, v102 offset:552
	ds_read_b32 v132, v102 offset:812
	ds_read_b32 v133, v102 offset:1072
	ds_read_b32 v134, v102 offset:1332
	ds_read_b32 v135, v102 offset:1592
	ds_read_b32 v136, v102 offset:1852
	s_waitcnt lgkmcnt(0)
	v_bfe_u32 v130, v98, 16, 1
	v_add3_u32 v98, v98, v130, s24
	v_bfe_u32 v130, v99, 16, 1
	v_lshrrev_b32_e32 v98, 16, v98
	v_add3_u32 v99, v99, v130, s24
	v_and_or_b32 v130, v99, s25, v98
	v_bfe_u32 v98, v131, 16, 1
	v_add3_u32 v98, v131, v98, s24
	v_bfe_u32 v99, v132, 16, 1
	v_lshrrev_b32_e32 v98, 16, v98
	v_add3_u32 v99, v132, v99, s24
	v_and_or_b32 v131, v99, s25, v98
	v_bfe_u32 v98, v133, 16, 1
	v_add3_u32 v98, v133, v98, s24
	v_bfe_u32 v99, v134, 16, 1
	v_lshrrev_b32_e32 v98, 16, v98
	v_add3_u32 v99, v134, v99, s24
	v_and_or_b32 v132, v99, s25, v98
	v_bfe_u32 v98, v135, 16, 1
	v_add3_u32 v98, v135, v98, s24
	v_bfe_u32 v99, v136, 16, 1
	v_lshrrev_b32_e32 v98, 16, v98
	v_add3_u32 v99, v136, v99, s24
	v_and_or_b32 v133, v99, s25, v98
	v_add_u32_e32 v98, 8, v85
	v_mad_i64_i32 v[98:99], s[0:1], v98, v2, 0
	v_lshl_add_u64 v[98:99], v[98:99], 1, v[6:7]
	global_store_dwordx4 v[98:99], v[130:133], off nt
	ds_read_b32 v98, v102 offset:64
	ds_read_b32 v99, v102 offset:324
	ds_read_b32 v131, v102 offset:584
	ds_read_b32 v132, v102 offset:844
	ds_read_b32 v133, v102 offset:1104
	ds_read_b32 v134, v102 offset:1364
	ds_read_b32 v135, v102 offset:1624
	ds_read_b32 v136, v102 offset:1884
	s_waitcnt lgkmcnt(0)
	v_bfe_u32 v130, v98, 16, 1
	v_add3_u32 v98, v98, v130, s24
	v_bfe_u32 v130, v99, 16, 1
	v_lshrrev_b32_e32 v98, 16, v98
	v_add3_u32 v99, v99, v130, s24
	v_and_or_b32 v130, v99, s25, v98
	v_bfe_u32 v98, v131, 16, 1
	v_add3_u32 v98, v131, v98, s24
	v_bfe_u32 v99, v132, 16, 1
	v_lshrrev_b32_e32 v98, 16, v98
	v_add3_u32 v99, v132, v99, s24
	v_and_or_b32 v131, v99, s25, v98
	v_bfe_u32 v98, v133, 16, 1
	v_add3_u32 v98, v133, v98, s24
	v_bfe_u32 v99, v134, 16, 1
	v_lshrrev_b32_e32 v98, 16, v98
	v_add3_u32 v99, v134, v99, s24
	v_and_or_b32 v132, v99, s25, v98
	v_bfe_u32 v98, v135, 16, 1
	v_add3_u32 v98, v135, v98, s24
	v_bfe_u32 v99, v136, 16, 1
	v_lshrrev_b32_e32 v98, 16, v98
	v_add3_u32 v99, v136, v99, s24
	v_and_or_b32 v133, v99, s25, v98
	v_add_u32_e32 v98, 16, v85
	v_mad_i64_i32 v[98:99], s[0:1], v98, v2, 0
	v_lshl_add_u64 v[98:99], v[98:99], 1, v[6:7]
	global_store_dwordx4 v[98:99], v[130:133], off nt
	ds_read_b32 v98, v102 offset:96
	ds_read_b32 v99, v102 offset:356
	ds_read_b32 v131, v102 offset:616
	ds_read_b32 v132, v102 offset:876
	ds_read_b32 v133, v102 offset:1136
	ds_read_b32 v134, v102 offset:1396
	ds_read_b32 v135, v102 offset:1656
	ds_read_b32 v136, v102 offset:1916
	s_waitcnt lgkmcnt(0)
	v_bfe_u32 v130, v98, 16, 1
	v_add3_u32 v98, v98, v130, s24
	v_bfe_u32 v130, v99, 16, 1
	v_lshrrev_b32_e32 v98, 16, v98
	v_add3_u32 v99, v99, v130, s24
	v_and_or_b32 v130, v99, s25, v98
	v_bfe_u32 v98, v131, 16, 1
	v_add3_u32 v98, v131, v98, s24
	v_bfe_u32 v99, v132, 16, 1
	v_lshrrev_b32_e32 v98, 16, v98
	v_add3_u32 v99, v132, v99, s24
	v_and_or_b32 v131, v99, s25, v98
	v_bfe_u32 v98, v133, 16, 1
	v_add3_u32 v98, v133, v98, s24
	v_bfe_u32 v99, v134, 16, 1
	v_lshrrev_b32_e32 v98, 16, v98
	v_add3_u32 v99, v134, v99, s24
	v_and_or_b32 v132, v99, s25, v98
	v_bfe_u32 v98, v135, 16, 1
	v_add3_u32 v98, v135, v98, s24
	v_bfe_u32 v99, v136, 16, 1
	v_lshrrev_b32_e32 v98, 16, v98
	v_add3_u32 v99, v136, v99, s24
	v_and_or_b32 v133, v99, s25, v98
	v_add_u32_e32 v98, 24, v85
	v_mad_i64_i32 v[98:99], s[0:1], v98, v2, 0
	v_lshl_add_u64 v[98:99], v[98:99], 1, v[6:7]
	global_store_dwordx4 v[98:99], v[130:133], off nt
	ds_read_b32 v98, v102 offset:128
	ds_read_b32 v99, v102 offset:388
	ds_read_b32 v131, v102 offset:648
	ds_read_b32 v132, v102 offset:908
	ds_read_b32 v133, v102 offset:1168
	ds_read_b32 v134, v102 offset:1428
	ds_read_b32 v135, v102 offset:1688
	ds_read_b32 v136, v102 offset:1948
	s_waitcnt lgkmcnt(0)
; #define LAS __attribute__((address_space(3)))
; __device__ __forceinline__ unsigned pk2(float lo, float hi) { return f2bf(lo) | (f2bf(hi) << 16); }
; __device__ __forceinline__ void item_store(const ItemPos p, LAS float* scr, int lane) {
;     const int c = lane & 7;
; #pragma unroll
;     for (int j = 0; j < 8; ++j) { const int n = (lane >> 3) + 8 * j; const LAS float* s = scr + (8 * c) * 65 + n;
;         u32x4 o; o.x = pk2(s[0 * 65], s[1 * 65]); o.y = pk2(s[2 * 65], s[3 * 65]); o.z = pk2(s[4 * 65], s[5 * 65]); o.w = pk2(s[6 * 65], s[7 * 65]);
;         __builtin_nontemporal_store(o, (u32x4*)(p.WT + (size_t)(p.rb + n) * p.K + p.k0 + 8 * c)); }
;     asm volatile("s_waitcnt lgkmcnt(0)" ::: "memory");
; }
; __device__ __forceinline__ void convert_range(unsigned char* lds, int lo, int hi, int w, int nworkers, int wave, int lane) {
;     ...
;         const int nx = it + nworkers; const bool more = nx < hi; ItemPos pn = p;
;         if (more) pn = item_load(tab, nx, lane, v, gv);
;         item_store(p, scr, lane);
;         if (!more) break;
;         it = nx; p = pn;
	v_bfe_u32 v130, v98, 16, 1
	v_add3_u32 v98, v98, v130, s24
	v_bfe_u32 v130, v99, 16, 1
	v_lshrrev_b32_e32 v98, 16, v98
	v_add3_u32 v99, v99, v130, s24
	v_and_or_b32 v130, v99, s25, v98
	v_bfe_u32 v98, v131, 16, 1
	v_add3_u32 v98, v131, v98, s24
	v_bfe_u32 v99, v132, 16, 1
	v_lshrrev_b32_e32 v98, 16, v98
	v_add3_u32 v99, v132, v99, s24
	v_and_or_b32 v131, v99, s25, v98
	v_bfe_u32 v98, v133, 16, 1
	v_add3_u32 v98, v133, v98, s24
	v_bfe_u32 v99, v134, 16, 1
	v_lshrrev_b32_e32 v98, 16, v98
	v_add3_u32 v99, v134, v99, s24
	v_and_or_b32 v132, v99, s25, v98
	v_bfe_u32 v98, v135, 16, 1
	v_add3_u32 v98, v135, v98, s24
	v_bfe_u32 v99, v136, 16, 1
	v_lshrrev_b32_e32 v98, 16, v98
	v_add3_u32 v99, v136, v99, s24
	v_and_or_b32 v133, v99, s25, v98
	v_add_u32_e32 v98, 32, v85
	v_mad_i64_i32 v[98:99], s[0:1], v98, v2, 0
	v_lshl_add_u64 v[98:99], v[98:99], 1, v[6:7]
	global_store_dwordx4 v[98:99], v[130:133], off nt
	ds_read_b32 v98, v102 offset:160
	ds_read_b32 v99, v102 offset:420
	ds_read_b32 v131, v102 offset:680
	ds_read_b32 v132, v102 offset:940
	ds_read_b32 v133, v102 offset:1200
	ds_read_b32 v134, v102 offset:1460
	ds_read_b32 v135, v102 offset:1720
	ds_read_b32 v136, v102 offset:1980
	s_waitcnt lgkmcnt(0)
	v_bfe_u32 v130, v98, 16, 1
	v_add3_u32 v98, v98, v130, s24
	v_bfe_u32 v130, v99, 16, 1
	v_lshrrev_b32_e32 v98, 16, v98
	v_add3_u32 v99, v99, v130, s24
	v_and_or_b32 v130, v99, s25, v98
	v_bfe_u32 v98, v131, 16, 1
	v_add3_u32 v98, v131, v98, s24
	v_bfe_u32 v99, v132, 16, 1
	v_lshrrev_b32_e32 v98, 16, v98
	v_add3_u32 v99, v132, v99, s24
	v_and_or_b32 v131, v99, s25, v98
	v_bfe_u32 v98, v133, 16, 1
	v_add3_u32 v98, v133, v98, s24
	v_bfe_u32 v99, v134, 16, 1
	v_lshrrev_b32_e32 v98, 16, v98
	v_add3_u32 v99, v134, v99, s24
	v_and_or_b32 v132, v99, s25, v98
	v_bfe_u32 v98, v135, 16, 1
	v_add3_u32 v98, v135, v98, s24
	v_bfe_u32 v99, v136, 16, 1
	v_lshrrev_b32_e32 v98, 16, v98
	v_add3_u32 v99, v136, v99, s24
	v_and_or_b32 v133, v99, s25, v98
	v_add_u32_e32 v98, 40, v85
	v_mad_i64_i32 v[98:99], s[0:1], v98, v2, 0
	v_lshl_add_u64 v[98:99], v[98:99], 1, v[6:7]
	global_store_dwordx4 v[98:99], v[130:133], off nt
	ds_read_b32 v98, v102 offset:192
	ds_read_b32 v99, v102 offset:452
	ds_read_b32 v131, v102 offset:712
	ds_read_b32 v132, v102 offset:972
	ds_read_b32 v133, v102 offset:1232
	ds_read_b32 v134, v102 offset:1492
	ds_read_b32 v135, v102 offset:1752
	ds_read_b32 v136, v102 offset:2012
	s_waitcnt lgkmcnt(0)
	v_bfe_u32 v130, v98, 16, 1
	v_add3_u32 v98, v98, v130, s24
	v_bfe_u32 v130, v99, 16, 1
	v_lshrrev_b32_e32 v98, 16, v98
	v_add3_u32 v99, v99, v130, s24
	v_and_or_b32 v130, v99, s25, v98
	v_bfe_u32 v98, v131, 16, 1
	v_add3_u32 v98, v131, v98, s24
	v_bfe_u32 v99, v132, 16, 1
	v_lshrrev_b32_e32 v98, 16, v98
	v_add3_u32 v99, v132, v99, s24
	v_and_or_b32 v131, v99, s25, v98
	v_bfe_u32 v98, v133, 16, 1
	v_add3_u32 v98, v133, v98, s24
	v_bfe_u32 v99, v134, 16, 1
	v_lshrrev_b32_e32 v98, 16, v98
	v_add3_u32 v99, v134, v99, s24
	v_and_or_b32 v132, v99, s25, v98
	v_bfe_u32 v98, v135, 16, 1
	v_add3_u32 v98, v135, v98, s24
	v_bfe_u32 v99, v136, 16, 1
	v_lshrrev_b32_e32 v98, 16, v98
	v_add3_u32 v99, v136, v99, s24
	v_and_or_b32 v133, v99, s25, v98
	v_add_u32_e32 v98, 48, v85
	v_mad_i64_i32 v[98:99], s[0:1], v98, v2, 0
	v_lshl_add_u64 v[98:99], v[98:99], 1, v[6:7]
	global_store_dwordx4 v[98:99], v[130:133], off nt
	ds_read_b32 v98, v102 offset:224
	ds_read_b32 v99, v102 offset:484
	ds_read_b32 v131, v102 offset:744
	ds_read_b32 v132, v102 offset:1004
	ds_read_b32 v133, v102 offset:1264
	ds_read_b32 v134, v102 offset:1524
	ds_read_b32 v135, v102 offset:1784
	ds_read_b32 v136, v102 offset:2044
	s_waitcnt lgkmcnt(0)
	v_bfe_u32 v130, v98, 16, 1
	v_add3_u32 v98, v98, v130, s24
	v_bfe_u32 v130, v99, 16, 1
	v_lshrrev_b32_e32 v98, 16, v98
	v_add3_u32 v99, v99, v130, s24
	v_and_or_b32 v130, v99, s25, v98
	v_bfe_u32 v98, v131, 16, 1
	v_add3_u32 v98, v131, v98, s24
	v_bfe_u32 v99, v132, 16, 1
	v_lshrrev_b32_e32 v98, 16, v98
	v_add3_u32 v99, v132, v99, s24
	v_and_or_b32 v131, v99, s25, v98
	v_bfe_u32 v98, v133, 16, 1
	v_add3_u32 v98, v133, v98, s24
	v_bfe_u32 v99, v134, 16, 1
	v_lshrrev_b32_e32 v98, 16, v98
	v_add3_u32 v99, v134, v99, s24
	v_and_or_b32 v132, v99, s25, v98
	v_bfe_u32 v98, v135, 16, 1
	v_add3_u32 v98, v135, v98, s24
	v_bfe_u32 v99, v136, 16, 1
	v_lshrrev_b32_e32 v98, 16, v98
	v_add3_u32 v99, v136, v99, s24
	v_add_u32_e32 v85, 56, v85
	v_and_or_b32 v133, v99, s25, v98
	v_mad_i64_i32 v[98:99], s[0:1], v85, v2, 0
	v_lshl_add_u64 v[6:7], v[98:99], 1, v[6:7]
	global_store_dwordx4 v[6:7], v[130:133], off nt
	s_waitcnt lgkmcnt(0)
	s_andn2_b64 vcc, exec, s[14:15]
	s_cbranch_vccnz .LBB0_254
	v_mov_b64_e32 v[8:9], v[74:75]
	v_mov_b32_e32 v2, v4
	v_mov_b32_e32 v3, v5
	s_mov_b32 s18, s27
	s_mov_b32 s20, s26
	s_branch .LBB0_254

; __device__ __forceinline__ ItemPos item_load(const XItem* tab, int it, int lane, f32x4 (&v)[16], float (&gv)[16]) {
;     int e = 0;
; #pragma unroll 1
;     for (int q = 1; q < 20; ++q) if (it >= tab[q].start) e = q;
;     const XItem x = tab[e]; const int item = it - x.start;
;     const int nblk = x.N >> 6, kb = item / nblk, nb = item - kb * nblk, k0 = kb << 6, n0 = nb << 6;
;     const int lr = lane >> 4, lc = (lane & 15) * 4;
;     const float* W = x.src + (size_t)(k0 + lr) * x.N + n0 + lc; const size_t rstep = (size_t)4 * x.N;
; #pragma unroll
;     for (int i = 0; i < 16; ++i) v[i] = __builtin_nontemporal_load((const f32x4*)(W + i * rstep));
; #pragma unroll
;     for (int i = 0; i < 16; ++i) gv[i] = x.g ? x.g[k0 + 4 * i + lr] : 1.0f;
;     ItemPos p; p.scaled = (x.g != nullptr); p.WT = x.dst; p.K = x.K; p.k0 = k0; p.rb = (x.mode == 0) ? n0 : ((n0 >> 7) * 256 + (x.mode - 1) * 128 + (n0 & 127));
;     return p;
.LBB0_301:
	v_mov_b32_e32 v3, s0
	ds_read_b32 v3, v3
	v_mov_b32_e32 v4, s1
	s_add_i32 s1, s1, 1
	s_add_i32 s0, s0, 40
	s_cmp_eq_u32 s1, 20
	s_waitcnt lgkmcnt(0)
	v_cmp_lt_i32_e32 vcc, s12, v3
	s_nop 1
	v_cndmask_b32_e32 v2, v4, v2, vcc
	s_cbranch_scc0 .LBB0_301
	v_mul_lo_u32 v2, v2, 40
	v_add_u32_e32 v2, 0, v2
	s_waitcnt vmcnt(0)
	v_add_u32_e32 v10, 0x20800, v2
	ds_read2_b64 v[2:5], v10 offset0:3 offset1:4
	ds_read2_b64 v[6:9], v10 offset1:1
	ds_read_b64 v[74:75], v10 offset:16
	v_ashrrev_i32_e32 v77, 4, v100
	v_lshlrev_b32_e32 v11, 2, v100
	v_mov_b32_e32 v79, 0
	s_waitcnt lgkmcnt(2)
	v_readfirstlane_b32 s2, v3
	s_ashr_i32 s0, s2, 6
	s_abs_i32 s1, s0
	v_cvt_f32_u32_e32 v3, s1
	s_sub_i32 s6, 0, s1
	v_readfirstlane_b32 s3, v5
	s_sub_i32 s3, s12, s3
	v_rcp_iflag_f32_e32 v3, v3
	s_abs_i32 s5, s3
	s_xor_b32 s4, s3, s0
	s_ashr_i32 s4, s4, 31
	v_mul_f32_e32 v3, 0x4f7ffffe, v3
	v_cvt_u32_f32_e32 v3, v3
	v_and_b32_e32 v5, 60, v11
	v_lshlrev_b32_e32 v78, 2, v5
	v_readfirstlane_b32 s7, v3
	s_mul_i32 s6, s6, s7
	s_mul_hi_u32 s6, s7, s6
	s_add_i32 s7, s7, s6
	s_mul_hi_u32 s6, s5, s7
	s_mul_i32 s7, s6, s1
	s_sub_i32 s5, s5, s7
	s_add_i32 s13, s6, 1
	s_sub_i32 s7, s5, s1
	s_cmp_ge_u32 s5, s1
	s_cselect_b32 s6, s13, s6
	s_cselect_b32 s5, s7, s5
	s_add_i32 s7, s6, 1
	s_cmp_ge_u32 s5, s1
	s_cselect_b32 s1, s7, s6
	s_xor_b32 s1, s1, s4
	s_sub_i32 s1, s1, s4
	s_mul_i32 s0, s1, s0
	s_lshl_b32 s18, s1, 6
	s_sub_i32 s13, s3, s0
	v_add_u32_e32 v80, s18, v77
	s_lshl_b32 s0, s13, 6
	v_mad_i64_i32 v[10:11], s[4:5], v80, s2, 0
	s_waitcnt lgkmcnt(1)
	v_lshl_add_u64 v[6:7], v[10:11], 2, v[6:7]
	s_ashr_i32 s1, s0, 31
	s_ashr_i32 s3, s2, 31
	v_lshl_add_u64 v[6:7], s[0:1], 2, v[6:7]
	v_lshl_add_u64 v[6:7], v[6:7], 0, v[78:79]
	s_lshl_b64 s[2:3], s[2:3], 4
	v_lshl_add_u64 v[18:19], v[6:7], 0, s[2:3]
	global_load_dwordx4 v[10:13], v[6:7], off nt
	global_load_dwordx4 v[14:17], v[18:19], off nt
	v_lshl_add_u64 v[6:7], v[18:19], 0, s[2:3]
	v_lshl_add_u64 v[26:27], v[6:7], 0, s[2:3]
	global_load_dwordx4 v[18:21], v[6:7], off nt
	global_load_dwordx4 v[22:25], v[26:27], off nt
	v_lshl_add_u64 v[6:7], v[26:27], 0, s[2:3]
	v_lshl_add_u64 v[34:35], v[6:7], 0, s[2:3]
	global_load_dwordx4 v[26:29], v[6:7], off nt
	global_load_dwordx4 v[30:33], v[34:35], off nt
	v_lshl_add_u64 v[6:7], v[34:35], 0, s[2:3]
	v_lshl_add_u64 v[42:43], v[6:7], 0, s[2:3]
	global_load_dwordx4 v[34:37], v[6:7], off nt
	global_load_dwordx4 v[38:41], v[42:43], off nt
	v_lshl_add_u64 v[6:7], v[42:43], 0, s[2:3]
	global_load_dwordx4 v[42:45], v[6:7], off nt
	v_lshl_add_u64 v[6:7], v[6:7], 0, s[2:3]
	global_load_dwordx4 v[46:49], v[6:7], off nt
	v_lshl_add_u64 v[6:7], v[6:7], 0, s[2:3]
	global_load_dwordx4 v[50:53], v[6:7], off nt
	v_lshl_add_u64 v[6:7], v[6:7], 0, s[2:3]
	global_load_dwordx4 v[54:57], v[6:7], off nt
	v_lshl_add_u64 v[6:7], v[6:7], 0, s[2:3]
	global_load_dwordx4 v[58:61], v[6:7], off nt
	v_lshl_add_u64 v[6:7], v[6:7], 0, s[2:3]
	global_load_dwordx4 v[62:65], v[6:7], off nt
	v_lshl_add_u64 v[6:7], v[6:7], 0, s[2:3]
	global_load_dwordx4 v[66:69], v[6:7], off nt
	v_lshl_add_u64 v[6:7], v[6:7], 0, s[2:3]
	global_load_dwordx4 v[70:73], v[6:7], off nt
	v_ashrrev_i32_e32 v81, 31, v80
	s_waitcnt lgkmcnt(0)
	v_cmp_ne_u64_e64 s[6:7], 0, v[74:75]
	s_and_b64 vcc, exec, s[6:7]
	v_lshl_add_u64 v[6:7], v[80:81], 2, v[74:75]
	s_cbranch_vccz .LBB0_446
	global_load_dword v80, v[6:7], off
	global_load_dword v81, v[6:7], off offset:16
	v_cndmask_b32_e64 v3, 0, 1, s[6:7]
	v_cmp_ne_u32_e64 s[4:5], 1, v3
	s_andn2_b64 vcc, exec, s[6:7]
	s_cbranch_vccnz .LBB0_447

; __device__ __forceinline__ ItemPos item_load(const XItem* tab, int it, int lane, f32x4 (&v)[16], float (&gv)[16]) {
;     ...
;     for (int i = 0; i < 16; ++i) gv[i] = x.g ? x.g[k0 + 4 * i + lr] : 1.0f;
.LBB0_306:
	s_and_b64 vcc, exec, s[4:5]
	s_cbranch_vccnz .LBB0_448
	global_load_dword v86, v[6:7], off offset:64
	global_load_dword v87, v[6:7], off offset:80
	s_cbranch_execnz .LBB0_309

; __device__ __forceinline__ ItemPos item_load(const XItem* tab, int it, int lane, f32x4 (&v)[16], float (&gv)[16]) {
;     ...
;     for (int i = 0; i < 16; ++i) gv[i] = x.g ? x.g[k0 + 4 * i + lr] : 1.0f;
.LBB0_309:
	s_and_b64 vcc, exec, s[4:5]
	s_cbranch_vccnz .LBB0_449
	global_load_dword v88, v[6:7], off offset:96
	global_load_dword v89, v[6:7], off offset:112
	s_cbranch_execnz .LBB0_312

; __device__ __forceinline__ ItemPos item_load(const XItem* tab, int it, int lane, f32x4 (&v)[16], float (&gv)[16]) {
;     ...
;     for (int i = 0; i < 16; ++i) gv[i] = x.g ? x.g[k0 + 4 * i + lr] : 1.0f;
.LBB0_312:
	s_and_b64 vcc, exec, s[4:5]
	s_cbranch_vccnz .LBB0_450
	global_load_dword v90, v[6:7], off offset:128
	global_load_dword v91, v[6:7], off offset:144
	s_cbranch_execnz .LBB0_315

; __device__ __forceinline__ ItemPos item_load(const XItem* tab, int it, int lane, f32x4 (&v)[16], float (&gv)[16]) {
;     ...
;     for (int i = 0; i < 16; ++i) gv[i] = x.g ? x.g[k0 + 4 * i + lr] : 1.0f;
.LBB0_315:
	s_and_b64 vcc, exec, s[4:5]
	s_cbranch_vccnz .LBB0_451
	global_load_dword v92, v[6:7], off offset:160
	global_load_dword v93, v[6:7], off offset:176
	s_cbranch_execnz .LBB0_318

; __device__ __forceinline__ ItemPos item_load(const XItem* tab, int it, int lane, f32x4 (&v)[16], float (&gv)[16]) {
;     ...
;     for (int i = 0; i < 16; ++i) gv[i] = x.g ? x.g[k0 + 4 * i + lr] : 1.0f;
.LBB0_318:
	s_and_b64 vcc, exec, s[4:5]
	s_cbranch_vccnz .LBB0_452
	global_load_dword v94, v[6:7], off offset:192
	global_load_dword v95, v[6:7], off offset:208
	s_cbranch_execnz .LBB0_321

; __device__ __forceinline__ ItemPos item_load(const XItem* tab, int it, int lane, f32x4 (&v)[16], float (&gv)[16]) {
;     ...
;     for (int i = 0; i < 16; ++i) gv[i] = x.g ? x.g[k0 + 4 * i + lr] : 1.0f;
.LBB0_321:
	s_and_b64 vcc, exec, s[4:5]
	s_cbranch_vccnz .LBB0_453
	global_load_dword v96, v[6:7], off offset:224
	global_load_dword v97, v[6:7], off offset:240
	s_cbranch_execnz .LBB0_324

; __device__ __forceinline__ ItemPos item_load(const XItem* tab, int it, int lane, f32x4 (&v)[16], float (&gv)[16]) {
;     int e = 0;
; #pragma unroll 1
;     for (int q = 1; q < 20; ++q) if (it >= tab[q].start) e = q;
;     const XItem x = tab[e]; const int item = it - x.start;
;     const int nblk = x.N >> 6, kb = item / nblk, nb = item - kb * nblk, k0 = kb << 6, n0 = nb << 6;
;     const int lr = lane >> 4, lc = (lane & 15) * 4;
;     const float* W = x.src + (size_t)(k0 + lr) * x.N + n0 + lc; const size_t rstep = (size_t)4 * x.N;
; #pragma unroll
;     for (int i = 0; i < 16; ++i) v[i] = __builtin_nontemporal_load((const f32x4*)(W + i * rstep));
; #pragma unroll
;     for (int i = 0; i < 16; ++i) gv[i] = x.g ? x.g[k0 + 4 * i + lr] : 1.0f;
;     ItemPos p; p.scaled = (x.g != nullptr); p.WT = x.dst; p.K = x.K; p.k0 = k0; p.rb = (x.mode == 0) ? n0 : ((n0 >> 7) * 256 + (x.mode - 1) * 128 + (n0 & 127));
;     return p;
.LBB0_330:
	v_mov_b32_e32 v5, s1
	ds_read_b32 v5, v5
	v_mov_b32_e32 v6, s0
	s_add_i32 s0, s0, 1
	s_add_i32 s1, s1, 40
	s_cmp_eq_u32 s0, 20
	s_waitcnt lgkmcnt(0)
	v_cmp_lt_i32_e32 vcc, s25, v5
	s_nop 1
	v_cndmask_b32_e32 v4, v6, v4, vcc
	s_cbranch_scc0 .LBB0_330
	v_mul_lo_u32 v4, v4, 40
	v_add_u32_e32 v4, 0, v4
	v_add_u32_e32 v10, 0x20800, v4
	ds_read2_b64 v[4:7], v10 offset0:3 offset1:4
	ds_read2_b64 v[72:75], v10 offset1:1
	ds_read_b64 v[80:81], v10 offset:16
	s_waitcnt lgkmcnt(2)
	v_readfirstlane_b32 s4, v5
	s_ashr_i32 s0, s4, 6
	s_abs_i32 s1, s0
	v_cvt_f32_u32_e32 v5, s1
	v_readfirstlane_b32 s5, v7
	s_sub_i32 s6, s25, s5
	s_xor_b32 s5, s6, s0
	v_rcp_iflag_f32_e32 v5, v5
	s_ashr_i32 s19, s5, 31
	s_sub_i32 s5, 0, s1
	s_abs_i32 s7, s6
	v_mul_f32_e32 v5, 0x4f7ffffe, v5
	v_cvt_u32_f32_e32 v5, v5
	s_nop 0
	v_readfirstlane_b32 s26, v5
	s_mul_i32 s5, s5, s26
	s_mul_hi_u32 s5, s26, s5
	s_add_i32 s26, s26, s5
	s_mul_hi_u32 s5, s7, s26
	s_mul_i32 s26, s5, s1
	s_sub_i32 s7, s7, s26
	s_add_i32 s27, s5, 1
	s_sub_i32 s26, s7, s1
	s_cmp_ge_u32 s7, s1
	s_cselect_b32 s5, s27, s5
	s_cselect_b32 s7, s26, s7
	s_add_i32 s26, s5, 1
	s_cmp_ge_u32 s7, s1
	s_cselect_b32 s1, s26, s5
	s_xor_b32 s1, s1, s19
	s_sub_i32 s1, s1, s19
	s_mul_i32 s0, s1, s0
	s_lshl_b32 s26, s1, 6
	s_sub_i32 s19, s6, s0
	v_add_u32_e32 v82, s26, v77
	s_lshl_b32 s0, s19, 6
	v_mad_i64_i32 v[10:11], s[6:7], v82, s4, 0
	s_waitcnt lgkmcnt(1)
	v_lshl_add_u64 v[10:11], v[10:11], 2, v[72:73]
	s_ashr_i32 s1, s0, 31
	s_ashr_i32 s5, s4, 31
	v_lshl_add_u64 v[10:11], s[0:1], 2, v[10:11]
	v_lshl_add_u64 v[18:19], v[10:11], 0, v[78:79]
	s_lshl_b64 s[4:5], s[4:5], 4
	v_lshl_add_u64 v[20:21], v[18:19], 0, s[4:5]
	v_lshl_add_u64 v[26:27], v[20:21], 0, s[4:5]
	v_lshl_add_u64 v[28:29], v[26:27], 0, s[4:5]
	v_lshl_add_u64 v[34:35], v[28:29], 0, s[4:5]
	v_lshl_add_u64 v[36:37], v[34:35], 0, s[4:5]
	v_lshl_add_u64 v[42:43], v[36:37], 0, s[4:5]
	v_lshl_add_u64 v[44:45], v[42:43], 0, s[4:5]
	v_lshl_add_u64 v[46:47], v[44:45], 0, s[4:5]
	v_lshl_add_u64 v[50:51], v[46:47], 0, s[4:5]
	v_lshl_add_u64 v[54:55], v[50:51], 0, s[4:5]
	v_lshl_add_u64 v[58:59], v[54:55], 0, s[4:5]
	v_lshl_add_u64 v[62:63], v[58:59], 0, s[4:5]
	v_lshl_add_u64 v[66:67], v[62:63], 0, s[4:5]
	v_lshl_add_u64 v[70:71], v[66:67], 0, s[4:5]
	global_load_dwordx4 v[10:13], v[18:19], off nt
	global_load_dwordx4 v[14:17], v[20:21], off nt
	s_nop 0
	global_load_dwordx4 v[18:21], v[26:27], off nt
	global_load_dwordx4 v[22:25], v[28:29], off nt
	s_nop 0
	global_load_dwordx4 v[26:29], v[34:35], off nt
	global_load_dwordx4 v[30:33], v[36:37], off nt
	s_nop 0
	global_load_dwordx4 v[34:37], v[42:43], off nt
	global_load_dwordx4 v[38:41], v[44:45], off nt
	v_ashrrev_i32_e32 v83, 31, v82
	global_load_dwordx4 v[42:45], v[46:47], off nt
	s_waitcnt lgkmcnt(0)
	v_cmp_ne_u64_e64 s[6:7], 0, v[80:81]
	global_load_dwordx4 v[46:49], v[50:51], off nt
	s_and_b64 vcc, exec, s[6:7]
	global_load_dwordx4 v[50:53], v[54:55], off nt
	v_lshl_add_u64 v[98:99], v[82:83], 2, v[80:81]
	global_load_dwordx4 v[54:57], v[58:59], off nt
	s_nop 0
	global_load_dwordx4 v[58:61], v[62:63], off nt
	s_nop 0
	global_load_dwordx4 v[62:65], v[66:67], off nt
	s_nop 0
	global_load_dwordx4 v[66:69], v[70:71], off nt
	v_lshl_add_u64 v[70:71], v[70:71], 0, s[4:5]
	global_load_dwordx4 v[70:73], v[70:71], off nt
	s_cbranch_vccz .LBB0_358
	global_load_dword v80, v[98:99], off
	global_load_dword v81, v[98:99], off offset:16
	s_cbranch_execnz .LBB0_334

; #define LAS __attribute__((address_space(3)))
; __device__ __forceinline__ unsigned f2bf(float f) { unsigned u = __builtin_bit_cast(unsigned, f); return (u + 0x7fffu + ((u >> 16) & 1u)) >> 16; }
; __device__ __forceinline__ unsigned pk2(float lo, float hi) { return f2bf(lo) | (f2bf(hi) << 16); }
; __device__ __forceinline__ void item_store(const ItemPos p, LAS float* scr, int lane) {
;     const int c = lane & 7;
; #pragma unroll
;     for (int j = 0; j < 8; ++j) { const int n = (lane >> 3) + 8 * j; const LAS float* s = scr + (8 * c) * 65 + n;
;         u32x4 o; o.x = pk2(s[0 * 65], s[1 * 65]); o.y = pk2(s[2 * 65], s[3 * 65]); o.z = pk2(s[4 * 65], s[5 * 65]); o.w = pk2(s[6 * 65], s[7 * 65]);
;         __builtin_nontemporal_store(o, (u32x4*)(p.WT + (size_t)(p.rb + n) * p.K + p.k0 + 8 * c)); }
;     asm volatile("s_waitcnt lgkmcnt(0)" ::: "memory");
; }
.LBB0_356:
	s_ashr_i32 s19, s18, 31
	s_lshl_b64 s[0:1], s[18:19], 1
	v_lshl_add_u64 v[6:7], v[8:9], 0, s[0:1]
	v_mov_b32_e32 v85, v79
	v_lshl_add_u64 v[6:7], v[6:7], 0, v[84:85]
	ds_read_b32 v85, v102
	ds_read_b32 v98, v102 offset:260
	ds_read_b32 v99, v102 offset:520
	ds_read_b32 v131, v102 offset:780
	ds_read_b32 v132, v102 offset:1040
	ds_read_b32 v133, v102 offset:1300
	ds_read_b32 v134, v102 offset:1560
	ds_read_b32 v135, v102 offset:1820
	s_waitcnt lgkmcnt(0)
	v_bfe_u32 v130, v85, 16, 1
	v_add3_u32 v85, v85, v130, s22
	v_bfe_u32 v130, v98, 16, 1
	v_lshrrev_b32_e32 v85, 16, v85
	v_add3_u32 v98, v98, v130, s22
	v_and_or_b32 v130, v98, s23, v85
	v_bfe_u32 v85, v99, 16, 1
	v_add3_u32 v85, v99, v85, s22
	v_bfe_u32 v98, v131, 16, 1
	v_lshrrev_b32_e32 v85, 16, v85
	v_add3_u32 v98, v131, v98, s22
	v_and_or_b32 v131, v98, s23, v85
	v_bfe_u32 v85, v132, 16, 1
	v_add3_u32 v85, v132, v85, s22
	v_bfe_u32 v98, v133, 16, 1
	v_lshrrev_b32_e32 v85, 16, v85
	v_add3_u32 v98, v133, v98, s22
	v_and_or_b32 v132, v98, s23, v85
	v_bfe_u32 v85, v134, 16, 1
	v_add3_u32 v85, v134, v85, s22
	v_bfe_u32 v98, v135, 16, 1
	v_lshrrev_b32_e32 v85, 16, v85
	v_add3_u32 v98, v135, v98, s22
	v_and_or_b32 v133, v98, s23, v85
	v_add_u32_e32 v85, v3, v101
	v_mad_i64_i32 v[98:99], s[0:1], v85, v2, 0
	v_lshl_add_u64 v[98:99], v[98:99], 1, v[6:7]
	global_store_dwordx4 v[98:99], v[130:133], off nt
	ds_read_b32 v98, v102 offset:32
	ds_read_b32 v99, v102 offset:292
	ds_read_b32 v131, v102 offset:552
	ds_read_b32 v132, v102 offset:812
	ds_read_b32 v133, v102 offset:1072
	ds_read_b32 v134, v102 offset:1332
	ds_read_b32 v135, v102 offset:1592
	ds_read_b32 v136, v102 offset:1852
	s_waitcnt lgkmcnt(0)
	v_bfe_u32 v130, v98, 16, 1
	v_add3_u32 v98, v98, v130, s22
	v_bfe_u32 v130, v99, 16, 1
	v_lshrrev_b32_e32 v98, 16, v98
	v_add3_u32 v99, v99, v130, s22
	v_and_or_b32 v130, v99, s23, v98
	v_bfe_u32 v98, v131, 16, 1
	v_add3_u32 v98, v131, v98, s22
	v_bfe_u32 v99, v132, 16, 1
	v_lshrrev_b32_e32 v98, 16, v98
	v_add3_u32 v99, v132, v99, s22
	v_and_or_b32 v131, v99, s23, v98
	v_bfe_u32 v98, v133, 16, 1
	v_add3_u32 v98, v133, v98, s22
	v_bfe_u32 v99, v134, 16, 1
	v_lshrrev_b32_e32 v98, 16, v98
	v_add3_u32 v99, v134, v99, s22
	v_and_or_b32 v132, v99, s23, v98
	v_bfe_u32 v98, v135, 16, 1
	v_add3_u32 v98, v135, v98, s22
	v_bfe_u32 v99, v136, 16, 1
	v_lshrrev_b32_e32 v98, 16, v98
	v_add3_u32 v99, v136, v99, s22
	v_and_or_b32 v133, v99, s23, v98
	v_add_u32_e32 v98, 8, v85
	v_mad_i64_i32 v[98:99], s[0:1], v98, v2, 0
	v_lshl_add_u64 v[98:99], v[98:99], 1, v[6:7]
	global_store_dwordx4 v[98:99], v[130:133], off nt
	ds_read_b32 v98, v102 offset:64
	ds_read_b32 v99, v102 offset:324
	ds_read_b32 v131, v102 offset:584
	ds_read_b32 v132, v102 offset:844
	ds_read_b32 v133, v102 offset:1104
	ds_read_b32 v134, v102 offset:1364
	ds_read_b32 v135, v102 offset:1624
	ds_read_b32 v136, v102 offset:1884
	s_waitcnt lgkmcnt(0)
	v_bfe_u32 v130, v98, 16, 1
	v_add3_u32 v98, v98, v130, s22
	v_bfe_u32 v130, v99, 16, 1
	v_lshrrev_b32_e32 v98, 16, v98
	v_add3_u32 v99, v99, v130, s22
	v_and_or_b32 v130, v99, s23, v98
	v_bfe_u32 v98, v131, 16, 1
	v_add3_u32 v98, v131, v98, s22
	v_bfe_u32 v99, v132, 16, 1
	v_lshrrev_b32_e32 v98, 16, v98
	v_add3_u32 v99, v132, v99, s22
	v_and_or_b32 v131, v99, s23, v98
	v_bfe_u32 v98, v133, 16, 1
	v_add3_u32 v98, v133, v98, s22
	v_bfe_u32 v99, v134, 16, 1
	v_lshrrev_b32_e32 v98, 16, v98
	v_add3_u32 v99, v134, v99, s22
	v_and_or_b32 v132, v99, s23, v98
	v_bfe_u32 v98, v135, 16, 1
	v_add3_u32 v98, v135, v98, s22
	v_bfe_u32 v99, v136, 16, 1
	v_lshrrev_b32_e32 v98, 16, v98
	v_add3_u32 v99, v136, v99, s22
	v_and_or_b32 v133, v99, s23, v98
	v_add_u32_e32 v98, 16, v85
	v_mad_i64_i32 v[98:99], s[0:1], v98, v2, 0
	v_lshl_add_u64 v[98:99], v[98:99], 1, v[6:7]
	global_store_dwordx4 v[98:99], v[130:133], off nt
	ds_read_b32 v98, v102 offset:96
	ds_read_b32 v99, v102 offset:356
	ds_read_b32 v131, v102 offset:616
	ds_read_b32 v132, v102 offset:876
	ds_read_b32 v133, v102 offset:1136
	ds_read_b32 v134, v102 offset:1396
	ds_read_b32 v135, v102 offset:1656
	ds_read_b32 v136, v102 offset:1916
	s_waitcnt lgkmcnt(0)
	v_bfe_u32 v130, v98, 16, 1
	v_add3_u32 v98, v98, v130, s22
	v_bfe_u32 v130, v99, 16, 1
	v_lshrrev_b32_e32 v98, 16, v98
	v_add3_u32 v99, v99, v130, s22
	v_and_or_b32 v130, v99, s23, v98
	v_bfe_u32 v98, v131, 16, 1
	v_add3_u32 v98, v131, v98, s22
	v_bfe_u32 v99, v132, 16, 1
	v_lshrrev_b32_e32 v98, 16, v98
	v_add3_u32 v99, v132, v99, s22
	v_and_or_b32 v131, v99, s23, v98
	v_bfe_u32 v98, v133, 16, 1
	v_add3_u32 v98, v133, v98, s22
	v_bfe_u32 v99, v134, 16, 1
	v_lshrrev_b32_e32 v98, 16, v98
	v_add3_u32 v99, v134, v99, s22
	v_and_or_b32 v132, v99, s23, v98
	v_bfe_u32 v98, v135, 16, 1
	v_add3_u32 v98, v135, v98, s22
	v_bfe_u32 v99, v136, 16, 1
	v_lshrrev_b32_e32 v98, 16, v98
	v_add3_u32 v99, v136, v99, s22
	v_and_or_b32 v133, v99, s23, v98
	v_add_u32_e32 v98, 24, v85
	v_mad_i64_i32 v[98:99], s[0:1], v98, v2, 0
	v_lshl_add_u64 v[98:99], v[98:99], 1, v[6:7]
	global_store_dwordx4 v[98:99], v[130:133], off nt
	ds_read_b32 v98, v102 offset:128
	ds_read_b32 v99, v102 offset:388
	ds_read_b32 v131, v102 offset:648
	ds_read_b32 v132, v102 offset:908
	ds_read_b32 v133, v102 offset:1168
	ds_read_b32 v134, v102 offset:1428
	ds_read_b32 v135, v102 offset:1688
	ds_read_b32 v136, v102 offset:1948
	s_waitcnt lgkmcnt(0)
; #define LAS __attribute__((address_space(3)))
; __device__ __forceinline__ unsigned pk2(float lo, float hi) { return f2bf(lo) | (f2bf(hi) << 16); }
; __device__ __forceinline__ void item_store(const ItemPos p, LAS float* scr, int lane) {
;     const int c = lane & 7;
; #pragma unroll
;     for (int j = 0; j < 8; ++j) { const int n = (lane >> 3) + 8 * j; const LAS float* s = scr + (8 * c) * 65 + n;
;         u32x4 o; o.x = pk2(s[0 * 65], s[1 * 65]); o.y = pk2(s[2 * 65], s[3 * 65]); o.z = pk2(s[4 * 65], s[5 * 65]); o.w = pk2(s[6 * 65], s[7 * 65]);
;         __builtin_nontemporal_store(o, (u32x4*)(p.WT + (size_t)(p.rb + n) * p.K + p.k0 + 8 * c)); }
;     asm volatile("s_waitcnt lgkmcnt(0)" ::: "memory");
; }
; __device__ __forceinline__ void convert_range(unsigned char* lds, int lo, int hi, int w, int nworkers, int wave, int lane) {
;     ...
;         const int nx = it + nworkers; const bool more = nx < hi; ItemPos pn = p;
;         if (more) pn = item_load(tab, nx, lane, v, gv);
;         item_store(p, scr, lane);
;         if (!more) break;
;         it = nx; p = pn;
	v_bfe_u32 v130, v98, 16, 1
	v_add3_u32 v98, v98, v130, s22
	v_bfe_u32 v130, v99, 16, 1
	v_lshrrev_b32_e32 v98, 16, v98
	v_add3_u32 v99, v99, v130, s22
	v_and_or_b32 v130, v99, s23, v98
	v_bfe_u32 v98, v131, 16, 1
	v_add3_u32 v98, v131, v98, s22
	v_bfe_u32 v99, v132, 16, 1
	v_lshrrev_b32_e32 v98, 16, v98
	v_add3_u32 v99, v132, v99, s22
	v_and_or_b32 v131, v99, s23, v98
	v_bfe_u32 v98, v133, 16, 1
	v_add3_u32 v98, v133, v98, s22
	v_bfe_u32 v99, v134, 16, 1
	v_lshrrev_b32_e32 v98, 16, v98
	v_add3_u32 v99, v134, v99, s22
	v_and_or_b32 v132, v99, s23, v98
	v_bfe_u32 v98, v135, 16, 1
	v_add3_u32 v98, v135, v98, s22
	v_bfe_u32 v99, v136, 16, 1
	v_lshrrev_b32_e32 v98, 16, v98
	v_add3_u32 v99, v136, v99, s22
	v_and_or_b32 v133, v99, s23, v98
	v_add_u32_e32 v98, 32, v85
	v_mad_i64_i32 v[98:99], s[0:1], v98, v2, 0
	v_lshl_add_u64 v[98:99], v[98:99], 1, v[6:7]
	global_store_dwordx4 v[98:99], v[130:133], off nt
	ds_read_b32 v98, v102 offset:160
	ds_read_b32 v99, v102 offset:420
	ds_read_b32 v131, v102 offset:680
	ds_read_b32 v132, v102 offset:940
	ds_read_b32 v133, v102 offset:1200
	ds_read_b32 v134, v102 offset:1460
	ds_read_b32 v135, v102 offset:1720
	ds_read_b32 v136, v102 offset:1980
	s_waitcnt lgkmcnt(0)
	v_bfe_u32 v130, v98, 16, 1
	v_add3_u32 v98, v98, v130, s22
	v_bfe_u32 v130, v99, 16, 1
	v_lshrrev_b32_e32 v98, 16, v98
	v_add3_u32 v99, v99, v130, s22
	v_and_or_b32 v130, v99, s23, v98
	v_bfe_u32 v98, v131, 16, 1
	v_add3_u32 v98, v131, v98, s22
	v_bfe_u32 v99, v132, 16, 1
	v_lshrrev_b32_e32 v98, 16, v98
	v_add3_u32 v99, v132, v99, s22
	v_and_or_b32 v131, v99, s23, v98
	v_bfe_u32 v98, v133, 16, 1
	v_add3_u32 v98, v133, v98, s22
	v_bfe_u32 v99, v134, 16, 1
	v_lshrrev_b32_e32 v98, 16, v98
	v_add3_u32 v99, v134, v99, s22
	v_and_or_b32 v132, v99, s23, v98
	v_bfe_u32 v98, v135, 16, 1
	v_add3_u32 v98, v135, v98, s22
	v_bfe_u32 v99, v136, 16, 1
	v_lshrrev_b32_e32 v98, 16, v98
	v_add3_u32 v99, v136, v99, s22
	v_and_or_b32 v133, v99, s23, v98
	v_add_u32_e32 v98, 40, v85
	v_mad_i64_i32 v[98:99], s[0:1], v98, v2, 0
	v_lshl_add_u64 v[98:99], v[98:99], 1, v[6:7]
	global_store_dwordx4 v[98:99], v[130:133], off nt
	ds_read_b32 v98, v102 offset:192
	ds_read_b32 v99, v102 offset:452
	ds_read_b32 v131, v102 offset:712
	ds_read_b32 v132, v102 offset:972
	ds_read_b32 v133, v102 offset:1232
	ds_read_b32 v134, v102 offset:1492
	ds_read_b32 v135, v102 offset:1752
	ds_read_b32 v136, v102 offset:2012
	s_waitcnt lgkmcnt(0)
	v_bfe_u32 v130, v98, 16, 1
	v_add3_u32 v98, v98, v130, s22
	v_bfe_u32 v130, v99, 16, 1
	v_lshrrev_b32_e32 v98, 16, v98
	v_add3_u32 v99, v99, v130, s22
	v_and_or_b32 v130, v99, s23, v98
	v_bfe_u32 v98, v131, 16, 1
	v_add3_u32 v98, v131, v98, s22
	v_bfe_u32 v99, v132, 16, 1
	v_lshrrev_b32_e32 v98, 16, v98
	v_add3_u32 v99, v132, v99, s22
	v_and_or_b32 v131, v99, s23, v98
	v_bfe_u32 v98, v133, 16, 1
	v_add3_u32 v98, v133, v98, s22
	v_bfe_u32 v99, v134, 16, 1
	v_lshrrev_b32_e32 v98, 16, v98
	v_add3_u32 v99, v134, v99, s22
	v_and_or_b32 v132, v99, s23, v98
	v_bfe_u32 v98, v135, 16, 1
	v_add3_u32 v98, v135, v98, s22
	v_bfe_u32 v99, v136, 16, 1
	v_lshrrev_b32_e32 v98, 16, v98
	v_add3_u32 v99, v136, v99, s22
	v_and_or_b32 v133, v99, s23, v98
	v_add_u32_e32 v98, 48, v85
	v_mad_i64_i32 v[98:99], s[0:1], v98, v2, 0
	v_lshl_add_u64 v[98:99], v[98:99], 1, v[6:7]
	global_store_dwordx4 v[98:99], v[130:133], off nt
	ds_read_b32 v98, v102 offset:224
	ds_read_b32 v99, v102 offset:484
	ds_read_b32 v131, v102 offset:744
	ds_read_b32 v132, v102 offset:1004
	ds_read_b32 v133, v102 offset:1264
	ds_read_b32 v134, v102 offset:1524
	ds_read_b32 v135, v102 offset:1784
	ds_read_b32 v136, v102 offset:2044
	s_waitcnt lgkmcnt(0)
	v_bfe_u32 v130, v98, 16, 1
	v_add3_u32 v98, v98, v130, s22
	v_bfe_u32 v130, v99, 16, 1
	v_lshrrev_b32_e32 v98, 16, v98
	v_add3_u32 v99, v99, v130, s22
	v_and_or_b32 v130, v99, s23, v98
	v_bfe_u32 v98, v131, 16, 1
	v_add3_u32 v98, v131, v98, s22
	v_bfe_u32 v99, v132, 16, 1
	v_lshrrev_b32_e32 v98, 16, v98
	v_add3_u32 v99, v132, v99, s22
	v_and_or_b32 v131, v99, s23, v98
	v_bfe_u32 v98, v133, 16, 1
	v_add3_u32 v98, v133, v98, s22
	v_bfe_u32 v99, v134, 16, 1
	v_lshrrev_b32_e32 v98, 16, v98
	v_add3_u32 v99, v134, v99, s22
	v_and_or_b32 v132, v99, s23, v98
	v_bfe_u32 v98, v135, 16, 1
	v_add3_u32 v98, v135, v98, s22
	v_bfe_u32 v99, v136, 16, 1
	v_lshrrev_b32_e32 v98, 16, v98
	v_add3_u32 v99, v136, v99, s22
	v_add_u32_e32 v85, 56, v85
	v_and_or_b32 v133, v99, s23, v98
	v_mad_i64_i32 v[98:99], s[0:1], v85, v2, 0
	v_lshl_add_u64 v[6:7], v[98:99], 1, v[6:7]
	global_store_dwordx4 v[6:7], v[130:133], off nt
	s_waitcnt lgkmcnt(0)
	s_andn2_b64 vcc, exec, s[14:15]
	s_cbranch_vccnz .LBB0_325
	v_mov_b64_e32 v[8:9], v[74:75]
	v_mov_b32_e32 v2, v4
	v_mov_b32_e32 v3, v5
	s_mov_b32 s18, s26
	s_mov_b32 s24, s25
	s_branch .LBB0_325

; __device__ __forceinline__ ItemPos item_load(const XItem* tab, int it, int lane, f32x4 (&v)[16], float (&gv)[16]) {
;     int e = 0;
; #pragma unroll 1
;     for (int q = 1; q < 20; ++q) if (it >= tab[q].start) e = q;
;     const XItem x = tab[e]; const int item = it - x.start;
;     const int nblk = x.N >> 6, kb = item / nblk, nb = item - kb * nblk, k0 = kb << 6, n0 = nb << 6;
;     const int lr = lane >> 4, lc = (lane & 15) * 4;
;     const float* W = x.src + (size_t)(k0 + lr) * x.N + n0 + lc; const size_t rstep = (size_t)4 * x.N;
; #pragma unroll
;     for (int i = 0; i < 16; ++i) v[i] = __builtin_nontemporal_load((const f32x4*)(W + i * rstep));
; #pragma unroll
;     for (int i = 0; i < 16; ++i) gv[i] = x.g ? x.g[k0 + 4 * i + lr] : 1.0f;
;     ItemPos p; p.scaled = (x.g != nullptr); p.WT = x.dst; p.K = x.K; p.k0 = k0; p.rb = (x.mode == 0) ? n0 : ((n0 >> 7) * 256 + (x.mode - 1) * 128 + (n0 & 127));
;     return p;
.LBB0_486:
	s_nop 0
	v_mov_b32_e32 v3, s3
	ds_read_b32 v3, v3
	v_mov_b32_e32 v4, s2
	s_add_i32 s2, s2, 1
	s_add_i32 s3, s3, 40
	s_cmp_eq_u32 s2, 20
	s_waitcnt lgkmcnt(0)
	v_cmp_lt_i32_e32 vcc, s15, v3
	s_nop 1
	v_cndmask_b32_e32 v2, v4, v2, vcc
	s_cbranch_scc0 .LBB0_486
	v_mul_lo_u32 v2, v2, 40
	v_add_u32_e32 v2, 0, v2
	s_waitcnt vmcnt(0)
	v_add_u32_e32 v10, 0x20800, v2
	ds_read2_b64 v[2:5], v10 offset0:3 offset1:4
	v_mbcnt_lo_u32_b32 v0, -1, v0
	v_mbcnt_hi_u32_b32 v74, -1, v0
	ds_read2_b64 v[6:9], v10 offset1:1
	ds_read_b64 v[76:77], v10 offset:16
	s_waitcnt lgkmcnt(2)
	v_readfirstlane_b32 s4, v3
	s_ashr_i32 s2, s4, 6
	s_abs_i32 s3, s2
	v_cvt_f32_u32_e32 v3, s3
	s_sub_i32 s10, 0, s3
	v_readfirstlane_b32 s5, v5
	s_sub_i32 s5, s15, s5
	v_rcp_iflag_f32_e32 v0, v3
	s_abs_i32 s9, s5
	s_xor_b32 s8, s5, s2
	s_ashr_i32 s8, s8, 31
	v_mul_f32_e32 v0, 0x4f7ffffe, v0
	v_cvt_u32_f32_e32 v0, v0
	v_ashrrev_i32_e32 v3, 4, v74
	v_readfirstlane_b32 s11, v0
	s_mul_i32 s10, s10, s11
	s_mul_hi_u32 s10, s11, s10
	s_add_i32 s11, s11, s10
	s_mul_hi_u32 s10, s9, s11
	s_mul_i32 s11, s10, s3
	s_sub_i32 s9, s9, s11
	s_add_i32 s18, s10, 1
	s_sub_i32 s11, s9, s3
	s_cmp_ge_u32 s9, s3
	s_cselect_b32 s10, s18, s10
	s_cselect_b32 s9, s11, s9
	s_add_i32 s11, s10, 1
	s_cmp_ge_u32 s9, s3
	s_cselect_b32 s3, s11, s10
	s_xor_b32 s3, s3, s8
	s_sub_i32 s3, s3, s8
	s_mul_i32 s2, s3, s2
	s_lshl_b32 s18, s3, 6
	s_sub_i32 s19, s5, s2
	v_add_u32_e32 v78, s18, v3
	s_lshl_b32 s2, s19, 6
	v_lshlrev_b32_e32 v0, 2, v74
	v_mad_i64_i32 v[10:11], s[8:9], v78, s4, 0
	v_and_b32_e32 v5, 60, v0
	s_waitcnt lgkmcnt(1)
	v_lshl_add_u64 v[6:7], v[10:11], 2, v[6:7]
	s_ashr_i32 s3, s2, 31
	s_ashr_i32 s5, s4, 31
	v_lshl_add_u64 v[6:7], s[2:3], 2, v[6:7]
	v_lshlrev_b32_e32 v0, 2, v5
	v_lshl_add_u64 v[6:7], v[6:7], 0, v[0:1]
	s_lshl_b64 s[4:5], s[4:5], 4
	v_lshl_add_u64 v[18:19], v[6:7], 0, s[4:5]
	global_load_dwordx4 v[10:13], v[6:7], off nt
	global_load_dwordx4 v[14:17], v[18:19], off nt
	v_lshl_add_u64 v[6:7], v[18:19], 0, s[4:5]
	v_lshl_add_u64 v[26:27], v[6:7], 0, s[4:5]
	global_load_dwordx4 v[18:21], v[6:7], off nt
	global_load_dwordx4 v[22:25], v[26:27], off nt
	v_lshl_add_u64 v[6:7], v[26:27], 0, s[4:5]
	v_lshl_add_u64 v[34:35], v[6:7], 0, s[4:5]
	global_load_dwordx4 v[26:29], v[6:7], off nt
	global_load_dwordx4 v[30:33], v[34:35], off nt
	v_lshl_add_u64 v[6:7], v[34:35], 0, s[4:5]
	v_lshl_add_u64 v[42:43], v[6:7], 0, s[4:5]
	global_load_dwordx4 v[34:37], v[6:7], off nt
	global_load_dwordx4 v[38:41], v[42:43], off nt
	v_lshl_add_u64 v[6:7], v[42:43], 0, s[4:5]
	global_load_dwordx4 v[42:45], v[6:7], off nt
	v_lshl_add_u64 v[6:7], v[6:7], 0, s[4:5]
	global_load_dwordx4 v[46:49], v[6:7], off nt
	v_lshl_add_u64 v[6:7], v[6:7], 0, s[4:5]
	global_load_dwordx4 v[50:53], v[6:7], off nt
	v_lshl_add_u64 v[6:7], v[6:7], 0, s[4:5]
	global_load_dwordx4 v[54:57], v[6:7], off nt
	v_lshl_add_u64 v[6:7], v[6:7], 0, s[4:5]
	global_load_dwordx4 v[58:61], v[6:7], off nt
	v_lshl_add_u64 v[6:7], v[6:7], 0, s[4:5]
	global_load_dwordx4 v[62:65], v[6:7], off nt
	v_lshl_add_u64 v[6:7], v[6:7], 0, s[4:5]
	global_load_dwordx4 v[66:69], v[6:7], off nt
	v_lshl_add_u64 v[6:7], v[6:7], 0, s[4:5]
	global_load_dwordx4 v[70:73], v[6:7], off nt
	v_ashrrev_i32_e32 v79, 31, v78
	s_waitcnt lgkmcnt(0)
	v_cmp_ne_u64_e64 s[10:11], 0, v[76:77]
	s_and_b64 vcc, exec, s[10:11]
	v_lshl_add_u64 v[6:7], v[78:79], 2, v[76:77]
	s_cbranch_vccnz .LBB0_488
	s_getpc_b64 s[98:99]

; __device__ __forceinline__ ItemPos item_load(const XItem* tab, int it, int lane, f32x4 (&v)[16], float (&gv)[16]) {
;     ...
;     for (int i = 0; i < 16; ++i) gv[i] = x.g ? x.g[k0 + 4 * i + lr] : 1.0f;
.LBB0_488:
	global_load_dword v76, v[6:7], off
	global_load_dword v77, v[6:7], off offset:16
	v_cndmask_b32_e64 v75, 0, 1, s[10:11]
	v_cmp_ne_u32_e64 s[8:9], 1, v75
	s_andn2_b64 vcc, exec, s[10:11]
	s_cbranch_vccz .LBB0_489
	s_getpc_b64 s[98:99]

; __device__ __forceinline__ ItemPos item_load(const XItem* tab, int it, int lane, f32x4 (&v)[16], float (&gv)[16]) {
;     ...
;     for (int i = 0; i < 16; ++i) gv[i] = x.g ? x.g[k0 + 4 * i + lr] : 1.0f;
.LBB0_489:
	global_load_dword v80, v[6:7], off offset:32
	global_load_dword v81, v[6:7], off offset:48
	s_cbranch_execnz .LBB0_491

; __device__ __forceinline__ ItemPos item_load(const XItem* tab, int it, int lane, f32x4 (&v)[16], float (&gv)[16]) {
;     ...
;     for (int i = 0; i < 16; ++i) gv[i] = x.g ? x.g[k0 + 4 * i + lr] : 1.0f;
.LBB0_492:
	global_load_dword v82, v[6:7], off offset:64
	global_load_dword v83, v[6:7], off offset:80
	s_cbranch_execnz .LBB0_494

; __device__ __forceinline__ ItemPos item_load(const XItem* tab, int it, int lane, f32x4 (&v)[16], float (&gv)[16]) {
;     ...
;     for (int i = 0; i < 16; ++i) gv[i] = x.g ? x.g[k0 + 4 * i + lr] : 1.0f;
.LBB0_495:
	global_load_dword v84, v[6:7], off offset:96
	global_load_dword v85, v[6:7], off offset:112
	s_cbranch_execnz .LBB0_497

; __device__ __forceinline__ ItemPos item_load(const XItem* tab, int it, int lane, f32x4 (&v)[16], float (&gv)[16]) {
;     ...
;     for (int i = 0; i < 16; ++i) gv[i] = x.g ? x.g[k0 + 4 * i + lr] : 1.0f;
.LBB0_498:
	global_load_dword v86, v[6:7], off offset:128
	global_load_dword v87, v[6:7], off offset:144
	s_cbranch_execnz .LBB0_500

; __device__ __forceinline__ ItemPos item_load(const XItem* tab, int it, int lane, f32x4 (&v)[16], float (&gv)[16]) {
;     ...
;     for (int i = 0; i < 16; ++i) gv[i] = x.g ? x.g[k0 + 4 * i + lr] : 1.0f;
.LBB0_501:
	global_load_dword v88, v[6:7], off offset:160
	global_load_dword v89, v[6:7], off offset:176
	s_cbranch_execnz .LBB0_503

; __device__ __forceinline__ ItemPos item_load(const XItem* tab, int it, int lane, f32x4 (&v)[16], float (&gv)[16]) {
;     ...
;     for (int i = 0; i < 16; ++i) gv[i] = x.g ? x.g[k0 + 4 * i + lr] : 1.0f;
.LBB0_504:
	global_load_dword v90, v[6:7], off offset:192
	global_load_dword v91, v[6:7], off offset:208
	s_cbranch_execnz .LBB0_506

; __device__ __forceinline__ ItemPos item_load(const XItem* tab, int it, int lane, f32x4 (&v)[16], float (&gv)[16]) {
;     ...
;     for (int i = 0; i < 16; ++i) gv[i] = x.g ? x.g[k0 + 4 * i + lr] : 1.0f;
.LBB0_507:
	global_load_dword v92, v[6:7], off offset:224
	global_load_dword v93, v[6:7], off offset:240
	s_cbranch_execnz .LBB0_509

; __device__ __forceinline__ ItemPos item_load(const XItem* tab, int it, int lane, f32x4 (&v)[16], float (&gv)[16]) {
;     int e = 0;
; #pragma unroll 1
;     for (int q = 1; q < 20; ++q) if (it >= tab[q].start) e = q;
;     const XItem x = tab[e]; const int item = it - x.start;
;     const int nblk = x.N >> 6, kb = item / nblk, nb = item - kb * nblk, k0 = kb << 6, n0 = nb << 6;
;     const int lr = lane >> 4, lc = (lane & 15) * 4;
;     const float* W = x.src + (size_t)(k0 + lr) * x.N + n0 + lc; const size_t rstep = (size_t)4 * x.N;
; #pragma unroll
;     for (int i = 0; i < 16; ++i) v[i] = __builtin_nontemporal_load((const f32x4*)(W + i * rstep));
; #pragma unroll
;     for (int i = 0; i < 16; ++i) gv[i] = x.g ? x.g[k0 + 4 * i + lr] : 1.0f;
;     ItemPos p; p.scaled = (x.g != nullptr); p.WT = x.dst; p.K = x.K; p.k0 = k0; p.rb = (x.mode == 0) ? n0 : ((n0 >> 7) * 256 + (x.mode - 1) * 128 + (n0 & 127));
;     return p;
.LBB0_515:
	v_mov_b32_e32 v5, s1
	ds_read_b32 v5, v5
	s_add_i32 s1, s1, 40
	s_waitcnt lgkmcnt(0)
	v_cmp_lt_i32_e32 vcc, s24, v5
	v_mov_b32_e32 v5, s2
	s_add_i32 s2, s2, 1
	v_cndmask_b32_e32 v4, v5, v4, vcc
	s_cmp_eq_u32 s2, 20
	s_cbranch_scc0 .LBB0_515
	v_mul_lo_u32 v4, v4, 40
	v_add_u32_e32 v4, 0, v4
	v_add_u32_e32 v10, 0x20800, v4
	ds_read2_b64 v[4:7], v10 offset0:3 offset1:4
	ds_read2_b64 v[72:75], v10 offset1:1
	ds_read_b64 v[76:77], v10 offset:16
	s_waitcnt lgkmcnt(2)
	v_readfirstlane_b32 s4, v5
	s_ashr_i32 s1, s4, 6
	s_abs_i32 s2, s1
	v_cvt_f32_u32_e32 v5, s2
	v_readfirstlane_b32 s3, v7
	s_sub_i32 s3, s24, s3
	s_xor_b32 s5, s3, s1
	v_rcp_iflag_f32_e32 v5, v5
	s_ashr_i32 s9, s5, 31
	s_sub_i32 s5, 0, s2
	s_abs_i32 s8, s3
	v_mul_f32_e32 v5, 0x4f7ffffe, v5
	v_cvt_u32_f32_e32 v5, v5
	s_nop 0
	v_readfirstlane_b32 s10, v5
	s_mul_i32 s5, s5, s10
	s_mul_hi_u32 s5, s10, s5
	s_add_i32 s10, s10, s5
	s_mul_hi_u32 s5, s8, s10
	s_mul_i32 s10, s5, s2
	s_sub_i32 s8, s8, s10
	s_add_i32 s11, s5, 1
	s_sub_i32 s10, s8, s2
	s_cmp_ge_u32 s8, s2
	s_cselect_b32 s5, s11, s5
	s_cselect_b32 s8, s10, s8
	s_add_i32 s10, s5, 1
	s_cmp_ge_u32 s8, s2
	s_cselect_b32 s2, s10, s5
	s_xor_b32 s2, s2, s9
	s_sub_i32 s2, s2, s9
	s_mul_i32 s8, s2, s1
	s_lshl_b32 s1, s2, 6
	s_sub_i32 s19, s3, s8
	v_add_u32_e32 v80, s1, v3
	s_lshl_b32 s2, s19, 6
	v_mad_i64_i32 v[10:11], s[8:9], v80, s4, 0
	s_waitcnt lgkmcnt(1)
	v_lshl_add_u64 v[10:11], v[10:11], 2, v[72:73]
	s_ashr_i32 s3, s2, 31
	s_ashr_i32 s5, s4, 31
	v_lshl_add_u64 v[10:11], s[2:3], 2, v[10:11]
	v_lshl_add_u64 v[10:11], v[10:11], 0, v[0:1]
	s_lshl_b64 s[4:5], s[4:5], 4
	v_lshl_add_u64 v[18:19], v[10:11], 0, s[4:5]
	global_load_dwordx4 v[10:13], v[10:11], off nt
	s_nop 0
	global_load_dwordx4 v[14:17], v[18:19], off nt
	v_lshl_add_u64 v[18:19], v[18:19], 0, s[4:5]
	v_lshl_add_u64 v[26:27], v[18:19], 0, s[4:5]
	global_load_dwordx4 v[18:21], v[18:19], off nt
	s_nop 0
	global_load_dwordx4 v[22:25], v[26:27], off nt
	v_lshl_add_u64 v[26:27], v[26:27], 0, s[4:5]
	v_lshl_add_u64 v[34:35], v[26:27], 0, s[4:5]
	global_load_dwordx4 v[26:29], v[26:27], off nt
	s_nop 0
	global_load_dwordx4 v[30:33], v[34:35], off nt
	v_lshl_add_u64 v[34:35], v[34:35], 0, s[4:5]
	v_lshl_add_u64 v[42:43], v[34:35], 0, s[4:5]
	v_lshl_add_u64 v[46:47], v[42:43], 0, s[4:5]
	v_lshl_add_u64 v[50:51], v[46:47], 0, s[4:5]
	v_lshl_add_u64 v[54:55], v[50:51], 0, s[4:5]
	v_lshl_add_u64 v[58:59], v[54:55], 0, s[4:5]
	v_lshl_add_u64 v[62:63], v[58:59], 0, s[4:5]
	v_lshl_add_u64 v[66:67], v[62:63], 0, s[4:5]
	v_lshl_add_u64 v[70:71], v[66:67], 0, s[4:5]
	global_load_dwordx4 v[34:37], v[34:35], off nt
	s_nop 0
	global_load_dwordx4 v[38:41], v[42:43], off nt
	v_ashrrev_i32_e32 v81, 31, v80
	global_load_dwordx4 v[42:45], v[46:47], off nt
	s_waitcnt lgkmcnt(0)
	v_cmp_ne_u64_e64 s[10:11], 0, v[76:77]
	global_load_dwordx4 v[46:49], v[50:51], off nt
	s_and_b64 vcc, exec, s[10:11]
	global_load_dwordx4 v[50:53], v[54:55], off nt
	v_lshl_add_u64 v[94:95], v[80:81], 2, v[76:77]
	global_load_dwordx4 v[54:57], v[58:59], off nt
	s_nop 0
	global_load_dwordx4 v[58:61], v[62:63], off nt
	s_nop 0
	global_load_dwordx4 v[62:65], v[66:67], off nt
	s_nop 0
	global_load_dwordx4 v[66:69], v[70:71], off nt
	v_lshl_add_u64 v[70:71], v[70:71], 0, s[4:5]
	global_load_dwordx4 v[70:73], v[70:71], off nt
	s_cbranch_vccz .LBB0_543
	global_load_dword v76, v[94:95], off
	global_load_dword v77, v[94:95], off offset:16
	s_cbranch_execnz .LBB0_519

; __device__ __forceinline__ ItemPos item_load(const XItem* tab, int it, int lane, f32x4 (&v)[16], float (&gv)[16]) {
;     ...
;     for (int i = 0; i < 16; ++i) gv[i] = x.g ? x.g[k0 + 4 * i + lr] : 1.0f;
.LBB0_519:
	v_cndmask_b32_e64 v5, 0, 1, s[10:11]
	v_cmp_ne_u32_e64 s[8:9], 1, v5
	s_andn2_b64 vcc, exec, s[10:11]
	s_cbranch_vccnz .LBB0_544
	global_load_dword v80, v[94:95], off offset:32
	global_load_dword v81, v[94:95], off offset:48
	s_cbranch_execnz .LBB0_522

; __device__ __forceinline__ ItemPos item_load(const XItem* tab, int it, int lane, f32x4 (&v)[16], float (&gv)[16]) {
;     ...
;     for (int i = 0; i < 16; ++i) gv[i] = x.g ? x.g[k0 + 4 * i + lr] : 1.0f;
.LBB0_522:
	s_and_b64 vcc, exec, s[8:9]
	s_cbranch_vccnz .LBB0_545
	global_load_dword v82, v[94:95], off offset:64
	global_load_dword v83, v[94:95], off offset:80
	s_cbranch_execnz .LBB0_525

; __device__ __forceinline__ ItemPos item_load(const XItem* tab, int it, int lane, f32x4 (&v)[16], float (&gv)[16]) {
;     ...
;     for (int i = 0; i < 16; ++i) gv[i] = x.g ? x.g[k0 + 4 * i + lr] : 1.0f;
.LBB0_525:
	s_and_b64 vcc, exec, s[8:9]
	s_cbranch_vccnz .LBB0_546
	global_load_dword v84, v[94:95], off offset:96
	global_load_dword v85, v[94:95], off offset:112
	s_cbranch_execnz .LBB0_528

; __device__ __forceinline__ ItemPos item_load(const XItem* tab, int it, int lane, f32x4 (&v)[16], float (&gv)[16]) {
;     ...
;     for (int i = 0; i < 16; ++i) gv[i] = x.g ? x.g[k0 + 4 * i + lr] : 1.0f;
.LBB0_528:
	s_and_b64 vcc, exec, s[8:9]
	s_cbranch_vccnz .LBB0_547
	global_load_dword v86, v[94:95], off offset:128
	global_load_dword v87, v[94:95], off offset:144
	s_cbranch_execnz .LBB0_531

; __device__ __forceinline__ ItemPos item_load(const XItem* tab, int it, int lane, f32x4 (&v)[16], float (&gv)[16]) {
;     ...
;     for (int i = 0; i < 16; ++i) gv[i] = x.g ? x.g[k0 + 4 * i + lr] : 1.0f;
.LBB0_531:
	s_and_b64 vcc, exec, s[8:9]
	s_cbranch_vccnz .LBB0_548
	global_load_dword v88, v[94:95], off offset:160
	global_load_dword v89, v[94:95], off offset:176
	s_cbranch_execnz .LBB0_534

; __device__ __forceinline__ ItemPos item_load(const XItem* tab, int it, int lane, f32x4 (&v)[16], float (&gv)[16]) {
;     ...
;     for (int i = 0; i < 16; ++i) gv[i] = x.g ? x.g[k0 + 4 * i + lr] : 1.0f;
.LBB0_534:
	s_and_b64 vcc, exec, s[8:9]
	s_cbranch_vccnz .LBB0_549
	global_load_dword v90, v[94:95], off offset:192
	global_load_dword v91, v[94:95], off offset:208
	s_cbranch_execnz .LBB0_537

; __device__ __forceinline__ ItemPos item_load(const XItem* tab, int it, int lane, f32x4 (&v)[16], float (&gv)[16]) {
;     ...
;     for (int i = 0; i < 16; ++i) gv[i] = x.g ? x.g[k0 + 4 * i + lr] : 1.0f;
.LBB0_537:
	s_and_b64 vcc, exec, s[8:9]
	s_cbranch_vccnz .LBB0_550
	global_load_dword v92, v[94:95], off offset:224
	global_load_dword v93, v[94:95], off offset:240
	s_cbranch_execnz .LBB0_540

; #define LAS __attribute__((address_space(3)))
; __device__ __forceinline__ unsigned f2bf(float f) { unsigned u = __builtin_bit_cast(unsigned, f); return (u + 0x7fffu + ((u >> 16) & 1u)) >> 16; }
; __device__ __forceinline__ unsigned pk2(float lo, float hi) { return f2bf(lo) | (f2bf(hi) << 16); }
; __device__ __forceinline__ void item_store(const ItemPos p, LAS float* scr, int lane) {
;     const int c = lane & 7;
; #pragma unroll
;     for (int j = 0; j < 8; ++j) { const int n = (lane >> 3) + 8 * j; const LAS float* s = scr + (8 * c) * 65 + n;
;         u32x4 o; o.x = pk2(s[0 * 65], s[1 * 65]); o.y = pk2(s[2 * 65], s[3 * 65]); o.z = pk2(s[4 * 65], s[5 * 65]); o.w = pk2(s[6 * 65], s[7 * 65]);
;         __builtin_nontemporal_store(o, (u32x4*)(p.WT + (size_t)(p.rb + n) * p.K + p.k0 + 8 * c)); }
;     asm volatile("s_waitcnt lgkmcnt(0)" ::: "memory");
; }
.LBB0_541:
	s_ashr_i32 s19, s18, 31
	s_lshl_b64 s[2:3], s[18:19], 1
	v_lshl_add_u64 v[6:7], v[8:9], 0, s[2:3]
	v_mov_b32_e32 v79, v1
	v_lshl_add_u64 v[6:7], v[6:7], 0, v[78:79]
	ds_read_b32 v79, v98
	ds_read_b32 v94, v98 offset:260
	s_mov_b32 s4, 0xffff0000
	s_andn2_b64 vcc, exec, s[22:23]
	s_waitcnt lgkmcnt(0)
	v_bfe_u32 v95, v79, 16, 1
	v_add3_u32 v79, v79, v95, s0
	v_bfe_u32 v95, v94, 16, 1
	v_lshrrev_b32_e32 v79, 16, v79
	v_add3_u32 v94, v94, v95, s0
	v_and_or_b32 v100, v94, s4, v79
	ds_read_b32 v79, v98 offset:520
	ds_read_b32 v94, v98 offset:780
	s_waitcnt lgkmcnt(0)
	v_bfe_u32 v95, v79, 16, 1
	v_add3_u32 v79, v79, v95, s0
	v_bfe_u32 v95, v94, 16, 1
	v_lshrrev_b32_e32 v79, 16, v79
	v_add3_u32 v94, v94, v95, s0
	v_and_or_b32 v101, v94, s4, v79
	ds_read_b32 v79, v98 offset:1040
	ds_read_b32 v94, v98 offset:1300
	s_waitcnt lgkmcnt(0)
	v_bfe_u32 v95, v79, 16, 1
	v_add3_u32 v79, v79, v95, s0
	v_bfe_u32 v95, v94, 16, 1
	v_lshrrev_b32_e32 v79, 16, v79
	v_add3_u32 v94, v94, v95, s0
	v_and_or_b32 v102, v94, s4, v79
	ds_read_b32 v79, v98 offset:1560
	ds_read_b32 v94, v98 offset:1820
	s_waitcnt lgkmcnt(0)
	v_bfe_u32 v95, v79, 16, 1
	v_add3_u32 v79, v79, v95, s0
	v_bfe_u32 v95, v94, 16, 1
	v_lshrrev_b32_e32 v79, 16, v79
	v_add3_u32 v94, v94, v95, s0
	v_and_or_b32 v103, v94, s4, v79
	v_add_u32_e32 v79, v96, v97
	v_mad_i64_i32 v[94:95], s[2:3], v79, v2, 0
	v_lshl_add_u64 v[94:95], v[94:95], 1, v[6:7]
	global_store_dwordx4 v[94:95], v[100:103], off nt
	ds_read_b32 v94, v98 offset:32
	ds_read_b32 v95, v98 offset:292
	s_waitcnt lgkmcnt(0)
	v_bfe_u32 v100, v94, 16, 1
	v_add3_u32 v94, v94, v100, s0
	v_bfe_u32 v100, v95, 16, 1
	v_lshrrev_b32_e32 v94, 16, v94
	v_add3_u32 v95, v95, v100, s0
	v_and_or_b32 v100, v95, s4, v94
	ds_read_b32 v94, v98 offset:552
	ds_read_b32 v95, v98 offset:812
	s_waitcnt lgkmcnt(0)
	v_bfe_u32 v101, v94, 16, 1
	v_add3_u32 v94, v94, v101, s0
	v_bfe_u32 v101, v95, 16, 1
	v_lshrrev_b32_e32 v94, 16, v94
	v_add3_u32 v95, v95, v101, s0
	v_and_or_b32 v101, v95, s4, v94
	ds_read_b32 v94, v98 offset:1072
	ds_read_b32 v95, v98 offset:1332
	s_waitcnt lgkmcnt(0)
	v_bfe_u32 v102, v94, 16, 1
	v_add3_u32 v94, v94, v102, s0
	v_bfe_u32 v102, v95, 16, 1
	v_lshrrev_b32_e32 v94, 16, v94
	v_add3_u32 v95, v95, v102, s0
	v_and_or_b32 v102, v95, s4, v94
	ds_read_b32 v94, v98 offset:1592
	ds_read_b32 v95, v98 offset:1852
	s_waitcnt lgkmcnt(0)
	v_bfe_u32 v103, v94, 16, 1
	v_add3_u32 v94, v94, v103, s0
	v_bfe_u32 v103, v95, 16, 1
	v_lshrrev_b32_e32 v94, 16, v94
	v_add3_u32 v95, v95, v103, s0
	v_and_or_b32 v103, v95, s4, v94
	v_add_u32_e32 v94, 8, v79
	v_mad_i64_i32 v[94:95], s[2:3], v94, v2, 0
	v_lshl_add_u64 v[94:95], v[94:95], 1, v[6:7]
	global_store_dwordx4 v[94:95], v[100:103], off nt
	ds_read_b32 v94, v98 offset:64
	ds_read_b32 v95, v98 offset:324
	s_waitcnt lgkmcnt(0)
	v_bfe_u32 v100, v94, 16, 1
	v_add3_u32 v94, v94, v100, s0
	v_bfe_u32 v100, v95, 16, 1
	v_lshrrev_b32_e32 v94, 16, v94
	v_add3_u32 v95, v95, v100, s0
	v_and_or_b32 v100, v95, s4, v94
	ds_read_b32 v94, v98 offset:584
	ds_read_b32 v95, v98 offset:844
	s_waitcnt lgkmcnt(0)
	v_bfe_u32 v101, v94, 16, 1
	v_add3_u32 v94, v94, v101, s0
	v_bfe_u32 v101, v95, 16, 1
	v_lshrrev_b32_e32 v94, 16, v94
	v_add3_u32 v95, v95, v101, s0
	v_and_or_b32 v101, v95, s4, v94
	ds_read_b32 v94, v98 offset:1104
	ds_read_b32 v95, v98 offset:1364
	s_waitcnt lgkmcnt(0)
	v_bfe_u32 v102, v94, 16, 1
	v_add3_u32 v94, v94, v102, s0
	v_bfe_u32 v102, v95, 16, 1
	v_lshrrev_b32_e32 v94, 16, v94
	v_add3_u32 v95, v95, v102, s0
	v_and_or_b32 v102, v95, s4, v94
	ds_read_b32 v94, v98 offset:1624
	ds_read_b32 v95, v98 offset:1884
	s_waitcnt lgkmcnt(0)
	v_bfe_u32 v103, v94, 16, 1
	v_add3_u32 v94, v94, v103, s0
	v_bfe_u32 v103, v95, 16, 1
	v_lshrrev_b32_e32 v94, 16, v94
	v_add3_u32 v95, v95, v103, s0
	v_and_or_b32 v103, v95, s4, v94
	v_add_u32_e32 v94, 16, v79
	v_mad_i64_i32 v[94:95], s[2:3], v94, v2, 0
	v_lshl_add_u64 v[94:95], v[94:95], 1, v[6:7]
	global_store_dwordx4 v[94:95], v[100:103], off nt
	ds_read_b32 v94, v98 offset:96
	ds_read_b32 v95, v98 offset:356
	s_waitcnt lgkmcnt(0)
	v_bfe_u32 v100, v94, 16, 1
	v_add3_u32 v94, v94, v100, s0
	v_bfe_u32 v100, v95, 16, 1
	v_lshrrev_b32_e32 v94, 16, v94
	v_add3_u32 v95, v95, v100, s0
	v_and_or_b32 v100, v95, s4, v94
	ds_read_b32 v94, v98 offset:616
	ds_read_b32 v95, v98 offset:876
	s_waitcnt lgkmcnt(0)
	v_bfe_u32 v101, v94, 16, 1
	v_add3_u32 v94, v94, v101, s0
	v_bfe_u32 v101, v95, 16, 1
	v_lshrrev_b32_e32 v94, 16, v94
	v_add3_u32 v95, v95, v101, s0
	v_and_or_b32 v101, v95, s4, v94
	ds_read_b32 v94, v98 offset:1136
	ds_read_b32 v95, v98 offset:1396
	s_waitcnt lgkmcnt(0)
	v_bfe_u32 v102, v94, 16, 1
	v_add3_u32 v94, v94, v102, s0
	v_bfe_u32 v102, v95, 16, 1
	v_lshrrev_b32_e32 v94, 16, v94
	v_add3_u32 v95, v95, v102, s0
	v_and_or_b32 v102, v95, s4, v94
	ds_read_b32 v94, v98 offset:1656
	ds_read_b32 v95, v98 offset:1916
	s_waitcnt lgkmcnt(0)
	v_bfe_u32 v103, v94, 16, 1
	v_add3_u32 v94, v94, v103, s0
	v_bfe_u32 v103, v95, 16, 1
	v_lshrrev_b32_e32 v94, 16, v94
	v_add3_u32 v95, v95, v103, s0
	v_and_or_b32 v103, v95, s4, v94
	v_add_u32_e32 v94, 24, v79
	v_mad_i64_i32 v[94:95], s[2:3], v94, v2, 0
	v_lshl_add_u64 v[94:95], v[94:95], 1, v[6:7]
	global_store_dwordx4 v[94:95], v[100:103], off nt
	ds_read_b32 v94, v98 offset:128
	ds_read_b32 v95, v98 offset:388
	s_waitcnt lgkmcnt(0)
; #define LAS __attribute__((address_space(3)))
; __device__ __forceinline__ unsigned pk2(float lo, float hi) { return f2bf(lo) | (f2bf(hi) << 16); }
; __device__ __forceinline__ void item_store(const ItemPos p, LAS float* scr, int lane) {
;     const int c = lane & 7;
; #pragma unroll
;     for (int j = 0; j < 8; ++j) { const int n = (lane >> 3) + 8 * j; const LAS float* s = scr + (8 * c) * 65 + n;
;         u32x4 o; o.x = pk2(s[0 * 65], s[1 * 65]); o.y = pk2(s[2 * 65], s[3 * 65]); o.z = pk2(s[4 * 65], s[5 * 65]); o.w = pk2(s[6 * 65], s[7 * 65]);
;         __builtin_nontemporal_store(o, (u32x4*)(p.WT + (size_t)(p.rb + n) * p.K + p.k0 + 8 * c)); }
;     asm volatile("s_waitcnt lgkmcnt(0)" ::: "memory");
; }
; __device__ __forceinline__ void convert_range(unsigned char* lds, int lo, int hi, int w, int nworkers, int wave, int lane) {
;     ...
;         const int nx = it + nworkers; const bool more = nx < hi; ItemPos pn = p;
;         if (more) pn = item_load(tab, nx, lane, v, gv);
;         item_store(p, scr, lane);
;         if (!more) break;
;         it = nx; p = pn;
	v_bfe_u32 v100, v94, 16, 1
	v_add3_u32 v94, v94, v100, s0
	v_bfe_u32 v100, v95, 16, 1
	v_lshrrev_b32_e32 v94, 16, v94
	v_add3_u32 v95, v95, v100, s0
	v_and_or_b32 v100, v95, s4, v94
	ds_read_b32 v94, v98 offset:648
	ds_read_b32 v95, v98 offset:908
	s_waitcnt lgkmcnt(0)
	v_bfe_u32 v101, v94, 16, 1
	v_add3_u32 v94, v94, v101, s0
	v_bfe_u32 v101, v95, 16, 1
	v_lshrrev_b32_e32 v94, 16, v94
	v_add3_u32 v95, v95, v101, s0
	v_and_or_b32 v101, v95, s4, v94
	ds_read_b32 v94, v98 offset:1168
	ds_read_b32 v95, v98 offset:1428
	s_waitcnt lgkmcnt(0)
	v_bfe_u32 v102, v94, 16, 1
	v_add3_u32 v94, v94, v102, s0
	v_bfe_u32 v102, v95, 16, 1
	v_lshrrev_b32_e32 v94, 16, v94
	v_add3_u32 v95, v95, v102, s0
	v_and_or_b32 v102, v95, s4, v94
	ds_read_b32 v94, v98 offset:1688
	ds_read_b32 v95, v98 offset:1948
	s_waitcnt lgkmcnt(0)
	v_bfe_u32 v103, v94, 16, 1
	v_add3_u32 v94, v94, v103, s0
	v_bfe_u32 v103, v95, 16, 1
	v_lshrrev_b32_e32 v94, 16, v94
	v_add3_u32 v95, v95, v103, s0
	v_and_or_b32 v103, v95, s4, v94
	v_add_u32_e32 v94, 32, v79
	v_mad_i64_i32 v[94:95], s[2:3], v94, v2, 0
	v_lshl_add_u64 v[94:95], v[94:95], 1, v[6:7]
	global_store_dwordx4 v[94:95], v[100:103], off nt
	ds_read_b32 v94, v98 offset:160
	ds_read_b32 v95, v98 offset:420
	s_waitcnt lgkmcnt(0)
	v_bfe_u32 v100, v94, 16, 1
	v_add3_u32 v94, v94, v100, s0
	v_bfe_u32 v100, v95, 16, 1
	v_lshrrev_b32_e32 v94, 16, v94
	v_add3_u32 v95, v95, v100, s0
	v_and_or_b32 v100, v95, s4, v94
	ds_read_b32 v94, v98 offset:680
	ds_read_b32 v95, v98 offset:940
	s_waitcnt lgkmcnt(0)
	v_bfe_u32 v101, v94, 16, 1
	v_add3_u32 v94, v94, v101, s0
	v_bfe_u32 v101, v95, 16, 1
	v_lshrrev_b32_e32 v94, 16, v94
	v_add3_u32 v95, v95, v101, s0
	v_and_or_b32 v101, v95, s4, v94
	ds_read_b32 v94, v98 offset:1200
	ds_read_b32 v95, v98 offset:1460
	s_waitcnt lgkmcnt(0)
	v_bfe_u32 v102, v94, 16, 1
	v_add3_u32 v94, v94, v102, s0
	v_bfe_u32 v102, v95, 16, 1
	v_lshrrev_b32_e32 v94, 16, v94
	v_add3_u32 v95, v95, v102, s0
	v_and_or_b32 v102, v95, s4, v94
	ds_read_b32 v94, v98 offset:1720
	ds_read_b32 v95, v98 offset:1980
	s_waitcnt lgkmcnt(0)
	v_bfe_u32 v103, v94, 16, 1
	v_add3_u32 v94, v94, v103, s0
	v_bfe_u32 v103, v95, 16, 1
	v_lshrrev_b32_e32 v94, 16, v94
	v_add3_u32 v95, v95, v103, s0
	v_and_or_b32 v103, v95, s4, v94
	v_add_u32_e32 v94, 40, v79
	v_mad_i64_i32 v[94:95], s[2:3], v94, v2, 0
	v_lshl_add_u64 v[94:95], v[94:95], 1, v[6:7]
	global_store_dwordx4 v[94:95], v[100:103], off nt
	ds_read_b32 v94, v98 offset:192
	ds_read_b32 v95, v98 offset:452
	s_waitcnt lgkmcnt(0)
	v_bfe_u32 v100, v94, 16, 1
	v_add3_u32 v94, v94, v100, s0
	v_bfe_u32 v100, v95, 16, 1
	v_lshrrev_b32_e32 v94, 16, v94
	v_add3_u32 v95, v95, v100, s0
	v_and_or_b32 v100, v95, s4, v94
	ds_read_b32 v94, v98 offset:712
	ds_read_b32 v95, v98 offset:972
	s_waitcnt lgkmcnt(0)
	v_bfe_u32 v101, v94, 16, 1
	v_add3_u32 v94, v94, v101, s0
	v_bfe_u32 v101, v95, 16, 1
	v_lshrrev_b32_e32 v94, 16, v94
	v_add3_u32 v95, v95, v101, s0
	v_and_or_b32 v101, v95, s4, v94
	ds_read_b32 v94, v98 offset:1232
	ds_read_b32 v95, v98 offset:1492
	s_waitcnt lgkmcnt(0)
	v_bfe_u32 v102, v94, 16, 1
	v_add3_u32 v94, v94, v102, s0
	v_bfe_u32 v102, v95, 16, 1
	v_lshrrev_b32_e32 v94, 16, v94
	v_add3_u32 v95, v95, v102, s0
	v_and_or_b32 v102, v95, s4, v94
	ds_read_b32 v94, v98 offset:1752
	ds_read_b32 v95, v98 offset:2012
	s_waitcnt lgkmcnt(0)
	v_bfe_u32 v103, v94, 16, 1
	v_add3_u32 v94, v94, v103, s0
	v_bfe_u32 v103, v95, 16, 1
	v_lshrrev_b32_e32 v94, 16, v94
	v_add3_u32 v95, v95, v103, s0
	v_and_or_b32 v103, v95, s4, v94
	v_add_u32_e32 v94, 48, v79
	v_mad_i64_i32 v[94:95], s[2:3], v94, v2, 0
	v_lshl_add_u64 v[94:95], v[94:95], 1, v[6:7]
	global_store_dwordx4 v[94:95], v[100:103], off nt
	ds_read_b32 v94, v98 offset:224
	ds_read_b32 v95, v98 offset:484
	v_add_u32_e32 v79, 56, v79
	s_waitcnt lgkmcnt(0)
	v_bfe_u32 v100, v94, 16, 1
	v_add3_u32 v94, v94, v100, s0
	v_bfe_u32 v100, v95, 16, 1
	v_lshrrev_b32_e32 v94, 16, v94
	v_add3_u32 v95, v95, v100, s0
	v_and_or_b32 v100, v95, s4, v94
	ds_read_b32 v94, v98 offset:744
	ds_read_b32 v95, v98 offset:1004
	s_waitcnt lgkmcnt(0)
	v_bfe_u32 v101, v94, 16, 1
	v_add3_u32 v94, v94, v101, s0
	v_bfe_u32 v101, v95, 16, 1
	v_lshrrev_b32_e32 v94, 16, v94
	v_add3_u32 v95, v95, v101, s0
	v_and_or_b32 v101, v95, s4, v94
	ds_read_b32 v94, v98 offset:1264
	ds_read_b32 v95, v98 offset:1524
	s_waitcnt lgkmcnt(0)
	v_bfe_u32 v102, v94, 16, 1
	v_add3_u32 v94, v94, v102, s0
	v_bfe_u32 v102, v95, 16, 1
	v_lshrrev_b32_e32 v94, 16, v94
	v_add3_u32 v95, v95, v102, s0
	v_and_or_b32 v102, v95, s4, v94
	ds_read_b32 v94, v98 offset:1784
	ds_read_b32 v95, v98 offset:2044
	s_waitcnt lgkmcnt(0)
	v_bfe_u32 v103, v94, 16, 1
	v_add3_u32 v94, v94, v103, s0
	v_bfe_u32 v103, v95, 16, 1
	v_lshrrev_b32_e32 v94, 16, v94
	v_add3_u32 v95, v95, v103, s0
	v_and_or_b32 v103, v95, s4, v94
	v_mad_i64_i32 v[94:95], s[2:3], v79, v2, 0
	v_lshl_add_u64 v[6:7], v[94:95], 1, v[6:7]
	global_store_dwordx4 v[6:7], v[100:103], off nt
	s_waitcnt lgkmcnt(0)
	s_cbranch_vccnz .LBB0_510
	v_mov_b64_e32 v[8:9], v[74:75]
	v_mov_b32_e32 v2, v4
	v_mov_b32_e32 v96, v5
	s_mov_b32 s18, s1
	s_mov_b32 s15, s24
	s_branch .LBB0_510

; __device__ __forceinline__ ItemPos item_load(const XItem* tab, int it, int lane, f32x4 (&v)[16], float (&gv)[16]) {
;     int e = 0;
; #pragma unroll 1
;     for (int q = 1; q < 20; ++q) if (it >= tab[q].start) e = q;
;     const XItem x = tab[e]; const int item = it - x.start;
;     const int nblk = x.N >> 6, kb = item / nblk, nb = item - kb * nblk, k0 = kb << 6, n0 = nb << 6;
;     const int lr = lane >> 4, lc = (lane & 15) * 4;
;     const float* W = x.src + (size_t)(k0 + lr) * x.N + n0 + lc; const size_t rstep = (size_t)4 * x.N;
; #pragma unroll
;     for (int i = 0; i < 16; ++i) v[i] = __builtin_nontemporal_load((const f32x4*)(W + i * rstep));
; #pragma unroll
;     for (int i = 0; i < 16; ++i) gv[i] = x.g ? x.g[k0 + 4 * i + lr] : 1.0f;
;     ItemPos p; p.scaled = (x.g != nullptr); p.WT = x.dst; p.K = x.K; p.k0 = k0; p.rb = (x.mode == 0) ? n0 : ((n0 >> 7) * 256 + (x.mode - 1) * 128 + (n0 & 127));
;     return p;
.LBB0_749:
	v_mov_b32_e32 v2, s1
	ds_read_b32 v2, v2
	v_mov_b32_e32 v3, s2
	s_add_i32 s2, s2, 1
	s_add_i32 s1, s1, 40
	s_cmp_eq_u32 s2, 20
	s_waitcnt lgkmcnt(0)
	v_cmp_lt_i32_e32 vcc, s20, v2
	s_nop 1
	v_cndmask_b32_e32 v0, v3, v0, vcc
	s_cbranch_scc0 .LBB0_749
	v_mul_lo_u32 v0, v0, 40
	v_add_u32_e32 v0, 0, v0
	v_add_u32_e32 v0, 0x20800, v0
	ds_read2_b64 v[2:5], v0 offset0:3 offset1:4
	ds_read2_b64 v[6:9], v0 offset1:1
	ds_read_b64 v[74:75], v0 offset:16
	v_ashrrev_i32_e32 v97, 4, v96
	v_lshlrev_b32_e32 v10, 2, v96
	s_waitcnt lgkmcnt(2)
	v_readfirstlane_b32 s4, v3
	s_ashr_i32 s1, s4, 6
	s_abs_i32 s2, s1
	v_cvt_f32_u32_e32 v3, s2
	s_sub_i32 s7, 0, s2
	v_readfirstlane_b32 s3, v5
	s_sub_i32 s3, s20, s3
	v_rcp_iflag_f32_e32 v0, v3
	s_abs_i32 s6, s3
	s_xor_b32 s5, s3, s1
	s_ashr_i32 s5, s5, 31
	v_mul_f32_e32 v0, 0x4f7ffffe, v0
	v_cvt_u32_f32_e32 v0, v0
	v_and_b32_e32 v5, 60, v10
	v_readfirstlane_b32 s8, v0
	s_mul_i32 s7, s7, s8
	s_mul_hi_u32 s7, s8, s7
	s_add_i32 s8, s8, s7
	s_mul_hi_u32 s7, s6, s8
	s_mul_i32 s8, s7, s2
	s_sub_i32 s6, s6, s8
	s_add_i32 s9, s7, 1
	s_sub_i32 s8, s6, s2
	s_cmp_ge_u32 s6, s2
	s_cselect_b32 s7, s9, s7
	s_cselect_b32 s6, s8, s6
	s_add_i32 s8, s7, 1
	s_cmp_ge_u32 s6, s2
	s_cselect_b32 s2, s8, s7
	s_xor_b32 s2, s2, s5
	s_sub_i32 s2, s2, s5
	s_mul_i32 s1, s2, s1
	s_lshl_b32 s10, s2, 6
	s_sub_i32 s1, s3, s1
	v_add_u32_e32 v76, s10, v97
	s_lshl_b32 s2, s1, 6
	v_mad_i64_i32 v[10:11], s[6:7], v76, s4, 0
	s_waitcnt lgkmcnt(1)
	v_lshl_add_u64 v[6:7], v[10:11], 2, v[6:7]
	s_ashr_i32 s3, s2, 31
	s_ashr_i32 s5, s4, 31
	v_lshl_add_u64 v[6:7], s[2:3], 2, v[6:7]
	v_lshlrev_b32_e32 v0, 2, v5
	v_lshl_add_u64 v[6:7], v[6:7], 0, v[0:1]
	s_lshl_b64 s[4:5], s[4:5], 4
	v_lshl_add_u64 v[18:19], v[6:7], 0, s[4:5]
	global_load_dwordx4 v[10:13], v[6:7], off nt
	global_load_dwordx4 v[14:17], v[18:19], off nt
	v_lshl_add_u64 v[6:7], v[18:19], 0, s[4:5]
	v_lshl_add_u64 v[26:27], v[6:7], 0, s[4:5]
	global_load_dwordx4 v[18:21], v[6:7], off nt
	global_load_dwordx4 v[22:25], v[26:27], off nt
	v_lshl_add_u64 v[6:7], v[26:27], 0, s[4:5]
	v_lshl_add_u64 v[34:35], v[6:7], 0, s[4:5]
	global_load_dwordx4 v[26:29], v[6:7], off nt
	global_load_dwordx4 v[30:33], v[34:35], off nt
	v_lshl_add_u64 v[6:7], v[34:35], 0, s[4:5]
	v_lshl_add_u64 v[42:43], v[6:7], 0, s[4:5]
	global_load_dwordx4 v[34:37], v[6:7], off nt
	global_load_dwordx4 v[38:41], v[42:43], off nt
	v_lshl_add_u64 v[6:7], v[42:43], 0, s[4:5]
	global_load_dwordx4 v[42:45], v[6:7], off nt
	v_lshl_add_u64 v[6:7], v[6:7], 0, s[4:5]
	global_load_dwordx4 v[46:49], v[6:7], off nt
	v_lshl_add_u64 v[6:7], v[6:7], 0, s[4:5]
	global_load_dwordx4 v[50:53], v[6:7], off nt
	v_lshl_add_u64 v[6:7], v[6:7], 0, s[4:5]
	global_load_dwordx4 v[54:57], v[6:7], off nt
	v_lshl_add_u64 v[6:7], v[6:7], 0, s[4:5]
	global_load_dwordx4 v[58:61], v[6:7], off nt
	v_lshl_add_u64 v[6:7], v[6:7], 0, s[4:5]
	global_load_dwordx4 v[62:65], v[6:7], off nt
	v_lshl_add_u64 v[6:7], v[6:7], 0, s[4:5]
	global_load_dwordx4 v[66:69], v[6:7], off nt
	v_lshl_add_u64 v[6:7], v[6:7], 0, s[4:5]
	global_load_dwordx4 v[70:73], v[6:7], off nt
	v_ashrrev_i32_e32 v77, 31, v76
	s_waitcnt lgkmcnt(0)
	v_cmp_ne_u64_e64 s[8:9], 0, v[74:75]
	s_and_b64 vcc, exec, s[8:9]
	v_lshl_add_u64 v[6:7], v[76:77], 2, v[74:75]
	s_cbranch_vccnz .LBB0_751
	s_getpc_b64 s[98:99]

; __device__ __forceinline__ ItemPos item_load(const XItem* tab, int it, int lane, f32x4 (&v)[16], float (&gv)[16]) {
;     ...
;     for (int i = 0; i < 16; ++i) gv[i] = x.g ? x.g[k0 + 4 * i + lr] : 1.0f;
.LBB0_751:
	global_load_dword v76, v[6:7], off
	global_load_dword v77, v[6:7], off offset:16
	v_cndmask_b32_e64 v3, 0, 1, s[8:9]
	v_cmp_ne_u32_e64 s[6:7], 1, v3
	s_andn2_b64 vcc, exec, s[8:9]
	s_cbranch_vccz .LBB0_752
	s_getpc_b64 s[98:99]

; __device__ __forceinline__ ItemPos item_load(const XItem* tab, int it, int lane, f32x4 (&v)[16], float (&gv)[16]) {
;     int e = 0;
; #pragma unroll 1
;     for (int q = 1; q < 20; ++q) if (it >= tab[q].start) e = q;
;     const XItem x = tab[e]; const int item = it - x.start;
;     const int nblk = x.N >> 6, kb = item / nblk, nb = item - kb * nblk, k0 = kb << 6, n0 = nb << 6;
;     const int lr = lane >> 4, lc = (lane & 15) * 4;
;     const float* W = x.src + (size_t)(k0 + lr) * x.N + n0 + lc; const size_t rstep = (size_t)4 * x.N;
; #pragma unroll
;     for (int i = 0; i < 16; ++i) v[i] = __builtin_nontemporal_load((const f32x4*)(W + i * rstep));
; #pragma unroll
;     for (int i = 0; i < 16; ++i) gv[i] = x.g ? x.g[k0 + 4 * i + lr] : 1.0f;
;     ItemPos p; p.scaled = (x.g != nullptr); p.WT = x.dst; p.K = x.K; p.k0 = k0; p.rb = (x.mode == 0) ? n0 : ((n0 >> 7) * 256 + (x.mode - 1) * 128 + (n0 & 127));
;     return p;
.LBB0_778:
	v_mov_b32_e32 v5, s1
	ds_read_b32 v5, v5
	s_add_i32 s1, s1, 40
	s_waitcnt lgkmcnt(0)
	v_cmp_lt_i32_e32 vcc, s21, v5
	v_mov_b32_e32 v5, s2
	s_add_i32 s2, s2, 1
	v_cndmask_b32_e32 v4, v5, v4, vcc
	s_cmp_eq_u32 s2, 20
	s_cbranch_scc0 .LBB0_778
	v_mul_lo_u32 v4, v4, 40
	v_add_u32_e32 v4, 0, v4
	v_add_u32_e32 v10, 0x20800, v4
	ds_read2_b64 v[4:7], v10 offset0:3 offset1:4
	ds_read2_b64 v[72:75], v10 offset1:1
	ds_read_b64 v[76:77], v10 offset:16
	s_waitcnt lgkmcnt(2)
	v_readfirstlane_b32 s4, v5
	s_ashr_i32 s1, s4, 6
	s_abs_i32 s2, s1
	v_cvt_f32_u32_e32 v5, s2
	v_readfirstlane_b32 s3, v7
	s_sub_i32 s3, s21, s3
	s_xor_b32 s5, s3, s1
	v_rcp_iflag_f32_e32 v5, v5
	s_ashr_i32 s7, s5, 31
	s_sub_i32 s5, 0, s2
	s_abs_i32 s6, s3
	v_mul_f32_e32 v5, 0x4f7ffffe, v5
	v_cvt_u32_f32_e32 v5, v5
	s_nop 0
	v_readfirstlane_b32 s8, v5
	s_mul_i32 s5, s5, s8
	s_mul_hi_u32 s5, s8, s5
	s_add_i32 s8, s8, s5
	s_mul_hi_u32 s5, s6, s8
	s_mul_i32 s8, s5, s2
	s_sub_i32 s6, s6, s8
	s_add_i32 s9, s5, 1
	s_sub_i32 s8, s6, s2
	s_cmp_ge_u32 s6, s2
	s_cselect_b32 s5, s9, s5
	s_cselect_b32 s6, s8, s6
	s_add_i32 s8, s5, 1
	s_cmp_ge_u32 s6, s2
	s_cselect_b32 s2, s8, s5
	s_xor_b32 s2, s2, s7
	s_sub_i32 s2, s2, s7
	s_mul_i32 s6, s2, s1
	s_lshl_b32 s1, s2, 6
	s_sub_i32 s11, s3, s6
	v_add_u32_e32 v80, s1, v97
	s_lshl_b32 s2, s11, 6
	v_mad_i64_i32 v[10:11], s[6:7], v80, s4, 0
	s_waitcnt lgkmcnt(1)
	v_lshl_add_u64 v[10:11], v[10:11], 2, v[72:73]
	s_ashr_i32 s3, s2, 31
	s_ashr_i32 s5, s4, 31
	v_lshl_add_u64 v[10:11], s[2:3], 2, v[10:11]
	v_lshl_add_u64 v[10:11], v[10:11], 0, v[0:1]
	s_lshl_b64 s[4:5], s[4:5], 4
	v_lshl_add_u64 v[18:19], v[10:11], 0, s[4:5]
	global_load_dwordx4 v[10:13], v[10:11], off nt
	s_nop 0
	global_load_dwordx4 v[14:17], v[18:19], off nt
	v_lshl_add_u64 v[18:19], v[18:19], 0, s[4:5]
	v_lshl_add_u64 v[26:27], v[18:19], 0, s[4:5]
	global_load_dwordx4 v[18:21], v[18:19], off nt
	s_nop 0
	global_load_dwordx4 v[22:25], v[26:27], off nt
	v_lshl_add_u64 v[26:27], v[26:27], 0, s[4:5]
	v_lshl_add_u64 v[34:35], v[26:27], 0, s[4:5]
	global_load_dwordx4 v[26:29], v[26:27], off nt
	s_nop 0
	global_load_dwordx4 v[30:33], v[34:35], off nt
	v_lshl_add_u64 v[34:35], v[34:35], 0, s[4:5]
	v_lshl_add_u64 v[42:43], v[34:35], 0, s[4:5]
	v_lshl_add_u64 v[46:47], v[42:43], 0, s[4:5]
	v_lshl_add_u64 v[50:51], v[46:47], 0, s[4:5]
	v_lshl_add_u64 v[54:55], v[50:51], 0, s[4:5]
	v_lshl_add_u64 v[58:59], v[54:55], 0, s[4:5]
	v_lshl_add_u64 v[62:63], v[58:59], 0, s[4:5]
	v_lshl_add_u64 v[66:67], v[62:63], 0, s[4:5]
	v_lshl_add_u64 v[70:71], v[66:67], 0, s[4:5]
	global_load_dwordx4 v[34:37], v[34:35], off nt
	s_nop 0
	global_load_dwordx4 v[38:41], v[42:43], off nt
	v_ashrrev_i32_e32 v81, 31, v80
	global_load_dwordx4 v[42:45], v[46:47], off nt
	s_waitcnt lgkmcnt(0)
	v_cmp_ne_u64_e64 s[8:9], 0, v[76:77]
	global_load_dwordx4 v[46:49], v[50:51], off nt
	s_and_b64 vcc, exec, s[8:9]
	global_load_dwordx4 v[50:53], v[54:55], off nt
	v_lshl_add_u64 v[94:95], v[80:81], 2, v[76:77]
	global_load_dwordx4 v[54:57], v[58:59], off nt
	s_nop 0
	global_load_dwordx4 v[58:61], v[62:63], off nt
	s_nop 0
	global_load_dwordx4 v[62:65], v[66:67], off nt
	s_nop 0
	global_load_dwordx4 v[66:69], v[70:71], off nt
	v_lshl_add_u64 v[70:71], v[70:71], 0, s[4:5]
	global_load_dwordx4 v[70:73], v[70:71], off nt
	s_cbranch_vccz .LBB0_806
	global_load_dword v76, v[94:95], off
	global_load_dword v77, v[94:95], off offset:16
	s_cbranch_execnz .LBB0_782

; __device__ __forceinline__ ItemPos item_load(const XItem* tab, int it, int lane, f32x4 (&v)[16], float (&gv)[16]) {
;     ...
;     for (int i = 0; i < 16; ++i) gv[i] = x.g ? x.g[k0 + 4 * i + lr] : 1.0f;
.LBB0_782:
	v_cndmask_b32_e64 v5, 0, 1, s[8:9]
	v_cmp_ne_u32_e64 s[6:7], 1, v5
	s_andn2_b64 vcc, exec, s[8:9]
	s_cbranch_vccnz .LBB0_807
	global_load_dword v80, v[94:95], off offset:32
	global_load_dword v81, v[94:95], off offset:48
	s_cbranch_execnz .LBB0_785

; __device__ __forceinline__ ItemPos item_load(const XItem* tab, int it, int lane, f32x4 (&v)[16], float (&gv)[16]) {
;     ...
;     for (int i = 0; i < 16; ++i) gv[i] = x.g ? x.g[k0 + 4 * i + lr] : 1.0f;
.LBB0_785:
	s_and_b64 vcc, exec, s[6:7]
	s_cbranch_vccnz .LBB0_808
	global_load_dword v82, v[94:95], off offset:64
	global_load_dword v83, v[94:95], off offset:80
	s_cbranch_execnz .LBB0_788

; __device__ __forceinline__ ItemPos item_load(const XItem* tab, int it, int lane, f32x4 (&v)[16], float (&gv)[16]) {
;     ...
;     for (int i = 0; i < 16; ++i) gv[i] = x.g ? x.g[k0 + 4 * i + lr] : 1.0f;
.LBB0_788:
	s_and_b64 vcc, exec, s[6:7]
	s_cbranch_vccnz .LBB0_809
	global_load_dword v84, v[94:95], off offset:96
	global_load_dword v85, v[94:95], off offset:112
	s_cbranch_execnz .LBB0_791

; __device__ __forceinline__ ItemPos item_load(const XItem* tab, int it, int lane, f32x4 (&v)[16], float (&gv)[16]) {
;     ...
;     for (int i = 0; i < 16; ++i) gv[i] = x.g ? x.g[k0 + 4 * i + lr] : 1.0f;
.LBB0_791:
	s_and_b64 vcc, exec, s[6:7]
	s_cbranch_vccnz .LBB0_810
	global_load_dword v86, v[94:95], off offset:128
	global_load_dword v87, v[94:95], off offset:144
	s_cbranch_execnz .LBB0_794

; __device__ __forceinline__ ItemPos item_load(const XItem* tab, int it, int lane, f32x4 (&v)[16], float (&gv)[16]) {
;     ...
;     for (int i = 0; i < 16; ++i) gv[i] = x.g ? x.g[k0 + 4 * i + lr] : 1.0f;
.LBB0_794:
	s_and_b64 vcc, exec, s[6:7]
	s_cbranch_vccnz .LBB0_811
	global_load_dword v88, v[94:95], off offset:160
	global_load_dword v89, v[94:95], off offset:176
	s_cbranch_execnz .LBB0_797

; __device__ __forceinline__ ItemPos item_load(const XItem* tab, int it, int lane, f32x4 (&v)[16], float (&gv)[16]) {
;     ...
;     for (int i = 0; i < 16; ++i) gv[i] = x.g ? x.g[k0 + 4 * i + lr] : 1.0f;
.LBB0_797:
	s_and_b64 vcc, exec, s[6:7]
	s_cbranch_vccnz .LBB0_812
	global_load_dword v90, v[94:95], off offset:192
	global_load_dword v91, v[94:95], off offset:208
	s_cbranch_execnz .LBB0_800

; __device__ __forceinline__ ItemPos item_load(const XItem* tab, int it, int lane, f32x4 (&v)[16], float (&gv)[16]) {
;     ...
;     for (int i = 0; i < 16; ++i) gv[i] = x.g ? x.g[k0 + 4 * i + lr] : 1.0f;
.LBB0_800:
	s_and_b64 vcc, exec, s[6:7]
	s_cbranch_vccnz .LBB0_813
	global_load_dword v92, v[94:95], off offset:224
	global_load_dword v93, v[94:95], off offset:240
	s_cbranch_execnz .LBB0_803

; #define LAS __attribute__((address_space(3)))
; __device__ __forceinline__ unsigned f2bf(float f) { unsigned u = __builtin_bit_cast(unsigned, f); return (u + 0x7fffu + ((u >> 16) & 1u)) >> 16; }
; __device__ __forceinline__ unsigned pk2(float lo, float hi) { return f2bf(lo) | (f2bf(hi) << 16); }
; __device__ __forceinline__ void item_store(const ItemPos p, LAS float* scr, int lane) {
;     const int c = lane & 7;
; #pragma unroll
;     for (int j = 0; j < 8; ++j) { const int n = (lane >> 3) + 8 * j; const LAS float* s = scr + (8 * c) * 65 + n;
;         u32x4 o; o.x = pk2(s[0 * 65], s[1 * 65]); o.y = pk2(s[2 * 65], s[3 * 65]); o.z = pk2(s[4 * 65], s[5 * 65]); o.w = pk2(s[6 * 65], s[7 * 65]);
;         __builtin_nontemporal_store(o, (u32x4*)(p.WT + (size_t)(p.rb + n) * p.K + p.k0 + 8 * c)); }
;     asm volatile("s_waitcnt lgkmcnt(0)" ::: "memory");
; }
.LBB0_804:
	s_ashr_i32 s11, s10, 31
	s_lshl_b64 s[2:3], s[10:11], 1
	v_lshl_add_u64 v[6:7], v[8:9], 0, s[2:3]
	v_mov_b32_e32 v79, v1
	v_lshl_add_u64 v[6:7], v[6:7], 0, v[78:79]
	ds_read_b32 v79, v99
	ds_read_b32 v94, v99 offset:260
	s_mov_b32 s4, 0xffff0000
	s_andn2_b64 vcc, exec, s[18:19]
	s_waitcnt lgkmcnt(0)
	v_bfe_u32 v95, v79, 16, 1
	v_add3_u32 v79, v79, v95, s0
	v_bfe_u32 v95, v94, 16, 1
	v_lshrrev_b32_e32 v79, 16, v79
	v_add3_u32 v94, v94, v95, s0
	v_and_or_b32 v102, v94, s4, v79
	ds_read_b32 v79, v99 offset:520
	ds_read_b32 v94, v99 offset:780
	s_waitcnt lgkmcnt(0)
	v_bfe_u32 v95, v79, 16, 1
	v_add3_u32 v79, v79, v95, s0
	v_bfe_u32 v95, v94, 16, 1
	v_lshrrev_b32_e32 v79, 16, v79
	v_add3_u32 v94, v94, v95, s0
	v_and_or_b32 v103, v94, s4, v79
	ds_read_b32 v79, v99 offset:1040
	ds_read_b32 v94, v99 offset:1300
	s_waitcnt lgkmcnt(0)
	v_bfe_u32 v95, v79, 16, 1
	v_add3_u32 v79, v79, v95, s0
	v_bfe_u32 v95, v94, 16, 1
	v_lshrrev_b32_e32 v79, 16, v79
	v_add3_u32 v94, v94, v95, s0
	v_and_or_b32 v104, v94, s4, v79
	ds_read_b32 v79, v99 offset:1560
	ds_read_b32 v94, v99 offset:1820
	s_waitcnt lgkmcnt(0)
	v_bfe_u32 v95, v79, 16, 1
	v_add3_u32 v79, v79, v95, s0
	v_bfe_u32 v95, v94, 16, 1
	v_lshrrev_b32_e32 v79, 16, v79
	v_add3_u32 v94, v94, v95, s0
	v_and_or_b32 v105, v94, s4, v79
	v_add_u32_e32 v79, v3, v98
	v_mad_i64_i32 v[94:95], s[2:3], v79, v2, 0
	v_lshl_add_u64 v[94:95], v[94:95], 1, v[6:7]
	global_store_dwordx4 v[94:95], v[102:105], off nt
	ds_read_b32 v94, v99 offset:32
	ds_read_b32 v95, v99 offset:292
	s_waitcnt lgkmcnt(0)
	v_bfe_u32 v101, v94, 16, 1
	v_add3_u32 v94, v94, v101, s0
	v_bfe_u32 v101, v95, 16, 1
	v_lshrrev_b32_e32 v94, 16, v94
	v_add3_u32 v95, v95, v101, s0
	v_and_or_b32 v102, v95, s4, v94
	ds_read_b32 v94, v99 offset:552
	ds_read_b32 v95, v99 offset:812
	s_waitcnt lgkmcnt(0)
	v_bfe_u32 v101, v94, 16, 1
	v_add3_u32 v94, v94, v101, s0
	v_bfe_u32 v101, v95, 16, 1
	v_lshrrev_b32_e32 v94, 16, v94
	v_add3_u32 v95, v95, v101, s0
	v_and_or_b32 v103, v95, s4, v94
	ds_read_b32 v94, v99 offset:1072
	ds_read_b32 v95, v99 offset:1332
	s_waitcnt lgkmcnt(0)
	v_bfe_u32 v101, v94, 16, 1
	v_add3_u32 v94, v94, v101, s0
	v_bfe_u32 v101, v95, 16, 1
	v_lshrrev_b32_e32 v94, 16, v94
	v_add3_u32 v95, v95, v101, s0
	v_and_or_b32 v104, v95, s4, v94
	ds_read_b32 v94, v99 offset:1592
	ds_read_b32 v95, v99 offset:1852
	s_waitcnt lgkmcnt(0)
	v_bfe_u32 v101, v94, 16, 1
	v_add3_u32 v94, v94, v101, s0
	v_bfe_u32 v101, v95, 16, 1
	v_lshrrev_b32_e32 v94, 16, v94
	v_add3_u32 v95, v95, v101, s0
	v_and_or_b32 v105, v95, s4, v94
	v_add_u32_e32 v94, 8, v79
	v_mad_i64_i32 v[94:95], s[2:3], v94, v2, 0
	v_lshl_add_u64 v[94:95], v[94:95], 1, v[6:7]
	global_store_dwordx4 v[94:95], v[102:105], off nt
	ds_read_b32 v94, v99 offset:64
	ds_read_b32 v95, v99 offset:324
	s_waitcnt lgkmcnt(0)
	v_bfe_u32 v101, v94, 16, 1
	v_add3_u32 v94, v94, v101, s0
	v_bfe_u32 v101, v95, 16, 1
	v_lshrrev_b32_e32 v94, 16, v94
	v_add3_u32 v95, v95, v101, s0
	v_and_or_b32 v102, v95, s4, v94
	ds_read_b32 v94, v99 offset:584
	ds_read_b32 v95, v99 offset:844
	s_waitcnt lgkmcnt(0)
	v_bfe_u32 v101, v94, 16, 1
	v_add3_u32 v94, v94, v101, s0
	v_bfe_u32 v101, v95, 16, 1
	v_lshrrev_b32_e32 v94, 16, v94
	v_add3_u32 v95, v95, v101, s0
	v_and_or_b32 v103, v95, s4, v94
	ds_read_b32 v94, v99 offset:1104
	ds_read_b32 v95, v99 offset:1364
	s_waitcnt lgkmcnt(0)
	v_bfe_u32 v101, v94, 16, 1
	v_add3_u32 v94, v94, v101, s0
	v_bfe_u32 v101, v95, 16, 1
	v_lshrrev_b32_e32 v94, 16, v94
	v_add3_u32 v95, v95, v101, s0
	v_and_or_b32 v104, v95, s4, v94
	ds_read_b32 v94, v99 offset:1624
	ds_read_b32 v95, v99 offset:1884
	s_waitcnt lgkmcnt(0)
	v_bfe_u32 v101, v94, 16, 1
	v_add3_u32 v94, v94, v101, s0
	v_bfe_u32 v101, v95, 16, 1
	v_lshrrev_b32_e32 v94, 16, v94
	v_add3_u32 v95, v95, v101, s0
	v_and_or_b32 v105, v95, s4, v94
	v_add_u32_e32 v94, 16, v79
	v_mad_i64_i32 v[94:95], s[2:3], v94, v2, 0
	v_lshl_add_u64 v[94:95], v[94:95], 1, v[6:7]
	global_store_dwordx4 v[94:95], v[102:105], off nt
	ds_read_b32 v94, v99 offset:96
	ds_read_b32 v95, v99 offset:356
	s_waitcnt lgkmcnt(0)
	v_bfe_u32 v101, v94, 16, 1
	v_add3_u32 v94, v94, v101, s0
	v_bfe_u32 v101, v95, 16, 1
	v_lshrrev_b32_e32 v94, 16, v94
	v_add3_u32 v95, v95, v101, s0
	v_and_or_b32 v102, v95, s4, v94
	ds_read_b32 v94, v99 offset:616
	ds_read_b32 v95, v99 offset:876
	s_waitcnt lgkmcnt(0)
	v_bfe_u32 v101, v94, 16, 1
	v_add3_u32 v94, v94, v101, s0
	v_bfe_u32 v101, v95, 16, 1
	v_lshrrev_b32_e32 v94, 16, v94
	v_add3_u32 v95, v95, v101, s0
	v_and_or_b32 v103, v95, s4, v94
	ds_read_b32 v94, v99 offset:1136
	ds_read_b32 v95, v99 offset:1396
	s_waitcnt lgkmcnt(0)
	v_bfe_u32 v101, v94, 16, 1
	v_add3_u32 v94, v94, v101, s0
	v_bfe_u32 v101, v95, 16, 1
	v_lshrrev_b32_e32 v94, 16, v94
	v_add3_u32 v95, v95, v101, s0
	v_and_or_b32 v104, v95, s4, v94
	ds_read_b32 v94, v99 offset:1656
	ds_read_b32 v95, v99 offset:1916
	s_waitcnt lgkmcnt(0)
	v_bfe_u32 v101, v94, 16, 1
	v_add3_u32 v94, v94, v101, s0
	v_bfe_u32 v101, v95, 16, 1
	v_lshrrev_b32_e32 v94, 16, v94
	v_add3_u32 v95, v95, v101, s0
	v_and_or_b32 v105, v95, s4, v94
	v_add_u32_e32 v94, 24, v79
	v_mad_i64_i32 v[94:95], s[2:3], v94, v2, 0
	v_lshl_add_u64 v[94:95], v[94:95], 1, v[6:7]
	global_store_dwordx4 v[94:95], v[102:105], off nt
	ds_read_b32 v94, v99 offset:128
	ds_read_b32 v95, v99 offset:388
	s_waitcnt lgkmcnt(0)
; #define LAS __attribute__((address_space(3)))
; __device__ __forceinline__ unsigned pk2(float lo, float hi) { return f2bf(lo) | (f2bf(hi) << 16); }
; __device__ __forceinline__ void item_store(const ItemPos p, LAS float* scr, int lane) {
;     const int c = lane & 7;
; #pragma unroll
;     for (int j = 0; j < 8; ++j) { const int n = (lane >> 3) + 8 * j; const LAS float* s = scr + (8 * c) * 65 + n;
;         u32x4 o; o.x = pk2(s[0 * 65], s[1 * 65]); o.y = pk2(s[2 * 65], s[3 * 65]); o.z = pk2(s[4 * 65], s[5 * 65]); o.w = pk2(s[6 * 65], s[7 * 65]);
;         __builtin_nontemporal_store(o, (u32x4*)(p.WT + (size_t)(p.rb + n) * p.K + p.k0 + 8 * c)); }
;     asm volatile("s_waitcnt lgkmcnt(0)" ::: "memory");
; }
; __device__ __forceinline__ void convert_range(unsigned char* lds, int lo, int hi, int w, int nworkers, int wave, int lane) {
;     ...
;         const int nx = it + nworkers; const bool more = nx < hi; ItemPos pn = p;
;         if (more) pn = item_load(tab, nx, lane, v, gv);
;         item_store(p, scr, lane);
;         if (!more) break;
;         it = nx; p = pn;
	v_bfe_u32 v101, v94, 16, 1
	v_add3_u32 v94, v94, v101, s0
	v_bfe_u32 v101, v95, 16, 1
	v_lshrrev_b32_e32 v94, 16, v94
	v_add3_u32 v95, v95, v101, s0
	v_and_or_b32 v102, v95, s4, v94
	ds_read_b32 v94, v99 offset:648
	ds_read_b32 v95, v99 offset:908
	s_waitcnt lgkmcnt(0)
	v_bfe_u32 v101, v94, 16, 1
	v_add3_u32 v94, v94, v101, s0
	v_bfe_u32 v101, v95, 16, 1
	v_lshrrev_b32_e32 v94, 16, v94
	v_add3_u32 v95, v95, v101, s0
	v_and_or_b32 v103, v95, s4, v94
	ds_read_b32 v94, v99 offset:1168
	ds_read_b32 v95, v99 offset:1428
	s_waitcnt lgkmcnt(0)
	v_bfe_u32 v101, v94, 16, 1
	v_add3_u32 v94, v94, v101, s0
	v_bfe_u32 v101, v95, 16, 1
	v_lshrrev_b32_e32 v94, 16, v94
	v_add3_u32 v95, v95, v101, s0
	v_and_or_b32 v104, v95, s4, v94
	ds_read_b32 v94, v99 offset:1688
	ds_read_b32 v95, v99 offset:1948
	s_waitcnt lgkmcnt(0)
	v_bfe_u32 v101, v94, 16, 1
	v_add3_u32 v94, v94, v101, s0
	v_bfe_u32 v101, v95, 16, 1
	v_lshrrev_b32_e32 v94, 16, v94
	v_add3_u32 v95, v95, v101, s0
	v_and_or_b32 v105, v95, s4, v94
	v_add_u32_e32 v94, 32, v79
	v_mad_i64_i32 v[94:95], s[2:3], v94, v2, 0
	v_lshl_add_u64 v[94:95], v[94:95], 1, v[6:7]
	global_store_dwordx4 v[94:95], v[102:105], off nt
	ds_read_b32 v94, v99 offset:160
	ds_read_b32 v95, v99 offset:420
	s_waitcnt lgkmcnt(0)
	v_bfe_u32 v101, v94, 16, 1
	v_add3_u32 v94, v94, v101, s0
	v_bfe_u32 v101, v95, 16, 1
	v_lshrrev_b32_e32 v94, 16, v94
	v_add3_u32 v95, v95, v101, s0
	v_and_or_b32 v102, v95, s4, v94
	ds_read_b32 v94, v99 offset:680
	ds_read_b32 v95, v99 offset:940
	s_waitcnt lgkmcnt(0)
	v_bfe_u32 v101, v94, 16, 1
	v_add3_u32 v94, v94, v101, s0
	v_bfe_u32 v101, v95, 16, 1
	v_lshrrev_b32_e32 v94, 16, v94
	v_add3_u32 v95, v95, v101, s0
	v_and_or_b32 v103, v95, s4, v94
	ds_read_b32 v94, v99 offset:1200
	ds_read_b32 v95, v99 offset:1460
	s_waitcnt lgkmcnt(0)
	v_bfe_u32 v101, v94, 16, 1
	v_add3_u32 v94, v94, v101, s0
	v_bfe_u32 v101, v95, 16, 1
	v_lshrrev_b32_e32 v94, 16, v94
	v_add3_u32 v95, v95, v101, s0
	v_and_or_b32 v104, v95, s4, v94
	ds_read_b32 v94, v99 offset:1720
	ds_read_b32 v95, v99 offset:1980
	s_waitcnt lgkmcnt(0)
	v_bfe_u32 v101, v94, 16, 1
	v_add3_u32 v94, v94, v101, s0
	v_bfe_u32 v101, v95, 16, 1
	v_lshrrev_b32_e32 v94, 16, v94
	v_add3_u32 v95, v95, v101, s0
	v_and_or_b32 v105, v95, s4, v94
	v_add_u32_e32 v94, 40, v79
	v_mad_i64_i32 v[94:95], s[2:3], v94, v2, 0
	v_lshl_add_u64 v[94:95], v[94:95], 1, v[6:7]
	global_store_dwordx4 v[94:95], v[102:105], off nt
	ds_read_b32 v94, v99 offset:192
	ds_read_b32 v95, v99 offset:452
	s_waitcnt lgkmcnt(0)
	v_bfe_u32 v101, v94, 16, 1
	v_add3_u32 v94, v94, v101, s0
	v_bfe_u32 v101, v95, 16, 1
	v_lshrrev_b32_e32 v94, 16, v94
	v_add3_u32 v95, v95, v101, s0
	v_and_or_b32 v102, v95, s4, v94
	ds_read_b32 v94, v99 offset:712
	ds_read_b32 v95, v99 offset:972
	s_waitcnt lgkmcnt(0)
	v_bfe_u32 v101, v94, 16, 1
	v_add3_u32 v94, v94, v101, s0
	v_bfe_u32 v101, v95, 16, 1
	v_lshrrev_b32_e32 v94, 16, v94
	v_add3_u32 v95, v95, v101, s0
	v_and_or_b32 v103, v95, s4, v94
	ds_read_b32 v94, v99 offset:1232
	ds_read_b32 v95, v99 offset:1492
	s_waitcnt lgkmcnt(0)
	v_bfe_u32 v101, v94, 16, 1
	v_add3_u32 v94, v94, v101, s0
	v_bfe_u32 v101, v95, 16, 1
	v_lshrrev_b32_e32 v94, 16, v94
	v_add3_u32 v95, v95, v101, s0
	v_and_or_b32 v104, v95, s4, v94
	ds_read_b32 v94, v99 offset:1752
	ds_read_b32 v95, v99 offset:2012
	s_waitcnt lgkmcnt(0)
	v_bfe_u32 v101, v94, 16, 1
	v_add3_u32 v94, v94, v101, s0
	v_bfe_u32 v101, v95, 16, 1
	v_lshrrev_b32_e32 v94, 16, v94
	v_add3_u32 v95, v95, v101, s0
	v_and_or_b32 v105, v95, s4, v94
	v_add_u32_e32 v94, 48, v79
	v_mad_i64_i32 v[94:95], s[2:3], v94, v2, 0
	v_lshl_add_u64 v[94:95], v[94:95], 1, v[6:7]
	global_store_dwordx4 v[94:95], v[102:105], off nt
	ds_read_b32 v94, v99 offset:224
	ds_read_b32 v95, v99 offset:484
	v_add_u32_e32 v79, 56, v79
	s_waitcnt lgkmcnt(0)
	v_bfe_u32 v101, v94, 16, 1
	v_add3_u32 v94, v94, v101, s0
	v_bfe_u32 v101, v95, 16, 1
	v_lshrrev_b32_e32 v94, 16, v94
	v_add3_u32 v95, v95, v101, s0
	v_and_or_b32 v102, v95, s4, v94
	ds_read_b32 v94, v99 offset:744
	ds_read_b32 v95, v99 offset:1004
	s_waitcnt lgkmcnt(0)
	v_bfe_u32 v101, v94, 16, 1
	v_add3_u32 v94, v94, v101, s0
	v_bfe_u32 v101, v95, 16, 1
	v_lshrrev_b32_e32 v94, 16, v94
	v_add3_u32 v95, v95, v101, s0
	v_and_or_b32 v103, v95, s4, v94
	ds_read_b32 v94, v99 offset:1264
	ds_read_b32 v95, v99 offset:1524
	s_waitcnt lgkmcnt(0)
	v_bfe_u32 v101, v94, 16, 1
	v_add3_u32 v94, v94, v101, s0
	v_bfe_u32 v101, v95, 16, 1
	v_lshrrev_b32_e32 v94, 16, v94
	v_add3_u32 v95, v95, v101, s0
	v_and_or_b32 v104, v95, s4, v94
	ds_read_b32 v94, v99 offset:1784
	ds_read_b32 v95, v99 offset:2044
	s_waitcnt lgkmcnt(0)
	v_bfe_u32 v101, v94, 16, 1
	v_add3_u32 v94, v94, v101, s0
	v_bfe_u32 v101, v95, 16, 1
	v_lshrrev_b32_e32 v94, 16, v94
	v_add3_u32 v95, v95, v101, s0
	v_and_or_b32 v105, v95, s4, v94
	v_mad_i64_i32 v[94:95], s[2:3], v79, v2, 0
	v_lshl_add_u64 v[6:7], v[94:95], 1, v[6:7]
	global_store_dwordx4 v[6:7], v[102:105], off nt
	s_waitcnt lgkmcnt(0)
	s_cbranch_vccnz .LBB0_773
	v_mov_b64_e32 v[8:9], v[74:75]
	v_mov_b32_e32 v2, v4
	v_mov_b32_e32 v3, v5
	s_mov_b32 s10, s1
	s_mov_b32 s20, s21
	s_branch .LBB0_773

; __device__ __forceinline__ ItemPos item_load(const XItem* tab, int it, int lane, f32x4 (&v)[16], float (&gv)[16]) {
;     int e = 0;
; #pragma unroll 1
;     for (int q = 1; q < 20; ++q) if (it >= tab[q].start) e = q;
;     const XItem x = tab[e]; const int item = it - x.start;
;     const int nblk = x.N >> 6, kb = item / nblk, nb = item - kb * nblk, k0 = kb << 6, n0 = nb << 6;
;     const int lr = lane >> 4, lc = (lane & 15) * 4;
;     const float* W = x.src + (size_t)(k0 + lr) * x.N + n0 + lc; const size_t rstep = (size_t)4 * x.N;
; #pragma unroll
;     for (int i = 0; i < 16; ++i) v[i] = __builtin_nontemporal_load((const f32x4*)(W + i * rstep));
; #pragma unroll
;     for (int i = 0; i < 16; ++i) gv[i] = x.g ? x.g[k0 + 4 * i + lr] : 1.0f;
;     ItemPos p; p.scaled = (x.g != nullptr); p.WT = x.dst; p.K = x.K; p.k0 = k0; p.rb = (x.mode == 0) ? n0 : ((n0 >> 7) * 256 + (x.mode - 1) * 128 + (n0 & 127));
;     return p;
.LBB0_818:
	v_mov_b32_e32 v2, s1
	ds_read_b32 v2, v2
	v_mov_b32_e32 v3, s2
	s_add_i32 s2, s2, 1
	s_add_i32 s1, s1, 40
	s_cmp_eq_u32 s2, 20
	s_waitcnt lgkmcnt(0)
	v_cmp_lt_i32_e32 vcc, s15, v2
	s_nop 1
	v_cndmask_b32_e32 v0, v3, v0, vcc
	s_cbranch_scc0 .LBB0_818
	v_mul_lo_u32 v0, v0, 40
	v_add_u32_e32 v0, 0, v0
	v_add_u32_e32 v0, 0x20800, v0
	ds_read2_b64 v[2:5], v0 offset0:3 offset1:4
	ds_read2_b64 v[6:9], v0 offset1:1
	ds_read_b64 v[74:75], v0 offset:16
	v_ashrrev_i32_e32 v97, 4, v96
	s_waitcnt vmcnt(0)
	v_lshlrev_b32_e32 v10, 2, v96
	s_waitcnt lgkmcnt(2)
	v_readfirstlane_b32 s4, v3
	s_ashr_i32 s1, s4, 6
	s_abs_i32 s2, s1
	v_cvt_f32_u32_e32 v3, s2
	s_sub_i32 s7, 0, s2
	v_readfirstlane_b32 s3, v5
	s_sub_i32 s3, s15, s3
	v_rcp_iflag_f32_e32 v0, v3
	s_abs_i32 s6, s3
	s_xor_b32 s5, s3, s1
	s_ashr_i32 s5, s5, 31
	v_mul_f32_e32 v0, 0x4f7ffffe, v0
	v_cvt_u32_f32_e32 v0, v0
	v_and_b32_e32 v5, 60, v10
	v_readfirstlane_b32 s8, v0
	s_mul_i32 s7, s7, s8
	s_mul_hi_u32 s7, s8, s7
	s_add_i32 s8, s8, s7
	s_mul_hi_u32 s7, s6, s8
	s_mul_i32 s8, s7, s2
	s_sub_i32 s6, s6, s8
	s_add_i32 s9, s7, 1
	s_sub_i32 s8, s6, s2
	s_cmp_ge_u32 s6, s2
	s_cselect_b32 s7, s9, s7
	s_cselect_b32 s6, s8, s6
	s_add_i32 s8, s7, 1
	s_cmp_ge_u32 s6, s2
	s_cselect_b32 s2, s8, s7
	s_xor_b32 s2, s2, s5
	s_sub_i32 s2, s2, s5
	s_mul_i32 s1, s2, s1
	s_lshl_b32 s10, s2, 6
	s_sub_i32 s1, s3, s1
	v_add_u32_e32 v76, s10, v97
	s_lshl_b32 s2, s1, 6
	v_mad_i64_i32 v[10:11], s[6:7], v76, s4, 0
	s_waitcnt lgkmcnt(1)
	v_lshl_add_u64 v[6:7], v[10:11], 2, v[6:7]
	s_ashr_i32 s3, s2, 31
	s_ashr_i32 s5, s4, 31
	v_lshl_add_u64 v[6:7], s[2:3], 2, v[6:7]
	v_lshlrev_b32_e32 v0, 2, v5
	v_lshl_add_u64 v[6:7], v[6:7], 0, v[0:1]
	s_lshl_b64 s[4:5], s[4:5], 4
	v_lshl_add_u64 v[18:19], v[6:7], 0, s[4:5]
	global_load_dwordx4 v[10:13], v[6:7], off nt
	global_load_dwordx4 v[14:17], v[18:19], off nt
	v_lshl_add_u64 v[6:7], v[18:19], 0, s[4:5]
	v_lshl_add_u64 v[26:27], v[6:7], 0, s[4:5]
	global_load_dwordx4 v[18:21], v[6:7], off nt
	global_load_dwordx4 v[22:25], v[26:27], off nt
	v_lshl_add_u64 v[6:7], v[26:27], 0, s[4:5]
	v_lshl_add_u64 v[34:35], v[6:7], 0, s[4:5]
	global_load_dwordx4 v[26:29], v[6:7], off nt
	global_load_dwordx4 v[30:33], v[34:35], off nt
	v_lshl_add_u64 v[6:7], v[34:35], 0, s[4:5]
	v_lshl_add_u64 v[42:43], v[6:7], 0, s[4:5]
	global_load_dwordx4 v[34:37], v[6:7], off nt
	global_load_dwordx4 v[38:41], v[42:43], off nt
	v_lshl_add_u64 v[6:7], v[42:43], 0, s[4:5]
	global_load_dwordx4 v[42:45], v[6:7], off nt
	v_lshl_add_u64 v[6:7], v[6:7], 0, s[4:5]
	global_load_dwordx4 v[46:49], v[6:7], off nt
	v_lshl_add_u64 v[6:7], v[6:7], 0, s[4:5]
	global_load_dwordx4 v[50:53], v[6:7], off nt
	v_lshl_add_u64 v[6:7], v[6:7], 0, s[4:5]
	global_load_dwordx4 v[54:57], v[6:7], off nt
	v_lshl_add_u64 v[6:7], v[6:7], 0, s[4:5]
	global_load_dwordx4 v[58:61], v[6:7], off nt
	v_lshl_add_u64 v[6:7], v[6:7], 0, s[4:5]
	global_load_dwordx4 v[62:65], v[6:7], off nt
	v_lshl_add_u64 v[6:7], v[6:7], 0, s[4:5]
	global_load_dwordx4 v[66:69], v[6:7], off nt
	v_lshl_add_u64 v[6:7], v[6:7], 0, s[4:5]
	global_load_dwordx4 v[70:73], v[6:7], off nt
	v_ashrrev_i32_e32 v77, 31, v76
	s_waitcnt lgkmcnt(0)
	v_cmp_ne_u64_e64 s[8:9], 0, v[74:75]
	s_and_b64 vcc, exec, s[8:9]
	v_lshl_add_u64 v[6:7], v[76:77], 2, v[74:75]
	s_cbranch_vccz .LBB0_1735
	global_load_dword v76, v[6:7], off
	global_load_dword v77, v[6:7], off offset:16
	v_cndmask_b32_e64 v3, 0, 1, s[8:9]
	v_cmp_ne_u32_e64 s[6:7], 1, v3
	s_andn2_b64 vcc, exec, s[8:9]
	s_cbranch_vccnz .LBB0_1736

; __device__ __forceinline__ ItemPos item_load(const XItem* tab, int it, int lane, f32x4 (&v)[16], float (&gv)[16]) {
;     ...
;     for (int i = 0; i < 16; ++i) gv[i] = x.g ? x.g[k0 + 4 * i + lr] : 1.0f;
.LBB0_823:
	s_and_b64 vcc, exec, s[6:7]
	s_cbranch_vccnz .LBB0_1737
	global_load_dword v82, v[6:7], off offset:64
	global_load_dword v83, v[6:7], off offset:80
	s_cbranch_execnz .LBB0_826

; __device__ __forceinline__ ItemPos item_load(const XItem* tab, int it, int lane, f32x4 (&v)[16], float (&gv)[16]) {
;     ...
;     for (int i = 0; i < 16; ++i) gv[i] = x.g ? x.g[k0 + 4 * i + lr] : 1.0f;
.LBB0_826:
	s_and_b64 vcc, exec, s[6:7]
	s_cbranch_vccnz .LBB0_1738
	global_load_dword v84, v[6:7], off offset:96
	global_load_dword v85, v[6:7], off offset:112
	s_cbranch_execnz .LBB0_829

; __device__ __forceinline__ ItemPos item_load(const XItem* tab, int it, int lane, f32x4 (&v)[16], float (&gv)[16]) {
;     ...
;     for (int i = 0; i < 16; ++i) gv[i] = x.g ? x.g[k0 + 4 * i + lr] : 1.0f;
.LBB0_829:
	s_and_b64 vcc, exec, s[6:7]
	s_cbranch_vccnz .LBB0_1739
	global_load_dword v86, v[6:7], off offset:128
	global_load_dword v87, v[6:7], off offset:144
	s_cbranch_execnz .LBB0_832

; __device__ __forceinline__ ItemPos item_load(const XItem* tab, int it, int lane, f32x4 (&v)[16], float (&gv)[16]) {
;     ...
;     for (int i = 0; i < 16; ++i) gv[i] = x.g ? x.g[k0 + 4 * i + lr] : 1.0f;
.LBB0_832:
	s_and_b64 vcc, exec, s[6:7]
	s_cbranch_vccnz .LBB0_1740
	global_load_dword v88, v[6:7], off offset:160
	global_load_dword v89, v[6:7], off offset:176
	s_cbranch_execnz .LBB0_835

; __device__ __forceinline__ ItemPos item_load(const XItem* tab, int it, int lane, f32x4 (&v)[16], float (&gv)[16]) {
;     ...
;     for (int i = 0; i < 16; ++i) gv[i] = x.g ? x.g[k0 + 4 * i + lr] : 1.0f;
.LBB0_835:
	s_and_b64 vcc, exec, s[6:7]
	s_cbranch_vccnz .LBB0_1741
	global_load_dword v90, v[6:7], off offset:192
	global_load_dword v91, v[6:7], off offset:208
	s_cbranch_execnz .LBB0_838

; __device__ __forceinline__ ItemPos item_load(const XItem* tab, int it, int lane, f32x4 (&v)[16], float (&gv)[16]) {
;     ...
;     for (int i = 0; i < 16; ++i) gv[i] = x.g ? x.g[k0 + 4 * i + lr] : 1.0f;
.LBB0_838:
	s_and_b64 vcc, exec, s[6:7]
	s_cbranch_vccnz .LBB0_1742
	global_load_dword v92, v[6:7], off offset:224
	global_load_dword v93, v[6:7], off offset:240
	s_cbranch_execnz .LBB0_841

; __device__ __forceinline__ ItemPos item_load(const XItem* tab, int it, int lane, f32x4 (&v)[16], float (&gv)[16]) {
;     int e = 0;
; #pragma unroll 1
;     for (int q = 1; q < 20; ++q) if (it >= tab[q].start) e = q;
;     const XItem x = tab[e]; const int item = it - x.start;
;     const int nblk = x.N >> 6, kb = item / nblk, nb = item - kb * nblk, k0 = kb << 6, n0 = nb << 6;
;     const int lr = lane >> 4, lc = (lane & 15) * 4;
;     const float* W = x.src + (size_t)(k0 + lr) * x.N + n0 + lc; const size_t rstep = (size_t)4 * x.N;
; #pragma unroll
;     for (int i = 0; i < 16; ++i) v[i] = __builtin_nontemporal_load((const f32x4*)(W + i * rstep));
; #pragma unroll
;     for (int i = 0; i < 16; ++i) gv[i] = x.g ? x.g[k0 + 4 * i + lr] : 1.0f;
;     ItemPos p; p.scaled = (x.g != nullptr); p.WT = x.dst; p.K = x.K; p.k0 = k0; p.rb = (x.mode == 0) ? n0 : ((n0 >> 7) * 256 + (x.mode - 1) * 128 + (n0 & 127));
;     return p;
.LBB0_847:
	v_mov_b32_e32 v5, s1
	ds_read_b32 v5, v5
	s_add_i32 s1, s1, 40
	s_waitcnt lgkmcnt(0)
	v_cmp_lt_i32_e32 vcc, s14, v5
	v_mov_b32_e32 v5, s2
	s_add_i32 s2, s2, 1
	v_cndmask_b32_e32 v4, v5, v4, vcc
	s_cmp_eq_u32 s2, 20
	s_cbranch_scc0 .LBB0_847
	v_mul_lo_u32 v4, v4, 40
	v_add_u32_e32 v4, 0, v4
	v_add_u32_e32 v10, 0x20800, v4
	ds_read2_b64 v[4:7], v10 offset0:3 offset1:4
	ds_read2_b64 v[72:75], v10 offset1:1
	ds_read_b64 v[76:77], v10 offset:16
	s_waitcnt lgkmcnt(2)
	v_readfirstlane_b32 s4, v5
	s_ashr_i32 s1, s4, 6
	s_abs_i32 s2, s1
	v_cvt_f32_u32_e32 v5, s2
	v_readfirstlane_b32 s3, v7
	s_sub_i32 s3, s14, s3
	s_xor_b32 s5, s3, s1
	v_rcp_iflag_f32_e32 v5, v5
	s_ashr_i32 s7, s5, 31
	s_sub_i32 s5, 0, s2
	s_abs_i32 s6, s3
	v_mul_f32_e32 v5, 0x4f7ffffe, v5
	v_cvt_u32_f32_e32 v5, v5
	s_nop 0
	v_readfirstlane_b32 s8, v5
	s_mul_i32 s5, s5, s8
	s_mul_hi_u32 s5, s8, s5
	s_add_i32 s8, s8, s5
	s_mul_hi_u32 s5, s6, s8
	s_mul_i32 s8, s5, s2
	s_sub_i32 s6, s6, s8
	s_add_i32 s9, s5, 1
	s_sub_i32 s8, s6, s2
	s_cmp_ge_u32 s6, s2
	s_cselect_b32 s5, s9, s5
	s_cselect_b32 s6, s8, s6
	s_add_i32 s8, s5, 1
	s_cmp_ge_u32 s6, s2
	s_cselect_b32 s2, s8, s5
	s_xor_b32 s2, s2, s7
	s_sub_i32 s2, s2, s7
	s_mul_i32 s6, s2, s1
	s_lshl_b32 s1, s2, 6
	s_sub_i32 s11, s3, s6
	v_add_u32_e32 v80, s1, v97
	s_lshl_b32 s2, s11, 6
	v_mad_i64_i32 v[10:11], s[6:7], v80, s4, 0
	s_waitcnt lgkmcnt(1)
	v_lshl_add_u64 v[10:11], v[10:11], 2, v[72:73]
	s_ashr_i32 s3, s2, 31
	s_ashr_i32 s5, s4, 31
	v_lshl_add_u64 v[10:11], s[2:3], 2, v[10:11]
	v_lshl_add_u64 v[10:11], v[10:11], 0, v[0:1]
	s_lshl_b64 s[4:5], s[4:5], 4
	v_lshl_add_u64 v[18:19], v[10:11], 0, s[4:5]
	global_load_dwordx4 v[10:13], v[10:11], off nt
	s_nop 0
	global_load_dwordx4 v[14:17], v[18:19], off nt
	v_lshl_add_u64 v[18:19], v[18:19], 0, s[4:5]
	v_lshl_add_u64 v[26:27], v[18:19], 0, s[4:5]
	global_load_dwordx4 v[18:21], v[18:19], off nt
	s_nop 0
	global_load_dwordx4 v[22:25], v[26:27], off nt
	v_lshl_add_u64 v[26:27], v[26:27], 0, s[4:5]
	v_lshl_add_u64 v[34:35], v[26:27], 0, s[4:5]
	global_load_dwordx4 v[26:29], v[26:27], off nt
	s_nop 0
	global_load_dwordx4 v[30:33], v[34:35], off nt
	v_lshl_add_u64 v[34:35], v[34:35], 0, s[4:5]
	v_lshl_add_u64 v[42:43], v[34:35], 0, s[4:5]
	v_lshl_add_u64 v[46:47], v[42:43], 0, s[4:5]
	v_lshl_add_u64 v[50:51], v[46:47], 0, s[4:5]
	v_lshl_add_u64 v[54:55], v[50:51], 0, s[4:5]
	v_lshl_add_u64 v[58:59], v[54:55], 0, s[4:5]
	v_lshl_add_u64 v[62:63], v[58:59], 0, s[4:5]
	v_lshl_add_u64 v[66:67], v[62:63], 0, s[4:5]
	v_lshl_add_u64 v[70:71], v[66:67], 0, s[4:5]
	global_load_dwordx4 v[34:37], v[34:35], off nt
	s_nop 0
	global_load_dwordx4 v[38:41], v[42:43], off nt
	v_ashrrev_i32_e32 v81, 31, v80
	global_load_dwordx4 v[42:45], v[46:47], off nt
	s_waitcnt lgkmcnt(0)
	v_cmp_ne_u64_e64 s[8:9], 0, v[76:77]
	global_load_dwordx4 v[46:49], v[50:51], off nt
	s_and_b64 vcc, exec, s[8:9]
	global_load_dwordx4 v[50:53], v[54:55], off nt
	v_lshl_add_u64 v[94:95], v[80:81], 2, v[76:77]
	global_load_dwordx4 v[54:57], v[58:59], off nt
	s_nop 0
	global_load_dwordx4 v[58:61], v[62:63], off nt
	s_nop 0
	global_load_dwordx4 v[62:65], v[66:67], off nt
	s_nop 0
	global_load_dwordx4 v[66:69], v[70:71], off nt
	v_lshl_add_u64 v[70:71], v[70:71], 0, s[4:5]
	global_load_dwordx4 v[70:73], v[70:71], off nt
	s_cbranch_vccz .LBB0_875
	global_load_dword v76, v[94:95], off
	global_load_dword v77, v[94:95], off offset:16
	s_cbranch_execnz .LBB0_851

; #define LAS __attribute__((address_space(3)))
; __device__ __forceinline__ unsigned pk2(float lo, float hi) { return f2bf(lo) | (f2bf(hi) << 16); }
; __device__ __forceinline__ void item_store(const ItemPos p, LAS float* scr, int lane) {
;     const int c = lane & 7;
; #pragma unroll
;     for (int j = 0; j < 8; ++j) { const int n = (lane >> 3) + 8 * j; const LAS float* s = scr + (8 * c) * 65 + n;
;         u32x4 o; o.x = pk2(s[0 * 65], s[1 * 65]); o.y = pk2(s[2 * 65], s[3 * 65]); o.z = pk2(s[4 * 65], s[5 * 65]); o.w = pk2(s[6 * 65], s[7 * 65]);
;         __builtin_nontemporal_store(o, (u32x4*)(p.WT + (size_t)(p.rb + n) * p.K + p.k0 + 8 * c)); }
;     asm volatile("s_waitcnt lgkmcnt(0)" ::: "memory");
; }
; __device__ __forceinline__ void convert_range(unsigned char* lds, int lo, int hi, int w, int nworkers, int wave, int lane) {
;     ...
;     for (;;) {
;         item_to_lds(v, gv, p.scaled, scr, lane);
;         const int nx = it + nworkers; const bool more = nx < hi; ItemPos pn = p;
;         if (more) pn = item_load(tab, nx, lane, v, gv);
;         item_store(p, scr, lane);
;         if (!more) break;
;         it = nx; p = pn;
;     }
.LBB0_873:
	s_ashr_i32 s11, s10, 31
	s_lshl_b64 s[2:3], s[10:11], 1
	v_lshl_add_u64 v[6:7], v[8:9], 0, s[2:3]
	v_mov_b32_e32 v79, v1
	v_lshl_add_u64 v[6:7], v[6:7], 0, v[78:79]
	ds_read_b32 v79, v96
	ds_read_b32 v94, v96 offset:260
	s_mov_b32 s4, 0xffff0000
	s_andn2_b64 vcc, exec, s[18:19]
	s_waitcnt lgkmcnt(0)
	v_bfe_u32 v95, v79, 16, 1
	v_add3_u32 v79, v79, v95, s0
	v_bfe_u32 v95, v94, 16, 1
	v_lshrrev_b32_e32 v79, 16, v79
	v_add3_u32 v94, v94, v95, s0
	v_and_or_b32 v100, v94, s4, v79
	ds_read_b32 v79, v96 offset:520
	ds_read_b32 v94, v96 offset:780
	s_waitcnt lgkmcnt(0)
	v_bfe_u32 v95, v79, 16, 1
	v_add3_u32 v79, v79, v95, s0
	v_bfe_u32 v95, v94, 16, 1
	v_lshrrev_b32_e32 v79, 16, v79
	v_add3_u32 v94, v94, v95, s0
	v_and_or_b32 v101, v94, s4, v79
	ds_read_b32 v79, v96 offset:1040
	ds_read_b32 v94, v96 offset:1300
	s_waitcnt lgkmcnt(0)
	v_bfe_u32 v95, v79, 16, 1
	v_add3_u32 v79, v79, v95, s0
	v_bfe_u32 v95, v94, 16, 1
	v_lshrrev_b32_e32 v79, 16, v79
	v_add3_u32 v94, v94, v95, s0
	v_and_or_b32 v102, v94, s4, v79
	ds_read_b32 v79, v96 offset:1560
	ds_read_b32 v94, v96 offset:1820
	s_waitcnt lgkmcnt(0)
	v_bfe_u32 v95, v79, 16, 1
	v_add3_u32 v79, v79, v95, s0
	v_bfe_u32 v95, v94, 16, 1
	v_lshrrev_b32_e32 v79, 16, v79
	v_add3_u32 v94, v94, v95, s0
	v_and_or_b32 v103, v94, s4, v79
	v_add_u32_e32 v79, v3, v98
	v_mad_i64_i32 v[94:95], s[2:3], v79, v2, 0
	v_lshl_add_u64 v[94:95], v[94:95], 1, v[6:7]
	global_store_dwordx4 v[94:95], v[100:103], off nt
	ds_read_b32 v94, v96 offset:32
	ds_read_b32 v95, v96 offset:292
	s_waitcnt lgkmcnt(0)
	v_bfe_u32 v100, v94, 16, 1
	v_add3_u32 v94, v94, v100, s0
	v_bfe_u32 v100, v95, 16, 1
	v_lshrrev_b32_e32 v94, 16, v94
	v_add3_u32 v95, v95, v100, s0
	v_and_or_b32 v100, v95, s4, v94
	ds_read_b32 v94, v96 offset:552
	ds_read_b32 v95, v96 offset:812
	s_waitcnt lgkmcnt(0)
	v_bfe_u32 v101, v94, 16, 1
	v_add3_u32 v94, v94, v101, s0
	v_bfe_u32 v101, v95, 16, 1
	v_lshrrev_b32_e32 v94, 16, v94
	v_add3_u32 v95, v95, v101, s0
	v_and_or_b32 v101, v95, s4, v94
	ds_read_b32 v94, v96 offset:1072
	ds_read_b32 v95, v96 offset:1332
	s_waitcnt lgkmcnt(0)
	v_bfe_u32 v102, v94, 16, 1
	v_add3_u32 v94, v94, v102, s0
	v_bfe_u32 v102, v95, 16, 1
	v_lshrrev_b32_e32 v94, 16, v94
	v_add3_u32 v95, v95, v102, s0
	v_and_or_b32 v102, v95, s4, v94
	ds_read_b32 v94, v96 offset:1592
	ds_read_b32 v95, v96 offset:1852
	s_waitcnt lgkmcnt(0)
	v_bfe_u32 v103, v94, 16, 1
	v_add3_u32 v94, v94, v103, s0
	v_bfe_u32 v103, v95, 16, 1
	v_lshrrev_b32_e32 v94, 16, v94
	v_add3_u32 v95, v95, v103, s0
	v_and_or_b32 v103, v95, s4, v94
	v_add_u32_e32 v94, 8, v79
	v_mad_i64_i32 v[94:95], s[2:3], v94, v2, 0
	v_lshl_add_u64 v[94:95], v[94:95], 1, v[6:7]
	global_store_dwordx4 v[94:95], v[100:103], off nt
	ds_read_b32 v94, v96 offset:64
	ds_read_b32 v95, v96 offset:324
	s_waitcnt lgkmcnt(0)
	v_bfe_u32 v100, v94, 16, 1
	v_add3_u32 v94, v94, v100, s0
	v_bfe_u32 v100, v95, 16, 1
	v_lshrrev_b32_e32 v94, 16, v94
	v_add3_u32 v95, v95, v100, s0
	v_and_or_b32 v100, v95, s4, v94
	ds_read_b32 v94, v96 offset:584
	ds_read_b32 v95, v96 offset:844
	s_waitcnt lgkmcnt(0)
	v_bfe_u32 v101, v94, 16, 1
	v_add3_u32 v94, v94, v101, s0
	v_bfe_u32 v101, v95, 16, 1
	v_lshrrev_b32_e32 v94, 16, v94
	v_add3_u32 v95, v95, v101, s0
	v_and_or_b32 v101, v95, s4, v94
	ds_read_b32 v94, v96 offset:1104
	ds_read_b32 v95, v96 offset:1364
	s_waitcnt lgkmcnt(0)
	v_bfe_u32 v102, v94, 16, 1
	v_add3_u32 v94, v94, v102, s0
	v_bfe_u32 v102, v95, 16, 1
	v_lshrrev_b32_e32 v94, 16, v94
	v_add3_u32 v95, v95, v102, s0
	v_and_or_b32 v102, v95, s4, v94
	ds_read_b32 v94, v96 offset:1624
	ds_read_b32 v95, v96 offset:1884
	s_waitcnt lgkmcnt(0)
	v_bfe_u32 v103, v94, 16, 1
	v_add3_u32 v94, v94, v103, s0
	v_bfe_u32 v103, v95, 16, 1
	v_lshrrev_b32_e32 v94, 16, v94
	v_add3_u32 v95, v95, v103, s0
	v_and_or_b32 v103, v95, s4, v94
	v_add_u32_e32 v94, 16, v79
	v_mad_i64_i32 v[94:95], s[2:3], v94, v2, 0
	v_lshl_add_u64 v[94:95], v[94:95], 1, v[6:7]
	global_store_dwordx4 v[94:95], v[100:103], off nt
	ds_read_b32 v94, v96 offset:96
	ds_read_b32 v95, v96 offset:356
	s_waitcnt lgkmcnt(0)
	v_bfe_u32 v100, v94, 16, 1
	v_add3_u32 v94, v94, v100, s0
	v_bfe_u32 v100, v95, 16, 1
	v_lshrrev_b32_e32 v94, 16, v94
	v_add3_u32 v95, v95, v100, s0
	v_and_or_b32 v100, v95, s4, v94
	ds_read_b32 v94, v96 offset:616
	ds_read_b32 v95, v96 offset:876
	s_waitcnt lgkmcnt(0)
	v_bfe_u32 v101, v94, 16, 1
	v_add3_u32 v94, v94, v101, s0
	v_bfe_u32 v101, v95, 16, 1
	v_lshrrev_b32_e32 v94, 16, v94
	v_add3_u32 v95, v95, v101, s0
	v_and_or_b32 v101, v95, s4, v94
	ds_read_b32 v94, v96 offset:1136
	ds_read_b32 v95, v96 offset:1396
	s_waitcnt lgkmcnt(0)
	v_bfe_u32 v102, v94, 16, 1
	v_add3_u32 v94, v94, v102, s0
	v_bfe_u32 v102, v95, 16, 1
	v_lshrrev_b32_e32 v94, 16, v94
	v_add3_u32 v95, v95, v102, s0
	v_and_or_b32 v102, v95, s4, v94
	ds_read_b32 v94, v96 offset:1656
	ds_read_b32 v95, v96 offset:1916
	s_waitcnt lgkmcnt(0)
	v_bfe_u32 v103, v94, 16, 1
	v_add3_u32 v94, v94, v103, s0
	v_bfe_u32 v103, v95, 16, 1
	v_lshrrev_b32_e32 v94, 16, v94
	v_add3_u32 v95, v95, v103, s0
	v_and_or_b32 v103, v95, s4, v94
	v_add_u32_e32 v94, 24, v79
	v_mad_i64_i32 v[94:95], s[2:3], v94, v2, 0
	v_lshl_add_u64 v[94:95], v[94:95], 1, v[6:7]
	global_store_dwordx4 v[94:95], v[100:103], off nt
	ds_read_b32 v94, v96 offset:128
	ds_read_b32 v95, v96 offset:388
	s_waitcnt lgkmcnt(0)
; #define LAS __attribute__((address_space(3)))
; __device__ __forceinline__ unsigned pk2(float lo, float hi) { return f2bf(lo) | (f2bf(hi) << 16); }
; __device__ __forceinline__ void item_store(const ItemPos p, LAS float* scr, int lane) {
;     const int c = lane & 7;
; #pragma unroll
;     for (int j = 0; j < 8; ++j) { const int n = (lane >> 3) + 8 * j; const LAS float* s = scr + (8 * c) * 65 + n;
;         u32x4 o; o.x = pk2(s[0 * 65], s[1 * 65]); o.y = pk2(s[2 * 65], s[3 * 65]); o.z = pk2(s[4 * 65], s[5 * 65]); o.w = pk2(s[6 * 65], s[7 * 65]);
;         __builtin_nontemporal_store(o, (u32x4*)(p.WT + (size_t)(p.rb + n) * p.K + p.k0 + 8 * c)); }
;     asm volatile("s_waitcnt lgkmcnt(0)" ::: "memory");
; }
; __device__ __forceinline__ void convert_range(unsigned char* lds, int lo, int hi, int w, int nworkers, int wave, int lane) {
;     ...
;     for (;;) {
;         item_to_lds(v, gv, p.scaled, scr, lane);
;         const int nx = it + nworkers; const bool more = nx < hi; ItemPos pn = p;
;         if (more) pn = item_load(tab, nx, lane, v, gv);
;         item_store(p, scr, lane);
;         if (!more) break;
;         it = nx; p = pn;
;     }
	v_bfe_u32 v100, v94, 16, 1
	v_add3_u32 v94, v94, v100, s0
	v_bfe_u32 v100, v95, 16, 1
	v_lshrrev_b32_e32 v94, 16, v94
	v_add3_u32 v95, v95, v100, s0
	v_and_or_b32 v100, v95, s4, v94
	ds_read_b32 v94, v96 offset:648
	ds_read_b32 v95, v96 offset:908
	s_waitcnt lgkmcnt(0)
	v_bfe_u32 v101, v94, 16, 1
	v_add3_u32 v94, v94, v101, s0
	v_bfe_u32 v101, v95, 16, 1
	v_lshrrev_b32_e32 v94, 16, v94
	v_add3_u32 v95, v95, v101, s0
	v_and_or_b32 v101, v95, s4, v94
	ds_read_b32 v94, v96 offset:1168
	ds_read_b32 v95, v96 offset:1428
	s_waitcnt lgkmcnt(0)
	v_bfe_u32 v102, v94, 16, 1
	v_add3_u32 v94, v94, v102, s0
	v_bfe_u32 v102, v95, 16, 1
	v_lshrrev_b32_e32 v94, 16, v94
	v_add3_u32 v95, v95, v102, s0
	v_and_or_b32 v102, v95, s4, v94
	ds_read_b32 v94, v96 offset:1688
	ds_read_b32 v95, v96 offset:1948
	s_waitcnt lgkmcnt(0)
	v_bfe_u32 v103, v94, 16, 1
	v_add3_u32 v94, v94, v103, s0
	v_bfe_u32 v103, v95, 16, 1
	v_lshrrev_b32_e32 v94, 16, v94
	v_add3_u32 v95, v95, v103, s0
	v_and_or_b32 v103, v95, s4, v94
	v_add_u32_e32 v94, 32, v79
	v_mad_i64_i32 v[94:95], s[2:3], v94, v2, 0
	v_lshl_add_u64 v[94:95], v[94:95], 1, v[6:7]
	global_store_dwordx4 v[94:95], v[100:103], off nt
	ds_read_b32 v94, v96 offset:160
	ds_read_b32 v95, v96 offset:420
	s_waitcnt lgkmcnt(0)
	v_bfe_u32 v100, v94, 16, 1
	v_add3_u32 v94, v94, v100, s0
	v_bfe_u32 v100, v95, 16, 1
	v_lshrrev_b32_e32 v94, 16, v94
	v_add3_u32 v95, v95, v100, s0
	v_and_or_b32 v100, v95, s4, v94
	ds_read_b32 v94, v96 offset:680
	ds_read_b32 v95, v96 offset:940
	s_waitcnt lgkmcnt(0)
	v_bfe_u32 v101, v94, 16, 1
	v_add3_u32 v94, v94, v101, s0
	v_bfe_u32 v101, v95, 16, 1
	v_lshrrev_b32_e32 v94, 16, v94
	v_add3_u32 v95, v95, v101, s0
	v_and_or_b32 v101, v95, s4, v94
	ds_read_b32 v94, v96 offset:1200
	ds_read_b32 v95, v96 offset:1460
	s_waitcnt lgkmcnt(0)
	v_bfe_u32 v102, v94, 16, 1
	v_add3_u32 v94, v94, v102, s0
	v_bfe_u32 v102, v95, 16, 1
	v_lshrrev_b32_e32 v94, 16, v94
	v_add3_u32 v95, v95, v102, s0
	v_and_or_b32 v102, v95, s4, v94
	ds_read_b32 v94, v96 offset:1720
	ds_read_b32 v95, v96 offset:1980
	s_waitcnt lgkmcnt(0)
	v_bfe_u32 v103, v94, 16, 1
	v_add3_u32 v94, v94, v103, s0
	v_bfe_u32 v103, v95, 16, 1
	v_lshrrev_b32_e32 v94, 16, v94
	v_add3_u32 v95, v95, v103, s0
	v_and_or_b32 v103, v95, s4, v94
	v_add_u32_e32 v94, 40, v79
	v_mad_i64_i32 v[94:95], s[2:3], v94, v2, 0
	v_lshl_add_u64 v[94:95], v[94:95], 1, v[6:7]
	global_store_dwordx4 v[94:95], v[100:103], off nt
	ds_read_b32 v94, v96 offset:192
	ds_read_b32 v95, v96 offset:452
	s_waitcnt lgkmcnt(0)
	v_bfe_u32 v100, v94, 16, 1
	v_add3_u32 v94, v94, v100, s0
	v_bfe_u32 v100, v95, 16, 1
	v_lshrrev_b32_e32 v94, 16, v94
	v_add3_u32 v95, v95, v100, s0
	v_and_or_b32 v100, v95, s4, v94
	ds_read_b32 v94, v96 offset:712
	ds_read_b32 v95, v96 offset:972
	s_waitcnt lgkmcnt(0)
	v_bfe_u32 v101, v94, 16, 1
	v_add3_u32 v94, v94, v101, s0
	v_bfe_u32 v101, v95, 16, 1
	v_lshrrev_b32_e32 v94, 16, v94
	v_add3_u32 v95, v95, v101, s0
	v_and_or_b32 v101, v95, s4, v94
	ds_read_b32 v94, v96 offset:1232
	ds_read_b32 v95, v96 offset:1492
	s_waitcnt lgkmcnt(0)
	v_bfe_u32 v102, v94, 16, 1
	v_add3_u32 v94, v94, v102, s0
	v_bfe_u32 v102, v95, 16, 1
	v_lshrrev_b32_e32 v94, 16, v94
	v_add3_u32 v95, v95, v102, s0
	v_and_or_b32 v102, v95, s4, v94
	ds_read_b32 v94, v96 offset:1752
	ds_read_b32 v95, v96 offset:2012
	s_waitcnt lgkmcnt(0)
	v_bfe_u32 v103, v94, 16, 1
	v_add3_u32 v94, v94, v103, s0
	v_bfe_u32 v103, v95, 16, 1
	v_lshrrev_b32_e32 v94, 16, v94
	v_add3_u32 v95, v95, v103, s0
	v_and_or_b32 v103, v95, s4, v94
	v_add_u32_e32 v94, 48, v79
	v_mad_i64_i32 v[94:95], s[2:3], v94, v2, 0
	v_lshl_add_u64 v[94:95], v[94:95], 1, v[6:7]
	global_store_dwordx4 v[94:95], v[100:103], off nt
	ds_read_b32 v94, v96 offset:224
	ds_read_b32 v95, v96 offset:484
	v_add_u32_e32 v79, 56, v79
	s_waitcnt lgkmcnt(0)
	v_bfe_u32 v100, v94, 16, 1
	v_add3_u32 v94, v94, v100, s0
	v_bfe_u32 v100, v95, 16, 1
	v_lshrrev_b32_e32 v94, 16, v94
	v_add3_u32 v95, v95, v100, s0
	v_and_or_b32 v100, v95, s4, v94
	ds_read_b32 v94, v96 offset:744
	ds_read_b32 v95, v96 offset:1004
	s_waitcnt lgkmcnt(0)
	v_bfe_u32 v101, v94, 16, 1
	v_add3_u32 v94, v94, v101, s0
	v_bfe_u32 v101, v95, 16, 1
	v_lshrrev_b32_e32 v94, 16, v94
	v_add3_u32 v95, v95, v101, s0
	v_and_or_b32 v101, v95, s4, v94
	ds_read_b32 v94, v96 offset:1264
	ds_read_b32 v95, v96 offset:1524
	s_waitcnt lgkmcnt(0)
	v_bfe_u32 v102, v94, 16, 1
	v_add3_u32 v94, v94, v102, s0
	v_bfe_u32 v102, v95, 16, 1
	v_lshrrev_b32_e32 v94, 16, v94
	v_add3_u32 v95, v95, v102, s0
	v_and_or_b32 v102, v95, s4, v94
	ds_read_b32 v94, v96 offset:1784
	ds_read_b32 v95, v96 offset:2044
	s_waitcnt lgkmcnt(0)
	v_bfe_u32 v103, v94, 16, 1
	v_add3_u32 v94, v94, v103, s0
	v_bfe_u32 v103, v95, 16, 1
	v_lshrrev_b32_e32 v94, 16, v94
	v_add3_u32 v95, v95, v103, s0
	v_and_or_b32 v103, v95, s4, v94
	v_mad_i64_i32 v[94:95], s[2:3], v79, v2, 0
	v_lshl_add_u64 v[6:7], v[94:95], 1, v[6:7]
	global_store_dwordx4 v[6:7], v[100:103], off nt
	s_waitcnt lgkmcnt(0)
	s_cbranch_vccnz .LBB0_842
	v_mov_b64_e32 v[8:9], v[74:75]
	v_mov_b32_e32 v2, v4
	v_mov_b32_e32 v3, v5
	s_mov_b32 s10, s1
	s_mov_b32 s15, s14
	s_branch .LBB0_842

; __device__ __forceinline__ void finishSM(f32x16& p0, f32x16& p1, float alpha, float& l_reg, bf16x8& pa0, bf16x8& pa1, bf16x8& pa2, bf16x8& pa3) {
; #pragma unroll
;   for (int r = 0; r < 16; ++r) p1[r] = __builtin_amdgcn_exp2f(p1[r]);
;   float ps = 0;
; #pragma unroll
;   for (int r = 0; r < 16; ++r) ps += p0[r];
; #pragma unroll
;   for (int r = 0; r < 16; ++r) ps += p1[r];
;   { auto rr = __builtin_amdgcn_permlane32_swap(__float_as_uint(ps), __float_as_uint(ps), false, false);
;     ps = __uint_as_float(rr[0]) + __uint_as_float(rr[1]); }
;   l_reg = l_reg * alpha + ps;
;   PK4(p0, 0, pa0); PK4(p0, 8, pa1); PK4(p1, 0, pa2); PK4(p1, 8, pa3);
; }
;   p0 = f32x16{}; p1 = f32x16{};
; #pragma unroll
;   for (int d0 = DLO; d0 < DHI; ++d0) { int cb = (d0 * 16 + hi * 8) * 2;
;     bf16x8 b0 = *reinterpret_cast<const bf16x8*>((const char*)Ks + KSWZ(r32, cb));
;     bf16x8 b1 = *reinterpret_cast<const bf16x8*>((const char*)Ks + KSWZ(32 + r32, cb));
;     p0 = __builtin_amdgcn_mfma_f32_32x32x16_bf16(b0, qr[d0], p0, 0, 0, 0);
;     p1 = __builtin_amdgcn_mfma_f32_32x32x16_bf16(b1, qr[d0], p1, 0, 0, 0); }
; }
; __device__ __forceinline__ int v_st(int k, int c) { const int kk = (k & ~0xC) | ((k & 4) << 1) | ((k & 8) >> 1); return ((kk >> 3) * 4 + (c >> 5)) * 512 + ((kk & 7) * 32 + (c & 31)) * 2; }
; __device__ __forceinline__ int v_rd_base(int lane) { return ((lane & 3) << 3) | (((lane >> 2) & 3) << 6) | (((lane >> 4) & 1) << 5) | (((lane >> 5) & 1) << 8); }
; template <int OFF> __device__ __forceinline__ s16x4 tr_read(int vb) {
;   s16x4 r; asm volatile("ds_read_b64_tr_b16 %0, %1 offset:%2" : "=&v"(r) : "v"(vb), "i"(OFF) : "memory"); return r;
; }
; template <int D0> __device__ __forceinline__ void pv_one(f32x16& od, int vb, bf16x8 pa0, bf16x8 pa1, bf16x8 pa2, bf16x8 pa3) {
;   const s16x4 l0 = tr_read<v_rd_off(D0, 0, 0)>(vb), h0 = tr_read<v_rd_off(D0, 0, 1)>(vb), l1 = tr_read<v_rd_off(D0, 1, 0)>(vb), h1 = tr_read<v_rd_off(D0, 1, 1)>(vb);
;   const s16x4 l2 = tr_read<v_rd_off(D0, 2, 0)>(vb), h2 = tr_read<v_rd_off(D0, 2, 1)>(vb), l3 = tr_read<v_rd_off(D0, 3, 0)>(vb), h3 = tr_read<v_rd_off(D0, 3, 1)>(vb);
;   asm volatile("s_waitcnt lgkmcnt(0)" ::: "memory"); SBAR();
;     ...
;   od = __builtin_amdgcn_mfma_f32_32x32x16_bf16(pa0, PK(l0, h0), od, 0, 0, 0);
;   od = __builtin_amdgcn_mfma_f32_32x32x16_bf16(pa1, PK(l1, h1), od, 0, 0, 0);
.LBB0_1002:
	ds_read_b128 v[66:69], v190 offset:49152
	ds_read_b128 v[70:73], v190 offset:57344
	v_add_f32_e32 v146, 0, v161
	v_add_f32_e32 v146, v167, v146
	v_add_f32_e32 v146, v147, v146
	s_waitcnt lgkmcnt(1)
	v_mfma_f32_32x32x16_bf16 v[82:97], v[66:69], v[102:105], 0
	v_add_f32_e32 v146, v166, v146
	v_add_f32_e32 v146, v148, v146
	ds_read_b128 v[186:189], v194 offset:49152
	ds_read_b128 v[208:211], v194 offset:57344
	v_add_f32_e32 v146, v160, v146
	v_add_f32_e32 v146, v149, v146
	v_add_f32_e32 v146, v159, v146
	v_add_f32_e32 v146, v156, v146
	s_waitcnt lgkmcnt(2)
	v_mfma_f32_32x32x16_bf16 v[66:81], v[70:73], v[102:105], 0
	v_add_f32_e32 v146, v158, v146
	v_add_f32_e32 v146, v154, v146
	v_add_f32_e32 v146, v157, v146
	v_exp_f32_e32 v142, v142
	v_add_f32_e32 v146, v152, v146
	v_exp_f32_e32 v143, v143
	v_add_f32_e32 v146, v155, v146
	s_waitcnt lgkmcnt(1)
	v_mfma_f32_32x32x16_bf16 v[82:97], v[186:189], v[98:101], v[82:97]
	v_exp_f32_e32 v140, v140
	v_add_f32_e32 v146, v151, v146
	v_exp_f32_e32 v141, v141
	v_add_f32_e32 v146, v153, v146
	v_exp_f32_e32 v134, v134
	v_add_f32_e32 v146, v142, v146
	v_exp_f32_e32 v135, v135
	s_waitcnt lgkmcnt(0)
	v_mfma_f32_32x32x16_bf16 v[66:81], v[208:211], v[98:101], v[66:81]
	ds_read_b128 v[186:189], v195 offset:49152
	ds_read_b128 v[208:211], v195 offset:57344
	v_add_f32_e32 v146, v143, v146
	v_exp_f32_e32 v132, v132
	v_add_f32_e32 v146, v140, v146
	v_exp_f32_e32 v133, v133
	v_add_f32_e32 v146, v141, v146
	v_exp_f32_e32 v130, v130
	s_waitcnt lgkmcnt(1)
	v_mfma_f32_32x32x16_bf16 v[82:97], v[186:189], v[106:109], v[82:97]
	v_add_f32_e32 v146, v134, v146
	v_exp_f32_e32 v131, v131
	v_add_f32_e32 v146, v135, v146
	v_exp_f32_e32 v144, v144
	v_add_f32_e32 v146, v132, v146
	v_exp_f32_e32 v145, v145
	v_add_f32_e32 v146, v133, v146
	s_waitcnt lgkmcnt(0)
	v_mfma_f32_32x32x16_bf16 v[66:81], v[208:211], v[106:109], v[66:81]
	ds_read_b128 v[186:189], v196 offset:49152
	ds_read_b128 v[208:211], v196 offset:57344
	v_exp_f32_e32 v138, v138
	v_add_f32_e32 v146, v130, v146
	v_exp_f32_e32 v139, v139
	v_add_f32_e32 v146, v131, v146
	v_exp_f32_e32 v136, v136
	v_add_f32_e32 v146, v144, v146
	s_waitcnt lgkmcnt(1)
	v_mfma_f32_32x32x16_bf16 v[82:97], v[186:189], v[110:113], v[82:97]
	v_exp_f32_e32 v137, v137
	v_add_f32_e32 v146, v145, v146
	v_add_f32_e32 v146, v138, v146
	v_add_f32_e32 v146, v139, v146
	v_add_f32_e32 v146, v136, v146
	v_add_f32_e32 v207, v137, v146
	v_cvt_pk_bf16_f32 v146, v161, v167
	s_waitcnt lgkmcnt(0)
	v_mfma_f32_32x32x16_bf16 v[66:81], v[208:211], v[110:113], v[66:81]
	v_mov_b32_e32 v208, v207
	v_cvt_pk_bf16_f32 v147, v147, v166
	v_cvt_pk_bf16_f32 v148, v148, v160
	s_nop 1
	v_permlane32_swap_b32_e32 v207, v208
	v_cvt_pk_bf16_f32 v149, v149, v159
	v_permlane32_swap_b32_e32 v146, v148
	v_cvt_pk_bf16_f32 v156, v156, v158
	v_cvt_pk_bf16_f32 v157, v154, v157
	v_cvt_pk_bf16_f32 v158, v152, v155
	v_cvt_pk_bf16_f32 v159, v151, v153
	v_cvt_pk_bf16_f32 v152, v142, v143
	v_cvt_pk_bf16_f32 v153, v140, v141
	v_cvt_pk_bf16_f32 v154, v134, v135
	v_cvt_pk_bf16_f32 v155, v132, v133
	v_cvt_pk_bf16_f32 v186, v130, v131
	v_cvt_pk_bf16_f32 v187, v144, v145
	v_cvt_pk_bf16_f32 v188, v138, v139
	v_cvt_pk_bf16_f32 v189, v136, v137
	v_permlane32_swap_b32_e32 v147, v149
	v_permlane32_swap_b32_e32 v156, v158
	v_permlane32_swap_b32_e32 v157, v159
	v_permlane32_swap_b32_e32 v152, v154
	v_permlane32_swap_b32_e32 v153, v155
	v_permlane32_swap_b32_e32 v186, v188
	v_permlane32_swap_b32_e32 v187, v189
	s_waitcnt vmcnt(0)
	ds_write_b128 v192, v[114:117]
	ds_write_b128 v193, v[118:121]
	ds_write_b128 v177, v[122:125] offset:32768
	ds_write_b128 v191, v[126:129] offset:32768
	v_lshl_add_u64 v[168:169], v[164:165], 0, v[0:1]
	s_mov_b32 s1, 0x18fb0000
	v_add_co_u32_e32 v130, vcc, s1, v168
	s_mov_b32 s1, 0x18ff8000
	s_nop 0
	v_addc_co_u32_e32 v131, vcc, 0, v169, vcc
	v_add_co_u32_e32 v134, vcc, s1, v168
	v_lshl_add_u64 v[166:167], v[162:163], 0, v[0:1]
	s_nop 0
	v_addc_co_u32_e32 v135, vcc, 0, v169, vcc
	s_mov_b32 s1, 0x1f648000
	v_add_co_u32_e32 v138, vcc, s1, v166
	s_mov_b32 s1, 0x1f654000
	s_nop 0
	v_addc_co_u32_e32 v139, vcc, 0, v167, vcc
	v_add_co_u32_e32 v142, vcc, s1, v166
	global_load_dwordx4 v[130:133], v[130:131], off
	s_nop 0
	global_load_dwordx4 v[134:137], v[134:135], off
	v_addc_co_u32_e32 v143, vcc, 0, v167, vcc
	global_load_dwordx4 v[138:141], v[138:139], off
	s_nop 0
	global_load_dwordx4 v[142:145], v[142:143], off
	ds_read_b64_tr_b16 v[210:211], v176 offset:0
	ds_read_b64_tr_b16 v[212:213], v176 offset:0x800
	ds_read_b64_tr_b16 v[214:215], v176 offset:0x1000
	ds_read_b64_tr_b16 v[216:217], v176 offset:0x1800
	ds_read_b64_tr_b16 v[218:219], v176 offset:0x2000
	ds_read_b64_tr_b16 v[220:221], v176 offset:0x2800
	ds_read_b64_tr_b16 v[222:223], v176 offset:0x3000
	ds_read_b64_tr_b16 v[224:225], v176 offset:0x3800
	s_waitcnt lgkmcnt(4)
	s_nop 0
	v_mfma_f32_32x32x16_bf16 v[2:17], v[146:149], v[210:213], v[2:17]
	ds_read_b64_tr_b16 v[210:211], v176 offset:0x200
	ds_read_b64_tr_b16 v[212:213], v176 offset:0xa00
	v_mfma_f32_32x32x16_bf16 v[2:17], v[156:159], v[214:217], v[2:17]
	ds_read_b64_tr_b16 v[214:215], v176 offset:0x1200
	ds_read_b64_tr_b16 v[216:217], v176 offset:0x1a00
	s_waitcnt lgkmcnt(4)
; #define SBAR() __builtin_amdgcn_sched_barrier(0)
; __device__ __forceinline__ void partialSM(f32x16& p0, f32x16& p1, float& m_reg, float& mn, float& alpha) {
;   constexpr float C = SCALE * 1.4426950408889634f;
;   float pmax = p0[0];
; #pragma unroll
;   for (int r = 1; r < 16; ++r) pmax = fmaxf(pmax, p0[r]);
; #pragma unroll
;   for (int r = 0; r < 16; ++r) pmax = fmaxf(pmax, p1[r]);
;   { auto rr = __builtin_amdgcn_permlane32_swap(__float_as_uint(pmax), __float_as_uint(pmax), false, false);
;     pmax = fmaxf(__uint_as_float(rr[0]), __uint_as_float(rr[1])); }
;   if (__builtin_expect(__all(pmax - m_reg <= THR / SCALE), 1)) { mn = m_reg; alpha = 1.f; }
;   else { mn = fmaxf(m_reg, pmax); alpha = __builtin_amdgcn_exp2f((m_reg - mn) * C); m_reg = mn; }
; template <int D0> __device__ __forceinline__ void pv_one(f32x16& od, int vb, bf16x8 pa0, bf16x8 pa1, bf16x8 pa2, bf16x8 pa3) {
;   const s16x4 l0 = tr_read<v_rd_off(D0, 0, 0)>(vb), h0 = tr_read<v_rd_off(D0, 0, 1)>(vb), l1 = tr_read<v_rd_off(D0, 1, 0)>(vb), h1 = tr_read<v_rd_off(D0, 1, 1)>(vb);
;   const s16x4 l2 = tr_read<v_rd_off(D0, 2, 0)>(vb), h2 = tr_read<v_rd_off(D0, 2, 1)>(vb), l3 = tr_read<v_rd_off(D0, 3, 0)>(vb), h3 = tr_read<v_rd_off(D0, 3, 1)>(vb);
;   asm volatile("s_waitcnt lgkmcnt(0)" ::: "memory"); SBAR();
;     ...
;   od = __builtin_amdgcn_mfma_f32_32x32x16_bf16(pa0, PK(l0, h0), od, 0, 0, 0);
;   od = __builtin_amdgcn_mfma_f32_32x32x16_bf16(pa1, PK(l1, h1), od, 0, 0, 0);
;   od = __builtin_amdgcn_mfma_f32_32x32x16_bf16(pa2, PK(l2, h2), od, 0, 0, 0);
;   od = __builtin_amdgcn_mfma_f32_32x32x16_bf16(pa3, PK(l3, h3), od, 0, 0, 0);
;     ...
; }
; __device__ __forceinline__ void pv_d0(f32x16* o, int vb, bf16x8 pa0, bf16x8 pa1, bf16x8 pa2, bf16x8 pa3) {
;   pv_one<0>(o[0], vb, pa0, pa1, pa2, pa3); pv_one<1>(o[1], vb, pa0, pa1, pa2, pa3); pv_one<2>(o[2], vb, pa0, pa1, pa2, pa3); pv_one<3>(o[3], vb, pa0, pa1, pa2, pa3);
	v_mfma_f32_32x32x16_bf16 v[2:17], v[152:155], v[218:221], v[2:17]
	ds_read_b64_tr_b16 v[218:219], v176 offset:0x2200
	ds_read_b64_tr_b16 v[220:221], v176 offset:0x2a00
	v_mfma_f32_32x32x16_bf16 v[2:17], v[186:189], v[222:225], v[2:17]
	ds_read_b64_tr_b16 v[222:223], v176 offset:0x3200
	ds_read_b64_tr_b16 v[224:225], v176 offset:0x3a00
	s_waitcnt lgkmcnt(4)
	v_mfma_f32_32x32x16_bf16 v[50:65], v[146:149], v[210:213], v[50:65]
	ds_read_b64_tr_b16 v[210:211], v176 offset:0x400
	ds_read_b64_tr_b16 v[212:213], v176 offset:0xc00
	v_mfma_f32_32x32x16_bf16 v[50:65], v[156:159], v[214:217], v[50:65]
	ds_read_b64_tr_b16 v[214:215], v176 offset:0x1400
	ds_read_b64_tr_b16 v[216:217], v176 offset:0x1c00
	s_waitcnt lgkmcnt(4)
	v_mfma_f32_32x32x16_bf16 v[50:65], v[152:155], v[218:221], v[50:65]
	ds_read_b64_tr_b16 v[218:219], v176 offset:0x2400
	ds_read_b64_tr_b16 v[220:221], v176 offset:0x2c00
	v_mfma_f32_32x32x16_bf16 v[50:65], v[186:189], v[222:225], v[50:65]
	ds_read_b64_tr_b16 v[222:223], v176 offset:0x3400
	ds_read_b64_tr_b16 v[224:225], v176 offset:0x3c00
	s_waitcnt lgkmcnt(4)
	v_mfma_f32_32x32x16_bf16 v[34:49], v[146:149], v[210:213], v[34:49]
	ds_read_b64_tr_b16 v[210:211], v176 offset:0x600
	ds_read_b64_tr_b16 v[212:213], v176 offset:0xe00
	v_mfma_f32_32x32x16_bf16 v[34:49], v[156:159], v[214:217], v[34:49]
	ds_read_b64_tr_b16 v[214:215], v176 offset:0x1600
	ds_read_b64_tr_b16 v[216:217], v176 offset:0x1e00
	s_waitcnt lgkmcnt(4)
	v_mfma_f32_32x32x16_bf16 v[34:49], v[152:155], v[218:221], v[34:49]
	ds_read_b64_tr_b16 v[218:219], v176 offset:0x2600
	ds_read_b64_tr_b16 v[220:221], v176 offset:0x2e00
	v_mfma_f32_32x32x16_bf16 v[34:49], v[186:189], v[222:225], v[34:49]
	ds_read_b64_tr_b16 v[222:223], v176 offset:0x3600
	ds_read_b64_tr_b16 v[224:225], v176 offset:0x3e00
	s_waitcnt lgkmcnt(4)
	v_mfma_f32_32x32x16_bf16 v[18:33], v[146:149], v[210:213], v[18:33]
	v_max_f32_e32 v146, v83, v83
	v_max_f32_e32 v147, v82, v82
	v_max_f32_e32 v146, v147, v146
	v_max3_f32 v146, v146, v84, v85
	v_max3_f32 v146, v146, v86, v87
	v_max3_f32 v146, v146, v88, v89
	v_max3_f32 v146, v146, v90, v91
	v_max3_f32 v146, v146, v92, v93
	v_max3_f32 v146, v146, v94, v95
	v_mfma_f32_32x32x16_bf16 v[18:33], v[156:159], v[214:217], v[18:33]
	v_max3_f32 v146, v146, v96, v97
	v_max3_f32 v146, v146, v66, v67
	v_max3_f32 v146, v146, v68, v69
	v_max3_f32 v146, v146, v70, v71
	v_max3_f32 v146, v146, v72, v73
	v_max3_f32 v146, v146, v74, v75
	v_max3_f32 v146, v146, v76, v77
	v_max3_f32 v146, v146, v78, v79
	s_waitcnt lgkmcnt(0)
	v_mfma_f32_32x32x16_bf16 v[18:33], v[152:155], v[218:221], v[18:33]
	v_max3_f32 v146, v146, v80, v81
	v_mov_b32_e32 v147, v146
	s_nop 1
	v_permlane32_swap_b32_e32 v146, v147
	v_max_f32_e32 v147, v147, v147
	v_max_f32_e32 v146, v146, v146
	v_max_f32_e32 v146, v146, v147
	v_sub_f32_e32 v147, v146, v150
	v_cmp_ge_f32_e32 vcc, s63, v147
	v_max_f32_e32 v147, v150, v150
	v_max_f32_e32 v146, v147, v146
	v_mfma_f32_32x32x16_bf16 v[18:33], v[186:189], v[222:225], v[18:33]
	v_sub_f32_e32 v147, v150, v146
	v_mul_f32_e32 v147, 0x3e0293ee, v147
	v_exp_f32_e32 v147, v147
	s_cmp_eq_u64 vcc, exec
	s_cselect_b64 s[8:9], -1, 0
	s_waitcnt vmcnt(4)
	v_cndmask_b32_e64 v209, v147, 1.0, s[8:9]
	v_cmp_gt_f32_e32 vcc, 1.0, v209
	s_cbranch_vccz .LBB0_1006
	s_and_saveexec_b64 s[2:3], s[6:7]
	ds_write_b32 v173, v209 offset:128
	s_or_b64 exec, exec, s[2:3]
	s_waitcnt lgkmcnt(0)
	v_add_u32_e32 v147, s15, v172
	ds_read_b128 v[152:155], v147 offset:224
	ds_read_b128 v[156:159], v147 offset:192
	ds_read_b128 v[186:189], v147 offset:160
	ds_read_b128 v[210:213], v147 offset:128
	s_waitcnt lgkmcnt(3)
	v_pk_mul_f32 v[14:15], v[14:15], v[152:153]
	s_waitcnt lgkmcnt(2)
	v_pk_mul_f32 v[10:11], v[10:11], v[156:157]
	s_waitcnt lgkmcnt(1)
	v_pk_mul_f32 v[6:7], v[6:7], v[186:187]
	v_pk_mul_f32 v[16:17], v[16:17], v[154:155]
	v_pk_mul_f32 v[12:13], v[12:13], v[158:159]
	v_pk_mul_f32 v[8:9], v[8:9], v[188:189]
	s_waitcnt lgkmcnt(0)
	v_pk_mul_f32 v[4:5], v[4:5], v[212:213]
	v_pk_mul_f32 v[2:3], v[2:3], v[210:211]
	v_pk_mul_f32 v[62:63], v[62:63], v[152:153]
	v_pk_mul_f32 v[58:59], v[58:59], v[156:157]
	v_pk_mul_f32 v[54:55], v[54:55], v[186:187]
	v_pk_mul_f32 v[64:65], v[64:65], v[154:155]
	v_pk_mul_f32 v[60:61], v[60:61], v[158:159]
	v_pk_mul_f32 v[56:57], v[56:57], v[188:189]
	v_pk_mul_f32 v[52:53], v[52:53], v[212:213]
	v_pk_mul_f32 v[50:51], v[50:51], v[210:211]
	v_pk_mul_f32 v[46:47], v[46:47], v[152:153]
	v_pk_mul_f32 v[42:43], v[42:43], v[156:157]
	v_pk_mul_f32 v[38:39], v[38:39], v[186:187]
	v_pk_mul_f32 v[48:49], v[48:49], v[154:155]
	v_pk_mul_f32 v[44:45], v[44:45], v[158:159]
	v_pk_mul_f32 v[40:41], v[40:41], v[188:189]
	v_pk_mul_f32 v[36:37], v[36:37], v[212:213]
	v_pk_mul_f32 v[34:35], v[34:35], v[210:211]
	v_pk_mul_f32 v[30:31], v[30:31], v[152:153]
	v_pk_mul_f32 v[26:27], v[26:27], v[156:157]
	v_pk_mul_f32 v[22:23], v[22:23], v[186:187]
	v_pk_mul_f32 v[32:33], v[32:33], v[154:155]
	v_pk_mul_f32 v[28:29], v[28:29], v[158:159]
	v_pk_mul_f32 v[24:25], v[24:25], v[188:189]
	v_pk_mul_f32 v[20:21], v[20:21], v[212:213]
	v_pk_mul_f32 v[18:19], v[18:19], v[210:211]

; #define SBAR() __builtin_amdgcn_sched_barrier(0)
; __device__ __forceinline__ void partialSM(f32x16& p0, f32x16& p1, float& m_reg, float& mn, float& alpha) {
;   constexpr float C = SCALE * 1.4426950408889634f;
;   float pmax = p0[0];
; #pragma unroll
;   for (int r = 1; r < 16; ++r) pmax = fmaxf(pmax, p0[r]);
; #pragma unroll
;   for (int r = 0; r < 16; ++r) pmax = fmaxf(pmax, p1[r]);
;   { auto rr = __builtin_amdgcn_permlane32_swap(__float_as_uint(pmax), __float_as_uint(pmax), false, false);
;     pmax = fmaxf(__uint_as_float(rr[0]), __uint_as_float(rr[1])); }
;   if (__builtin_expect(__all(pmax - m_reg <= THR / SCALE), 1)) { mn = m_reg; alpha = 1.f; }
;   else { mn = fmaxf(m_reg, pmax); alpha = __builtin_amdgcn_exp2f((m_reg - mn) * C); m_reg = mn; }
; template <int D0> __device__ __forceinline__ void pv_one(f32x16& od, int vb, bf16x8 pa0, bf16x8 pa1, bf16x8 pa2, bf16x8 pa3) {
;   const s16x4 l0 = tr_read<v_rd_off(D0, 0, 0)>(vb), h0 = tr_read<v_rd_off(D0, 0, 1)>(vb), l1 = tr_read<v_rd_off(D0, 1, 0)>(vb), h1 = tr_read<v_rd_off(D0, 1, 1)>(vb);
;   const s16x4 l2 = tr_read<v_rd_off(D0, 2, 0)>(vb), h2 = tr_read<v_rd_off(D0, 2, 1)>(vb), l3 = tr_read<v_rd_off(D0, 3, 0)>(vb), h3 = tr_read<v_rd_off(D0, 3, 1)>(vb);
;   asm volatile("s_waitcnt lgkmcnt(0)" ::: "memory"); SBAR();
;     ...
;   od = __builtin_amdgcn_mfma_f32_32x32x16_bf16(pa0, PK(l0, h0), od, 0, 0, 0);
;   od = __builtin_amdgcn_mfma_f32_32x32x16_bf16(pa1, PK(l1, h1), od, 0, 0, 0);
;   od = __builtin_amdgcn_mfma_f32_32x32x16_bf16(pa2, PK(l2, h2), od, 0, 0, 0);
;   od = __builtin_amdgcn_mfma_f32_32x32x16_bf16(pa3, PK(l3, h3), od, 0, 0, 0);
;     ...
; }
; __device__ __forceinline__ void pv_d0(f32x16* o, int vb, bf16x8 pa0, bf16x8 pa1, bf16x8 pa2, bf16x8 pa3) {
;   pv_one<0>(o[0], vb, pa0, pa1, pa2, pa3); pv_one<1>(o[1], vb, pa0, pa1, pa2, pa3); pv_one<2>(o[2], vb, pa0, pa1, pa2, pa3); pv_one<3>(o[3], vb, pa0, pa1, pa2, pa3);
.LBB0_1008:
	ds_read_b64_tr_b16 v[166:167], v175 offset:0
	ds_read_b64_tr_b16 v[168:169], v175 offset:0x800
	ds_read_b64_tr_b16 v[186:187], v175 offset:0x1000
	ds_read_b64_tr_b16 v[188:189], v175 offset:0x1800
	ds_read_b64_tr_b16 v[214:215], v175 offset:0x2000
	ds_read_b64_tr_b16 v[216:217], v175 offset:0x2800
	ds_read_b64_tr_b16 v[218:219], v175 offset:0x3000
	ds_read_b64_tr_b16 v[220:221], v175 offset:0x3800
	s_waitcnt lgkmcnt(4)
	s_nop 0
	v_mfma_f32_32x32x16_bf16 v[2:17], v[146:149], v[166:169], v[2:17]
	ds_read_b64_tr_b16 v[166:167], v175 offset:0x200
	ds_read_b64_tr_b16 v[168:169], v175 offset:0xa00
	v_mfma_f32_32x32x16_bf16 v[2:17], v[150:153], v[186:189], v[2:17]
	ds_read_b64_tr_b16 v[186:187], v175 offset:0x1200
	ds_read_b64_tr_b16 v[188:189], v175 offset:0x1a00
	s_waitcnt lgkmcnt(4)
	v_mfma_f32_32x32x16_bf16 v[2:17], v[154:157], v[214:217], v[2:17]
	ds_read_b64_tr_b16 v[214:215], v175 offset:0x2200
	ds_read_b64_tr_b16 v[216:217], v175 offset:0x2a00
	v_mfma_f32_32x32x16_bf16 v[2:17], v[158:161], v[218:221], v[2:17]
	ds_read_b64_tr_b16 v[218:219], v175 offset:0x3200
	ds_read_b64_tr_b16 v[220:221], v175 offset:0x3a00
	s_waitcnt lgkmcnt(4)
	v_mfma_f32_32x32x16_bf16 v[50:65], v[146:149], v[166:169], v[50:65]
	ds_read_b64_tr_b16 v[166:167], v175 offset:0x400
	ds_read_b64_tr_b16 v[168:169], v175 offset:0xc00
	v_mfma_f32_32x32x16_bf16 v[50:65], v[150:153], v[186:189], v[50:65]
	ds_read_b64_tr_b16 v[186:187], v175 offset:0x1400
	ds_read_b64_tr_b16 v[188:189], v175 offset:0x1c00
	s_waitcnt lgkmcnt(4)
	v_mfma_f32_32x32x16_bf16 v[50:65], v[154:157], v[214:217], v[50:65]
	ds_read_b64_tr_b16 v[214:215], v175 offset:0x2400
	ds_read_b64_tr_b16 v[216:217], v175 offset:0x2c00
	v_mfma_f32_32x32x16_bf16 v[50:65], v[158:161], v[218:221], v[50:65]
	ds_read_b64_tr_b16 v[218:219], v175 offset:0x3400
	ds_read_b64_tr_b16 v[220:221], v175 offset:0x3c00
	s_waitcnt lgkmcnt(4)
	v_mfma_f32_32x32x16_bf16 v[34:49], v[146:149], v[166:169], v[34:49]
	ds_read_b64_tr_b16 v[166:167], v175 offset:0x600
	ds_read_b64_tr_b16 v[168:169], v175 offset:0xe00
	v_mfma_f32_32x32x16_bf16 v[34:49], v[150:153], v[186:189], v[34:49]
	ds_read_b64_tr_b16 v[186:187], v175 offset:0x1600
	ds_read_b64_tr_b16 v[188:189], v175 offset:0x1e00
	s_waitcnt lgkmcnt(4)
	v_mfma_f32_32x32x16_bf16 v[34:49], v[154:157], v[214:217], v[34:49]
	ds_read_b64_tr_b16 v[214:215], v175 offset:0x2600
	ds_read_b64_tr_b16 v[216:217], v175 offset:0x2e00
	v_mfma_f32_32x32x16_bf16 v[34:49], v[158:161], v[218:221], v[34:49]
	ds_read_b64_tr_b16 v[218:219], v175 offset:0x3600
	ds_read_b64_tr_b16 v[220:221], v175 offset:0x3e00
	s_waitcnt lgkmcnt(4)
	v_mfma_f32_32x32x16_bf16 v[18:33], v[146:149], v[166:169], v[18:33]
	v_max_f32_e32 v146, v83, v83
	v_max_f32_e32 v147, v82, v82
	v_max_f32_e32 v146, v147, v146
	v_max3_f32 v146, v146, v84, v85
	v_max3_f32 v146, v146, v86, v87
	v_max3_f32 v146, v146, v88, v89
	v_max3_f32 v146, v146, v90, v91
	v_max3_f32 v146, v146, v92, v93
	v_max3_f32 v146, v146, v94, v95
	v_mfma_f32_32x32x16_bf16 v[18:33], v[150:153], v[186:189], v[18:33]
	v_max3_f32 v146, v146, v96, v97
	v_max3_f32 v146, v146, v66, v67
	v_max3_f32 v146, v146, v68, v69
	v_max3_f32 v146, v146, v70, v71
	v_max3_f32 v146, v146, v72, v73
	v_max3_f32 v146, v146, v74, v75
	v_max3_f32 v146, v146, v76, v77
	v_max3_f32 v146, v146, v78, v79
	s_waitcnt lgkmcnt(0)
	v_mfma_f32_32x32x16_bf16 v[18:33], v[154:157], v[214:217], v[18:33]
	v_max3_f32 v146, v146, v80, v81
	v_mov_b32_e32 v147, v146
	s_nop 1
	v_permlane32_swap_b32_e32 v146, v147
	v_max_f32_e32 v147, v147, v147
	v_max_f32_e32 v146, v146, v146
	v_max_f32_e32 v146, v146, v147
	v_sub_f32_e32 v147, v146, v210
	v_cmp_ge_f32_e32 vcc, s63, v147
	v_max_f32_e32 v147, v210, v210
	v_max_f32_e32 v147, v147, v146
	v_mfma_f32_32x32x16_bf16 v[18:33], v[158:161], v[218:221], v[18:33]
	v_sub_f32_e32 v146, v210, v147
	v_mul_f32_e32 v146, 0x3e0293ee, v146
	v_exp_f32_e32 v146, v146
	s_cmp_eq_u64 vcc, exec
	s_cselect_b64 s[8:9], -1, 0
	s_waitcnt vmcnt(4)
	v_cndmask_b32_e64 v146, v146, 1.0, s[8:9]
	v_cmp_gt_f32_e32 vcc, 1.0, v146
	s_cbranch_vccz .LBB0_1012
	s_and_saveexec_b64 s[4:5], s[6:7]
	ds_write_b32 v173, v146 offset:128
	s_or_b64 exec, exec, s[4:5]
	s_waitcnt lgkmcnt(0)
	v_add_u32_e32 v142, s15, v172
	ds_read_b128 v[130:133], v142 offset:224
	ds_read_b128 v[134:137], v142 offset:192
	ds_read_b128 v[138:141], v142 offset:160
	ds_read_b128 v[142:145], v142 offset:128
	s_waitcnt lgkmcnt(3)
	v_pk_mul_f32 v[14:15], v[14:15], v[130:131]
	s_waitcnt lgkmcnt(2)
	v_pk_mul_f32 v[10:11], v[10:11], v[134:135]
	s_waitcnt lgkmcnt(1)
	v_pk_mul_f32 v[6:7], v[6:7], v[138:139]
	v_pk_mul_f32 v[16:17], v[16:17], v[132:133]
	v_pk_mul_f32 v[12:13], v[12:13], v[136:137]
	v_pk_mul_f32 v[8:9], v[8:9], v[140:141]
	s_waitcnt lgkmcnt(0)
	v_pk_mul_f32 v[4:5], v[4:5], v[144:145]
	v_pk_mul_f32 v[2:3], v[2:3], v[142:143]
	v_pk_mul_f32 v[62:63], v[62:63], v[130:131]
	v_pk_mul_f32 v[58:59], v[58:59], v[134:135]
	v_pk_mul_f32 v[54:55], v[54:55], v[138:139]
	v_pk_mul_f32 v[64:65], v[64:65], v[132:133]
	v_pk_mul_f32 v[60:61], v[60:61], v[136:137]
	v_pk_mul_f32 v[56:57], v[56:57], v[140:141]
	v_pk_mul_f32 v[52:53], v[52:53], v[144:145]
	v_pk_mul_f32 v[50:51], v[50:51], v[142:143]
	v_pk_mul_f32 v[46:47], v[46:47], v[130:131]
	v_pk_mul_f32 v[42:43], v[42:43], v[134:135]
	v_pk_mul_f32 v[38:39], v[38:39], v[138:139]
	v_pk_mul_f32 v[48:49], v[48:49], v[132:133]
	v_pk_mul_f32 v[44:45], v[44:45], v[136:137]
	v_pk_mul_f32 v[40:41], v[40:41], v[140:141]
	v_pk_mul_f32 v[36:37], v[36:37], v[144:145]
	v_pk_mul_f32 v[34:35], v[34:35], v[142:143]
	v_pk_mul_f32 v[30:31], v[30:31], v[130:131]
	v_pk_mul_f32 v[26:27], v[26:27], v[134:135]
	v_pk_mul_f32 v[22:23], v[22:23], v[138:139]
	v_pk_mul_f32 v[32:33], v[32:33], v[132:133]
	v_pk_mul_f32 v[28:29], v[28:29], v[136:137]
	v_pk_mul_f32 v[24:25], v[24:25], v[140:141]
	v_pk_mul_f32 v[20:21], v[20:21], v[144:145]
	v_pk_mul_f32 v[18:19], v[18:19], v[142:143]

; __device__ __forceinline__ void finishSM(f32x16& p0, f32x16& p1, float alpha, float& l_reg, bf16x8& pa0, bf16x8& pa1, bf16x8& pa2, bf16x8& pa3) {
; #pragma unroll
;   for (int r = 0; r < 16; ++r) p1[r] = __builtin_amdgcn_exp2f(p1[r]);
;   float ps = 0;
; #pragma unroll
;   for (int r = 0; r < 16; ++r) ps += p0[r];
; #pragma unroll
;   for (int r = 0; r < 16; ++r) ps += p1[r];
;   { auto rr = __builtin_amdgcn_permlane32_swap(__float_as_uint(ps), __float_as_uint(ps), false, false);
;     ps = __uint_as_float(rr[0]) + __uint_as_float(rr[1]); }
;   l_reg = l_reg * alpha + ps;
;   PK4(p0, 0, pa0); PK4(p0, 8, pa1); PK4(p1, 0, pa2); PK4(p1, 8, pa3);
; }
;   p0 = f32x16{}; p1 = f32x16{};
; #pragma unroll
;   for (int d0 = DLO; d0 < DHI; ++d0) { int cb = (d0 * 16 + hi * 8) * 2;
;     bf16x8 b0 = *reinterpret_cast<const bf16x8*>((const char*)Ks + KSWZ(r32, cb));
;     bf16x8 b1 = *reinterpret_cast<const bf16x8*>((const char*)Ks + KSWZ(32 + r32, cb));
;     p0 = __builtin_amdgcn_mfma_f32_32x32x16_bf16(b0, qr[d0], p0, 0, 0, 0);
;     p1 = __builtin_amdgcn_mfma_f32_32x32x16_bf16(b1, qr[d0], p1, 0, 0, 0); }
; }
; __device__ __forceinline__ int v_st(int k, int c) { const int kk = (k & ~0xC) | ((k & 4) << 1) | ((k & 8) >> 1); return ((kk >> 3) * 4 + (c >> 5)) * 512 + ((kk & 7) * 32 + (c & 31)) * 2; }
; __device__ __forceinline__ int v_rd_base(int lane) { return ((lane & 3) << 3) | (((lane >> 2) & 3) << 6) | (((lane >> 4) & 1) << 5) | (((lane >> 5) & 1) << 8); }
; template <int OFF> __device__ __forceinline__ s16x4 tr_read(int vb) {
;   s16x4 r; asm volatile("ds_read_b64_tr_b16 %0, %1 offset:%2" : "=&v"(r) : "v"(vb), "i"(OFF) : "memory"); return r;
; }
; template <int D0> __device__ __forceinline__ void pv_one(f32x16& od, int vb, bf16x8 pa0, bf16x8 pa1, bf16x8 pa2, bf16x8 pa3) {
;   const s16x4 l0 = tr_read<v_rd_off(D0, 0, 0)>(vb), h0 = tr_read<v_rd_off(D0, 0, 1)>(vb), l1 = tr_read<v_rd_off(D0, 1, 0)>(vb), h1 = tr_read<v_rd_off(D0, 1, 1)>(vb);
;   const s16x4 l2 = tr_read<v_rd_off(D0, 2, 0)>(vb), h2 = tr_read<v_rd_off(D0, 2, 1)>(vb), l3 = tr_read<v_rd_off(D0, 3, 0)>(vb), h3 = tr_read<v_rd_off(D0, 3, 1)>(vb);
;   asm volatile("s_waitcnt lgkmcnt(0)" ::: "memory"); SBAR();
;     ...
;   od = __builtin_amdgcn_mfma_f32_32x32x16_bf16(pa0, PK(l0, h0), od, 0, 0, 0);
;   od = __builtin_amdgcn_mfma_f32_32x32x16_bf16(pa1, PK(l1, h1), od, 0, 0, 0);
.LBB0_1014:
	ds_read_b128 v[66:69], v190 offset:49152
	ds_read_b128 v[70:73], v190 offset:57344
	v_add_f32_e32 v0, 0, v161
	v_add_f32_e32 v0, v167, v0
	v_add_f32_e32 v0, v147, v0
	s_waitcnt lgkmcnt(1)
	v_mfma_f32_32x32x16_bf16 v[82:97], v[66:69], v[102:105], 0
	v_add_f32_e32 v0, v166, v0
	v_add_f32_e32 v0, v148, v0
	v_add_f32_e32 v0, v160, v0
	v_add_f32_e32 v0, v149, v0
	v_add_f32_e32 v0, v159, v0
	v_add_f32_e32 v0, v156, v0
	v_add_f32_e32 v0, v158, v0
	s_waitcnt lgkmcnt(0)
	v_mfma_f32_32x32x16_bf16 v[66:81], v[70:73], v[102:105], 0
	ds_read_b128 v[102:105], v194 offset:49152
	ds_read_b128 v[114:117], v194 offset:57344
	v_add_f32_e32 v0, v154, v0
	v_add_f32_e32 v0, v157, v0
	v_add_f32_e32 v0, v152, v0
	v_add_f32_e32 v0, v155, v0
	v_add_f32_e32 v0, v151, v0
	v_add_f32_e32 v0, v153, v0
	s_waitcnt lgkmcnt(1)
	v_mfma_f32_32x32x16_bf16 v[82:97], v[102:105], v[98:101], v[82:97]
	v_exp_f32_e32 v118, v145
	v_exp_f32_e32 v119, v138
	v_exp_f32_e32 v120, v139
	v_exp_f32_e32 v121, v136
	v_exp_f32_e32 v122, v137
	s_waitcnt lgkmcnt(0)
	v_mfma_f32_32x32x16_bf16 v[66:81], v[114:117], v[98:101], v[66:81]
	ds_read_b128 v[98:101], v195 offset:49152
	ds_read_b128 v[102:105], v195 offset:57344
	v_exp_f32_e32 v114, v133
	v_exp_f32_e32 v115, v130
	v_exp_f32_e32 v116, v131
	v_exp_f32_e32 v117, v144
	s_waitcnt lgkmcnt(1)
	v_mfma_f32_32x32x16_bf16 v[82:97], v[98:101], v[106:109], v[82:97]
	s_waitcnt lgkmcnt(0)
	v_mfma_f32_32x32x16_bf16 v[66:81], v[102:105], v[106:109], v[66:81]
	ds_read_b128 v[98:101], v196 offset:49152
	ds_read_b128 v[102:105], v196 offset:57344
	v_exp_f32_e32 v108, v143
	v_exp_f32_e32 v109, v140
	s_waitcnt lgkmcnt(1)
	v_mfma_f32_32x32x16_bf16 v[82:97], v[98:101], v[110:113], v[82:97]
	v_exp_f32_e32 v99, v142
	v_cvt_pk_bf16_f32 v100, v161, v167
	v_cvt_pk_bf16_f32 v101, v147, v166
	s_nop 0
	v_add_f32_e32 v0, v99, v0
	v_add_f32_e32 v0, v108, v0
	v_add_f32_e32 v0, v109, v0
	s_waitcnt lgkmcnt(0)
	v_mfma_f32_32x32x16_bf16 v[66:81], v[102:105], v[110:113], v[66:81]
	v_exp_f32_e32 v110, v141
	v_exp_f32_e32 v111, v134
	v_exp_f32_e32 v112, v135
	v_exp_f32_e32 v113, v132
	v_add_f32_e32 v0, v110, v0
	v_add_f32_e32 v0, v111, v0
	v_add_f32_e32 v0, v112, v0
	v_add_f32_e32 v0, v113, v0
	v_add_f32_e32 v0, v114, v0
	v_add_f32_e32 v0, v115, v0
	v_add_f32_e32 v0, v116, v0
	v_add_f32_e32 v0, v117, v0
	v_add_f32_e32 v0, v118, v0
	v_add_f32_e32 v0, v119, v0
	v_add_f32_e32 v0, v120, v0
	v_add_f32_e32 v0, v121, v0
	v_add_f32_e32 v0, v122, v0
	v_mov_b32_e32 v98, v0
	v_cvt_pk_bf16_f32 v102, v148, v160
	s_nop 1
	v_permlane32_swap_b32_e32 v0, v98
	v_cvt_pk_bf16_f32 v103, v149, v159
	v_permlane32_swap_b32_e32 v100, v102
	v_cvt_pk_bf16_f32 v104, v156, v158
	v_cvt_pk_bf16_f32 v105, v154, v157
	v_cvt_pk_bf16_f32 v106, v152, v155
	v_cvt_pk_bf16_f32 v107, v151, v153
	v_cvt_pk_bf16_f32 v108, v99, v108
	v_cvt_pk_bf16_f32 v109, v109, v110
	v_cvt_pk_bf16_f32 v110, v111, v112
	v_cvt_pk_bf16_f32 v111, v113, v114
	v_cvt_pk_bf16_f32 v112, v115, v116
	v_cvt_pk_bf16_f32 v113, v117, v118
	v_cvt_pk_bf16_f32 v114, v119, v120
	v_cvt_pk_bf16_f32 v115, v121, v122
	v_permlane32_swap_b32_e32 v101, v103
	v_permlane32_swap_b32_e32 v104, v106
	v_permlane32_swap_b32_e32 v105, v107
	v_permlane32_swap_b32_e32 v108, v110
	v_permlane32_swap_b32_e32 v109, v111
	v_permlane32_swap_b32_e32 v112, v114
	v_permlane32_swap_b32_e32 v113, v115
	ds_read_b64_tr_b16 v[116:117], v176 offset:0
	ds_read_b64_tr_b16 v[118:119], v176 offset:0x800
	ds_read_b64_tr_b16 v[120:121], v176 offset:0x1000
	ds_read_b64_tr_b16 v[122:123], v176 offset:0x1800
	ds_read_b64_tr_b16 v[124:125], v176 offset:0x2000
	ds_read_b64_tr_b16 v[126:127], v176 offset:0x2800
	ds_read_b64_tr_b16 v[128:129], v176 offset:0x3000
	ds_read_b64_tr_b16 v[130:131], v176 offset:0x3800
	s_waitcnt lgkmcnt(4)
	s_nop 0
	v_mfma_f32_32x32x16_bf16 v[2:17], v[100:103], v[116:119], v[2:17]
	ds_read_b64_tr_b16 v[116:117], v176 offset:0x200
	ds_read_b64_tr_b16 v[118:119], v176 offset:0xa00
	v_mfma_f32_32x32x16_bf16 v[2:17], v[104:107], v[120:123], v[2:17]
	ds_read_b64_tr_b16 v[120:121], v176 offset:0x1200
	ds_read_b64_tr_b16 v[122:123], v176 offset:0x1a00
	s_waitcnt lgkmcnt(4)
	v_mfma_f32_32x32x16_bf16 v[2:17], v[108:111], v[124:127], v[2:17]
	ds_read_b64_tr_b16 v[124:125], v176 offset:0x2200
	ds_read_b64_tr_b16 v[126:127], v176 offset:0x2a00
	v_mfma_f32_32x32x16_bf16 v[2:17], v[112:115], v[128:131], v[2:17]
	ds_read_b64_tr_b16 v[128:129], v176 offset:0x3200
	ds_read_b64_tr_b16 v[130:131], v176 offset:0x3a00
	s_waitcnt lgkmcnt(4)
	v_mfma_f32_32x32x16_bf16 v[50:65], v[100:103], v[116:119], v[50:65]
	ds_read_b64_tr_b16 v[116:117], v176 offset:0x400
	ds_read_b64_tr_b16 v[118:119], v176 offset:0xc00
	v_mfma_f32_32x32x16_bf16 v[50:65], v[104:107], v[120:123], v[50:65]
	ds_read_b64_tr_b16 v[120:121], v176 offset:0x1400
	ds_read_b64_tr_b16 v[122:123], v176 offset:0x1c00
	s_waitcnt lgkmcnt(4)
	v_mfma_f32_32x32x16_bf16 v[50:65], v[108:111], v[124:127], v[50:65]
	ds_read_b64_tr_b16 v[124:125], v176 offset:0x2400
	ds_read_b64_tr_b16 v[126:127], v176 offset:0x2c00
	v_mfma_f32_32x32x16_bf16 v[50:65], v[112:115], v[128:131], v[50:65]
	ds_read_b64_tr_b16 v[128:129], v176 offset:0x3400
	ds_read_b64_tr_b16 v[130:131], v176 offset:0x3c00
	s_waitcnt lgkmcnt(4)
	v_mfma_f32_32x32x16_bf16 v[34:49], v[100:103], v[116:119], v[34:49]
	ds_read_b64_tr_b16 v[116:117], v176 offset:0x600
	ds_read_b64_tr_b16 v[118:119], v176 offset:0xe00
	v_mfma_f32_32x32x16_bf16 v[34:49], v[104:107], v[120:123], v[34:49]
	ds_read_b64_tr_b16 v[120:121], v176 offset:0x1600
	ds_read_b64_tr_b16 v[122:123], v176 offset:0x1e00
	s_waitcnt lgkmcnt(4)
; #define SBAR() __builtin_amdgcn_sched_barrier(0)
; __device__ __forceinline__ void partialSM(f32x16& p0, f32x16& p1, float& m_reg, float& mn, float& alpha) {
;   constexpr float C = SCALE * 1.4426950408889634f;
;   float pmax = p0[0];
; #pragma unroll
;   for (int r = 1; r < 16; ++r) pmax = fmaxf(pmax, p0[r]);
; #pragma unroll
;   for (int r = 0; r < 16; ++r) pmax = fmaxf(pmax, p1[r]);
;   { auto rr = __builtin_amdgcn_permlane32_swap(__float_as_uint(pmax), __float_as_uint(pmax), false, false);
;     pmax = fmaxf(__uint_as_float(rr[0]), __uint_as_float(rr[1])); }
;   if (__builtin_expect(__all(pmax - m_reg <= THR / SCALE), 1)) { mn = m_reg; alpha = 1.f; }
;   else { mn = fmaxf(m_reg, pmax); alpha = __builtin_amdgcn_exp2f((m_reg - mn) * C); m_reg = mn; }
;   float mnC = -mn * C;
; #pragma unroll
;   for (int r = 0; r < 16; ++r) p0[r] = fmaf(p0[r], C, mnC);
; #pragma unroll
;   for (int r = 0; r < 16; ++r) p1[r] = fmaf(p1[r], C, mnC);
; #pragma unroll
;   for (int r = 0; r < 16; ++r) p0[r] = __builtin_amdgcn_exp2f(p0[r]);
; }
; template <int D0> __device__ __forceinline__ void pv_one(f32x16& od, int vb, bf16x8 pa0, bf16x8 pa1, bf16x8 pa2, bf16x8 pa3) {
;   const s16x4 l0 = tr_read<v_rd_off(D0, 0, 0)>(vb), h0 = tr_read<v_rd_off(D0, 0, 1)>(vb), l1 = tr_read<v_rd_off(D0, 1, 0)>(vb), h1 = tr_read<v_rd_off(D0, 1, 1)>(vb);
;   const s16x4 l2 = tr_read<v_rd_off(D0, 2, 0)>(vb), h2 = tr_read<v_rd_off(D0, 2, 1)>(vb), l3 = tr_read<v_rd_off(D0, 3, 0)>(vb), h3 = tr_read<v_rd_off(D0, 3, 1)>(vb);
;   asm volatile("s_waitcnt lgkmcnt(0)" ::: "memory"); SBAR();
;     ...
;   od = __builtin_amdgcn_mfma_f32_32x32x16_bf16(pa0, PK(l0, h0), od, 0, 0, 0);
;   od = __builtin_amdgcn_mfma_f32_32x32x16_bf16(pa1, PK(l1, h1), od, 0, 0, 0);
;   od = __builtin_amdgcn_mfma_f32_32x32x16_bf16(pa2, PK(l2, h2), od, 0, 0, 0);
;   od = __builtin_amdgcn_mfma_f32_32x32x16_bf16(pa3, PK(l3, h3), od, 0, 0, 0);
;     ...
; }
; __device__ __forceinline__ void pv_d0(f32x16* o, int vb, bf16x8 pa0, bf16x8 pa1, bf16x8 pa2, bf16x8 pa3) {
;   pv_one<0>(o[0], vb, pa0, pa1, pa2, pa3); pv_one<1>(o[1], vb, pa0, pa1, pa2, pa3); pv_one<2>(o[2], vb, pa0, pa1, pa2, pa3); pv_one<3>(o[3], vb, pa0, pa1, pa2, pa3);
	v_mfma_f32_32x32x16_bf16 v[34:49], v[108:111], v[124:127], v[34:49]
	ds_read_b64_tr_b16 v[124:125], v176 offset:0x2600
	ds_read_b64_tr_b16 v[126:127], v176 offset:0x2e00
	v_mfma_f32_32x32x16_bf16 v[34:49], v[112:115], v[128:131], v[34:49]
	ds_read_b64_tr_b16 v[128:129], v176 offset:0x3600
	ds_read_b64_tr_b16 v[130:131], v176 offset:0x3e00
	s_waitcnt lgkmcnt(4)
	v_mfma_f32_32x32x16_bf16 v[18:33], v[100:103], v[116:119], v[18:33]
	v_max_f32_e32 v99, v83, v83
	v_max_f32_e32 v100, v82, v82
	v_max_f32_e32 v99, v100, v99
	v_max3_f32 v99, v99, v84, v85
	v_max3_f32 v99, v99, v86, v87
	v_max3_f32 v99, v99, v88, v89
	v_max3_f32 v99, v99, v90, v91
	v_max3_f32 v99, v99, v92, v93
	v_max3_f32 v99, v99, v94, v95
	v_mfma_f32_32x32x16_bf16 v[18:33], v[104:107], v[120:123], v[18:33]
	v_max3_f32 v99, v99, v96, v97
	v_max3_f32 v99, v99, v66, v67
	v_max3_f32 v99, v99, v68, v69
	v_max3_f32 v99, v99, v70, v71
	v_max3_f32 v99, v99, v72, v73
	v_max3_f32 v99, v99, v74, v75
	v_max3_f32 v99, v99, v76, v77
	v_max3_f32 v99, v99, v78, v79
	s_waitcnt lgkmcnt(0)
	v_mfma_f32_32x32x16_bf16 v[18:33], v[108:111], v[124:127], v[18:33]
	v_max3_f32 v99, v99, v80, v81
	v_mov_b32_e32 v100, v99
	s_nop 1
	v_permlane32_swap_b32_e32 v99, v100
	v_max_f32_e32 v100, v100, v100
	v_max_f32_e32 v99, v99, v99
	v_max_f32_e32 v99, v99, v100
	v_sub_f32_e32 v100, v99, v150
	v_cmp_ge_f32_e32 vcc, s63, v100
	v_max_f32_e32 v100, v150, v150
	v_max_f32_e32 v100, v100, v99
	v_mfma_f32_32x32x16_bf16 v[18:33], v[112:115], v[128:131], v[18:33]
	v_sub_f32_e32 v99, v150, v100
	v_mul_f32_e32 v99, 0x3e0293ee, v99
	v_exp_f32_e32 v99, v99
	s_cmp_eq_u64 vcc, exec
	s_cselect_b64 s[8:9], -1, 0
	v_cndmask_b32_e64 v99, v99, 1.0, s[8:9]
	v_cmp_gt_f32_e32 vcc, 1.0, v99
	s_barrier
	s_cbranch_vccz .LBB0_1018
	s_and_saveexec_b64 s[2:3], s[6:7]
	ds_write_b32 v173, v99 offset:128
	s_or_b64 exec, exec, s[2:3]
	s_waitcnt lgkmcnt(0)
	v_add_u32_e32 v101, s15, v172
	ds_read_b128 v[102:105], v101 offset:224
	ds_read_b128 v[106:109], v101 offset:192
	ds_read_b128 v[110:113], v101 offset:160
	ds_read_b128 v[114:117], v101 offset:128
	s_waitcnt lgkmcnt(3)
	v_pk_mul_f32 v[14:15], v[14:15], v[102:103]
	s_waitcnt lgkmcnt(2)
	v_pk_mul_f32 v[10:11], v[10:11], v[106:107]
	s_waitcnt lgkmcnt(1)
	v_pk_mul_f32 v[6:7], v[6:7], v[110:111]
	v_pk_mul_f32 v[16:17], v[16:17], v[104:105]
	v_pk_mul_f32 v[12:13], v[12:13], v[108:109]
	v_pk_mul_f32 v[8:9], v[8:9], v[112:113]
	s_waitcnt lgkmcnt(0)
	v_pk_mul_f32 v[4:5], v[4:5], v[116:117]
	v_pk_mul_f32 v[2:3], v[2:3], v[114:115]
	v_pk_mul_f32 v[62:63], v[62:63], v[102:103]
	v_pk_mul_f32 v[58:59], v[58:59], v[106:107]
	v_pk_mul_f32 v[54:55], v[54:55], v[110:111]
	v_pk_mul_f32 v[64:65], v[64:65], v[104:105]
	v_pk_mul_f32 v[60:61], v[60:61], v[108:109]
	v_pk_mul_f32 v[56:57], v[56:57], v[112:113]
	v_pk_mul_f32 v[52:53], v[52:53], v[116:117]
	v_pk_mul_f32 v[50:51], v[50:51], v[114:115]
	v_pk_mul_f32 v[46:47], v[46:47], v[102:103]
	v_pk_mul_f32 v[42:43], v[42:43], v[106:107]
	v_pk_mul_f32 v[38:39], v[38:39], v[110:111]
	v_pk_mul_f32 v[48:49], v[48:49], v[104:105]
	v_pk_mul_f32 v[44:45], v[44:45], v[108:109]
	v_pk_mul_f32 v[40:41], v[40:41], v[112:113]
	v_pk_mul_f32 v[36:37], v[36:37], v[116:117]
	v_pk_mul_f32 v[34:35], v[34:35], v[114:115]
	v_pk_mul_f32 v[30:31], v[30:31], v[102:103]
	v_pk_mul_f32 v[26:27], v[26:27], v[106:107]
	v_pk_mul_f32 v[22:23], v[22:23], v[110:111]
	v_pk_mul_f32 v[32:33], v[32:33], v[104:105]
	v_pk_mul_f32 v[28:29], v[28:29], v[108:109]
	v_pk_mul_f32 v[24:25], v[24:25], v[112:113]
	v_pk_mul_f32 v[20:21], v[20:21], v[116:117]
	v_pk_mul_f32 v[18:19], v[18:19], v[114:115]
.LBB0_1018:
	v_cndmask_b32_e64 v100, v100, v150, s[8:9]
	v_mul_f32_e32 v100, 0xbe0293ee, v100
	v_fmamk_f32 v82, v82, 0x3e0293ee, v100
	v_fmamk_f32 v83, v83, 0x3e0293ee, v100
	v_fmamk_f32 v101, v84, 0x3e0293ee, v100
	v_exp_f32_e32 v84, v82
	v_fmamk_f32 v102, v86, 0x3e0293ee, v100
	v_exp_f32_e32 v86, v83
	v_fmamk_f32 v85, v85, 0x3e0293ee, v100
	v_exp_f32_e32 v82, v101
	v_fmamk_f32 v66, v66, 0x3e0293ee, v100
	v_exp_f32_e32 v85, v85
	v_fmamk_f32 v103, v87, 0x3e0293ee, v100
	v_fmamk_f32 v112, v96, 0x3e0293ee, v100
	v_fmamk_f32 v96, v77, 0x3e0293ee, v100
	v_exp_f32_e32 v77, v102
	v_exp_f32_e32 v101, v66
	v_add_f32_e32 v66, 0, v84
	v_fmamk_f32 v104, v88, 0x3e0293ee, v100
	v_exp_f32_e32 v83, v103
	v_add_f32_e32 v66, v86, v66
	v_fmamk_f32 v105, v89, 0x3e0293ee, v100
	v_fmamk_f32 v111, v95, 0x3e0293ee, v100
	v_fmamk_f32 v95, v76, 0x3e0293ee, v100
	v_exp_f32_e32 v76, v104
	v_add_f32_e32 v66, v82, v66
	v_fmamk_f32 v106, v90, 0x3e0293ee, v100
	v_fmamk_f32 v113, v97, 0x3e0293ee, v100
	v_fmamk_f32 v97, v78, 0x3e0293ee, v100
	v_exp_f32_e32 v78, v105
	v_add_f32_e32 v66, v85, v66
	v_fmamk_f32 v107, v91, 0x3e0293ee, v100
	v_fmamk_f32 v108, v92, 0x3e0293ee, v100
	v_fmamk_f32 v92, v73, 0x3e0293ee, v100
	v_exp_f32_e32 v73, v106
	v_add_f32_e32 v66, v77, v66
	v_fmamk_f32 v110, v94, 0x3e0293ee, v100
	v_fmamk_f32 v94, v75, 0x3e0293ee, v100
	v_exp_f32_e32 v75, v107
	v_add_f32_e32 v66, v83, v66
	v_fmamk_f32 v109, v93, 0x3e0293ee, v100
	v_fmamk_f32 v90, v71, 0x3e0293ee, v100
	v_exp_f32_e32 v71, v108
	v_add_f32_e32 v66, v76, v66
	v_fmamk_f32 v93, v74, 0x3e0293ee, v100
	v_exp_f32_e32 v74, v109
	v_add_f32_e32 v66, v78, v66
	v_fmamk_f32 v88, v69, 0x3e0293ee, v100
	v_exp_f32_e32 v69, v110
	v_add_f32_e32 v66, v73, v66
	v_fmamk_f32 v91, v72, 0x3e0293ee, v100
	v_exp_f32_e32 v72, v111
	v_add_f32_e32 v66, v75, v66
	v_fmamk_f32 v87, v68, 0x3e0293ee, v100
	v_exp_f32_e32 v68, v112
	v_add_f32_e32 v66, v71, v66
	v_fmamk_f32 v89, v70, 0x3e0293ee, v100
	v_exp_f32_e32 v70, v113
	v_add_f32_e32 v66, v74, v66
	v_fmamk_f32 v67, v67, 0x3e0293ee, v100
; __device__ __forceinline__ void finishSM(f32x16& p0, f32x16& p1, float alpha, float& l_reg, bf16x8& pa0, bf16x8& pa1, bf16x8& pa2, bf16x8& pa3) {
; #pragma unroll
;   for (int r = 0; r < 16; ++r) p1[r] = __builtin_amdgcn_exp2f(p1[r]);
;   float ps = 0;
; #pragma unroll
;   for (int r = 0; r < 16; ++r) ps += p0[r];
; #pragma unroll
;   for (int r = 0; r < 16; ++r) ps += p1[r];
;   { auto rr = __builtin_amdgcn_permlane32_swap(__float_as_uint(ps), __float_as_uint(ps), false, false);
;     ps = __uint_as_float(rr[0]) + __uint_as_float(rr[1]); }
;   l_reg = l_reg * alpha + ps;
;   PK4(p0, 0, pa0); PK4(p0, 8, pa1); PK4(p1, 0, pa2); PK4(p1, 8, pa3);
; }
;   p0 = f32x16{}; p1 = f32x16{};
; #pragma unroll
;   for (int d0 = DLO; d0 < DHI; ++d0) { int cb = (d0 * 16 + hi * 8) * 2;
;     bf16x8 b0 = *reinterpret_cast<const bf16x8*>((const char*)Ks + KSWZ(r32, cb));
;     bf16x8 b1 = *reinterpret_cast<const bf16x8*>((const char*)Ks + KSWZ(32 + r32, cb));
;     p0 = __builtin_amdgcn_mfma_f32_32x32x16_bf16(b0, qr[d0], p0, 0, 0, 0);
;     p1 = __builtin_amdgcn_mfma_f32_32x32x16_bf16(b1, qr[d0], p1, 0, 0, 0); }
; }
; __device__ __forceinline__ int v_st(int k, int c) { const int kk = (k & ~0xC) | ((k & 4) << 1) | ((k & 8) >> 1); return ((kk >> 3) * 4 + (c >> 5)) * 512 + ((kk & 7) * 32 + (c & 31)) * 2; }
; __device__ __forceinline__ int v_rd_base(int lane) { return ((lane & 3) << 3) | (((lane >> 2) & 3) << 6) | (((lane >> 4) & 1) << 5) | (((lane >> 5) & 1) << 8); }
; template <int OFF> __device__ __forceinline__ s16x4 tr_read(int vb) {
;   s16x4 r; asm volatile("ds_read_b64_tr_b16 %0, %1 offset:%2" : "=&v"(r) : "v"(vb), "i"(OFF) : "memory"); return r;
; }
; template <int D0> __device__ __forceinline__ void pv_one(f32x16& od, int vb, bf16x8 pa0, bf16x8 pa1, bf16x8 pa2, bf16x8 pa3) {
;   const s16x4 l0 = tr_read<v_rd_off(D0, 0, 0)>(vb), h0 = tr_read<v_rd_off(D0, 0, 1)>(vb), l1 = tr_read<v_rd_off(D0, 1, 0)>(vb), h1 = tr_read<v_rd_off(D0, 1, 1)>(vb);
;   const s16x4 l2 = tr_read<v_rd_off(D0, 2, 0)>(vb), h2 = tr_read<v_rd_off(D0, 2, 1)>(vb), l3 = tr_read<v_rd_off(D0, 3, 0)>(vb), h3 = tr_read<v_rd_off(D0, 3, 1)>(vb);
;   asm volatile("s_waitcnt lgkmcnt(0)" ::: "memory"); SBAR();
;     ...
;   od = __builtin_amdgcn_mfma_f32_32x32x16_bf16(pa0, PK(l0, h0), od, 0, 0, 0);
;   od = __builtin_amdgcn_mfma_f32_32x32x16_bf16(pa1, PK(l1, h1), od, 0, 0, 0);
	v_add_f32_e32 v66, v69, v66
	v_exp_f32_e32 v102, v67
	v_add_f32_e32 v66, v72, v66
	v_exp_f32_e32 v87, v87
	v_add_f32_e32 v66, v68, v66
	v_exp_f32_e32 v88, v88
	v_add_f32_e32 v66, v70, v66
	v_exp_f32_e32 v89, v89
	v_add_f32_e32 v66, v101, v66
	v_exp_f32_e32 v90, v90
	v_add_f32_e32 v66, v102, v66
	v_exp_f32_e32 v91, v91
	v_add_f32_e32 v66, v87, v66
	v_exp_f32_e32 v92, v92
	v_add_f32_e32 v66, v88, v66
	v_exp_f32_e32 v93, v93
	v_add_f32_e32 v66, v89, v66
	v_exp_f32_e32 v94, v94
	v_add_f32_e32 v66, v90, v66
	v_exp_f32_e32 v95, v95
	v_add_f32_e32 v66, v91, v66
	v_exp_f32_e32 v96, v96
	v_add_f32_e32 v66, v92, v66
	v_fmamk_f32 v79, v79, 0x3e0293ee, v100
	v_exp_f32_e32 v97, v97
	v_add_f32_e32 v66, v93, v66
	v_fmamk_f32 v80, v80, 0x3e0293ee, v100
	v_exp_f32_e32 v103, v79
	v_add_f32_e32 v66, v94, v66
	v_fmac_f32_e32 v100, 0x3e0293ee, v81
	v_exp_f32_e32 v104, v80
	v_add_f32_e32 v66, v95, v66
	v_exp_f32_e32 v100, v100
	v_add_f32_e32 v66, v96, v66
	v_add_f32_e32 v66, v97, v66
	v_add_f32_e32 v66, v103, v66
	v_add_f32_e32 v66, v104, v66
	v_add_f32_e32 v66, v100, v66
	v_mov_b32_e32 v67, v66
	s_nop 1
	v_permlane32_swap_b32_e32 v66, v67
	v_cvt_pk_bf16_f32 v80, v84, v86
	v_cvt_pk_bf16_f32 v81, v82, v85
	v_cvt_pk_bf16_f32 v82, v77, v83
	v_cvt_pk_bf16_f32 v83, v76, v78
	v_cvt_pk_bf16_f32 v76, v73, v75
	v_cvt_pk_bf16_f32 v77, v71, v74
	v_cvt_pk_bf16_f32 v78, v69, v72
	v_cvt_pk_bf16_f32 v79, v68, v70
	v_cvt_pk_bf16_f32 v68, v101, v102
	v_cvt_pk_bf16_f32 v69, v87, v88
	v_cvt_pk_bf16_f32 v70, v89, v90
	v_cvt_pk_bf16_f32 v71, v91, v92
	v_cvt_pk_bf16_f32 v72, v93, v94
	v_cvt_pk_bf16_f32 v73, v95, v96
	v_cvt_pk_bf16_f32 v74, v97, v103
	v_cvt_pk_bf16_f32 v75, v104, v100
	s_nop 0
	v_permlane32_swap_b32_e32 v80, v82
	v_permlane32_swap_b32_e32 v81, v83
	v_permlane32_swap_b32_e32 v76, v78
	v_permlane32_swap_b32_e32 v77, v79
	v_permlane32_swap_b32_e32 v68, v70
	v_permlane32_swap_b32_e32 v69, v71
	v_permlane32_swap_b32_e32 v72, v74
	v_permlane32_swap_b32_e32 v73, v75
	ds_read_b64_tr_b16 v[84:85], v175 offset:0
	ds_read_b64_tr_b16 v[86:87], v175 offset:0x800
	ds_read_b64_tr_b16 v[88:89], v175 offset:0x1000
	ds_read_b64_tr_b16 v[90:91], v175 offset:0x1800
	ds_read_b64_tr_b16 v[92:93], v175 offset:0x2000
	ds_read_b64_tr_b16 v[94:95], v175 offset:0x2800
	ds_read_b64_tr_b16 v[100:101], v175 offset:0x3000
	ds_read_b64_tr_b16 v[102:103], v175 offset:0x3800
	s_waitcnt lgkmcnt(4)
	s_nop 0
	v_mfma_f32_32x32x16_bf16 v[2:17], v[80:83], v[84:87], v[2:17]
	ds_read_b64_tr_b16 v[84:85], v175 offset:0x200
	ds_read_b64_tr_b16 v[86:87], v175 offset:0xa00
	v_mfma_f32_32x32x16_bf16 v[2:17], v[76:79], v[88:91], v[2:17]
	ds_read_b64_tr_b16 v[88:89], v175 offset:0x1200
	ds_read_b64_tr_b16 v[90:91], v175 offset:0x1a00
	s_waitcnt lgkmcnt(4)
	v_mfma_f32_32x32x16_bf16 v[2:17], v[68:71], v[92:95], v[2:17]
	ds_read_b64_tr_b16 v[92:93], v175 offset:0x2200
	ds_read_b64_tr_b16 v[94:95], v175 offset:0x2a00
	v_mfma_f32_32x32x16_bf16 v[2:17], v[72:75], v[100:103], v[2:17]
	ds_read_b64_tr_b16 v[100:101], v175 offset:0x3200
	ds_read_b64_tr_b16 v[102:103], v175 offset:0x3a00
	s_waitcnt lgkmcnt(4)
	v_mfma_f32_32x32x16_bf16 v[50:65], v[80:83], v[84:87], v[50:65]
	ds_read_b64_tr_b16 v[84:85], v175 offset:0x400
	ds_read_b64_tr_b16 v[86:87], v175 offset:0xc00
	v_mfma_f32_32x32x16_bf16 v[50:65], v[76:79], v[88:91], v[50:65]
	ds_read_b64_tr_b16 v[88:89], v175 offset:0x1400
	ds_read_b64_tr_b16 v[90:91], v175 offset:0x1c00
	s_waitcnt lgkmcnt(4)
	v_mfma_f32_32x32x16_bf16 v[50:65], v[68:71], v[92:95], v[50:65]
	ds_read_b64_tr_b16 v[92:93], v175 offset:0x2400
	ds_read_b64_tr_b16 v[94:95], v175 offset:0x2c00
	v_mfma_f32_32x32x16_bf16 v[50:65], v[72:75], v[100:103], v[50:65]
	ds_read_b64_tr_b16 v[100:101], v175 offset:0x3400
	ds_read_b64_tr_b16 v[102:103], v175 offset:0x3c00
	s_waitcnt lgkmcnt(4)
	v_mfma_f32_32x32x16_bf16 v[34:49], v[80:83], v[84:87], v[34:49]
	ds_read_b64_tr_b16 v[84:85], v175 offset:0x600
	ds_read_b64_tr_b16 v[86:87], v175 offset:0xe00
	v_mfma_f32_32x32x16_bf16 v[34:49], v[76:79], v[88:91], v[34:49]
	ds_read_b64_tr_b16 v[88:89], v175 offset:0x1600
	ds_read_b64_tr_b16 v[90:91], v175 offset:0x1e00
	s_waitcnt lgkmcnt(4)
	v_mfma_f32_32x32x16_bf16 v[34:49], v[68:71], v[92:95], v[34:49]
	ds_read_b64_tr_b16 v[92:93], v175 offset:0x2600
	ds_read_b64_tr_b16 v[94:95], v175 offset:0x2e00
	v_mfma_f32_32x32x16_bf16 v[34:49], v[72:75], v[100:103], v[34:49]
	ds_read_b64_tr_b16 v[100:101], v175 offset:0x3600
	ds_read_b64_tr_b16 v[102:103], v175 offset:0x3e00
	s_waitcnt lgkmcnt(4)
	v_mfma_f32_32x32x16_bf16 v[18:33], v[80:83], v[84:87], v[18:33]
	v_mfma_f32_32x32x16_bf16 v[18:33], v[76:79], v[88:91], v[18:33]
	s_waitcnt lgkmcnt(0)
	v_mfma_f32_32x32x16_bf16 v[18:33], v[68:71], v[92:95], v[18:33]
	v_mfma_f32_32x32x16_bf16 v[18:33], v[72:75], v[100:103], v[18:33]
	s_and_saveexec_b64 s[2:3], s[6:7]
	v_add_f32_e32 v0, v0, v98
	v_fmac_f32_e32 v0, v174, v146
	v_add_f32_e32 v66, v66, v67
	v_fmac_f32_e32 v66, v0, v99
	ds_write_b32 v173, v66
	s_or_b64 exec, exec, s[2:3]
	s_waitcnt lgkmcnt(0)
	v_add_u32_e32 v0, s15, v172
	ds_read_b128 v[66:69], v0
	ds_read_b128 v[70:73], v0 offset:32
	s_mul_hi_i32 s3, s10, s14
	s_mul_i32 s2, s10, s14
	s_lshl_b64 s[2:3], s[2:3], 1
	s_waitcnt lgkmcnt(1)
	v_rcp_f32_e32 v74, v66
	v_rcp_f32_e32 v75, v67
	v_rcp_f32_e32 v76, v68
	v_rcp_f32_e32 v77, v69
	ds_read_b128 v[66:69], v0 offset:64
	s_add_u32 s2, s82, s2
	s_waitcnt lgkmcnt(1)
	v_rcp_f32_e32 v78, v70
	v_rcp_f32_e32 v79, v71
	v_rcp_f32_e32 v80, v72
	v_rcp_f32_e32 v81, v73
	ds_read_b128 v[70:73], v0 offset:96
	s_addc_u32 s3, s83, s3
	v_lshlrev_b32_e32 v86, 2, v171
	v_lshlrev_b32_e32 v0, 1, v170
	s_waitcnt lgkmcnt(1)
; __device__ __forceinline__ int crow(int r, int hi) { return (r & 3) + 8 * (r >> 2) + 4 * hi; }
; __device__ __forceinline__ unsigned cvtpk(float lo, float hi) { unsigned r; asm volatile("v_cvt_pk_bf16_f32 %0, %1, %2" : "=v"(r) : "v"(lo), "v"(hi)); return r; }
; template <int DLO, int DHI>
; __device__ __forceinline__ void attn_dense_body(const int g_wave, const bf16* __restrict__ Qb, const bf16* __restrict__ Kh, const bf16* __restrict__ Vh,
;                                                 bf16* __restrict__ Ob, int ldo, char* lds) {
;     ...
;   if (hi == 0) li_l[r32] = l_reg; asm volatile("s_waitcnt lgkmcnt(0)" ::: "memory");
;   float rli[16];
; #pragma unroll
;   for (int r = 0; r < 16; ++r) rli[r] = __builtin_amdgcn_rcpf(li_l[crow(r, hi)]);
;   unsigned short* Ow = (unsigned short*)Ob + (long)(wid * QBLK) * ldo;
; #pragma unroll
;   for (int r = 0; r < 16; ++r) { int orow = crow(r, hi);
; #pragma unroll
;     for (int d0 = 0; d0 < 4; ++d0) Ow[(long)orow * ldo + d0 * 32 + r32] = (unsigned short)(cvtpk(o[d0][r] * rli[r], 0.f) & 0xffffu); }
	v_rcp_f32_e32 v82, v66
	v_rcp_f32_e32 v83, v67
	v_rcp_f32_e32 v84, v68
	v_rcp_f32_e32 v85, v69
	v_lshl_add_u64 v[66:67], s[2:3], 0, v[0:1]
	v_mad_i64_i32 v[68:69], s[2:3], s10, v86, 0
	v_mul_f32_e32 v0, v2, v74
	v_lshl_add_u64 v[68:69], v[68:69], 1, v[66:67]
	v_cvt_pk_bf16_f32 v0, v0, v1
	global_store_short v[68:69], v0, off
	v_mul_f32_e32 v0, v50, v74
	v_cvt_pk_bf16_f32 v0, v0, v1
	global_store_short v[68:69], v0, off offset:64
	v_mul_f32_e32 v0, v34, v74
	v_cvt_pk_bf16_f32 v0, v0, v1
	global_store_short v[68:69], v0, off offset:128
	v_mul_f32_e32 v0, v18, v74
	v_cvt_pk_bf16_f32 v0, v0, v1
	global_store_short v[68:69], v0, off offset:192
	v_or_b32_e32 v0, 1, v86
	v_mad_i64_i32 v[68:69], s[2:3], s10, v0, 0
	v_mul_f32_e32 v0, v3, v75
	v_lshl_add_u64 v[68:69], v[68:69], 1, v[66:67]
	v_cvt_pk_bf16_f32 v0, v0, v1
	global_store_short v[68:69], v0, off
	v_mul_f32_e32 v0, v51, v75
	v_cvt_pk_bf16_f32 v0, v0, v1
	global_store_short v[68:69], v0, off offset:64
	v_mul_f32_e32 v0, v35, v75
	v_cvt_pk_bf16_f32 v0, v0, v1
	global_store_short v[68:69], v0, off offset:128
	v_mul_f32_e32 v0, v19, v75
	v_cvt_pk_bf16_f32 v0, v0, v1
	global_store_short v[68:69], v0, off offset:192
	v_or_b32_e32 v0, 2, v86
	v_mad_i64_i32 v[2:3], s[2:3], s10, v0, 0
	v_mul_f32_e32 v0, v4, v76
	v_lshl_add_u64 v[2:3], v[2:3], 1, v[66:67]
	v_cvt_pk_bf16_f32 v0, v0, v1
	global_store_short v[2:3], v0, off
	v_mul_f32_e32 v0, v52, v76
	v_cvt_pk_bf16_f32 v0, v0, v1
	global_store_short v[2:3], v0, off offset:64
	v_mul_f32_e32 v0, v36, v76
	v_cvt_pk_bf16_f32 v0, v0, v1
	global_store_short v[2:3], v0, off offset:128
	v_mul_f32_e32 v0, v20, v76
	v_cvt_pk_bf16_f32 v0, v0, v1
	global_store_short v[2:3], v0, off offset:192
	v_or_b32_e32 v0, 3, v86
	v_mad_i64_i32 v[2:3], s[2:3], s10, v0, 0
	v_mul_f32_e32 v0, v5, v77
	v_lshl_add_u64 v[2:3], v[2:3], 1, v[66:67]
	v_cvt_pk_bf16_f32 v0, v0, v1
	global_store_short v[2:3], v0, off
	v_mul_f32_e32 v0, v53, v77
	v_cvt_pk_bf16_f32 v0, v0, v1
	global_store_short v[2:3], v0, off offset:64
	v_mul_f32_e32 v0, v37, v77
	v_cvt_pk_bf16_f32 v0, v0, v1
	global_store_short v[2:3], v0, off offset:128
	v_mul_f32_e32 v0, v21, v77
	v_cvt_pk_bf16_f32 v0, v0, v1
	global_store_short v[2:3], v0, off offset:192
	v_add_u32_e32 v0, 8, v86
	v_mad_i64_i32 v[2:3], s[2:3], s10, v0, 0
	v_mul_f32_e32 v0, v6, v78
	v_lshl_add_u64 v[2:3], v[2:3], 1, v[66:67]
	v_cvt_pk_bf16_f32 v0, v0, v1
	global_store_short v[2:3], v0, off
	v_mul_f32_e32 v0, v54, v78
	v_cvt_pk_bf16_f32 v0, v0, v1
	global_store_short v[2:3], v0, off offset:64
	v_mul_f32_e32 v0, v38, v78
	v_cvt_pk_bf16_f32 v0, v0, v1
	global_store_short v[2:3], v0, off offset:128
	v_mul_f32_e32 v0, v22, v78
	v_cvt_pk_bf16_f32 v0, v0, v1
	global_store_short v[2:3], v0, off offset:192
	v_add_u32_e32 v0, 9, v86
	v_mad_i64_i32 v[2:3], s[2:3], s10, v0, 0
	v_mul_f32_e32 v0, v7, v79
	v_lshl_add_u64 v[2:3], v[2:3], 1, v[66:67]
	v_cvt_pk_bf16_f32 v0, v0, v1
	global_store_short v[2:3], v0, off
	v_mul_f32_e32 v0, v55, v79
	v_cvt_pk_bf16_f32 v0, v0, v1
	global_store_short v[2:3], v0, off offset:64
	v_mul_f32_e32 v0, v39, v79
	v_cvt_pk_bf16_f32 v0, v0, v1
	global_store_short v[2:3], v0, off offset:128
	v_mul_f32_e32 v0, v23, v79
	v_cvt_pk_bf16_f32 v0, v0, v1
	global_store_short v[2:3], v0, off offset:192
	v_add_u32_e32 v0, 10, v86
	v_mad_i64_i32 v[2:3], s[2:3], s10, v0, 0
	v_mul_f32_e32 v0, v8, v80
	v_lshl_add_u64 v[2:3], v[2:3], 1, v[66:67]
	v_cvt_pk_bf16_f32 v0, v0, v1
	global_store_short v[2:3], v0, off
	v_mul_f32_e32 v0, v56, v80
	v_cvt_pk_bf16_f32 v0, v0, v1
	global_store_short v[2:3], v0, off offset:64
	v_mul_f32_e32 v0, v40, v80
	v_cvt_pk_bf16_f32 v0, v0, v1
	global_store_short v[2:3], v0, off offset:128
	v_mul_f32_e32 v0, v24, v80
	v_cvt_pk_bf16_f32 v0, v0, v1
	global_store_short v[2:3], v0, off offset:192
	v_add_u32_e32 v0, 11, v86
	v_mad_i64_i32 v[2:3], s[2:3], s10, v0, 0
	v_mul_f32_e32 v0, v9, v81
	v_lshl_add_u64 v[2:3], v[2:3], 1, v[66:67]
	v_cvt_pk_bf16_f32 v0, v0, v1
	global_store_short v[2:3], v0, off
	v_mul_f32_e32 v0, v57, v81
	v_cvt_pk_bf16_f32 v0, v0, v1
	global_store_short v[2:3], v0, off offset:64
	v_mul_f32_e32 v0, v41, v81
	v_cvt_pk_bf16_f32 v0, v0, v1
	global_store_short v[2:3], v0, off offset:128
	v_mul_f32_e32 v0, v25, v81
	v_cvt_pk_bf16_f32 v0, v0, v1
	global_store_short v[2:3], v0, off offset:192
	v_add_u32_e32 v0, 16, v86
	v_mad_i64_i32 v[2:3], s[2:3], s10, v0, 0
	v_mul_f32_e32 v0, v10, v82
	v_lshl_add_u64 v[2:3], v[2:3], 1, v[66:67]
	v_cvt_pk_bf16_f32 v0, v0, v1
	global_store_short v[2:3], v0, off
	v_mul_f32_e32 v0, v58, v82
	v_cvt_pk_bf16_f32 v0, v0, v1
	global_store_short v[2:3], v0, off offset:64
	v_mul_f32_e32 v0, v42, v82
	v_cvt_pk_bf16_f32 v0, v0, v1
	global_store_short v[2:3], v0, off offset:128
	v_mul_f32_e32 v0, v26, v82
	v_cvt_pk_bf16_f32 v0, v0, v1
	global_store_short v[2:3], v0, off offset:192
	v_add_u32_e32 v0, 17, v86
	v_mad_i64_i32 v[2:3], s[2:3], s10, v0, 0
	v_mul_f32_e32 v0, v11, v83
	v_lshl_add_u64 v[2:3], v[2:3], 1, v[66:67]
	v_cvt_pk_bf16_f32 v0, v0, v1
	global_store_short v[2:3], v0, off
	v_mul_f32_e32 v0, v59, v83
	v_cvt_pk_bf16_f32 v0, v0, v1
	global_store_short v[2:3], v0, off offset:64
	v_mul_f32_e32 v0, v43, v83
	v_cvt_pk_bf16_f32 v0, v0, v1
	global_store_short v[2:3], v0, off offset:128
	v_mul_f32_e32 v0, v27, v83
	v_cvt_pk_bf16_f32 v0, v0, v1
	global_store_short v[2:3], v0, off offset:192
	v_add_u32_e32 v0, 18, v86
	v_mad_i64_i32 v[2:3], s[2:3], s10, v0, 0
	v_mul_f32_e32 v0, v12, v84
	v_lshl_add_u64 v[2:3], v[2:3], 1, v[66:67]
	v_cvt_pk_bf16_f32 v0, v0, v1
	global_store_short v[2:3], v0, off
	v_mul_f32_e32 v0, v60, v84
	v_cvt_pk_bf16_f32 v0, v0, v1
	global_store_short v[2:3], v0, off offset:64
	v_mul_f32_e32 v0, v44, v84
	v_cvt_pk_bf16_f32 v0, v0, v1
	global_store_short v[2:3], v0, off offset:128
	v_mul_f32_e32 v0, v28, v84
	v_cvt_pk_bf16_f32 v0, v0, v1
	global_store_short v[2:3], v0, off offset:192
	v_add_u32_e32 v0, 19, v86
	v_mad_i64_i32 v[2:3], s[2:3], s10, v0, 0
	v_mul_f32_e32 v0, v13, v85
	v_lshl_add_u64 v[2:3], v[2:3], 1, v[66:67]
	v_cvt_pk_bf16_f32 v0, v0, v1
	global_store_short v[2:3], v0, off
	v_mul_f32_e32 v0, v61, v85
	v_cvt_pk_bf16_f32 v0, v0, v1
	global_store_short v[2:3], v0, off offset:64
	v_mul_f32_e32 v0, v45, v85
	s_waitcnt lgkmcnt(0)
; __device__ __forceinline__ int crow(int r, int hi) { return (r & 3) + 8 * (r >> 2) + 4 * hi; }
; __device__ __forceinline__ unsigned cvtpk(float lo, float hi) { unsigned r; asm volatile("v_cvt_pk_bf16_f32 %0, %1, %2" : "=v"(r) : "v"(lo), "v"(hi)); return r; }
; template <int DLO, int DHI>
; __device__ __forceinline__ void attn_dense_body(const int g_wave, const bf16* __restrict__ Qb, const bf16* __restrict__ Kh, const bf16* __restrict__ Vh,
;                                                 bf16* __restrict__ Ob, int ldo, char* lds) {
;     ...
;   for (int r = 0; r < 16; ++r) rli[r] = __builtin_amdgcn_rcpf(li_l[crow(r, hi)]);
;   unsigned short* Ow = (unsigned short*)Ob + (long)(wid * QBLK) * ldo;
; #pragma unroll
;   for (int r = 0; r < 16; ++r) { int orow = crow(r, hi);
; #pragma unroll
;     for (int d0 = 0; d0 < 4; ++d0) Ow[(long)orow * ldo + d0 * 32 + r32] = (unsigned short)(cvtpk(o[d0][r] * rli[r], 0.f) & 0xffffu); }
;   __syncthreads();
	v_rcp_f32_e32 v70, v70
	v_cvt_pk_bf16_f32 v0, v0, v1
	global_store_short v[2:3], v0, off offset:128
	v_mul_f32_e32 v0, v29, v85
	v_cvt_pk_bf16_f32 v0, v0, v1
	global_store_short v[2:3], v0, off offset:192
	v_add_u32_e32 v0, 24, v86
	v_mad_i64_i32 v[2:3], s[2:3], s10, v0, 0
	v_mul_f32_e32 v0, v14, v70
	v_lshl_add_u64 v[2:3], v[2:3], 1, v[66:67]
	v_cvt_pk_bf16_f32 v0, v0, v1
	global_store_short v[2:3], v0, off
	v_mul_f32_e32 v0, v62, v70
	v_cvt_pk_bf16_f32 v0, v0, v1
	global_store_short v[2:3], v0, off offset:64
	v_mul_f32_e32 v0, v46, v70
	v_rcp_f32_e32 v71, v71
	v_cvt_pk_bf16_f32 v0, v0, v1
	global_store_short v[2:3], v0, off offset:128
	v_mul_f32_e32 v0, v30, v70
	v_cvt_pk_bf16_f32 v0, v0, v1
	global_store_short v[2:3], v0, off offset:192
	v_add_u32_e32 v0, 25, v86
	v_mad_i64_i32 v[2:3], s[2:3], s10, v0, 0
	v_mul_f32_e32 v0, v15, v71
	v_lshl_add_u64 v[2:3], v[2:3], 1, v[66:67]
	v_cvt_pk_bf16_f32 v0, v0, v1
	global_store_short v[2:3], v0, off
	v_mul_f32_e32 v0, v63, v71
	v_cvt_pk_bf16_f32 v0, v0, v1
	global_store_short v[2:3], v0, off offset:64
	v_mul_f32_e32 v0, v47, v71
	v_rcp_f32_e32 v72, v72
	v_cvt_pk_bf16_f32 v0, v0, v1
	global_store_short v[2:3], v0, off offset:128
	v_mul_f32_e32 v0, v31, v71
	v_cvt_pk_bf16_f32 v0, v0, v1
	global_store_short v[2:3], v0, off offset:192
	v_add_u32_e32 v0, 26, v86
	v_mad_i64_i32 v[2:3], s[2:3], s10, v0, 0
	v_mul_f32_e32 v0, v16, v72
	v_lshl_add_u64 v[2:3], v[2:3], 1, v[66:67]
	v_cvt_pk_bf16_f32 v0, v0, v1
	global_store_short v[2:3], v0, off
	v_mul_f32_e32 v0, v64, v72
	v_cvt_pk_bf16_f32 v0, v0, v1
	global_store_short v[2:3], v0, off offset:64
	v_mul_f32_e32 v0, v48, v72
	v_rcp_f32_e32 v73, v73
	v_cvt_pk_bf16_f32 v0, v0, v1
	global_store_short v[2:3], v0, off offset:128
	v_mul_f32_e32 v0, v32, v72
	v_cvt_pk_bf16_f32 v0, v0, v1
	global_store_short v[2:3], v0, off offset:192
	v_add_u32_e32 v0, 27, v86
	v_mad_i64_i32 v[2:3], s[2:3], s10, v0, 0
	v_mul_f32_e32 v0, v17, v73
	v_lshl_add_u64 v[2:3], v[2:3], 1, v[66:67]
	v_cvt_pk_bf16_f32 v0, v0, v1
	global_store_short v[2:3], v0, off
	v_mul_f32_e32 v0, v65, v73
	v_cvt_pk_bf16_f32 v0, v0, v1
	global_store_short v[2:3], v0, off offset:64
	v_mul_f32_e32 v0, v49, v73
	v_cvt_pk_bf16_f32 v0, v0, v1
	global_store_short v[2:3], v0, off offset:128
	v_mul_f32_e32 v0, v33, v73
	v_cvt_pk_bf16_f32 v0, v0, v1
	global_store_short v[2:3], v0, off offset:192
	s_waitcnt vmcnt(63) expcnt(7) lgkmcnt(15)
	s_barrier
	s_branch .LBB0_1062

; __device__ __forceinline__ void finishSM(f32x16& p0, f32x16& p1, float alpha, float& l_reg, bf16x8& pa0, bf16x8& pa1, bf16x8& pa2, bf16x8& pa3) {
; #pragma unroll
;   for (int r = 0; r < 16; ++r) p1[r] = __builtin_amdgcn_exp2f(p1[r]);
;   float ps = 0;
; #pragma unroll
;   for (int r = 0; r < 16; ++r) ps += p0[r];
; #pragma unroll
;   for (int r = 0; r < 16; ++r) ps += p1[r];
;   { auto rr = __builtin_amdgcn_permlane32_swap(__float_as_uint(ps), __float_as_uint(ps), false, false);
;     ps = __uint_as_float(rr[0]) + __uint_as_float(rr[1]); }
;   l_reg = l_reg * alpha + ps;
;   PK4(p0, 0, pa0); PK4(p0, 8, pa1); PK4(p1, 0, pa2); PK4(p1, 8, pa3);
; }
;   p0 = f32x16{}; p1 = f32x16{};
; #pragma unroll
;   for (int d0 = DLO; d0 < DHI; ++d0) { int cb = (d0 * 16 + hi * 8) * 2;
;     bf16x8 b0 = *reinterpret_cast<const bf16x8*>((const char*)Ks + KSWZ(r32, cb));
;     bf16x8 b1 = *reinterpret_cast<const bf16x8*>((const char*)Ks + KSWZ(32 + r32, cb));
;     p0 = __builtin_amdgcn_mfma_f32_32x32x16_bf16(b0, qr[d0], p0, 0, 0, 0);
;     p1 = __builtin_amdgcn_mfma_f32_32x32x16_bf16(b1, qr[d0], p1, 0, 0, 0); }
; }
; __device__ __forceinline__ int v_st(int k, int c) { const int kk = (k & ~0xC) | ((k & 4) << 1) | ((k & 8) >> 1); return ((kk >> 3) * 4 + (c >> 5)) * 512 + ((kk & 7) * 32 + (c & 31)) * 2; }
; __device__ __forceinline__ int v_rd_base(int lane) { return ((lane & 3) << 3) | (((lane >> 2) & 3) << 6) | (((lane >> 4) & 1) << 5) | (((lane >> 5) & 1) << 8); }
; template <int OFF> __device__ __forceinline__ s16x4 tr_read(int vb) {
;   s16x4 r; asm volatile("ds_read_b64_tr_b16 %0, %1 offset:%2" : "=&v"(r) : "v"(vb), "i"(OFF) : "memory"); return r;
; }
; template <int D0> __device__ __forceinline__ void pv_one(f32x16& od, int vb, bf16x8 pa0, bf16x8 pa1, bf16x8 pa2, bf16x8 pa3) {
;   const s16x4 l0 = tr_read<v_rd_off(D0, 0, 0)>(vb), h0 = tr_read<v_rd_off(D0, 0, 1)>(vb), l1 = tr_read<v_rd_off(D0, 1, 0)>(vb), h1 = tr_read<v_rd_off(D0, 1, 1)>(vb);
;   const s16x4 l2 = tr_read<v_rd_off(D0, 2, 0)>(vb), h2 = tr_read<v_rd_off(D0, 2, 1)>(vb), l3 = tr_read<v_rd_off(D0, 3, 0)>(vb), h3 = tr_read<v_rd_off(D0, 3, 1)>(vb);
;   asm volatile("s_waitcnt lgkmcnt(0)" ::: "memory"); SBAR();
;     ...
;   od = __builtin_amdgcn_mfma_f32_32x32x16_bf16(pa0, PK(l0, h0), od, 0, 0, 0);
;   od = __builtin_amdgcn_mfma_f32_32x32x16_bf16(pa1, PK(l1, h1), od, 0, 0, 0);
.LBB0_1022:
	ds_read_b128 v[66:69], v177 offset:49152
	ds_read_b128 v[70:73], v177 offset:57344
	v_add_f32_e32 v146, 0, v161
	v_add_f32_e32 v146, v167, v146
	v_add_f32_e32 v146, v147, v146
	s_waitcnt lgkmcnt(1)
	v_mfma_f32_32x32x16_bf16 v[82:97], v[66:69], v[102:105], 0
	v_add_f32_e32 v146, v166, v146
	v_add_f32_e32 v146, v148, v146
	ds_read_b128 v[186:189], v194 offset:49152
	ds_read_b128 v[208:211], v194 offset:57344
	v_add_f32_e32 v146, v160, v146
	v_add_f32_e32 v146, v149, v146
	v_add_f32_e32 v146, v159, v146
	v_add_f32_e32 v146, v156, v146
	s_waitcnt lgkmcnt(2)
	v_mfma_f32_32x32x16_bf16 v[66:81], v[70:73], v[102:105], 0
	v_add_f32_e32 v146, v158, v146
	v_add_f32_e32 v146, v154, v146
	v_add_f32_e32 v146, v157, v146
	v_exp_f32_e32 v142, v142
	v_add_f32_e32 v146, v152, v146
	v_exp_f32_e32 v143, v143
	v_add_f32_e32 v146, v155, v146
	s_waitcnt lgkmcnt(1)
	v_mfma_f32_32x32x16_bf16 v[82:97], v[186:189], v[98:101], v[82:97]
	v_exp_f32_e32 v140, v140
	v_add_f32_e32 v146, v151, v146
	v_exp_f32_e32 v141, v141
	v_add_f32_e32 v146, v153, v146
	v_exp_f32_e32 v134, v134
	v_add_f32_e32 v146, v142, v146
	v_exp_f32_e32 v135, v135
	s_waitcnt lgkmcnt(0)
	v_mfma_f32_32x32x16_bf16 v[66:81], v[208:211], v[98:101], v[66:81]
	ds_read_b128 v[186:189], v195 offset:49152
	ds_read_b128 v[208:211], v195 offset:57344
	v_add_f32_e32 v146, v143, v146
	v_exp_f32_e32 v132, v132
	v_add_f32_e32 v146, v140, v146
	v_exp_f32_e32 v133, v133
	v_add_f32_e32 v146, v141, v146
	v_exp_f32_e32 v130, v130
	s_waitcnt lgkmcnt(1)
	v_mfma_f32_32x32x16_bf16 v[82:97], v[186:189], v[106:109], v[82:97]
	v_add_f32_e32 v146, v134, v146
	v_exp_f32_e32 v131, v131
	v_add_f32_e32 v146, v135, v146
	v_exp_f32_e32 v144, v144
	v_add_f32_e32 v146, v132, v146
	v_exp_f32_e32 v145, v145
	v_add_f32_e32 v146, v133, v146
	s_waitcnt lgkmcnt(0)
	v_mfma_f32_32x32x16_bf16 v[66:81], v[208:211], v[106:109], v[66:81]
	ds_read_b128 v[186:189], v196 offset:49152
	ds_read_b128 v[208:211], v196 offset:57344
	v_exp_f32_e32 v138, v138
	v_add_f32_e32 v146, v130, v146
	v_exp_f32_e32 v139, v139
	v_add_f32_e32 v146, v131, v146
	v_exp_f32_e32 v136, v136
	v_add_f32_e32 v146, v144, v146
	s_waitcnt lgkmcnt(1)
	v_mfma_f32_32x32x16_bf16 v[82:97], v[186:189], v[110:113], v[82:97]
	v_exp_f32_e32 v137, v137
	v_add_f32_e32 v146, v145, v146
	v_add_f32_e32 v146, v138, v146
	v_add_f32_e32 v146, v139, v146
	v_add_f32_e32 v146, v136, v146
	v_add_f32_e32 v207, v137, v146
	v_cvt_pk_bf16_f32 v146, v161, v167
	s_waitcnt lgkmcnt(0)
	v_mfma_f32_32x32x16_bf16 v[66:81], v[208:211], v[110:113], v[66:81]
	v_mov_b32_e32 v208, v207
	v_cvt_pk_bf16_f32 v147, v147, v166
	v_cvt_pk_bf16_f32 v148, v148, v160
	s_nop 1
	v_permlane32_swap_b32_e32 v207, v208
	v_cvt_pk_bf16_f32 v149, v149, v159
	v_permlane32_swap_b32_e32 v146, v148
	v_cvt_pk_bf16_f32 v156, v156, v158
	v_cvt_pk_bf16_f32 v157, v154, v157
	v_cvt_pk_bf16_f32 v158, v152, v155
	v_cvt_pk_bf16_f32 v159, v151, v153
	v_cvt_pk_bf16_f32 v152, v142, v143
	v_cvt_pk_bf16_f32 v153, v140, v141
	v_cvt_pk_bf16_f32 v154, v134, v135
	v_cvt_pk_bf16_f32 v155, v132, v133
	v_cvt_pk_bf16_f32 v186, v130, v131
	v_cvt_pk_bf16_f32 v187, v144, v145
	v_cvt_pk_bf16_f32 v188, v138, v139
	v_cvt_pk_bf16_f32 v189, v136, v137
	v_permlane32_swap_b32_e32 v147, v149
	v_permlane32_swap_b32_e32 v156, v158
	v_permlane32_swap_b32_e32 v157, v159
	v_permlane32_swap_b32_e32 v152, v154
	v_permlane32_swap_b32_e32 v153, v155
	v_permlane32_swap_b32_e32 v186, v188
	v_permlane32_swap_b32_e32 v187, v189
	s_waitcnt vmcnt(0)
	ds_write_b128 v192, v[114:117]
	ds_write_b128 v193, v[118:121]
	ds_write_b128 v190, v[122:125] offset:32768
	ds_write_b128 v191, v[126:129] offset:32768
	v_lshl_add_u64 v[168:169], v[164:165], 0, v[0:1]
	s_mov_b32 s1, 0x18fb0000
	v_add_co_u32_e32 v130, vcc, s1, v168
	s_mov_b32 s1, 0x18ff8000
	s_nop 0
	v_addc_co_u32_e32 v131, vcc, 0, v169, vcc
	v_add_co_u32_e32 v134, vcc, s1, v168
	v_lshl_add_u64 v[166:167], v[162:163], 0, v[0:1]
	s_nop 0
	v_addc_co_u32_e32 v135, vcc, 0, v169, vcc
	s_mov_b32 s1, 0x1f648000
	v_add_co_u32_e32 v138, vcc, s1, v166
	s_mov_b32 s1, 0x1f654000
	s_nop 0
	v_addc_co_u32_e32 v139, vcc, 0, v167, vcc
	v_add_co_u32_e32 v142, vcc, s1, v166
	global_load_dwordx4 v[130:133], v[130:131], off
	s_nop 0
	global_load_dwordx4 v[134:137], v[134:135], off
	v_addc_co_u32_e32 v143, vcc, 0, v167, vcc
	global_load_dwordx4 v[138:141], v[138:139], off
	s_nop 0
	global_load_dwordx4 v[142:145], v[142:143], off
	ds_read_b64_tr_b16 v[210:211], v176 offset:0
	ds_read_b64_tr_b16 v[212:213], v176 offset:0x800
	ds_read_b64_tr_b16 v[214:215], v176 offset:0x1000
	ds_read_b64_tr_b16 v[216:217], v176 offset:0x1800
	ds_read_b64_tr_b16 v[218:219], v176 offset:0x2000
	ds_read_b64_tr_b16 v[220:221], v176 offset:0x2800
	ds_read_b64_tr_b16 v[222:223], v176 offset:0x3000
	ds_read_b64_tr_b16 v[224:225], v176 offset:0x3800
	s_waitcnt lgkmcnt(4)
	s_nop 0
	v_mfma_f32_32x32x16_bf16 v[2:17], v[146:149], v[210:213], v[2:17]
	ds_read_b64_tr_b16 v[210:211], v176 offset:0x200
	ds_read_b64_tr_b16 v[212:213], v176 offset:0xa00
	v_mfma_f32_32x32x16_bf16 v[2:17], v[156:159], v[214:217], v[2:17]
	ds_read_b64_tr_b16 v[214:215], v176 offset:0x1200
	ds_read_b64_tr_b16 v[216:217], v176 offset:0x1a00
	s_waitcnt lgkmcnt(4)
; #define SBAR() __builtin_amdgcn_sched_barrier(0)
; __device__ __forceinline__ void partialSM(f32x16& p0, f32x16& p1, float& m_reg, float& mn, float& alpha) {
;   constexpr float C = SCALE * 1.4426950408889634f;
;   float pmax = p0[0];
; #pragma unroll
;   for (int r = 1; r < 16; ++r) pmax = fmaxf(pmax, p0[r]);
; #pragma unroll
;   for (int r = 0; r < 16; ++r) pmax = fmaxf(pmax, p1[r]);
;   { auto rr = __builtin_amdgcn_permlane32_swap(__float_as_uint(pmax), __float_as_uint(pmax), false, false);
;     pmax = fmaxf(__uint_as_float(rr[0]), __uint_as_float(rr[1])); }
;   if (__builtin_expect(__all(pmax - m_reg <= THR / SCALE), 1)) { mn = m_reg; alpha = 1.f; }
;   else { mn = fmaxf(m_reg, pmax); alpha = __builtin_amdgcn_exp2f((m_reg - mn) * C); m_reg = mn; }
; template <int D0> __device__ __forceinline__ void pv_one(f32x16& od, int vb, bf16x8 pa0, bf16x8 pa1, bf16x8 pa2, bf16x8 pa3) {
;   const s16x4 l0 = tr_read<v_rd_off(D0, 0, 0)>(vb), h0 = tr_read<v_rd_off(D0, 0, 1)>(vb), l1 = tr_read<v_rd_off(D0, 1, 0)>(vb), h1 = tr_read<v_rd_off(D0, 1, 1)>(vb);
;   const s16x4 l2 = tr_read<v_rd_off(D0, 2, 0)>(vb), h2 = tr_read<v_rd_off(D0, 2, 1)>(vb), l3 = tr_read<v_rd_off(D0, 3, 0)>(vb), h3 = tr_read<v_rd_off(D0, 3, 1)>(vb);
;   asm volatile("s_waitcnt lgkmcnt(0)" ::: "memory"); SBAR();
;     ...
;   od = __builtin_amdgcn_mfma_f32_32x32x16_bf16(pa0, PK(l0, h0), od, 0, 0, 0);
;   od = __builtin_amdgcn_mfma_f32_32x32x16_bf16(pa1, PK(l1, h1), od, 0, 0, 0);
;   od = __builtin_amdgcn_mfma_f32_32x32x16_bf16(pa2, PK(l2, h2), od, 0, 0, 0);
;   od = __builtin_amdgcn_mfma_f32_32x32x16_bf16(pa3, PK(l3, h3), od, 0, 0, 0);
;     ...
; }
; __device__ __forceinline__ void pv_d0(f32x16* o, int vb, bf16x8 pa0, bf16x8 pa1, bf16x8 pa2, bf16x8 pa3) {
;   pv_one<0>(o[0], vb, pa0, pa1, pa2, pa3); pv_one<1>(o[1], vb, pa0, pa1, pa2, pa3); pv_one<2>(o[2], vb, pa0, pa1, pa2, pa3); pv_one<3>(o[3], vb, pa0, pa1, pa2, pa3);
	v_mfma_f32_32x32x16_bf16 v[2:17], v[152:155], v[218:221], v[2:17]
	ds_read_b64_tr_b16 v[218:219], v176 offset:0x2200
	ds_read_b64_tr_b16 v[220:221], v176 offset:0x2a00
	v_mfma_f32_32x32x16_bf16 v[2:17], v[186:189], v[222:225], v[2:17]
	ds_read_b64_tr_b16 v[222:223], v176 offset:0x3200
	ds_read_b64_tr_b16 v[224:225], v176 offset:0x3a00
	s_waitcnt lgkmcnt(4)
	v_mfma_f32_32x32x16_bf16 v[50:65], v[146:149], v[210:213], v[50:65]
	ds_read_b64_tr_b16 v[210:211], v176 offset:0x400
	ds_read_b64_tr_b16 v[212:213], v176 offset:0xc00
	v_mfma_f32_32x32x16_bf16 v[50:65], v[156:159], v[214:217], v[50:65]
	ds_read_b64_tr_b16 v[214:215], v176 offset:0x1400
	ds_read_b64_tr_b16 v[216:217], v176 offset:0x1c00
	s_waitcnt lgkmcnt(4)
	v_mfma_f32_32x32x16_bf16 v[50:65], v[152:155], v[218:221], v[50:65]
	ds_read_b64_tr_b16 v[218:219], v176 offset:0x2400
	ds_read_b64_tr_b16 v[220:221], v176 offset:0x2c00
	v_mfma_f32_32x32x16_bf16 v[50:65], v[186:189], v[222:225], v[50:65]
	ds_read_b64_tr_b16 v[222:223], v176 offset:0x3400
	ds_read_b64_tr_b16 v[224:225], v176 offset:0x3c00
	s_waitcnt lgkmcnt(4)
	v_mfma_f32_32x32x16_bf16 v[34:49], v[146:149], v[210:213], v[34:49]
	ds_read_b64_tr_b16 v[210:211], v176 offset:0x600
	ds_read_b64_tr_b16 v[212:213], v176 offset:0xe00
	v_mfma_f32_32x32x16_bf16 v[34:49], v[156:159], v[214:217], v[34:49]
	ds_read_b64_tr_b16 v[214:215], v176 offset:0x1600
	ds_read_b64_tr_b16 v[216:217], v176 offset:0x1e00
	s_waitcnt lgkmcnt(4)
	v_mfma_f32_32x32x16_bf16 v[34:49], v[152:155], v[218:221], v[34:49]
	ds_read_b64_tr_b16 v[218:219], v176 offset:0x2600
	ds_read_b64_tr_b16 v[220:221], v176 offset:0x2e00
	v_mfma_f32_32x32x16_bf16 v[34:49], v[186:189], v[222:225], v[34:49]
	ds_read_b64_tr_b16 v[222:223], v176 offset:0x3600
	ds_read_b64_tr_b16 v[224:225], v176 offset:0x3e00
	s_waitcnt lgkmcnt(4)
	v_mfma_f32_32x32x16_bf16 v[18:33], v[146:149], v[210:213], v[18:33]
	v_max_f32_e32 v146, v83, v83
	v_max_f32_e32 v147, v82, v82
	v_max_f32_e32 v146, v147, v146
	v_max3_f32 v146, v146, v84, v85
	v_max3_f32 v146, v146, v86, v87
	v_max3_f32 v146, v146, v88, v89
	v_max3_f32 v146, v146, v90, v91
	v_max3_f32 v146, v146, v92, v93
	v_max3_f32 v146, v146, v94, v95
	v_mfma_f32_32x32x16_bf16 v[18:33], v[156:159], v[214:217], v[18:33]
	v_max3_f32 v146, v146, v96, v97
	v_max3_f32 v146, v146, v66, v67
	v_max3_f32 v146, v146, v68, v69
	v_max3_f32 v146, v146, v70, v71
	v_max3_f32 v146, v146, v72, v73
	v_max3_f32 v146, v146, v74, v75
	v_max3_f32 v146, v146, v76, v77
	v_max3_f32 v146, v146, v78, v79
	s_waitcnt lgkmcnt(0)
	v_mfma_f32_32x32x16_bf16 v[18:33], v[152:155], v[218:221], v[18:33]
	v_max3_f32 v146, v146, v80, v81
	v_mov_b32_e32 v147, v146
	s_nop 1
	v_permlane32_swap_b32_e32 v146, v147
	v_max_f32_e32 v147, v147, v147
	v_max_f32_e32 v146, v146, v146
	v_max_f32_e32 v146, v146, v147
	v_sub_f32_e32 v147, v146, v150
	v_cmp_ge_f32_e32 vcc, s63, v147
	v_max_f32_e32 v147, v150, v150
	v_max_f32_e32 v146, v147, v146
	v_mfma_f32_32x32x16_bf16 v[18:33], v[186:189], v[222:225], v[18:33]
	v_sub_f32_e32 v147, v150, v146
	v_mul_f32_e32 v147, 0x3e0293ee, v147
	v_exp_f32_e32 v147, v147
	s_cmp_eq_u64 vcc, exec
	s_cselect_b64 s[8:9], -1, 0
	s_waitcnt vmcnt(4)
	v_cndmask_b32_e64 v209, v147, 1.0, s[8:9]
	v_cmp_gt_f32_e32 vcc, 1.0, v209
	s_cbranch_vccz .LBB0_1026
	s_and_saveexec_b64 s[2:3], s[6:7]
	ds_write_b32 v173, v209 offset:128
	s_or_b64 exec, exec, s[2:3]
	s_waitcnt lgkmcnt(0)
	v_add_u32_e32 v147, s15, v172
	ds_read_b128 v[152:155], v147 offset:224
	ds_read_b128 v[156:159], v147 offset:192
	ds_read_b128 v[186:189], v147 offset:160
	ds_read_b128 v[210:213], v147 offset:128
	s_waitcnt lgkmcnt(3)
	v_pk_mul_f32 v[14:15], v[14:15], v[152:153]
	s_waitcnt lgkmcnt(2)
	v_pk_mul_f32 v[10:11], v[10:11], v[156:157]
	s_waitcnt lgkmcnt(1)
	v_pk_mul_f32 v[6:7], v[6:7], v[186:187]
	v_pk_mul_f32 v[16:17], v[16:17], v[154:155]
	v_pk_mul_f32 v[12:13], v[12:13], v[158:159]
	v_pk_mul_f32 v[8:9], v[8:9], v[188:189]
	s_waitcnt lgkmcnt(0)
	v_pk_mul_f32 v[4:5], v[4:5], v[212:213]
	v_pk_mul_f32 v[2:3], v[2:3], v[210:211]
	v_pk_mul_f32 v[62:63], v[62:63], v[152:153]
	v_pk_mul_f32 v[58:59], v[58:59], v[156:157]
	v_pk_mul_f32 v[54:55], v[54:55], v[186:187]
	v_pk_mul_f32 v[64:65], v[64:65], v[154:155]
	v_pk_mul_f32 v[60:61], v[60:61], v[158:159]
	v_pk_mul_f32 v[56:57], v[56:57], v[188:189]
	v_pk_mul_f32 v[52:53], v[52:53], v[212:213]
	v_pk_mul_f32 v[50:51], v[50:51], v[210:211]
	v_pk_mul_f32 v[46:47], v[46:47], v[152:153]
	v_pk_mul_f32 v[42:43], v[42:43], v[156:157]
	v_pk_mul_f32 v[38:39], v[38:39], v[186:187]
	v_pk_mul_f32 v[48:49], v[48:49], v[154:155]
	v_pk_mul_f32 v[44:45], v[44:45], v[158:159]
	v_pk_mul_f32 v[40:41], v[40:41], v[188:189]
	v_pk_mul_f32 v[36:37], v[36:37], v[212:213]
	v_pk_mul_f32 v[34:35], v[34:35], v[210:211]
	v_pk_mul_f32 v[30:31], v[30:31], v[152:153]
	v_pk_mul_f32 v[26:27], v[26:27], v[156:157]
	v_pk_mul_f32 v[22:23], v[22:23], v[186:187]
	v_pk_mul_f32 v[32:33], v[32:33], v[154:155]
	v_pk_mul_f32 v[28:29], v[28:29], v[158:159]
	v_pk_mul_f32 v[24:25], v[24:25], v[188:189]
	v_pk_mul_f32 v[20:21], v[20:21], v[212:213]
	v_pk_mul_f32 v[18:19], v[18:19], v[210:211]

; __device__ __forceinline__ void finishSM(f32x16& p0, f32x16& p1, float alpha, float& l_reg, bf16x8& pa0, bf16x8& pa1, bf16x8& pa2, bf16x8& pa3) {
; #pragma unroll
;   for (int r = 0; r < 16; ++r) p1[r] = __builtin_amdgcn_exp2f(p1[r]);
;   float ps = 0;
; #pragma unroll
;   for (int r = 0; r < 16; ++r) ps += p0[r];
; #pragma unroll
;   for (int r = 0; r < 16; ++r) ps += p1[r];
;   { auto rr = __builtin_amdgcn_permlane32_swap(__float_as_uint(ps), __float_as_uint(ps), false, false);
;     ps = __uint_as_float(rr[0]) + __uint_as_float(rr[1]); }
;   l_reg = l_reg * alpha + ps;
;   PK4(p0, 0, pa0); PK4(p0, 8, pa1); PK4(p1, 0, pa2); PK4(p1, 8, pa3);
; }
;   p0 = f32x16{}; p1 = f32x16{};
; #pragma unroll
;   for (int d0 = DLO; d0 < DHI; ++d0) { int cb = (d0 * 16 + hi * 8) * 2;
;     bf16x8 b0 = *reinterpret_cast<const bf16x8*>((const char*)Ks + KSWZ(r32, cb));
;     bf16x8 b1 = *reinterpret_cast<const bf16x8*>((const char*)Ks + KSWZ(32 + r32, cb));
;     p0 = __builtin_amdgcn_mfma_f32_32x32x16_bf16(b0, qr[d0], p0, 0, 0, 0);
;     p1 = __builtin_amdgcn_mfma_f32_32x32x16_bf16(b1, qr[d0], p1, 0, 0, 0); }
; }
; __device__ __forceinline__ int v_st(int k, int c) { const int kk = (k & ~0xC) | ((k & 4) << 1) | ((k & 8) >> 1); return ((kk >> 3) * 4 + (c >> 5)) * 512 + ((kk & 7) * 32 + (c & 31)) * 2; }
; __device__ __forceinline__ int v_rd_base(int lane) { return ((lane & 3) << 3) | (((lane >> 2) & 3) << 6) | (((lane >> 4) & 1) << 5) | (((lane >> 5) & 1) << 8); }
; template <int OFF> __device__ __forceinline__ s16x4 tr_read(int vb) {
;   s16x4 r; asm volatile("ds_read_b64_tr_b16 %0, %1 offset:%2" : "=&v"(r) : "v"(vb), "i"(OFF) : "memory"); return r;
; }
; template <int D0> __device__ __forceinline__ void pv_one(f32x16& od, int vb, bf16x8 pa0, bf16x8 pa1, bf16x8 pa2, bf16x8 pa3) {
;   const s16x4 l0 = tr_read<v_rd_off(D0, 0, 0)>(vb), h0 = tr_read<v_rd_off(D0, 0, 1)>(vb), l1 = tr_read<v_rd_off(D0, 1, 0)>(vb), h1 = tr_read<v_rd_off(D0, 1, 1)>(vb);
;   const s16x4 l2 = tr_read<v_rd_off(D0, 2, 0)>(vb), h2 = tr_read<v_rd_off(D0, 2, 1)>(vb), l3 = tr_read<v_rd_off(D0, 3, 0)>(vb), h3 = tr_read<v_rd_off(D0, 3, 1)>(vb);
;   asm volatile("s_waitcnt lgkmcnt(0)" ::: "memory"); SBAR();
;     ...
;   od = __builtin_amdgcn_mfma_f32_32x32x16_bf16(pa0, PK(l0, h0), od, 0, 0, 0);
;   od = __builtin_amdgcn_mfma_f32_32x32x16_bf16(pa1, PK(l1, h1), od, 0, 0, 0);
.LBB0_1034:
	ds_read_b128 v[66:69], v177 offset:49152
	ds_read_b128 v[70:73], v177 offset:57344
	v_add_f32_e32 v0, 0, v161
	v_add_f32_e32 v0, v167, v0
	v_add_f32_e32 v0, v147, v0
	s_waitcnt lgkmcnt(1)
	v_mfma_f32_32x32x16_bf16 v[82:97], v[66:69], v[102:105], 0
	v_add_f32_e32 v0, v166, v0
	v_add_f32_e32 v0, v148, v0
	v_add_f32_e32 v0, v160, v0
	v_add_f32_e32 v0, v149, v0
	v_add_f32_e32 v0, v159, v0
	v_add_f32_e32 v0, v156, v0
	v_add_f32_e32 v0, v158, v0
	s_waitcnt lgkmcnt(0)
	v_mfma_f32_32x32x16_bf16 v[66:81], v[70:73], v[102:105], 0
	ds_read_b128 v[102:105], v194 offset:49152
	ds_read_b128 v[114:117], v194 offset:57344
	v_add_f32_e32 v0, v154, v0
	v_add_f32_e32 v0, v157, v0
	v_add_f32_e32 v0, v152, v0
	v_add_f32_e32 v0, v155, v0
	v_add_f32_e32 v0, v151, v0
	v_add_f32_e32 v0, v153, v0
	s_waitcnt lgkmcnt(1)
	v_mfma_f32_32x32x16_bf16 v[82:97], v[102:105], v[98:101], v[82:97]
	v_exp_f32_e32 v118, v145
	v_exp_f32_e32 v119, v138
	v_exp_f32_e32 v120, v139
	v_exp_f32_e32 v121, v136
	v_exp_f32_e32 v122, v137
	s_waitcnt lgkmcnt(0)
	v_mfma_f32_32x32x16_bf16 v[66:81], v[114:117], v[98:101], v[66:81]
	ds_read_b128 v[98:101], v195 offset:49152
	ds_read_b128 v[102:105], v195 offset:57344
	v_exp_f32_e32 v114, v133
	v_exp_f32_e32 v115, v130
	v_exp_f32_e32 v116, v131
	v_exp_f32_e32 v117, v144
	s_waitcnt lgkmcnt(1)
	v_mfma_f32_32x32x16_bf16 v[82:97], v[98:101], v[106:109], v[82:97]
	s_waitcnt lgkmcnt(0)
	v_mfma_f32_32x32x16_bf16 v[66:81], v[102:105], v[106:109], v[66:81]
	ds_read_b128 v[98:101], v196 offset:49152
	ds_read_b128 v[102:105], v196 offset:57344
	v_exp_f32_e32 v108, v143
	v_exp_f32_e32 v109, v140
	s_waitcnt lgkmcnt(1)
	v_mfma_f32_32x32x16_bf16 v[82:97], v[98:101], v[110:113], v[82:97]
	v_exp_f32_e32 v99, v142
	v_cvt_pk_bf16_f32 v100, v161, v167
	v_cvt_pk_bf16_f32 v101, v147, v166
	s_nop 0
	v_add_f32_e32 v0, v99, v0
	v_add_f32_e32 v0, v108, v0
	v_add_f32_e32 v0, v109, v0
	s_waitcnt lgkmcnt(0)
	v_mfma_f32_32x32x16_bf16 v[66:81], v[102:105], v[110:113], v[66:81]
	v_exp_f32_e32 v110, v141
	v_exp_f32_e32 v111, v134
	v_exp_f32_e32 v112, v135
	v_exp_f32_e32 v113, v132
	v_add_f32_e32 v0, v110, v0
	v_add_f32_e32 v0, v111, v0
	v_add_f32_e32 v0, v112, v0
	v_add_f32_e32 v0, v113, v0
	v_add_f32_e32 v0, v114, v0
	v_add_f32_e32 v0, v115, v0
	v_add_f32_e32 v0, v116, v0
	v_add_f32_e32 v0, v117, v0
	v_add_f32_e32 v0, v118, v0
	v_add_f32_e32 v0, v119, v0
	v_add_f32_e32 v0, v120, v0
	v_add_f32_e32 v0, v121, v0
	v_add_f32_e32 v0, v122, v0
	v_mov_b32_e32 v98, v0
	v_cvt_pk_bf16_f32 v102, v148, v160
	s_nop 1
	v_permlane32_swap_b32_e32 v0, v98
	v_cvt_pk_bf16_f32 v103, v149, v159
	v_permlane32_swap_b32_e32 v100, v102
	v_cvt_pk_bf16_f32 v104, v156, v158
	v_cvt_pk_bf16_f32 v105, v154, v157
	v_cvt_pk_bf16_f32 v106, v152, v155
	v_cvt_pk_bf16_f32 v107, v151, v153
	v_cvt_pk_bf16_f32 v108, v99, v108
	v_cvt_pk_bf16_f32 v109, v109, v110
	v_cvt_pk_bf16_f32 v110, v111, v112
	v_cvt_pk_bf16_f32 v111, v113, v114
	v_cvt_pk_bf16_f32 v112, v115, v116
	v_cvt_pk_bf16_f32 v113, v117, v118
	v_cvt_pk_bf16_f32 v114, v119, v120
	v_cvt_pk_bf16_f32 v115, v121, v122
	v_permlane32_swap_b32_e32 v101, v103
	v_permlane32_swap_b32_e32 v104, v106
	v_permlane32_swap_b32_e32 v105, v107
	v_permlane32_swap_b32_e32 v108, v110
	v_permlane32_swap_b32_e32 v109, v111
	v_permlane32_swap_b32_e32 v112, v114
	v_permlane32_swap_b32_e32 v113, v115
	ds_read_b64_tr_b16 v[116:117], v176 offset:0
	ds_read_b64_tr_b16 v[118:119], v176 offset:0x800
	ds_read_b64_tr_b16 v[120:121], v176 offset:0x1000
	ds_read_b64_tr_b16 v[122:123], v176 offset:0x1800
	ds_read_b64_tr_b16 v[124:125], v176 offset:0x2000
	ds_read_b64_tr_b16 v[126:127], v176 offset:0x2800
	ds_read_b64_tr_b16 v[128:129], v176 offset:0x3000
	ds_read_b64_tr_b16 v[130:131], v176 offset:0x3800
	s_waitcnt lgkmcnt(4)
	s_nop 0
	v_mfma_f32_32x32x16_bf16 v[2:17], v[100:103], v[116:119], v[2:17]
	ds_read_b64_tr_b16 v[116:117], v176 offset:0x200
	ds_read_b64_tr_b16 v[118:119], v176 offset:0xa00
	v_mfma_f32_32x32x16_bf16 v[2:17], v[104:107], v[120:123], v[2:17]
	ds_read_b64_tr_b16 v[120:121], v176 offset:0x1200
	ds_read_b64_tr_b16 v[122:123], v176 offset:0x1a00
	s_waitcnt lgkmcnt(4)
	v_mfma_f32_32x32x16_bf16 v[2:17], v[108:111], v[124:127], v[2:17]
	ds_read_b64_tr_b16 v[124:125], v176 offset:0x2200
	ds_read_b64_tr_b16 v[126:127], v176 offset:0x2a00
	v_mfma_f32_32x32x16_bf16 v[2:17], v[112:115], v[128:131], v[2:17]
	ds_read_b64_tr_b16 v[128:129], v176 offset:0x3200
	ds_read_b64_tr_b16 v[130:131], v176 offset:0x3a00
	s_waitcnt lgkmcnt(4)
	v_mfma_f32_32x32x16_bf16 v[50:65], v[100:103], v[116:119], v[50:65]
	ds_read_b64_tr_b16 v[116:117], v176 offset:0x400
	ds_read_b64_tr_b16 v[118:119], v176 offset:0xc00
	v_mfma_f32_32x32x16_bf16 v[50:65], v[104:107], v[120:123], v[50:65]
	ds_read_b64_tr_b16 v[120:121], v176 offset:0x1400
	ds_read_b64_tr_b16 v[122:123], v176 offset:0x1c00
	s_waitcnt lgkmcnt(4)
	v_mfma_f32_32x32x16_bf16 v[50:65], v[108:111], v[124:127], v[50:65]
	ds_read_b64_tr_b16 v[124:125], v176 offset:0x2400
	ds_read_b64_tr_b16 v[126:127], v176 offset:0x2c00
	v_mfma_f32_32x32x16_bf16 v[50:65], v[112:115], v[128:131], v[50:65]
	ds_read_b64_tr_b16 v[128:129], v176 offset:0x3400
	ds_read_b64_tr_b16 v[130:131], v176 offset:0x3c00
	s_waitcnt lgkmcnt(4)
	v_mfma_f32_32x32x16_bf16 v[34:49], v[100:103], v[116:119], v[34:49]
	ds_read_b64_tr_b16 v[116:117], v176 offset:0x600
	ds_read_b64_tr_b16 v[118:119], v176 offset:0xe00
	v_mfma_f32_32x32x16_bf16 v[34:49], v[104:107], v[120:123], v[34:49]
	ds_read_b64_tr_b16 v[120:121], v176 offset:0x1600
	ds_read_b64_tr_b16 v[122:123], v176 offset:0x1e00
	s_waitcnt lgkmcnt(4)
; #define SBAR() __builtin_amdgcn_sched_barrier(0)
; __device__ __forceinline__ void partialSM(f32x16& p0, f32x16& p1, float& m_reg, float& mn, float& alpha) {
;   constexpr float C = SCALE * 1.4426950408889634f;
;   float pmax = p0[0];
; #pragma unroll
;   for (int r = 1; r < 16; ++r) pmax = fmaxf(pmax, p0[r]);
; #pragma unroll
;   for (int r = 0; r < 16; ++r) pmax = fmaxf(pmax, p1[r]);
;   { auto rr = __builtin_amdgcn_permlane32_swap(__float_as_uint(pmax), __float_as_uint(pmax), false, false);
;     pmax = fmaxf(__uint_as_float(rr[0]), __uint_as_float(rr[1])); }
;   if (__builtin_expect(__all(pmax - m_reg <= THR / SCALE), 1)) { mn = m_reg; alpha = 1.f; }
;   else { mn = fmaxf(m_reg, pmax); alpha = __builtin_amdgcn_exp2f((m_reg - mn) * C); m_reg = mn; }
;   float mnC = -mn * C;
; #pragma unroll
;   for (int r = 0; r < 16; ++r) p0[r] = fmaf(p0[r], C, mnC);
; #pragma unroll
;   for (int r = 0; r < 16; ++r) p1[r] = fmaf(p1[r], C, mnC);
; #pragma unroll
;   for (int r = 0; r < 16; ++r) p0[r] = __builtin_amdgcn_exp2f(p0[r]);
; }
; template <int D0> __device__ __forceinline__ void pv_one(f32x16& od, int vb, bf16x8 pa0, bf16x8 pa1, bf16x8 pa2, bf16x8 pa3) {
;   const s16x4 l0 = tr_read<v_rd_off(D0, 0, 0)>(vb), h0 = tr_read<v_rd_off(D0, 0, 1)>(vb), l1 = tr_read<v_rd_off(D0, 1, 0)>(vb), h1 = tr_read<v_rd_off(D0, 1, 1)>(vb);
;   const s16x4 l2 = tr_read<v_rd_off(D0, 2, 0)>(vb), h2 = tr_read<v_rd_off(D0, 2, 1)>(vb), l3 = tr_read<v_rd_off(D0, 3, 0)>(vb), h3 = tr_read<v_rd_off(D0, 3, 1)>(vb);
;   asm volatile("s_waitcnt lgkmcnt(0)" ::: "memory"); SBAR();
;     ...
;   od = __builtin_amdgcn_mfma_f32_32x32x16_bf16(pa0, PK(l0, h0), od, 0, 0, 0);
;   od = __builtin_amdgcn_mfma_f32_32x32x16_bf16(pa1, PK(l1, h1), od, 0, 0, 0);
;   od = __builtin_amdgcn_mfma_f32_32x32x16_bf16(pa2, PK(l2, h2), od, 0, 0, 0);
;   od = __builtin_amdgcn_mfma_f32_32x32x16_bf16(pa3, PK(l3, h3), od, 0, 0, 0);
;     ...
; }
; __device__ __forceinline__ void pv_d0(f32x16* o, int vb, bf16x8 pa0, bf16x8 pa1, bf16x8 pa2, bf16x8 pa3) {
;   pv_one<0>(o[0], vb, pa0, pa1, pa2, pa3); pv_one<1>(o[1], vb, pa0, pa1, pa2, pa3); pv_one<2>(o[2], vb, pa0, pa1, pa2, pa3); pv_one<3>(o[3], vb, pa0, pa1, pa2, pa3);
	v_mfma_f32_32x32x16_bf16 v[34:49], v[108:111], v[124:127], v[34:49]
	ds_read_b64_tr_b16 v[124:125], v176 offset:0x2600
	ds_read_b64_tr_b16 v[126:127], v176 offset:0x2e00
	v_mfma_f32_32x32x16_bf16 v[34:49], v[112:115], v[128:131], v[34:49]
	ds_read_b64_tr_b16 v[128:129], v176 offset:0x3600
	ds_read_b64_tr_b16 v[130:131], v176 offset:0x3e00
	s_waitcnt lgkmcnt(4)
	v_mfma_f32_32x32x16_bf16 v[18:33], v[100:103], v[116:119], v[18:33]
	v_max_f32_e32 v99, v83, v83
	v_max_f32_e32 v100, v82, v82
	v_max_f32_e32 v99, v100, v99
	v_max3_f32 v99, v99, v84, v85
	v_max3_f32 v99, v99, v86, v87
	v_max3_f32 v99, v99, v88, v89
	v_max3_f32 v99, v99, v90, v91
	v_max3_f32 v99, v99, v92, v93
	v_max3_f32 v99, v99, v94, v95
	v_mfma_f32_32x32x16_bf16 v[18:33], v[104:107], v[120:123], v[18:33]
	v_max3_f32 v99, v99, v96, v97
	v_max3_f32 v99, v99, v66, v67
	v_max3_f32 v99, v99, v68, v69
	v_max3_f32 v99, v99, v70, v71
	v_max3_f32 v99, v99, v72, v73
	v_max3_f32 v99, v99, v74, v75
	v_max3_f32 v99, v99, v76, v77
	v_max3_f32 v99, v99, v78, v79
	s_waitcnt lgkmcnt(0)
	v_mfma_f32_32x32x16_bf16 v[18:33], v[108:111], v[124:127], v[18:33]
	v_max3_f32 v99, v99, v80, v81
	v_mov_b32_e32 v100, v99
	s_nop 1
	v_permlane32_swap_b32_e32 v99, v100
	v_max_f32_e32 v100, v100, v100
	v_max_f32_e32 v99, v99, v99
	v_max_f32_e32 v99, v99, v100
	v_sub_f32_e32 v100, v99, v150
	v_cmp_ge_f32_e32 vcc, s63, v100
	v_max_f32_e32 v100, v150, v150
	v_max_f32_e32 v100, v100, v99
	v_mfma_f32_32x32x16_bf16 v[18:33], v[112:115], v[128:131], v[18:33]
	v_sub_f32_e32 v99, v150, v100
	v_mul_f32_e32 v99, 0x3e0293ee, v99
	v_exp_f32_e32 v99, v99
	s_cmp_eq_u64 vcc, exec
	s_cselect_b64 s[8:9], -1, 0
	v_cndmask_b32_e64 v99, v99, 1.0, s[8:9]
	v_cmp_gt_f32_e32 vcc, 1.0, v99
	s_barrier
	s_cbranch_vccz .LBB0_1038
	s_and_saveexec_b64 s[2:3], s[6:7]
	ds_write_b32 v173, v99 offset:128
	s_or_b64 exec, exec, s[2:3]
	s_waitcnt lgkmcnt(0)
	v_add_u32_e32 v101, s15, v172
	ds_read_b128 v[102:105], v101 offset:224
	ds_read_b128 v[106:109], v101 offset:192
	ds_read_b128 v[110:113], v101 offset:160
	ds_read_b128 v[114:117], v101 offset:128
	s_waitcnt lgkmcnt(3)
	v_pk_mul_f32 v[14:15], v[14:15], v[102:103]
	s_waitcnt lgkmcnt(2)
	v_pk_mul_f32 v[10:11], v[10:11], v[106:107]
	s_waitcnt lgkmcnt(1)
	v_pk_mul_f32 v[6:7], v[6:7], v[110:111]
	v_pk_mul_f32 v[16:17], v[16:17], v[104:105]
	v_pk_mul_f32 v[12:13], v[12:13], v[108:109]
	v_pk_mul_f32 v[8:9], v[8:9], v[112:113]
	s_waitcnt lgkmcnt(0)
	v_pk_mul_f32 v[4:5], v[4:5], v[116:117]
	v_pk_mul_f32 v[2:3], v[2:3], v[114:115]
	v_pk_mul_f32 v[62:63], v[62:63], v[102:103]
	v_pk_mul_f32 v[58:59], v[58:59], v[106:107]
	v_pk_mul_f32 v[54:55], v[54:55], v[110:111]
	v_pk_mul_f32 v[64:65], v[64:65], v[104:105]
	v_pk_mul_f32 v[60:61], v[60:61], v[108:109]
	v_pk_mul_f32 v[56:57], v[56:57], v[112:113]
	v_pk_mul_f32 v[52:53], v[52:53], v[116:117]
	v_pk_mul_f32 v[50:51], v[50:51], v[114:115]
	v_pk_mul_f32 v[46:47], v[46:47], v[102:103]
	v_pk_mul_f32 v[42:43], v[42:43], v[106:107]
	v_pk_mul_f32 v[38:39], v[38:39], v[110:111]
	v_pk_mul_f32 v[48:49], v[48:49], v[104:105]
	v_pk_mul_f32 v[44:45], v[44:45], v[108:109]
	v_pk_mul_f32 v[40:41], v[40:41], v[112:113]
	v_pk_mul_f32 v[36:37], v[36:37], v[116:117]
	v_pk_mul_f32 v[34:35], v[34:35], v[114:115]
	v_pk_mul_f32 v[30:31], v[30:31], v[102:103]
	v_pk_mul_f32 v[26:27], v[26:27], v[106:107]
	v_pk_mul_f32 v[22:23], v[22:23], v[110:111]
	v_pk_mul_f32 v[32:33], v[32:33], v[104:105]
	v_pk_mul_f32 v[28:29], v[28:29], v[108:109]
	v_pk_mul_f32 v[24:25], v[24:25], v[112:113]
	v_pk_mul_f32 v[20:21], v[20:21], v[116:117]
	v_pk_mul_f32 v[18:19], v[18:19], v[114:115]
.LBB0_1038:
	v_cndmask_b32_e64 v100, v100, v150, s[8:9]
	v_mul_f32_e32 v100, 0xbe0293ee, v100
	v_fmamk_f32 v82, v82, 0x3e0293ee, v100
	v_fmamk_f32 v83, v83, 0x3e0293ee, v100
	v_fmamk_f32 v101, v84, 0x3e0293ee, v100
	v_exp_f32_e32 v84, v82
	v_fmamk_f32 v102, v86, 0x3e0293ee, v100
	v_exp_f32_e32 v86, v83
	v_fmamk_f32 v85, v85, 0x3e0293ee, v100
	v_exp_f32_e32 v82, v101
	v_fmamk_f32 v66, v66, 0x3e0293ee, v100
	v_exp_f32_e32 v85, v85
	v_fmamk_f32 v103, v87, 0x3e0293ee, v100
	v_fmamk_f32 v112, v96, 0x3e0293ee, v100
	v_fmamk_f32 v96, v77, 0x3e0293ee, v100
	v_exp_f32_e32 v77, v102
	v_exp_f32_e32 v101, v66
	v_add_f32_e32 v66, 0, v84
	v_fmamk_f32 v104, v88, 0x3e0293ee, v100
	v_exp_f32_e32 v83, v103
	v_add_f32_e32 v66, v86, v66
	v_fmamk_f32 v105, v89, 0x3e0293ee, v100
	v_fmamk_f32 v111, v95, 0x3e0293ee, v100
	v_fmamk_f32 v95, v76, 0x3e0293ee, v100
	v_exp_f32_e32 v76, v104
	v_add_f32_e32 v66, v82, v66
	v_fmamk_f32 v106, v90, 0x3e0293ee, v100
	v_fmamk_f32 v113, v97, 0x3e0293ee, v100
	v_fmamk_f32 v97, v78, 0x3e0293ee, v100
	v_exp_f32_e32 v78, v105
	v_add_f32_e32 v66, v85, v66
	v_fmamk_f32 v107, v91, 0x3e0293ee, v100
	v_fmamk_f32 v108, v92, 0x3e0293ee, v100
	v_fmamk_f32 v92, v73, 0x3e0293ee, v100
	v_exp_f32_e32 v73, v106
	v_add_f32_e32 v66, v77, v66
	v_fmamk_f32 v110, v94, 0x3e0293ee, v100
	v_fmamk_f32 v94, v75, 0x3e0293ee, v100
	v_exp_f32_e32 v75, v107
	v_add_f32_e32 v66, v83, v66
	v_fmamk_f32 v109, v93, 0x3e0293ee, v100
	v_fmamk_f32 v90, v71, 0x3e0293ee, v100
	v_exp_f32_e32 v71, v108
	v_add_f32_e32 v66, v76, v66
	v_fmamk_f32 v93, v74, 0x3e0293ee, v100
	v_exp_f32_e32 v74, v109
	v_add_f32_e32 v66, v78, v66
	v_fmamk_f32 v88, v69, 0x3e0293ee, v100
	v_exp_f32_e32 v69, v110
	v_add_f32_e32 v66, v73, v66
	v_fmamk_f32 v91, v72, 0x3e0293ee, v100
	v_exp_f32_e32 v72, v111
	v_add_f32_e32 v66, v75, v66
	v_fmamk_f32 v87, v68, 0x3e0293ee, v100
	v_exp_f32_e32 v68, v112
	v_add_f32_e32 v66, v71, v66
	v_fmamk_f32 v89, v70, 0x3e0293ee, v100
	v_exp_f32_e32 v70, v113
	v_add_f32_e32 v66, v74, v66
	v_fmamk_f32 v67, v67, 0x3e0293ee, v100
; __device__ __forceinline__ void finishSM(f32x16& p0, f32x16& p1, float alpha, float& l_reg, bf16x8& pa0, bf16x8& pa1, bf16x8& pa2, bf16x8& pa3) {
; #pragma unroll
;   for (int r = 0; r < 16; ++r) p1[r] = __builtin_amdgcn_exp2f(p1[r]);
;   float ps = 0;
; #pragma unroll
;   for (int r = 0; r < 16; ++r) ps += p0[r];
; #pragma unroll
;   for (int r = 0; r < 16; ++r) ps += p1[r];
;   { auto rr = __builtin_amdgcn_permlane32_swap(__float_as_uint(ps), __float_as_uint(ps), false, false);
;     ps = __uint_as_float(rr[0]) + __uint_as_float(rr[1]); }
;   l_reg = l_reg * alpha + ps;
;   PK4(p0, 0, pa0); PK4(p0, 8, pa1); PK4(p1, 0, pa2); PK4(p1, 8, pa3);
; }
;   p0 = f32x16{}; p1 = f32x16{};
; #pragma unroll
;   for (int d0 = DLO; d0 < DHI; ++d0) { int cb = (d0 * 16 + hi * 8) * 2;
;     bf16x8 b0 = *reinterpret_cast<const bf16x8*>((const char*)Ks + KSWZ(r32, cb));
;     bf16x8 b1 = *reinterpret_cast<const bf16x8*>((const char*)Ks + KSWZ(32 + r32, cb));
;     p0 = __builtin_amdgcn_mfma_f32_32x32x16_bf16(b0, qr[d0], p0, 0, 0, 0);
;     p1 = __builtin_amdgcn_mfma_f32_32x32x16_bf16(b1, qr[d0], p1, 0, 0, 0); }
; }
; __device__ __forceinline__ int v_st(int k, int c) { const int kk = (k & ~0xC) | ((k & 4) << 1) | ((k & 8) >> 1); return ((kk >> 3) * 4 + (c >> 5)) * 512 + ((kk & 7) * 32 + (c & 31)) * 2; }
; __device__ __forceinline__ int v_rd_base(int lane) { return ((lane & 3) << 3) | (((lane >> 2) & 3) << 6) | (((lane >> 4) & 1) << 5) | (((lane >> 5) & 1) << 8); }
; template <int OFF> __device__ __forceinline__ s16x4 tr_read(int vb) {
;   s16x4 r; asm volatile("ds_read_b64_tr_b16 %0, %1 offset:%2" : "=&v"(r) : "v"(vb), "i"(OFF) : "memory"); return r;
; }
; template <int D0> __device__ __forceinline__ void pv_one(f32x16& od, int vb, bf16x8 pa0, bf16x8 pa1, bf16x8 pa2, bf16x8 pa3) {
;   const s16x4 l0 = tr_read<v_rd_off(D0, 0, 0)>(vb), h0 = tr_read<v_rd_off(D0, 0, 1)>(vb), l1 = tr_read<v_rd_off(D0, 1, 0)>(vb), h1 = tr_read<v_rd_off(D0, 1, 1)>(vb);
;   const s16x4 l2 = tr_read<v_rd_off(D0, 2, 0)>(vb), h2 = tr_read<v_rd_off(D0, 2, 1)>(vb), l3 = tr_read<v_rd_off(D0, 3, 0)>(vb), h3 = tr_read<v_rd_off(D0, 3, 1)>(vb);
;   asm volatile("s_waitcnt lgkmcnt(0)" ::: "memory"); SBAR();
;     ...
;   od = __builtin_amdgcn_mfma_f32_32x32x16_bf16(pa0, PK(l0, h0), od, 0, 0, 0);
;   od = __builtin_amdgcn_mfma_f32_32x32x16_bf16(pa1, PK(l1, h1), od, 0, 0, 0);
	v_add_f32_e32 v66, v69, v66
	v_exp_f32_e32 v102, v67
	v_add_f32_e32 v66, v72, v66
	v_exp_f32_e32 v87, v87
	v_add_f32_e32 v66, v68, v66
	v_exp_f32_e32 v88, v88
	v_add_f32_e32 v66, v70, v66
	v_exp_f32_e32 v89, v89
	v_add_f32_e32 v66, v101, v66
	v_exp_f32_e32 v90, v90
	v_add_f32_e32 v66, v102, v66
	v_exp_f32_e32 v91, v91
	v_add_f32_e32 v66, v87, v66
	v_exp_f32_e32 v92, v92
	v_add_f32_e32 v66, v88, v66
	v_exp_f32_e32 v93, v93
	v_add_f32_e32 v66, v89, v66
	v_exp_f32_e32 v94, v94
	v_add_f32_e32 v66, v90, v66
	v_exp_f32_e32 v95, v95
	v_add_f32_e32 v66, v91, v66
	v_exp_f32_e32 v96, v96
	v_add_f32_e32 v66, v92, v66
	v_fmamk_f32 v79, v79, 0x3e0293ee, v100
	v_exp_f32_e32 v97, v97
	v_add_f32_e32 v66, v93, v66
	v_fmamk_f32 v80, v80, 0x3e0293ee, v100
	v_exp_f32_e32 v103, v79
	v_add_f32_e32 v66, v94, v66
	v_fmac_f32_e32 v100, 0x3e0293ee, v81
	v_exp_f32_e32 v104, v80
	v_add_f32_e32 v66, v95, v66
	v_exp_f32_e32 v100, v100
	v_add_f32_e32 v66, v96, v66
	v_add_f32_e32 v66, v97, v66
	v_add_f32_e32 v66, v103, v66
	v_add_f32_e32 v66, v104, v66
	v_add_f32_e32 v66, v100, v66
	v_mov_b32_e32 v67, v66
	s_nop 1
	v_permlane32_swap_b32_e32 v66, v67
	v_cvt_pk_bf16_f32 v80, v84, v86
	v_cvt_pk_bf16_f32 v81, v82, v85
	v_cvt_pk_bf16_f32 v82, v77, v83
	v_cvt_pk_bf16_f32 v83, v76, v78
	v_cvt_pk_bf16_f32 v76, v73, v75
	v_cvt_pk_bf16_f32 v77, v71, v74
	v_cvt_pk_bf16_f32 v78, v69, v72
	v_cvt_pk_bf16_f32 v79, v68, v70
	v_cvt_pk_bf16_f32 v68, v101, v102
	v_cvt_pk_bf16_f32 v69, v87, v88
	v_cvt_pk_bf16_f32 v70, v89, v90
	v_cvt_pk_bf16_f32 v71, v91, v92
	v_cvt_pk_bf16_f32 v72, v93, v94
	v_cvt_pk_bf16_f32 v73, v95, v96
	v_cvt_pk_bf16_f32 v74, v97, v103
	v_cvt_pk_bf16_f32 v75, v104, v100
	s_nop 0
	v_permlane32_swap_b32_e32 v80, v82
	v_permlane32_swap_b32_e32 v81, v83
	v_permlane32_swap_b32_e32 v76, v78
	v_permlane32_swap_b32_e32 v77, v79
	v_permlane32_swap_b32_e32 v68, v70
	v_permlane32_swap_b32_e32 v69, v71
	v_permlane32_swap_b32_e32 v72, v74
	v_permlane32_swap_b32_e32 v73, v75
	ds_read_b64_tr_b16 v[84:85], v175 offset:0
	ds_read_b64_tr_b16 v[86:87], v175 offset:0x800
	ds_read_b64_tr_b16 v[88:89], v175 offset:0x1000
	ds_read_b64_tr_b16 v[90:91], v175 offset:0x1800
	ds_read_b64_tr_b16 v[92:93], v175 offset:0x2000
	ds_read_b64_tr_b16 v[94:95], v175 offset:0x2800
	ds_read_b64_tr_b16 v[100:101], v175 offset:0x3000
	ds_read_b64_tr_b16 v[102:103], v175 offset:0x3800
	s_waitcnt lgkmcnt(4)
	s_nop 0
	v_mfma_f32_32x32x16_bf16 v[2:17], v[80:83], v[84:87], v[2:17]
	ds_read_b64_tr_b16 v[84:85], v175 offset:0x200
	ds_read_b64_tr_b16 v[86:87], v175 offset:0xa00
	v_mfma_f32_32x32x16_bf16 v[2:17], v[76:79], v[88:91], v[2:17]
	ds_read_b64_tr_b16 v[88:89], v175 offset:0x1200
	ds_read_b64_tr_b16 v[90:91], v175 offset:0x1a00
	s_waitcnt lgkmcnt(4)
	v_mfma_f32_32x32x16_bf16 v[2:17], v[68:71], v[92:95], v[2:17]
	ds_read_b64_tr_b16 v[92:93], v175 offset:0x2200
	ds_read_b64_tr_b16 v[94:95], v175 offset:0x2a00
	v_mfma_f32_32x32x16_bf16 v[2:17], v[72:75], v[100:103], v[2:17]
	ds_read_b64_tr_b16 v[100:101], v175 offset:0x3200
	ds_read_b64_tr_b16 v[102:103], v175 offset:0x3a00
	s_waitcnt lgkmcnt(4)
	v_mfma_f32_32x32x16_bf16 v[50:65], v[80:83], v[84:87], v[50:65]
	ds_read_b64_tr_b16 v[84:85], v175 offset:0x400
	ds_read_b64_tr_b16 v[86:87], v175 offset:0xc00
	v_mfma_f32_32x32x16_bf16 v[50:65], v[76:79], v[88:91], v[50:65]
	ds_read_b64_tr_b16 v[88:89], v175 offset:0x1400
	ds_read_b64_tr_b16 v[90:91], v175 offset:0x1c00
	s_waitcnt lgkmcnt(4)
	v_mfma_f32_32x32x16_bf16 v[50:65], v[68:71], v[92:95], v[50:65]
	ds_read_b64_tr_b16 v[92:93], v175 offset:0x2400
	ds_read_b64_tr_b16 v[94:95], v175 offset:0x2c00
	v_mfma_f32_32x32x16_bf16 v[50:65], v[72:75], v[100:103], v[50:65]
	ds_read_b64_tr_b16 v[100:101], v175 offset:0x3400
	ds_read_b64_tr_b16 v[102:103], v175 offset:0x3c00
	s_waitcnt lgkmcnt(4)
	v_mfma_f32_32x32x16_bf16 v[34:49], v[80:83], v[84:87], v[34:49]
	ds_read_b64_tr_b16 v[84:85], v175 offset:0x600
	ds_read_b64_tr_b16 v[86:87], v175 offset:0xe00
	v_mfma_f32_32x32x16_bf16 v[34:49], v[76:79], v[88:91], v[34:49]
	ds_read_b64_tr_b16 v[88:89], v175 offset:0x1600
	ds_read_b64_tr_b16 v[90:91], v175 offset:0x1e00
	s_waitcnt lgkmcnt(4)
	v_mfma_f32_32x32x16_bf16 v[34:49], v[68:71], v[92:95], v[34:49]
	ds_read_b64_tr_b16 v[92:93], v175 offset:0x2600
	ds_read_b64_tr_b16 v[94:95], v175 offset:0x2e00
	v_mfma_f32_32x32x16_bf16 v[34:49], v[72:75], v[100:103], v[34:49]
	ds_read_b64_tr_b16 v[100:101], v175 offset:0x3600
	ds_read_b64_tr_b16 v[102:103], v175 offset:0x3e00
	s_waitcnt lgkmcnt(4)
	v_mfma_f32_32x32x16_bf16 v[18:33], v[80:83], v[84:87], v[18:33]
	v_mfma_f32_32x32x16_bf16 v[18:33], v[76:79], v[88:91], v[18:33]
	s_waitcnt lgkmcnt(0)
	v_mfma_f32_32x32x16_bf16 v[18:33], v[68:71], v[92:95], v[18:33]
	v_mfma_f32_32x32x16_bf16 v[18:33], v[72:75], v[100:103], v[18:33]
	s_and_saveexec_b64 s[2:3], s[6:7]
	v_add_f32_e32 v0, v0, v98
	v_fmac_f32_e32 v0, v174, v146
	v_add_f32_e32 v66, v66, v67
	v_fmac_f32_e32 v66, v0, v99
	ds_write_b32 v173, v66
	s_or_b64 exec, exec, s[2:3]
	s_waitcnt lgkmcnt(0)
	v_add_u32_e32 v0, s15, v172
	ds_read_b128 v[66:69], v0
	ds_read_b128 v[70:73], v0 offset:32
	s_mul_hi_i32 s3, s10, s14
	s_mul_i32 s2, s10, s14
	s_lshl_b64 s[2:3], s[2:3], 1
	s_waitcnt lgkmcnt(1)
	v_rcp_f32_e32 v74, v66
	v_rcp_f32_e32 v75, v67
	v_rcp_f32_e32 v76, v68
	v_rcp_f32_e32 v77, v69
	ds_read_b128 v[66:69], v0 offset:64
	s_add_u32 s2, s82, s2
	s_waitcnt lgkmcnt(1)
	v_rcp_f32_e32 v78, v70
	v_rcp_f32_e32 v79, v71
	v_rcp_f32_e32 v80, v72
	v_rcp_f32_e32 v81, v73
	ds_read_b128 v[70:73], v0 offset:96
	s_addc_u32 s3, s83, s3
	v_lshlrev_b32_e32 v86, 2, v171
	v_lshlrev_b32_e32 v0, 1, v170
	s_waitcnt lgkmcnt(1)
; __device__ __forceinline__ int crow(int r, int hi) { return (r & 3) + 8 * (r >> 2) + 4 * hi; }
; __device__ __forceinline__ unsigned cvtpk(float lo, float hi) { unsigned r; asm volatile("v_cvt_pk_bf16_f32 %0, %1, %2" : "=v"(r) : "v"(lo), "v"(hi)); return r; }
; template <int DLO, int DHI>
; __device__ __forceinline__ void attn_dense_body(const int g_wave, const bf16* __restrict__ Qb, const bf16* __restrict__ Kh, const bf16* __restrict__ Vh,
;                                                 bf16* __restrict__ Ob, int ldo, char* lds) {
;     ...
;   if (hi == 0) li_l[r32] = l_reg; asm volatile("s_waitcnt lgkmcnt(0)" ::: "memory");
;   float rli[16];
; #pragma unroll
;   for (int r = 0; r < 16; ++r) rli[r] = __builtin_amdgcn_rcpf(li_l[crow(r, hi)]);
;   unsigned short* Ow = (unsigned short*)Ob + (long)(wid * QBLK) * ldo;
; #pragma unroll
;   for (int r = 0; r < 16; ++r) { int orow = crow(r, hi);
; #pragma unroll
;     for (int d0 = 0; d0 < 4; ++d0) Ow[(long)orow * ldo + d0 * 32 + r32] = (unsigned short)(cvtpk(o[d0][r] * rli[r], 0.f) & 0xffffu); }
	v_rcp_f32_e32 v82, v66
	v_rcp_f32_e32 v83, v67
	v_rcp_f32_e32 v84, v68
	v_rcp_f32_e32 v85, v69
	v_lshl_add_u64 v[66:67], s[2:3], 0, v[0:1]
	v_mad_i64_i32 v[68:69], s[2:3], s10, v86, 0
	v_mul_f32_e32 v0, v2, v74
	v_lshl_add_u64 v[68:69], v[68:69], 1, v[66:67]
	v_cvt_pk_bf16_f32 v0, v0, v1
	global_store_short v[68:69], v0, off
	v_mul_f32_e32 v0, v50, v74
	v_cvt_pk_bf16_f32 v0, v0, v1
	global_store_short v[68:69], v0, off offset:64
	v_mul_f32_e32 v0, v34, v74
	v_cvt_pk_bf16_f32 v0, v0, v1
	global_store_short v[68:69], v0, off offset:128
	v_mul_f32_e32 v0, v18, v74
	v_cvt_pk_bf16_f32 v0, v0, v1
	global_store_short v[68:69], v0, off offset:192
	v_or_b32_e32 v0, 1, v86
	v_mad_i64_i32 v[68:69], s[2:3], s10, v0, 0
	v_mul_f32_e32 v0, v3, v75
	v_lshl_add_u64 v[68:69], v[68:69], 1, v[66:67]
	v_cvt_pk_bf16_f32 v0, v0, v1
	global_store_short v[68:69], v0, off
	v_mul_f32_e32 v0, v51, v75
	v_cvt_pk_bf16_f32 v0, v0, v1
	global_store_short v[68:69], v0, off offset:64
	v_mul_f32_e32 v0, v35, v75
	v_cvt_pk_bf16_f32 v0, v0, v1
	global_store_short v[68:69], v0, off offset:128
	v_mul_f32_e32 v0, v19, v75
	v_cvt_pk_bf16_f32 v0, v0, v1
	global_store_short v[68:69], v0, off offset:192
	v_or_b32_e32 v0, 2, v86
	v_mad_i64_i32 v[2:3], s[2:3], s10, v0, 0
	v_mul_f32_e32 v0, v4, v76
	v_lshl_add_u64 v[2:3], v[2:3], 1, v[66:67]
	v_cvt_pk_bf16_f32 v0, v0, v1
	global_store_short v[2:3], v0, off
	v_mul_f32_e32 v0, v52, v76
	v_cvt_pk_bf16_f32 v0, v0, v1
	global_store_short v[2:3], v0, off offset:64
	v_mul_f32_e32 v0, v36, v76
	v_cvt_pk_bf16_f32 v0, v0, v1
	global_store_short v[2:3], v0, off offset:128
	v_mul_f32_e32 v0, v20, v76
	v_cvt_pk_bf16_f32 v0, v0, v1
	global_store_short v[2:3], v0, off offset:192
	v_or_b32_e32 v0, 3, v86
	v_mad_i64_i32 v[2:3], s[2:3], s10, v0, 0
	v_mul_f32_e32 v0, v5, v77
	v_lshl_add_u64 v[2:3], v[2:3], 1, v[66:67]
	v_cvt_pk_bf16_f32 v0, v0, v1
	global_store_short v[2:3], v0, off
	v_mul_f32_e32 v0, v53, v77
	v_cvt_pk_bf16_f32 v0, v0, v1
	global_store_short v[2:3], v0, off offset:64
	v_mul_f32_e32 v0, v37, v77
	v_cvt_pk_bf16_f32 v0, v0, v1
	global_store_short v[2:3], v0, off offset:128
	v_mul_f32_e32 v0, v21, v77
	v_cvt_pk_bf16_f32 v0, v0, v1
	global_store_short v[2:3], v0, off offset:192
	v_add_u32_e32 v0, 8, v86
	v_mad_i64_i32 v[2:3], s[2:3], s10, v0, 0
	v_mul_f32_e32 v0, v6, v78
	v_lshl_add_u64 v[2:3], v[2:3], 1, v[66:67]
	v_cvt_pk_bf16_f32 v0, v0, v1
	global_store_short v[2:3], v0, off
	v_mul_f32_e32 v0, v54, v78
	v_cvt_pk_bf16_f32 v0, v0, v1
	global_store_short v[2:3], v0, off offset:64
	v_mul_f32_e32 v0, v38, v78
	v_cvt_pk_bf16_f32 v0, v0, v1
	global_store_short v[2:3], v0, off offset:128
	v_mul_f32_e32 v0, v22, v78
	v_cvt_pk_bf16_f32 v0, v0, v1
	global_store_short v[2:3], v0, off offset:192
	v_add_u32_e32 v0, 9, v86
	v_mad_i64_i32 v[2:3], s[2:3], s10, v0, 0
	v_mul_f32_e32 v0, v7, v79
	v_lshl_add_u64 v[2:3], v[2:3], 1, v[66:67]
	v_cvt_pk_bf16_f32 v0, v0, v1
	global_store_short v[2:3], v0, off
	v_mul_f32_e32 v0, v55, v79
	v_cvt_pk_bf16_f32 v0, v0, v1
	global_store_short v[2:3], v0, off offset:64
	v_mul_f32_e32 v0, v39, v79
	v_cvt_pk_bf16_f32 v0, v0, v1
	global_store_short v[2:3], v0, off offset:128
	v_mul_f32_e32 v0, v23, v79
	v_cvt_pk_bf16_f32 v0, v0, v1
	global_store_short v[2:3], v0, off offset:192
	v_add_u32_e32 v0, 10, v86
	v_mad_i64_i32 v[2:3], s[2:3], s10, v0, 0
	v_mul_f32_e32 v0, v8, v80
	v_lshl_add_u64 v[2:3], v[2:3], 1, v[66:67]
	v_cvt_pk_bf16_f32 v0, v0, v1
	global_store_short v[2:3], v0, off
	v_mul_f32_e32 v0, v56, v80
	v_cvt_pk_bf16_f32 v0, v0, v1
	global_store_short v[2:3], v0, off offset:64
	v_mul_f32_e32 v0, v40, v80
	v_cvt_pk_bf16_f32 v0, v0, v1
	global_store_short v[2:3], v0, off offset:128
	v_mul_f32_e32 v0, v24, v80
	v_cvt_pk_bf16_f32 v0, v0, v1
	global_store_short v[2:3], v0, off offset:192
	v_add_u32_e32 v0, 11, v86
	v_mad_i64_i32 v[2:3], s[2:3], s10, v0, 0
	v_mul_f32_e32 v0, v9, v81
	v_lshl_add_u64 v[2:3], v[2:3], 1, v[66:67]
	v_cvt_pk_bf16_f32 v0, v0, v1
	global_store_short v[2:3], v0, off
	v_mul_f32_e32 v0, v57, v81
	v_cvt_pk_bf16_f32 v0, v0, v1
	global_store_short v[2:3], v0, off offset:64
	v_mul_f32_e32 v0, v41, v81
	v_cvt_pk_bf16_f32 v0, v0, v1
	global_store_short v[2:3], v0, off offset:128
	v_mul_f32_e32 v0, v25, v81
	v_cvt_pk_bf16_f32 v0, v0, v1
	global_store_short v[2:3], v0, off offset:192
	v_add_u32_e32 v0, 16, v86
	v_mad_i64_i32 v[2:3], s[2:3], s10, v0, 0
	v_mul_f32_e32 v0, v10, v82
	v_lshl_add_u64 v[2:3], v[2:3], 1, v[66:67]
	v_cvt_pk_bf16_f32 v0, v0, v1
	global_store_short v[2:3], v0, off
	v_mul_f32_e32 v0, v58, v82
	v_cvt_pk_bf16_f32 v0, v0, v1
	global_store_short v[2:3], v0, off offset:64
	v_mul_f32_e32 v0, v42, v82
	v_cvt_pk_bf16_f32 v0, v0, v1
	global_store_short v[2:3], v0, off offset:128
	v_mul_f32_e32 v0, v26, v82
	v_cvt_pk_bf16_f32 v0, v0, v1
	global_store_short v[2:3], v0, off offset:192
	v_add_u32_e32 v0, 17, v86
	v_mad_i64_i32 v[2:3], s[2:3], s10, v0, 0
	v_mul_f32_e32 v0, v11, v83
	v_lshl_add_u64 v[2:3], v[2:3], 1, v[66:67]
	v_cvt_pk_bf16_f32 v0, v0, v1
	global_store_short v[2:3], v0, off
	v_mul_f32_e32 v0, v59, v83
	v_cvt_pk_bf16_f32 v0, v0, v1
	global_store_short v[2:3], v0, off offset:64
	v_mul_f32_e32 v0, v43, v83
	v_cvt_pk_bf16_f32 v0, v0, v1
	global_store_short v[2:3], v0, off offset:128
	v_mul_f32_e32 v0, v27, v83
	v_cvt_pk_bf16_f32 v0, v0, v1
	global_store_short v[2:3], v0, off offset:192
	v_add_u32_e32 v0, 18, v86
	v_mad_i64_i32 v[2:3], s[2:3], s10, v0, 0
	v_mul_f32_e32 v0, v12, v84
	v_lshl_add_u64 v[2:3], v[2:3], 1, v[66:67]
	v_cvt_pk_bf16_f32 v0, v0, v1
	global_store_short v[2:3], v0, off
	v_mul_f32_e32 v0, v60, v84
	v_cvt_pk_bf16_f32 v0, v0, v1
	global_store_short v[2:3], v0, off offset:64
	v_mul_f32_e32 v0, v44, v84
	v_cvt_pk_bf16_f32 v0, v0, v1
	global_store_short v[2:3], v0, off offset:128
	v_mul_f32_e32 v0, v28, v84
	v_cvt_pk_bf16_f32 v0, v0, v1
	global_store_short v[2:3], v0, off offset:192
	v_add_u32_e32 v0, 19, v86
	v_mad_i64_i32 v[2:3], s[2:3], s10, v0, 0
	v_mul_f32_e32 v0, v13, v85
	v_lshl_add_u64 v[2:3], v[2:3], 1, v[66:67]
	v_cvt_pk_bf16_f32 v0, v0, v1
	global_store_short v[2:3], v0, off
	v_mul_f32_e32 v0, v61, v85
	v_cvt_pk_bf16_f32 v0, v0, v1
	global_store_short v[2:3], v0, off offset:64
	v_mul_f32_e32 v0, v45, v85
	s_waitcnt lgkmcnt(0)
; __device__ __forceinline__ int crow(int r, int hi) { return (r & 3) + 8 * (r >> 2) + 4 * hi; }
; __device__ __forceinline__ unsigned cvtpk(float lo, float hi) { unsigned r; asm volatile("v_cvt_pk_bf16_f32 %0, %1, %2" : "=v"(r) : "v"(lo), "v"(hi)); return r; }
; template <int DLO, int DHI>
; __device__ __forceinline__ void attn_dense_body(const int g_wave, const bf16* __restrict__ Qb, const bf16* __restrict__ Kh, const bf16* __restrict__ Vh,
;                                                 bf16* __restrict__ Ob, int ldo, char* lds) {
;     ...
;   for (int r = 0; r < 16; ++r) rli[r] = __builtin_amdgcn_rcpf(li_l[crow(r, hi)]);
;   unsigned short* Ow = (unsigned short*)Ob + (long)(wid * QBLK) * ldo;
; #pragma unroll
;   for (int r = 0; r < 16; ++r) { int orow = crow(r, hi);
; #pragma unroll
;     for (int d0 = 0; d0 < 4; ++d0) Ow[(long)orow * ldo + d0 * 32 + r32] = (unsigned short)(cvtpk(o[d0][r] * rli[r], 0.f) & 0xffffu); }
;   __syncthreads();
	v_rcp_f32_e32 v70, v70
	v_cvt_pk_bf16_f32 v0, v0, v1
	global_store_short v[2:3], v0, off offset:128
	v_mul_f32_e32 v0, v29, v85
	v_cvt_pk_bf16_f32 v0, v0, v1
	global_store_short v[2:3], v0, off offset:192
	v_add_u32_e32 v0, 24, v86
	v_mad_i64_i32 v[2:3], s[2:3], s10, v0, 0
	v_mul_f32_e32 v0, v14, v70
	v_lshl_add_u64 v[2:3], v[2:3], 1, v[66:67]
	v_cvt_pk_bf16_f32 v0, v0, v1
	global_store_short v[2:3], v0, off
	v_mul_f32_e32 v0, v62, v70
	v_cvt_pk_bf16_f32 v0, v0, v1
	global_store_short v[2:3], v0, off offset:64
	v_mul_f32_e32 v0, v46, v70
	v_rcp_f32_e32 v71, v71
	v_cvt_pk_bf16_f32 v0, v0, v1
	global_store_short v[2:3], v0, off offset:128
	v_mul_f32_e32 v0, v30, v70
	v_cvt_pk_bf16_f32 v0, v0, v1
	global_store_short v[2:3], v0, off offset:192
	v_add_u32_e32 v0, 25, v86
	v_mad_i64_i32 v[2:3], s[2:3], s10, v0, 0
	v_mul_f32_e32 v0, v15, v71
	v_lshl_add_u64 v[2:3], v[2:3], 1, v[66:67]
	v_cvt_pk_bf16_f32 v0, v0, v1
	global_store_short v[2:3], v0, off
	v_mul_f32_e32 v0, v63, v71
	v_cvt_pk_bf16_f32 v0, v0, v1
	global_store_short v[2:3], v0, off offset:64
	v_mul_f32_e32 v0, v47, v71
	v_rcp_f32_e32 v72, v72
	v_cvt_pk_bf16_f32 v0, v0, v1
	global_store_short v[2:3], v0, off offset:128
	v_mul_f32_e32 v0, v31, v71
	v_cvt_pk_bf16_f32 v0, v0, v1
	global_store_short v[2:3], v0, off offset:192
	v_add_u32_e32 v0, 26, v86
	v_mad_i64_i32 v[2:3], s[2:3], s10, v0, 0
	v_mul_f32_e32 v0, v16, v72
	v_lshl_add_u64 v[2:3], v[2:3], 1, v[66:67]
	v_cvt_pk_bf16_f32 v0, v0, v1
	global_store_short v[2:3], v0, off
	v_mul_f32_e32 v0, v64, v72
	v_cvt_pk_bf16_f32 v0, v0, v1
	global_store_short v[2:3], v0, off offset:64
	v_mul_f32_e32 v0, v48, v72
	v_rcp_f32_e32 v73, v73
	v_cvt_pk_bf16_f32 v0, v0, v1
	global_store_short v[2:3], v0, off offset:128
	v_mul_f32_e32 v0, v32, v72
	v_cvt_pk_bf16_f32 v0, v0, v1
	global_store_short v[2:3], v0, off offset:192
	v_add_u32_e32 v0, 27, v86
	v_mad_i64_i32 v[2:3], s[2:3], s10, v0, 0
	v_mul_f32_e32 v0, v17, v73
	v_lshl_add_u64 v[2:3], v[2:3], 1, v[66:67]
	v_cvt_pk_bf16_f32 v0, v0, v1
	global_store_short v[2:3], v0, off
	v_mul_f32_e32 v0, v65, v73
	v_cvt_pk_bf16_f32 v0, v0, v1
	global_store_short v[2:3], v0, off offset:64
	v_mul_f32_e32 v0, v49, v73
	v_cvt_pk_bf16_f32 v0, v0, v1
	global_store_short v[2:3], v0, off offset:128
	v_mul_f32_e32 v0, v33, v73
	v_cvt_pk_bf16_f32 v0, v0, v1
	global_store_short v[2:3], v0, off offset:192
	s_waitcnt vmcnt(63) expcnt(7) lgkmcnt(15)
	s_barrier
	s_mov_b64 s[4:5], 0

; __device__ __forceinline__ void finishSM(f32x16& p0, f32x16& p1, float alpha, float& l_reg, bf16x8& pa0, bf16x8& pa1, bf16x8& pa2, bf16x8& pa3) {
; #pragma unroll
;   for (int r = 0; r < 16; ++r) p1[r] = __builtin_amdgcn_exp2f(p1[r]);
;   float ps = 0;
; #pragma unroll
;   for (int r = 0; r < 16; ++r) ps += p0[r];
; #pragma unroll
;   for (int r = 0; r < 16; ++r) ps += p1[r];
;   { auto rr = __builtin_amdgcn_permlane32_swap(__float_as_uint(ps), __float_as_uint(ps), false, false);
;     ps = __uint_as_float(rr[0]) + __uint_as_float(rr[1]); }
;   l_reg = l_reg * alpha + ps;
;   PK4(p0, 0, pa0); PK4(p0, 8, pa1); PK4(p1, 0, pa2); PK4(p1, 8, pa3);
; }
;   p0 = f32x16{}; p1 = f32x16{};
; #pragma unroll
;   for (int d0 = DLO; d0 < DHI; ++d0) { int cb = (d0 * 16 + hi * 8) * 2;
;     bf16x8 b0 = *reinterpret_cast<const bf16x8*>((const char*)Ks + KSWZ(r32, cb));
;     bf16x8 b1 = *reinterpret_cast<const bf16x8*>((const char*)Ks + KSWZ(32 + r32, cb));
;     p0 = __builtin_amdgcn_mfma_f32_32x32x16_bf16(b0, qr[d0], p0, 0, 0, 0);
;     p1 = __builtin_amdgcn_mfma_f32_32x32x16_bf16(b1, qr[d0], p1, 0, 0, 0); }
; }
; __device__ __forceinline__ int v_st(int k, int c) { const int kk = (k & ~0xC) | ((k & 4) << 1) | ((k & 8) >> 1); return ((kk >> 3) * 4 + (c >> 5)) * 512 + ((kk & 7) * 32 + (c & 31)) * 2; }
; __device__ __forceinline__ int v_rd_base(int lane) { return ((lane & 3) << 3) | (((lane >> 2) & 3) << 6) | (((lane >> 4) & 1) << 5) | (((lane >> 5) & 1) << 8); }
; template <int OFF> __device__ __forceinline__ s16x4 tr_read(int vb) {
;   s16x4 r; asm volatile("ds_read_b64_tr_b16 %0, %1 offset:%2" : "=&v"(r) : "v"(vb), "i"(OFF) : "memory"); return r;
; }
; template <int D0> __device__ __forceinline__ void pv_one(f32x16& od, int vb, bf16x8 pa0, bf16x8 pa1, bf16x8 pa2, bf16x8 pa3) {
;   const s16x4 l0 = tr_read<v_rd_off(D0, 0, 0)>(vb), h0 = tr_read<v_rd_off(D0, 0, 1)>(vb), l1 = tr_read<v_rd_off(D0, 1, 0)>(vb), h1 = tr_read<v_rd_off(D0, 1, 1)>(vb);
;   const s16x4 l2 = tr_read<v_rd_off(D0, 2, 0)>(vb), h2 = tr_read<v_rd_off(D0, 2, 1)>(vb), l3 = tr_read<v_rd_off(D0, 3, 0)>(vb), h3 = tr_read<v_rd_off(D0, 3, 1)>(vb);
;   asm volatile("s_waitcnt lgkmcnt(0)" ::: "memory"); SBAR();
;     ...
;   od = __builtin_amdgcn_mfma_f32_32x32x16_bf16(pa0, PK(l0, h0), od, 0, 0, 0);
;   od = __builtin_amdgcn_mfma_f32_32x32x16_bf16(pa1, PK(l1, h1), od, 0, 0, 0);
.LBB0_1043:
	ds_read_b128 v[66:69], v218 offset:49152
	ds_read_b128 v[70:73], v218 offset:57344
	ds_read_b128 v[228:231], v225 offset:49152
	ds_read_b128 v[232:235], v225 offset:57344
	v_add_f32_e32 v162, 0, v177
	v_add_f32_e32 v162, v195, v162
	s_waitcnt lgkmcnt(3)
	v_mfma_f32_32x32x16_bf16 v[82:97], v[66:69], v[118:121], 0
	v_add_f32_e32 v162, v163, v162
	v_add_f32_e32 v162, v194, v162
	v_add_f32_e32 v162, v164, v162
	v_add_f32_e32 v162, v176, v162
	v_add_f32_e32 v162, v165, v162
	v_add_f32_e32 v162, v175, v162
	v_add_f32_e32 v162, v166, v162
	s_waitcnt lgkmcnt(2)
	v_mfma_f32_32x32x16_bf16 v[66:81], v[70:73], v[118:121], 0
	v_add_f32_e32 v162, v174, v162
	v_add_f32_e32 v162, v167, v162
	v_add_f32_e32 v162, v173, v162
	v_exp_f32_e32 v158, v158
	v_add_f32_e32 v162, v168, v162
	v_exp_f32_e32 v159, v159
	v_add_f32_e32 v162, v172, v162
	s_waitcnt lgkmcnt(1)
	v_mfma_f32_32x32x16_bf16 v[82:97], v[228:231], v[110:113], v[82:97]
	v_exp_f32_e32 v156, v156
	v_add_f32_e32 v162, v169, v162
	v_exp_f32_e32 v157, v157
	v_add_f32_e32 v162, v171, v162
	v_exp_f32_e32 v150, v150
	v_add_f32_e32 v162, v158, v162
	v_exp_f32_e32 v151, v151
	s_waitcnt lgkmcnt(0)
	v_mfma_f32_32x32x16_bf16 v[66:81], v[232:235], v[110:113], v[66:81]
	ds_read_b128 v[228:231], v224 offset:49152
	ds_read_b128 v[232:235], v224 offset:57344
	v_add_f32_e32 v162, v159, v162
	v_exp_f32_e32 v148, v148
	v_add_f32_e32 v162, v156, v162
	v_exp_f32_e32 v149, v149
	v_add_f32_e32 v162, v157, v162
	v_exp_f32_e32 v146, v146
	s_waitcnt lgkmcnt(1)
	v_mfma_f32_32x32x16_bf16 v[82:97], v[228:231], v[126:129], v[82:97]
	v_add_f32_e32 v162, v150, v162
	v_exp_f32_e32 v147, v147
	v_add_f32_e32 v162, v151, v162
	v_exp_f32_e32 v160, v160
	v_add_f32_e32 v162, v148, v162
	v_exp_f32_e32 v161, v161
	v_add_f32_e32 v162, v149, v162
	s_waitcnt lgkmcnt(0)
	v_mfma_f32_32x32x16_bf16 v[66:81], v[232:235], v[126:129], v[66:81]
	ds_read_b128 v[228:231], v222 offset:49152
	ds_read_b128 v[232:235], v222 offset:57344
	v_exp_f32_e32 v154, v154
	v_add_f32_e32 v162, v146, v162
	v_exp_f32_e32 v155, v155
	v_add_f32_e32 v162, v147, v162
	v_exp_f32_e32 v152, v152
	v_add_f32_e32 v162, v160, v162
	s_waitcnt lgkmcnt(1)
	v_mfma_f32_32x32x16_bf16 v[82:97], v[228:231], v[122:125], v[82:97]
	v_exp_f32_e32 v153, v153
	v_add_f32_e32 v162, v161, v162
	v_add_f32_e32 v162, v154, v162
	v_add_f32_e32 v162, v155, v162
	v_add_f32_e32 v162, v152, v162
	v_add_f32_e32 v227, v153, v162
	s_waitcnt lgkmcnt(0)
	v_mfma_f32_32x32x16_bf16 v[66:81], v[232:235], v[122:125], v[66:81]
	ds_read_b128 v[228:231], v220 offset:49152
	ds_read_b128 v[232:235], v220 offset:57344
	s_waitcnt lgkmcnt(1)
	v_mfma_f32_32x32x16_bf16 v[82:97], v[228:231], v[114:117], v[82:97]
	s_waitcnt lgkmcnt(0)
	v_mfma_f32_32x32x16_bf16 v[66:81], v[232:235], v[114:117], v[66:81]
	ds_read_b128 v[228:231], v219 offset:49152
	ds_read_b128 v[232:235], v219 offset:57344
	s_waitcnt lgkmcnt(1)
	v_mfma_f32_32x32x16_bf16 v[82:97], v[228:231], v[106:109], v[82:97]
	s_waitcnt lgkmcnt(0)
	v_mfma_f32_32x32x16_bf16 v[66:81], v[232:235], v[106:109], v[66:81]
	ds_read_b128 v[228:231], v221 offset:49152
	ds_read_b128 v[232:235], v221 offset:57344
	s_waitcnt lgkmcnt(1)
	v_mfma_f32_32x32x16_bf16 v[82:97], v[228:231], v[102:105], v[82:97]
	s_waitcnt lgkmcnt(0)
	v_mfma_f32_32x32x16_bf16 v[66:81], v[232:235], v[102:105], v[66:81]
	ds_read_b128 v[228:231], v223 offset:49152
	ds_read_b128 v[232:235], v223 offset:57344
	v_cvt_pk_bf16_f32 v162, v177, v195
	v_cvt_pk_bf16_f32 v163, v163, v194
	v_cvt_pk_bf16_f32 v164, v164, v176
	v_cvt_pk_bf16_f32 v165, v165, v175
	v_cvt_pk_bf16_f32 v166, v166, v174
	v_cvt_pk_bf16_f32 v167, v167, v173
	s_waitcnt lgkmcnt(1)
	v_mfma_f32_32x32x16_bf16 v[82:97], v[228:231], v[98:101], v[82:97]
	v_mov_b32_e32 v228, v227
	s_nop 1
	v_permlane32_swap_b32_e32 v227, v228
	v_permlane32_swap_b32_e32 v162, v164
	v_cvt_pk_bf16_f32 v168, v168, v172
	v_cvt_pk_bf16_f32 v169, v169, v171
	s_waitcnt lgkmcnt(0)
	v_mfma_f32_32x32x16_bf16 v[66:81], v[232:235], v[98:101], v[66:81]
	v_cvt_pk_bf16_f32 v172, v158, v159
	v_cvt_pk_bf16_f32 v173, v156, v157
	v_cvt_pk_bf16_f32 v174, v150, v151
	v_cvt_pk_bf16_f32 v175, v148, v149
	v_cvt_pk_bf16_f32 v230, v146, v147
	v_cvt_pk_bf16_f32 v231, v160, v161
	v_cvt_pk_bf16_f32 v232, v154, v155
	v_cvt_pk_bf16_f32 v233, v152, v153
	v_permlane32_swap_b32_e32 v163, v165
	v_permlane32_swap_b32_e32 v166, v168
	v_permlane32_swap_b32_e32 v167, v169
	v_permlane32_swap_b32_e32 v172, v174
	v_permlane32_swap_b32_e32 v173, v175
	v_permlane32_swap_b32_e32 v230, v232
	v_permlane32_swap_b32_e32 v231, v233
	s_waitcnt vmcnt(0)
	ds_write_b128 v216, v[130:133]
	ds_write_b128 v217, v[134:137]
	ds_write_b128 v214, v[138:141] offset:32768
	ds_write_b128 v215, v[142:145] offset:32768
	v_lshl_add_u64 v[196:197], v[192:193], 0, v[0:1]
	s_mov_b32 s1, 0x18fb0000
	v_add_co_u32_e32 v146, vcc, s1, v196
	s_mov_b32 s1, 0x18ff8000
	s_nop 0
	v_addc_co_u32_e32 v147, vcc, 0, v197, vcc
	v_add_co_u32_e32 v150, vcc, s1, v196
	v_lshl_add_u64 v[194:195], v[190:191], 0, v[0:1]
	s_nop 0
	v_addc_co_u32_e32 v151, vcc, 0, v197, vcc
	s_mov_b32 s1, 0x1f648000
	v_add_co_u32_e32 v154, vcc, s1, v194
	s_mov_b32 s1, 0x1f654000
	s_nop 0
	v_addc_co_u32_e32 v155, vcc, 0, v195, vcc
	v_add_co_u32_e32 v158, vcc, s1, v194
	global_load_dwordx4 v[146:149], v[146:147], off
	s_nop 0
	global_load_dwordx4 v[150:153], v[150:151], off
	v_addc_co_u32_e32 v159, vcc, 0, v195, vcc
	global_load_dwordx4 v[154:157], v[154:155], off
	s_nop 0
	global_load_dwordx4 v[158:161], v[158:159], off
	ds_read_b64_tr_b16 v[234:235], v213 offset:0
	ds_read_b64_tr_b16 v[236:237], v213 offset:0x800
	ds_read_b64_tr_b16 v[238:239], v213 offset:0x1000
	ds_read_b64_tr_b16 v[240:241], v213 offset:0x1800
	ds_read_b64_tr_b16 v[242:243], v213 offset:0x2000
	ds_read_b64_tr_b16 v[244:245], v213 offset:0x2800
	ds_read_b64_tr_b16 v[246:247], v213 offset:0x3000
	ds_read_b64_tr_b16 v[248:249], v213 offset:0x3800
	s_waitcnt lgkmcnt(4)
; #define SBAR() __builtin_amdgcn_sched_barrier(0)
; __device__ __forceinline__ void partialSM(f32x16& p0, f32x16& p1, float& m_reg, float& mn, float& alpha) {
;   constexpr float C = SCALE * 1.4426950408889634f;
;   float pmax = p0[0];
; #pragma unroll
;   for (int r = 1; r < 16; ++r) pmax = fmaxf(pmax, p0[r]);
; #pragma unroll
;   for (int r = 0; r < 16; ++r) pmax = fmaxf(pmax, p1[r]);
;   { auto rr = __builtin_amdgcn_permlane32_swap(__float_as_uint(pmax), __float_as_uint(pmax), false, false);
;     pmax = fmaxf(__uint_as_float(rr[0]), __uint_as_float(rr[1])); }
;   if (__builtin_expect(__all(pmax - m_reg <= THR / SCALE), 1)) { mn = m_reg; alpha = 1.f; }
;   else { mn = fmaxf(m_reg, pmax); alpha = __builtin_amdgcn_exp2f((m_reg - mn) * C); m_reg = mn; }
; template <int D0> __device__ __forceinline__ void pv_one(f32x16& od, int vb, bf16x8 pa0, bf16x8 pa1, bf16x8 pa2, bf16x8 pa3) {
;   const s16x4 l0 = tr_read<v_rd_off(D0, 0, 0)>(vb), h0 = tr_read<v_rd_off(D0, 0, 1)>(vb), l1 = tr_read<v_rd_off(D0, 1, 0)>(vb), h1 = tr_read<v_rd_off(D0, 1, 1)>(vb);
;   const s16x4 l2 = tr_read<v_rd_off(D0, 2, 0)>(vb), h2 = tr_read<v_rd_off(D0, 2, 1)>(vb), l3 = tr_read<v_rd_off(D0, 3, 0)>(vb), h3 = tr_read<v_rd_off(D0, 3, 1)>(vb);
;   asm volatile("s_waitcnt lgkmcnt(0)" ::: "memory"); SBAR();
;     ...
;   od = __builtin_amdgcn_mfma_f32_32x32x16_bf16(pa0, PK(l0, h0), od, 0, 0, 0);
;   od = __builtin_amdgcn_mfma_f32_32x32x16_bf16(pa1, PK(l1, h1), od, 0, 0, 0);
;   od = __builtin_amdgcn_mfma_f32_32x32x16_bf16(pa2, PK(l2, h2), od, 0, 0, 0);
;   od = __builtin_amdgcn_mfma_f32_32x32x16_bf16(pa3, PK(l3, h3), od, 0, 0, 0);
;     ...
; }
; __device__ __forceinline__ void pv_d0(f32x16* o, int vb, bf16x8 pa0, bf16x8 pa1, bf16x8 pa2, bf16x8 pa3) {
;   pv_one<0>(o[0], vb, pa0, pa1, pa2, pa3); pv_one<1>(o[1], vb, pa0, pa1, pa2, pa3); pv_one<2>(o[2], vb, pa0, pa1, pa2, pa3); pv_one<3>(o[3], vb, pa0, pa1, pa2, pa3);
	s_nop 0
	v_mfma_f32_32x32x16_bf16 v[2:17], v[162:165], v[234:237], v[2:17]
	ds_read_b64_tr_b16 v[234:235], v213 offset:0x200
	ds_read_b64_tr_b16 v[236:237], v213 offset:0xa00
	v_mfma_f32_32x32x16_bf16 v[2:17], v[166:169], v[238:241], v[2:17]
	ds_read_b64_tr_b16 v[238:239], v213 offset:0x1200
	ds_read_b64_tr_b16 v[240:241], v213 offset:0x1a00
	s_waitcnt lgkmcnt(4)
	v_mfma_f32_32x32x16_bf16 v[2:17], v[172:175], v[242:245], v[2:17]
	ds_read_b64_tr_b16 v[242:243], v213 offset:0x2200
	ds_read_b64_tr_b16 v[244:245], v213 offset:0x2a00
	v_mfma_f32_32x32x16_bf16 v[2:17], v[230:233], v[246:249], v[2:17]
	ds_read_b64_tr_b16 v[246:247], v213 offset:0x3200
	ds_read_b64_tr_b16 v[248:249], v213 offset:0x3a00
	s_waitcnt lgkmcnt(4)
	v_mfma_f32_32x32x16_bf16 v[50:65], v[162:165], v[234:237], v[50:65]
	ds_read_b64_tr_b16 v[234:235], v213 offset:0x400
	ds_read_b64_tr_b16 v[236:237], v213 offset:0xc00
	v_mfma_f32_32x32x16_bf16 v[50:65], v[166:169], v[238:241], v[50:65]
	ds_read_b64_tr_b16 v[238:239], v213 offset:0x1400
	ds_read_b64_tr_b16 v[240:241], v213 offset:0x1c00
	s_waitcnt lgkmcnt(4)
	v_mfma_f32_32x32x16_bf16 v[50:65], v[172:175], v[242:245], v[50:65]
	ds_read_b64_tr_b16 v[242:243], v213 offset:0x2400
	ds_read_b64_tr_b16 v[244:245], v213 offset:0x2c00
	v_mfma_f32_32x32x16_bf16 v[50:65], v[230:233], v[246:249], v[50:65]
	ds_read_b64_tr_b16 v[246:247], v213 offset:0x3400
	ds_read_b64_tr_b16 v[248:249], v213 offset:0x3c00
	s_waitcnt lgkmcnt(4)
	v_mfma_f32_32x32x16_bf16 v[34:49], v[162:165], v[234:237], v[34:49]
	ds_read_b64_tr_b16 v[234:235], v213 offset:0x600
	ds_read_b64_tr_b16 v[236:237], v213 offset:0xe00
	v_mfma_f32_32x32x16_bf16 v[34:49], v[166:169], v[238:241], v[34:49]
	ds_read_b64_tr_b16 v[238:239], v213 offset:0x1600
	ds_read_b64_tr_b16 v[240:241], v213 offset:0x1e00
	s_waitcnt lgkmcnt(4)
	v_mfma_f32_32x32x16_bf16 v[34:49], v[172:175], v[242:245], v[34:49]
	ds_read_b64_tr_b16 v[242:243], v213 offset:0x2600
	ds_read_b64_tr_b16 v[244:245], v213 offset:0x2e00
	v_mfma_f32_32x32x16_bf16 v[34:49], v[230:233], v[246:249], v[34:49]
	ds_read_b64_tr_b16 v[246:247], v213 offset:0x3600
	ds_read_b64_tr_b16 v[248:249], v213 offset:0x3e00
	s_waitcnt lgkmcnt(4)
	v_mfma_f32_32x32x16_bf16 v[18:33], v[162:165], v[234:237], v[18:33]
	v_max_f32_e32 v162, v83, v83
	v_max_f32_e32 v163, v82, v82
	v_max_f32_e32 v162, v163, v162
	v_max3_f32 v162, v162, v84, v85
	v_max3_f32 v162, v162, v86, v87
	v_max3_f32 v162, v162, v88, v89
	v_max3_f32 v162, v162, v90, v91
	v_max3_f32 v162, v162, v92, v93
	v_max3_f32 v162, v162, v94, v95
	v_mfma_f32_32x32x16_bf16 v[18:33], v[166:169], v[238:241], v[18:33]
	v_max3_f32 v162, v162, v96, v97
	v_max3_f32 v162, v162, v66, v67
	v_max3_f32 v162, v162, v68, v69
	v_max3_f32 v162, v162, v70, v71
	v_max3_f32 v162, v162, v72, v73
	v_max3_f32 v162, v162, v74, v75
	v_max3_f32 v162, v162, v76, v77
	v_max3_f32 v162, v162, v78, v79
	s_waitcnt lgkmcnt(0)
	v_mfma_f32_32x32x16_bf16 v[18:33], v[172:175], v[242:245], v[18:33]
	v_max3_f32 v162, v162, v80, v81
	v_mov_b32_e32 v163, v162
	s_nop 1
	v_permlane32_swap_b32_e32 v162, v163
	v_max_f32_e32 v163, v163, v163
	v_max_f32_e32 v162, v162, v162
	v_max_f32_e32 v162, v162, v163
	v_sub_f32_e32 v163, v162, v170
	v_cmp_ge_f32_e32 vcc, s63, v163
	v_max_f32_e32 v163, v170, v170
	v_max_f32_e32 v162, v163, v162
	v_mfma_f32_32x32x16_bf16 v[18:33], v[230:233], v[246:249], v[18:33]
	v_sub_f32_e32 v163, v170, v162
	v_mul_f32_e32 v163, 0x3e0293ee, v163
	v_exp_f32_e32 v163, v163
	s_cmp_eq_u64 vcc, exec
	s_cselect_b64 s[8:9], -1, 0
	s_waitcnt vmcnt(4)
	v_cndmask_b32_e64 v229, v163, 1.0, s[8:9]
	v_cmp_gt_f32_e32 vcc, 1.0, v229
	s_cbranch_vccz .LBB0_1047
	s_and_saveexec_b64 s[2:3], s[6:7]
	ds_write_b32 v210, v229 offset:128
	s_or_b64 exec, exec, s[2:3]
	s_waitcnt lgkmcnt(0)
	v_add_u32_e32 v163, s15, v209
	ds_read_b128 v[164:167], v163 offset:224
	ds_read_b128 v[172:175], v163 offset:192
	ds_read_b128 v[230:233], v163 offset:160
	ds_read_b128 v[234:237], v163 offset:128
	s_waitcnt lgkmcnt(3)
	v_pk_mul_f32 v[14:15], v[14:15], v[164:165]
	s_waitcnt lgkmcnt(2)
	v_pk_mul_f32 v[10:11], v[10:11], v[172:173]
	s_waitcnt lgkmcnt(1)
	v_pk_mul_f32 v[6:7], v[6:7], v[230:231]
	v_pk_mul_f32 v[16:17], v[16:17], v[166:167]
	v_pk_mul_f32 v[12:13], v[12:13], v[174:175]
	v_pk_mul_f32 v[8:9], v[8:9], v[232:233]
	s_waitcnt lgkmcnt(0)
	v_pk_mul_f32 v[4:5], v[4:5], v[236:237]
	v_pk_mul_f32 v[2:3], v[2:3], v[234:235]
	v_pk_mul_f32 v[62:63], v[62:63], v[164:165]
	v_pk_mul_f32 v[58:59], v[58:59], v[172:173]
	v_pk_mul_f32 v[54:55], v[54:55], v[230:231]
	v_pk_mul_f32 v[64:65], v[64:65], v[166:167]
	v_pk_mul_f32 v[60:61], v[60:61], v[174:175]
	v_pk_mul_f32 v[56:57], v[56:57], v[232:233]
	v_pk_mul_f32 v[52:53], v[52:53], v[236:237]
	v_pk_mul_f32 v[50:51], v[50:51], v[234:235]
	v_pk_mul_f32 v[46:47], v[46:47], v[164:165]
	v_pk_mul_f32 v[42:43], v[42:43], v[172:173]
	v_pk_mul_f32 v[38:39], v[38:39], v[230:231]
	v_pk_mul_f32 v[48:49], v[48:49], v[166:167]
	v_pk_mul_f32 v[44:45], v[44:45], v[174:175]
	v_pk_mul_f32 v[40:41], v[40:41], v[232:233]
	v_pk_mul_f32 v[36:37], v[36:37], v[236:237]
	v_pk_mul_f32 v[34:35], v[34:35], v[234:235]
	v_pk_mul_f32 v[30:31], v[30:31], v[164:165]
	v_pk_mul_f32 v[26:27], v[26:27], v[172:173]
	v_pk_mul_f32 v[22:23], v[22:23], v[230:231]
	v_pk_mul_f32 v[32:33], v[32:33], v[166:167]
	v_pk_mul_f32 v[28:29], v[28:29], v[174:175]
	v_pk_mul_f32 v[24:25], v[24:25], v[232:233]
	v_pk_mul_f32 v[20:21], v[20:21], v[236:237]
	v_pk_mul_f32 v[18:19], v[18:19], v[234:235]

; #define SBAR() __builtin_amdgcn_sched_barrier(0)
; __device__ __forceinline__ void partialSM(f32x16& p0, f32x16& p1, float& m_reg, float& mn, float& alpha) {
;   constexpr float C = SCALE * 1.4426950408889634f;
;   float pmax = p0[0];
; #pragma unroll
;   for (int r = 1; r < 16; ++r) pmax = fmaxf(pmax, p0[r]);
; #pragma unroll
;   for (int r = 0; r < 16; ++r) pmax = fmaxf(pmax, p1[r]);
;   { auto rr = __builtin_amdgcn_permlane32_swap(__float_as_uint(pmax), __float_as_uint(pmax), false, false);
;     pmax = fmaxf(__uint_as_float(rr[0]), __uint_as_float(rr[1])); }
;   if (__builtin_expect(__all(pmax - m_reg <= THR / SCALE), 1)) { mn = m_reg; alpha = 1.f; }
;   else { mn = fmaxf(m_reg, pmax); alpha = __builtin_amdgcn_exp2f((m_reg - mn) * C); m_reg = mn; }
; template <int D0> __device__ __forceinline__ void pv_one(f32x16& od, int vb, bf16x8 pa0, bf16x8 pa1, bf16x8 pa2, bf16x8 pa3) {
;   const s16x4 l0 = tr_read<v_rd_off(D0, 0, 0)>(vb), h0 = tr_read<v_rd_off(D0, 0, 1)>(vb), l1 = tr_read<v_rd_off(D0, 1, 0)>(vb), h1 = tr_read<v_rd_off(D0, 1, 1)>(vb);
;   const s16x4 l2 = tr_read<v_rd_off(D0, 2, 0)>(vb), h2 = tr_read<v_rd_off(D0, 2, 1)>(vb), l3 = tr_read<v_rd_off(D0, 3, 0)>(vb), h3 = tr_read<v_rd_off(D0, 3, 1)>(vb);
;   asm volatile("s_waitcnt lgkmcnt(0)" ::: "memory"); SBAR();
;     ...
;   od = __builtin_amdgcn_mfma_f32_32x32x16_bf16(pa0, PK(l0, h0), od, 0, 0, 0);
;   od = __builtin_amdgcn_mfma_f32_32x32x16_bf16(pa1, PK(l1, h1), od, 0, 0, 0);
;   od = __builtin_amdgcn_mfma_f32_32x32x16_bf16(pa2, PK(l2, h2), od, 0, 0, 0);
;   od = __builtin_amdgcn_mfma_f32_32x32x16_bf16(pa3, PK(l3, h3), od, 0, 0, 0);
;     ...
; }
; __device__ __forceinline__ void pv_d0(f32x16* o, int vb, bf16x8 pa0, bf16x8 pa1, bf16x8 pa2, bf16x8 pa3) {
;   pv_one<0>(o[0], vb, pa0, pa1, pa2, pa3); pv_one<1>(o[1], vb, pa0, pa1, pa2, pa3); pv_one<2>(o[2], vb, pa0, pa1, pa2, pa3); pv_one<3>(o[3], vb, pa0, pa1, pa2, pa3);
.LBB0_1049:
	ds_read_b64_tr_b16 v[186:187], v212 offset:0
	ds_read_b64_tr_b16 v[188:189], v212 offset:0x800
	ds_read_b64_tr_b16 v[194:195], v212 offset:0x1000
	ds_read_b64_tr_b16 v[196:197], v212 offset:0x1800
	ds_read_b64_tr_b16 v[234:235], v212 offset:0x2000
	ds_read_b64_tr_b16 v[236:237], v212 offset:0x2800
	ds_read_b64_tr_b16 v[238:239], v212 offset:0x3000
	ds_read_b64_tr_b16 v[240:241], v212 offset:0x3800
	s_waitcnt lgkmcnt(4)
	s_nop 0
	v_mfma_f32_32x32x16_bf16 v[2:17], v[162:165], v[186:189], v[2:17]
	ds_read_b64_tr_b16 v[186:187], v212 offset:0x200
	ds_read_b64_tr_b16 v[188:189], v212 offset:0xa00
	v_mfma_f32_32x32x16_bf16 v[2:17], v[166:169], v[194:197], v[2:17]
	ds_read_b64_tr_b16 v[194:195], v212 offset:0x1200
	ds_read_b64_tr_b16 v[196:197], v212 offset:0x1a00
	s_waitcnt lgkmcnt(4)
	v_mfma_f32_32x32x16_bf16 v[2:17], v[170:173], v[234:237], v[2:17]
	ds_read_b64_tr_b16 v[234:235], v212 offset:0x2200
	ds_read_b64_tr_b16 v[236:237], v212 offset:0x2a00
	v_mfma_f32_32x32x16_bf16 v[2:17], v[174:177], v[238:241], v[2:17]
	ds_read_b64_tr_b16 v[238:239], v212 offset:0x3200
	ds_read_b64_tr_b16 v[240:241], v212 offset:0x3a00
	s_waitcnt lgkmcnt(4)
	v_mfma_f32_32x32x16_bf16 v[50:65], v[162:165], v[186:189], v[50:65]
	ds_read_b64_tr_b16 v[186:187], v212 offset:0x400
	ds_read_b64_tr_b16 v[188:189], v212 offset:0xc00
	v_mfma_f32_32x32x16_bf16 v[50:65], v[166:169], v[194:197], v[50:65]
	ds_read_b64_tr_b16 v[194:195], v212 offset:0x1400
	ds_read_b64_tr_b16 v[196:197], v212 offset:0x1c00
	s_waitcnt lgkmcnt(4)
	v_mfma_f32_32x32x16_bf16 v[50:65], v[170:173], v[234:237], v[50:65]
	ds_read_b64_tr_b16 v[234:235], v212 offset:0x2400
	ds_read_b64_tr_b16 v[236:237], v212 offset:0x2c00
	v_mfma_f32_32x32x16_bf16 v[50:65], v[174:177], v[238:241], v[50:65]
	ds_read_b64_tr_b16 v[238:239], v212 offset:0x3400
	ds_read_b64_tr_b16 v[240:241], v212 offset:0x3c00
	s_waitcnt lgkmcnt(4)
	v_mfma_f32_32x32x16_bf16 v[34:49], v[162:165], v[186:189], v[34:49]
	ds_read_b64_tr_b16 v[186:187], v212 offset:0x600
	ds_read_b64_tr_b16 v[188:189], v212 offset:0xe00
	v_mfma_f32_32x32x16_bf16 v[34:49], v[166:169], v[194:197], v[34:49]
	ds_read_b64_tr_b16 v[194:195], v212 offset:0x1600
	ds_read_b64_tr_b16 v[196:197], v212 offset:0x1e00
	s_waitcnt lgkmcnt(4)
	v_mfma_f32_32x32x16_bf16 v[34:49], v[170:173], v[234:237], v[34:49]
	ds_read_b64_tr_b16 v[234:235], v212 offset:0x2600
	ds_read_b64_tr_b16 v[236:237], v212 offset:0x2e00
	v_mfma_f32_32x32x16_bf16 v[34:49], v[174:177], v[238:241], v[34:49]
	ds_read_b64_tr_b16 v[238:239], v212 offset:0x3600
	ds_read_b64_tr_b16 v[240:241], v212 offset:0x3e00
	s_waitcnt lgkmcnt(4)
	v_mfma_f32_32x32x16_bf16 v[18:33], v[162:165], v[186:189], v[18:33]
	v_max_f32_e32 v162, v83, v83
	v_max_f32_e32 v163, v82, v82
	v_max_f32_e32 v162, v163, v162
	v_max3_f32 v162, v162, v84, v85
	v_max3_f32 v162, v162, v86, v87
	v_max3_f32 v162, v162, v88, v89
	v_max3_f32 v162, v162, v90, v91
	v_max3_f32 v162, v162, v92, v93
	v_max3_f32 v162, v162, v94, v95
	v_mfma_f32_32x32x16_bf16 v[18:33], v[166:169], v[194:197], v[18:33]
	v_max3_f32 v162, v162, v96, v97
	v_max3_f32 v162, v162, v66, v67
	v_max3_f32 v162, v162, v68, v69
	v_max3_f32 v162, v162, v70, v71
	v_max3_f32 v162, v162, v72, v73
	v_max3_f32 v162, v162, v74, v75
	v_max3_f32 v162, v162, v76, v77
	v_max3_f32 v162, v162, v78, v79
	s_waitcnt lgkmcnt(0)
	v_mfma_f32_32x32x16_bf16 v[18:33], v[170:173], v[234:237], v[18:33]
	v_max3_f32 v162, v162, v80, v81
	v_mov_b32_e32 v163, v162
	s_nop 1
	v_permlane32_swap_b32_e32 v162, v163
	v_max_f32_e32 v163, v163, v163
	v_max_f32_e32 v162, v162, v162
	v_max_f32_e32 v162, v162, v163
	v_sub_f32_e32 v163, v162, v230
	v_cmp_ge_f32_e32 vcc, s63, v163
	v_max_f32_e32 v163, v230, v230
	v_max_f32_e32 v163, v163, v162
	v_mfma_f32_32x32x16_bf16 v[18:33], v[174:177], v[238:241], v[18:33]
	v_sub_f32_e32 v162, v230, v163
	v_mul_f32_e32 v162, 0x3e0293ee, v162
	v_exp_f32_e32 v162, v162
	s_cmp_eq_u64 vcc, exec
	s_cselect_b64 s[8:9], -1, 0
	s_waitcnt vmcnt(4)
	v_cndmask_b32_e64 v162, v162, 1.0, s[8:9]
	v_cmp_gt_f32_e32 vcc, 1.0, v162
	s_cbranch_vccz .LBB0_1053
	s_and_saveexec_b64 s[4:5], s[6:7]
	ds_write_b32 v210, v162 offset:128
	s_or_b64 exec, exec, s[4:5]
	s_waitcnt lgkmcnt(0)
	v_add_u32_e32 v158, s15, v209
	ds_read_b128 v[146:149], v158 offset:224
	ds_read_b128 v[150:153], v158 offset:192
	ds_read_b128 v[154:157], v158 offset:160
	ds_read_b128 v[158:161], v158 offset:128
	s_waitcnt lgkmcnt(3)
	v_pk_mul_f32 v[14:15], v[14:15], v[146:147]
	s_waitcnt lgkmcnt(2)
	v_pk_mul_f32 v[10:11], v[10:11], v[150:151]
	s_waitcnt lgkmcnt(1)
	v_pk_mul_f32 v[6:7], v[6:7], v[154:155]
	v_pk_mul_f32 v[16:17], v[16:17], v[148:149]
	v_pk_mul_f32 v[12:13], v[12:13], v[152:153]
	v_pk_mul_f32 v[8:9], v[8:9], v[156:157]
	s_waitcnt lgkmcnt(0)
	v_pk_mul_f32 v[4:5], v[4:5], v[160:161]
	v_pk_mul_f32 v[2:3], v[2:3], v[158:159]
	v_pk_mul_f32 v[62:63], v[62:63], v[146:147]
	v_pk_mul_f32 v[58:59], v[58:59], v[150:151]
	v_pk_mul_f32 v[54:55], v[54:55], v[154:155]
	v_pk_mul_f32 v[64:65], v[64:65], v[148:149]
	v_pk_mul_f32 v[60:61], v[60:61], v[152:153]
	v_pk_mul_f32 v[56:57], v[56:57], v[156:157]
	v_pk_mul_f32 v[52:53], v[52:53], v[160:161]
	v_pk_mul_f32 v[50:51], v[50:51], v[158:159]
	v_pk_mul_f32 v[46:47], v[46:47], v[146:147]
	v_pk_mul_f32 v[42:43], v[42:43], v[150:151]
	v_pk_mul_f32 v[38:39], v[38:39], v[154:155]
	v_pk_mul_f32 v[48:49], v[48:49], v[148:149]
	v_pk_mul_f32 v[44:45], v[44:45], v[152:153]
	v_pk_mul_f32 v[40:41], v[40:41], v[156:157]
	v_pk_mul_f32 v[36:37], v[36:37], v[160:161]
	v_pk_mul_f32 v[34:35], v[34:35], v[158:159]
	v_pk_mul_f32 v[30:31], v[30:31], v[146:147]
	v_pk_mul_f32 v[26:27], v[26:27], v[150:151]
	v_pk_mul_f32 v[22:23], v[22:23], v[154:155]
	v_pk_mul_f32 v[32:33], v[32:33], v[148:149]
	v_pk_mul_f32 v[28:29], v[28:29], v[152:153]
	v_pk_mul_f32 v[24:25], v[24:25], v[156:157]
	v_pk_mul_f32 v[20:21], v[20:21], v[160:161]
	v_pk_mul_f32 v[18:19], v[18:19], v[158:159]

; __device__ __forceinline__ void finishSM(f32x16& p0, f32x16& p1, float alpha, float& l_reg, bf16x8& pa0, bf16x8& pa1, bf16x8& pa2, bf16x8& pa3) {
; #pragma unroll
;   for (int r = 0; r < 16; ++r) p1[r] = __builtin_amdgcn_exp2f(p1[r]);
;   float ps = 0;
; #pragma unroll
;   for (int r = 0; r < 16; ++r) ps += p0[r];
; #pragma unroll
;   for (int r = 0; r < 16; ++r) ps += p1[r];
;   { auto rr = __builtin_amdgcn_permlane32_swap(__float_as_uint(ps), __float_as_uint(ps), false, false);
;     ps = __uint_as_float(rr[0]) + __uint_as_float(rr[1]); }
;   l_reg = l_reg * alpha + ps;
;   PK4(p0, 0, pa0); PK4(p0, 8, pa1); PK4(p1, 0, pa2); PK4(p1, 8, pa3);
; }
;   p0 = f32x16{}; p1 = f32x16{};
; #pragma unroll
;   for (int d0 = DLO; d0 < DHI; ++d0) { int cb = (d0 * 16 + hi * 8) * 2;
;     bf16x8 b0 = *reinterpret_cast<const bf16x8*>((const char*)Ks + KSWZ(r32, cb));
;     bf16x8 b1 = *reinterpret_cast<const bf16x8*>((const char*)Ks + KSWZ(32 + r32, cb));
;     p0 = __builtin_amdgcn_mfma_f32_32x32x16_bf16(b0, qr[d0], p0, 0, 0, 0);
;     p1 = __builtin_amdgcn_mfma_f32_32x32x16_bf16(b1, qr[d0], p1, 0, 0, 0); }
; }
; __device__ __forceinline__ int v_st(int k, int c) { const int kk = (k & ~0xC) | ((k & 4) << 1) | ((k & 8) >> 1); return ((kk >> 3) * 4 + (c >> 5)) * 512 + ((kk & 7) * 32 + (c & 31)) * 2; }
; __device__ __forceinline__ int v_rd_base(int lane) { return ((lane & 3) << 3) | (((lane >> 2) & 3) << 6) | (((lane >> 4) & 1) << 5) | (((lane >> 5) & 1) << 8); }
; template <int OFF> __device__ __forceinline__ s16x4 tr_read(int vb) {
;   s16x4 r; asm volatile("ds_read_b64_tr_b16 %0, %1 offset:%2" : "=&v"(r) : "v"(vb), "i"(OFF) : "memory"); return r;
; }
; template <int D0> __device__ __forceinline__ void pv_one(f32x16& od, int vb, bf16x8 pa0, bf16x8 pa1, bf16x8 pa2, bf16x8 pa3) {
;   const s16x4 l0 = tr_read<v_rd_off(D0, 0, 0)>(vb), h0 = tr_read<v_rd_off(D0, 0, 1)>(vb), l1 = tr_read<v_rd_off(D0, 1, 0)>(vb), h1 = tr_read<v_rd_off(D0, 1, 1)>(vb);
;   const s16x4 l2 = tr_read<v_rd_off(D0, 2, 0)>(vb), h2 = tr_read<v_rd_off(D0, 2, 1)>(vb), l3 = tr_read<v_rd_off(D0, 3, 0)>(vb), h3 = tr_read<v_rd_off(D0, 3, 1)>(vb);
;   asm volatile("s_waitcnt lgkmcnt(0)" ::: "memory"); SBAR();
;     ...
;   od = __builtin_amdgcn_mfma_f32_32x32x16_bf16(pa0, PK(l0, h0), od, 0, 0, 0);
;   od = __builtin_amdgcn_mfma_f32_32x32x16_bf16(pa1, PK(l1, h1), od, 0, 0, 0);
.LBB0_1055:
	ds_read_b128 v[66:69], v218 offset:49152
	ds_read_b128 v[70:73], v218 offset:57344
	v_add_f32_e32 v0, 0, v177
	v_add_f32_e32 v0, v195, v0
	v_add_f32_e32 v0, v163, v0
	s_waitcnt lgkmcnt(1)
	v_mfma_f32_32x32x16_bf16 v[82:97], v[66:69], v[118:121], 0
	v_add_f32_e32 v0, v194, v0
	v_add_f32_e32 v0, v164, v0
	v_add_f32_e32 v0, v176, v0
	v_add_f32_e32 v0, v165, v0
	v_add_f32_e32 v0, v175, v0
	v_add_f32_e32 v0, v166, v0
	v_add_f32_e32 v0, v174, v0
	s_waitcnt lgkmcnt(0)
	v_mfma_f32_32x32x16_bf16 v[66:81], v[70:73], v[118:121], 0
	ds_read_b128 v[118:121], v225 offset:49152
	ds_read_b128 v[130:133], v225 offset:57344
	v_add_f32_e32 v0, v167, v0
	v_add_f32_e32 v0, v173, v0
	v_add_f32_e32 v0, v168, v0
	v_add_f32_e32 v0, v172, v0
	v_add_f32_e32 v0, v169, v0
	v_add_f32_e32 v0, v171, v0
	s_waitcnt lgkmcnt(1)
	v_mfma_f32_32x32x16_bf16 v[82:97], v[118:121], v[110:113], v[82:97]
	s_waitcnt lgkmcnt(0)
	v_mfma_f32_32x32x16_bf16 v[66:81], v[130:133], v[110:113], v[66:81]
	ds_read_b128 v[110:113], v224 offset:49152
	ds_read_b128 v[118:121], v224 offset:57344
	s_waitcnt lgkmcnt(1)
	v_mfma_f32_32x32x16_bf16 v[82:97], v[110:113], v[126:129], v[82:97]
	s_waitcnt lgkmcnt(0)
	v_mfma_f32_32x32x16_bf16 v[66:81], v[118:121], v[126:129], v[66:81]
	ds_read_b128 v[110:113], v222 offset:49152
	ds_read_b128 v[118:121], v222 offset:57344
	s_waitcnt lgkmcnt(1)
	v_mfma_f32_32x32x16_bf16 v[82:97], v[110:113], v[122:125], v[82:97]
	s_waitcnt lgkmcnt(0)
	v_mfma_f32_32x32x16_bf16 v[66:81], v[118:121], v[122:125], v[66:81]
	ds_read_b128 v[110:113], v220 offset:49152
	ds_read_b128 v[118:121], v220 offset:57344
	v_exp_f32_e32 v122, v153
	s_waitcnt lgkmcnt(1)
	v_mfma_f32_32x32x16_bf16 v[82:97], v[110:113], v[114:117], v[82:97]
	s_waitcnt lgkmcnt(0)
	v_mfma_f32_32x32x16_bf16 v[66:81], v[118:121], v[114:117], v[66:81]
	ds_read_b128 v[110:113], v219 offset:49152
	ds_read_b128 v[114:117], v219 offset:57344
	v_exp_f32_e32 v118, v161
	v_exp_f32_e32 v119, v154
	v_exp_f32_e32 v120, v155
	v_exp_f32_e32 v121, v152
	s_waitcnt lgkmcnt(1)
	v_mfma_f32_32x32x16_bf16 v[82:97], v[110:113], v[106:109], v[82:97]
	s_waitcnt lgkmcnt(0)
	v_mfma_f32_32x32x16_bf16 v[66:81], v[114:117], v[106:109], v[66:81]
	ds_read_b128 v[106:109], v221 offset:49152
	ds_read_b128 v[110:113], v221 offset:57344
	v_exp_f32_e32 v114, v149
	v_exp_f32_e32 v115, v146
	v_exp_f32_e32 v116, v147
	v_exp_f32_e32 v117, v160
	s_waitcnt lgkmcnt(1)
	v_mfma_f32_32x32x16_bf16 v[82:97], v[106:109], v[102:105], v[82:97]
	s_waitcnt lgkmcnt(0)
	v_mfma_f32_32x32x16_bf16 v[66:81], v[110:113], v[102:105], v[66:81]
	ds_read_b128 v[102:105], v223 offset:49152
	ds_read_b128 v[106:109], v223 offset:57344
	v_exp_f32_e32 v110, v157
	v_exp_f32_e32 v111, v150
	v_exp_f32_e32 v112, v151
	v_exp_f32_e32 v113, v148
	s_waitcnt lgkmcnt(1)
	v_mfma_f32_32x32x16_bf16 v[82:97], v[102:105], v[98:101], v[82:97]
	s_waitcnt lgkmcnt(0)
	v_mfma_f32_32x32x16_bf16 v[66:81], v[106:109], v[98:101], v[66:81]
	v_exp_f32_e32 v99, v158
	v_exp_f32_e32 v108, v159
	v_exp_f32_e32 v109, v156
	v_cvt_pk_bf16_f32 v100, v177, v195
	v_add_f32_e32 v0, v99, v0
	v_add_f32_e32 v0, v108, v0
	v_add_f32_e32 v0, v109, v0
	v_add_f32_e32 v0, v110, v0
	v_add_f32_e32 v0, v111, v0
	v_add_f32_e32 v0, v112, v0
	v_add_f32_e32 v0, v113, v0
	v_add_f32_e32 v0, v114, v0
	v_add_f32_e32 v0, v115, v0
	v_add_f32_e32 v0, v116, v0
	v_add_f32_e32 v0, v117, v0
	v_add_f32_e32 v0, v118, v0
	v_add_f32_e32 v0, v119, v0
	v_add_f32_e32 v0, v120, v0
	v_add_f32_e32 v0, v121, v0
	v_add_f32_e32 v0, v122, v0
	v_mov_b32_e32 v98, v0
	v_cvt_pk_bf16_f32 v101, v163, v194
	v_cvt_pk_bf16_f32 v102, v164, v176
	s_nop 1
	v_permlane32_swap_b32_e32 v0, v98
	v_cvt_pk_bf16_f32 v103, v165, v175
	v_permlane32_swap_b32_e32 v100, v102
	v_cvt_pk_bf16_f32 v104, v166, v174
	v_cvt_pk_bf16_f32 v105, v167, v173
	v_cvt_pk_bf16_f32 v106, v168, v172
	v_cvt_pk_bf16_f32 v107, v169, v171
	v_cvt_pk_bf16_f32 v108, v99, v108
	v_cvt_pk_bf16_f32 v109, v109, v110
	v_cvt_pk_bf16_f32 v110, v111, v112
	v_cvt_pk_bf16_f32 v111, v113, v114
	v_cvt_pk_bf16_f32 v112, v115, v116
	v_cvt_pk_bf16_f32 v113, v117, v118
	v_cvt_pk_bf16_f32 v114, v119, v120
	v_cvt_pk_bf16_f32 v115, v121, v122
	v_permlane32_swap_b32_e32 v101, v103
	v_permlane32_swap_b32_e32 v104, v106
	v_permlane32_swap_b32_e32 v105, v107
	v_permlane32_swap_b32_e32 v108, v110
	v_permlane32_swap_b32_e32 v109, v111
	v_permlane32_swap_b32_e32 v112, v114
	v_permlane32_swap_b32_e32 v113, v115
	ds_read_b64_tr_b16 v[116:117], v213 offset:0
	ds_read_b64_tr_b16 v[118:119], v213 offset:0x800
	ds_read_b64_tr_b16 v[120:121], v213 offset:0x1000
	ds_read_b64_tr_b16 v[122:123], v213 offset:0x1800
	ds_read_b64_tr_b16 v[124:125], v213 offset:0x2000
	ds_read_b64_tr_b16 v[126:127], v213 offset:0x2800
	ds_read_b64_tr_b16 v[128:129], v213 offset:0x3000
	ds_read_b64_tr_b16 v[130:131], v213 offset:0x3800
	s_waitcnt lgkmcnt(4)
	s_nop 0
	v_mfma_f32_32x32x16_bf16 v[2:17], v[100:103], v[116:119], v[2:17]
	ds_read_b64_tr_b16 v[116:117], v213 offset:0x200
	ds_read_b64_tr_b16 v[118:119], v213 offset:0xa00
	v_mfma_f32_32x32x16_bf16 v[2:17], v[104:107], v[120:123], v[2:17]
	ds_read_b64_tr_b16 v[120:121], v213 offset:0x1200
	ds_read_b64_tr_b16 v[122:123], v213 offset:0x1a00
	s_waitcnt lgkmcnt(4)
	v_mfma_f32_32x32x16_bf16 v[2:17], v[108:111], v[124:127], v[2:17]
	ds_read_b64_tr_b16 v[124:125], v213 offset:0x2200
	ds_read_b64_tr_b16 v[126:127], v213 offset:0x2a00
	v_mfma_f32_32x32x16_bf16 v[2:17], v[112:115], v[128:131], v[2:17]
	ds_read_b64_tr_b16 v[128:129], v213 offset:0x3200
	ds_read_b64_tr_b16 v[130:131], v213 offset:0x3a00
	s_waitcnt lgkmcnt(4)
; #define SBAR() __builtin_amdgcn_sched_barrier(0)
; __device__ __forceinline__ void partialSM(f32x16& p0, f32x16& p1, float& m_reg, float& mn, float& alpha) {
;   constexpr float C = SCALE * 1.4426950408889634f;
;   float pmax = p0[0];
; #pragma unroll
;   for (int r = 1; r < 16; ++r) pmax = fmaxf(pmax, p0[r]);
; #pragma unroll
;   for (int r = 0; r < 16; ++r) pmax = fmaxf(pmax, p1[r]);
;   { auto rr = __builtin_amdgcn_permlane32_swap(__float_as_uint(pmax), __float_as_uint(pmax), false, false);
;     pmax = fmaxf(__uint_as_float(rr[0]), __uint_as_float(rr[1])); }
;   if (__builtin_expect(__all(pmax - m_reg <= THR / SCALE), 1)) { mn = m_reg; alpha = 1.f; }
;   else { mn = fmaxf(m_reg, pmax); alpha = __builtin_amdgcn_exp2f((m_reg - mn) * C); m_reg = mn; }
; template <int D0> __device__ __forceinline__ void pv_one(f32x16& od, int vb, bf16x8 pa0, bf16x8 pa1, bf16x8 pa2, bf16x8 pa3) {
;   const s16x4 l0 = tr_read<v_rd_off(D0, 0, 0)>(vb), h0 = tr_read<v_rd_off(D0, 0, 1)>(vb), l1 = tr_read<v_rd_off(D0, 1, 0)>(vb), h1 = tr_read<v_rd_off(D0, 1, 1)>(vb);
;   const s16x4 l2 = tr_read<v_rd_off(D0, 2, 0)>(vb), h2 = tr_read<v_rd_off(D0, 2, 1)>(vb), l3 = tr_read<v_rd_off(D0, 3, 0)>(vb), h3 = tr_read<v_rd_off(D0, 3, 1)>(vb);
;   asm volatile("s_waitcnt lgkmcnt(0)" ::: "memory"); SBAR();
;     ...
;   od = __builtin_amdgcn_mfma_f32_32x32x16_bf16(pa0, PK(l0, h0), od, 0, 0, 0);
;   od = __builtin_amdgcn_mfma_f32_32x32x16_bf16(pa1, PK(l1, h1), od, 0, 0, 0);
;   od = __builtin_amdgcn_mfma_f32_32x32x16_bf16(pa2, PK(l2, h2), od, 0, 0, 0);
;   od = __builtin_amdgcn_mfma_f32_32x32x16_bf16(pa3, PK(l3, h3), od, 0, 0, 0);
;     ...
; }
; __device__ __forceinline__ void pv_d0(f32x16* o, int vb, bf16x8 pa0, bf16x8 pa1, bf16x8 pa2, bf16x8 pa3) {
;   pv_one<0>(o[0], vb, pa0, pa1, pa2, pa3); pv_one<1>(o[1], vb, pa0, pa1, pa2, pa3); pv_one<2>(o[2], vb, pa0, pa1, pa2, pa3); pv_one<3>(o[3], vb, pa0, pa1, pa2, pa3);
	v_mfma_f32_32x32x16_bf16 v[50:65], v[100:103], v[116:119], v[50:65]
	ds_read_b64_tr_b16 v[116:117], v213 offset:0x400
	ds_read_b64_tr_b16 v[118:119], v213 offset:0xc00
	v_mfma_f32_32x32x16_bf16 v[50:65], v[104:107], v[120:123], v[50:65]
	ds_read_b64_tr_b16 v[120:121], v213 offset:0x1400
	ds_read_b64_tr_b16 v[122:123], v213 offset:0x1c00
	s_waitcnt lgkmcnt(4)
	v_mfma_f32_32x32x16_bf16 v[50:65], v[108:111], v[124:127], v[50:65]
	ds_read_b64_tr_b16 v[124:125], v213 offset:0x2400
	ds_read_b64_tr_b16 v[126:127], v213 offset:0x2c00
	v_mfma_f32_32x32x16_bf16 v[50:65], v[112:115], v[128:131], v[50:65]
	ds_read_b64_tr_b16 v[128:129], v213 offset:0x3400
	ds_read_b64_tr_b16 v[130:131], v213 offset:0x3c00
	s_waitcnt lgkmcnt(4)
	v_mfma_f32_32x32x16_bf16 v[34:49], v[100:103], v[116:119], v[34:49]
	ds_read_b64_tr_b16 v[116:117], v213 offset:0x600
	ds_read_b64_tr_b16 v[118:119], v213 offset:0xe00
	v_mfma_f32_32x32x16_bf16 v[34:49], v[104:107], v[120:123], v[34:49]
	ds_read_b64_tr_b16 v[120:121], v213 offset:0x1600
	ds_read_b64_tr_b16 v[122:123], v213 offset:0x1e00
	s_waitcnt lgkmcnt(4)
	v_mfma_f32_32x32x16_bf16 v[34:49], v[108:111], v[124:127], v[34:49]
	ds_read_b64_tr_b16 v[124:125], v213 offset:0x2600
	ds_read_b64_tr_b16 v[126:127], v213 offset:0x2e00
	v_mfma_f32_32x32x16_bf16 v[34:49], v[112:115], v[128:131], v[34:49]
	ds_read_b64_tr_b16 v[128:129], v213 offset:0x3600
	ds_read_b64_tr_b16 v[130:131], v213 offset:0x3e00
	s_waitcnt lgkmcnt(4)
	v_mfma_f32_32x32x16_bf16 v[18:33], v[100:103], v[116:119], v[18:33]
	v_max_f32_e32 v99, v83, v83
	v_max_f32_e32 v100, v82, v82
	v_max_f32_e32 v99, v100, v99
	v_max3_f32 v99, v99, v84, v85
	v_max3_f32 v99, v99, v86, v87
	v_max3_f32 v99, v99, v88, v89
	v_max3_f32 v99, v99, v90, v91
	v_max3_f32 v99, v99, v92, v93
	v_max3_f32 v99, v99, v94, v95
	v_mfma_f32_32x32x16_bf16 v[18:33], v[104:107], v[120:123], v[18:33]
	v_max3_f32 v99, v99, v96, v97
	v_max3_f32 v99, v99, v66, v67
	v_max3_f32 v99, v99, v68, v69
	v_max3_f32 v99, v99, v70, v71
	v_max3_f32 v99, v99, v72, v73
	v_max3_f32 v99, v99, v74, v75
	v_max3_f32 v99, v99, v76, v77
	v_max3_f32 v99, v99, v78, v79
	s_waitcnt lgkmcnt(0)
	v_mfma_f32_32x32x16_bf16 v[18:33], v[108:111], v[124:127], v[18:33]
	v_max3_f32 v99, v99, v80, v81
	v_mov_b32_e32 v100, v99
	s_nop 1
	v_permlane32_swap_b32_e32 v99, v100
	v_max_f32_e32 v100, v100, v100
	v_max_f32_e32 v99, v99, v99
	v_max_f32_e32 v99, v99, v100
	v_sub_f32_e32 v100, v99, v170
	v_cmp_ge_f32_e32 vcc, s63, v100
	v_max_f32_e32 v100, v170, v170
	v_max_f32_e32 v100, v100, v99
	v_mfma_f32_32x32x16_bf16 v[18:33], v[112:115], v[128:131], v[18:33]
	v_sub_f32_e32 v99, v170, v100
	v_mul_f32_e32 v99, 0x3e0293ee, v99
	v_exp_f32_e32 v99, v99
	s_cmp_eq_u64 vcc, exec
	s_cselect_b64 s[8:9], -1, 0
	v_cndmask_b32_e64 v99, v99, 1.0, s[8:9]
	v_cmp_gt_f32_e32 vcc, 1.0, v99
	s_barrier
	s_cbranch_vccz .LBB0_1059
	s_and_saveexec_b64 s[2:3], s[6:7]
	ds_write_b32 v210, v99 offset:128
	s_or_b64 exec, exec, s[2:3]
	s_waitcnt lgkmcnt(0)
	v_add_u32_e32 v101, s15, v209
	ds_read_b128 v[102:105], v101 offset:224
	ds_read_b128 v[106:109], v101 offset:192
	ds_read_b128 v[110:113], v101 offset:160
	ds_read_b128 v[114:117], v101 offset:128
	s_waitcnt lgkmcnt(3)
	v_pk_mul_f32 v[14:15], v[14:15], v[102:103]
	s_waitcnt lgkmcnt(2)
	v_pk_mul_f32 v[10:11], v[10:11], v[106:107]
	s_waitcnt lgkmcnt(1)
	v_pk_mul_f32 v[6:7], v[6:7], v[110:111]
	v_pk_mul_f32 v[16:17], v[16:17], v[104:105]
	v_pk_mul_f32 v[12:13], v[12:13], v[108:109]
	v_pk_mul_f32 v[8:9], v[8:9], v[112:113]
	s_waitcnt lgkmcnt(0)
	v_pk_mul_f32 v[4:5], v[4:5], v[116:117]
	v_pk_mul_f32 v[2:3], v[2:3], v[114:115]
	v_pk_mul_f32 v[62:63], v[62:63], v[102:103]
	v_pk_mul_f32 v[58:59], v[58:59], v[106:107]
	v_pk_mul_f32 v[54:55], v[54:55], v[110:111]
	v_pk_mul_f32 v[64:65], v[64:65], v[104:105]
	v_pk_mul_f32 v[60:61], v[60:61], v[108:109]
	v_pk_mul_f32 v[56:57], v[56:57], v[112:113]
	v_pk_mul_f32 v[52:53], v[52:53], v[116:117]
	v_pk_mul_f32 v[50:51], v[50:51], v[114:115]
	v_pk_mul_f32 v[46:47], v[46:47], v[102:103]
	v_pk_mul_f32 v[42:43], v[42:43], v[106:107]
	v_pk_mul_f32 v[38:39], v[38:39], v[110:111]
	v_pk_mul_f32 v[48:49], v[48:49], v[104:105]
	v_pk_mul_f32 v[44:45], v[44:45], v[108:109]
	v_pk_mul_f32 v[40:41], v[40:41], v[112:113]
	v_pk_mul_f32 v[36:37], v[36:37], v[116:117]
	v_pk_mul_f32 v[34:35], v[34:35], v[114:115]
	v_pk_mul_f32 v[30:31], v[30:31], v[102:103]
	v_pk_mul_f32 v[26:27], v[26:27], v[106:107]
	v_pk_mul_f32 v[22:23], v[22:23], v[110:111]
	v_pk_mul_f32 v[32:33], v[32:33], v[104:105]
	v_pk_mul_f32 v[28:29], v[28:29], v[108:109]
	v_pk_mul_f32 v[24:25], v[24:25], v[112:113]
	v_pk_mul_f32 v[20:21], v[20:21], v[116:117]
	v_pk_mul_f32 v[18:19], v[18:19], v[114:115]
; __device__ __forceinline__ void partialSM(f32x16& p0, f32x16& p1, float& m_reg, float& mn, float& alpha) {
;     ...
;   float mnC = -mn * C;
; #pragma unroll
;   for (int r = 0; r < 16; ++r) p0[r] = fmaf(p0[r], C, mnC);
; #pragma unroll
;   for (int r = 0; r < 16; ++r) p1[r] = fmaf(p1[r], C, mnC);
; #pragma unroll
;   for (int r = 0; r < 16; ++r) p0[r] = __builtin_amdgcn_exp2f(p0[r]);
; }
; __device__ __forceinline__ void finishSM(f32x16& p0, f32x16& p1, float alpha, float& l_reg, bf16x8& pa0, bf16x8& pa1, bf16x8& pa2, bf16x8& pa3) {
; #pragma unroll
;   for (int r = 0; r < 16; ++r) p1[r] = __builtin_amdgcn_exp2f(p1[r]);
;   float ps = 0;
; #pragma unroll
;   for (int r = 0; r < 16; ++r) ps += p0[r];
; #pragma unroll
;   for (int r = 0; r < 16; ++r) ps += p1[r];
;   { auto rr = __builtin_amdgcn_permlane32_swap(__float_as_uint(ps), __float_as_uint(ps), false, false);
;     ps = __uint_as_float(rr[0]) + __uint_as_float(rr[1]); }
;   l_reg = l_reg * alpha + ps;
;   PK4(p0, 0, pa0); PK4(p0, 8, pa1); PK4(p1, 0, pa2); PK4(p1, 8, pa3);
; }
;   p0 = f32x16{}; p1 = f32x16{};
; #pragma unroll
;   for (int d0 = DLO; d0 < DHI; ++d0) { int cb = (d0 * 16 + hi * 8) * 2;
;     bf16x8 b0 = *reinterpret_cast<const bf16x8*>((const char*)Ks + KSWZ(r32, cb));
;     bf16x8 b1 = *reinterpret_cast<const bf16x8*>((const char*)Ks + KSWZ(32 + r32, cb));
;     p0 = __builtin_amdgcn_mfma_f32_32x32x16_bf16(b0, qr[d0], p0, 0, 0, 0);
;     p1 = __builtin_amdgcn_mfma_f32_32x32x16_bf16(b1, qr[d0], p1, 0, 0, 0); }
; }
; __device__ __forceinline__ int v_st(int k, int c) { const int kk = (k & ~0xC) | ((k & 4) << 1) | ((k & 8) >> 1); return ((kk >> 3) * 4 + (c >> 5)) * 512 + ((kk & 7) * 32 + (c & 31)) * 2; }
; __device__ __forceinline__ int v_rd_base(int lane) { return ((lane & 3) << 3) | (((lane >> 2) & 3) << 6) | (((lane >> 4) & 1) << 5) | (((lane >> 5) & 1) << 8); }
; template <int OFF> __device__ __forceinline__ s16x4 tr_read(int vb) {
;   s16x4 r; asm volatile("ds_read_b64_tr_b16 %0, %1 offset:%2" : "=&v"(r) : "v"(vb), "i"(OFF) : "memory"); return r;
; }
; template <int D0> __device__ __forceinline__ void pv_one(f32x16& od, int vb, bf16x8 pa0, bf16x8 pa1, bf16x8 pa2, bf16x8 pa3) {
;   const s16x4 l0 = tr_read<v_rd_off(D0, 0, 0)>(vb), h0 = tr_read<v_rd_off(D0, 0, 1)>(vb), l1 = tr_read<v_rd_off(D0, 1, 0)>(vb), h1 = tr_read<v_rd_off(D0, 1, 1)>(vb);
.LBB0_1059:
	v_cndmask_b32_e64 v100, v100, v170, s[8:9]
	v_mul_f32_e32 v100, 0xbe0293ee, v100
	v_fmamk_f32 v82, v82, 0x3e0293ee, v100
	v_fmamk_f32 v83, v83, 0x3e0293ee, v100
	v_fmamk_f32 v101, v84, 0x3e0293ee, v100
	v_exp_f32_e32 v84, v82
	v_fmamk_f32 v102, v86, 0x3e0293ee, v100
	v_exp_f32_e32 v86, v83
	v_fmamk_f32 v85, v85, 0x3e0293ee, v100
	v_exp_f32_e32 v82, v101
	v_fmamk_f32 v66, v66, 0x3e0293ee, v100
	v_exp_f32_e32 v85, v85
	v_fmamk_f32 v103, v87, 0x3e0293ee, v100
	v_fmamk_f32 v112, v96, 0x3e0293ee, v100
	v_fmamk_f32 v96, v77, 0x3e0293ee, v100
	v_exp_f32_e32 v77, v102
	v_exp_f32_e32 v101, v66
	v_add_f32_e32 v66, 0, v84
	v_fmamk_f32 v104, v88, 0x3e0293ee, v100
	v_exp_f32_e32 v83, v103
	v_add_f32_e32 v66, v86, v66
	v_fmamk_f32 v105, v89, 0x3e0293ee, v100
	v_fmamk_f32 v111, v95, 0x3e0293ee, v100
	v_fmamk_f32 v95, v76, 0x3e0293ee, v100
	v_exp_f32_e32 v76, v104
	v_add_f32_e32 v66, v82, v66
	v_fmamk_f32 v106, v90, 0x3e0293ee, v100
	v_fmamk_f32 v113, v97, 0x3e0293ee, v100
	v_fmamk_f32 v97, v78, 0x3e0293ee, v100
	v_exp_f32_e32 v78, v105
	v_add_f32_e32 v66, v85, v66
	v_fmamk_f32 v107, v91, 0x3e0293ee, v100
	v_fmamk_f32 v108, v92, 0x3e0293ee, v100
	v_fmamk_f32 v92, v73, 0x3e0293ee, v100
	v_exp_f32_e32 v73, v106
	v_add_f32_e32 v66, v77, v66
	v_fmamk_f32 v110, v94, 0x3e0293ee, v100
	v_fmamk_f32 v94, v75, 0x3e0293ee, v100
	v_exp_f32_e32 v75, v107
	v_add_f32_e32 v66, v83, v66
	v_fmamk_f32 v109, v93, 0x3e0293ee, v100
	v_fmamk_f32 v90, v71, 0x3e0293ee, v100
	v_exp_f32_e32 v71, v108
	v_add_f32_e32 v66, v76, v66
	v_fmamk_f32 v93, v74, 0x3e0293ee, v100
	v_exp_f32_e32 v74, v109
	v_add_f32_e32 v66, v78, v66
	v_fmamk_f32 v88, v69, 0x3e0293ee, v100
	v_exp_f32_e32 v69, v110
	v_add_f32_e32 v66, v73, v66
	v_fmamk_f32 v91, v72, 0x3e0293ee, v100
	v_exp_f32_e32 v72, v111
	v_add_f32_e32 v66, v75, v66
	v_fmamk_f32 v87, v68, 0x3e0293ee, v100
	v_exp_f32_e32 v68, v112
	v_add_f32_e32 v66, v71, v66
	v_fmamk_f32 v89, v70, 0x3e0293ee, v100
	v_exp_f32_e32 v70, v113
	v_add_f32_e32 v66, v74, v66
	v_fmamk_f32 v67, v67, 0x3e0293ee, v100
	v_add_f32_e32 v66, v69, v66
	v_exp_f32_e32 v102, v67
	v_add_f32_e32 v66, v72, v66
	v_exp_f32_e32 v87, v87
	v_add_f32_e32 v66, v68, v66
	v_exp_f32_e32 v88, v88
	v_add_f32_e32 v66, v70, v66
	v_exp_f32_e32 v89, v89
	v_add_f32_e32 v66, v101, v66
	v_exp_f32_e32 v90, v90
	v_add_f32_e32 v66, v102, v66
	v_exp_f32_e32 v91, v91
	v_add_f32_e32 v66, v87, v66
	v_exp_f32_e32 v92, v92
	v_add_f32_e32 v66, v88, v66
	v_exp_f32_e32 v93, v93
	v_add_f32_e32 v66, v89, v66
	v_exp_f32_e32 v94, v94
	v_add_f32_e32 v66, v90, v66
	v_exp_f32_e32 v95, v95
	v_add_f32_e32 v66, v91, v66
	v_exp_f32_e32 v96, v96
	v_add_f32_e32 v66, v92, v66
	v_fmamk_f32 v79, v79, 0x3e0293ee, v100
	v_exp_f32_e32 v97, v97
	v_add_f32_e32 v66, v93, v66
	v_fmamk_f32 v80, v80, 0x3e0293ee, v100
	v_exp_f32_e32 v103, v79
	v_add_f32_e32 v66, v94, v66
	v_fmac_f32_e32 v100, 0x3e0293ee, v81
	v_exp_f32_e32 v104, v80
	v_add_f32_e32 v66, v95, v66
	v_exp_f32_e32 v100, v100
	v_add_f32_e32 v66, v96, v66
	v_add_f32_e32 v66, v97, v66
	v_add_f32_e32 v66, v103, v66
	v_add_f32_e32 v66, v104, v66
	v_add_f32_e32 v66, v100, v66
	v_mov_b32_e32 v67, v66
	s_nop 1
	v_permlane32_swap_b32_e32 v66, v67
	v_cvt_pk_bf16_f32 v80, v84, v86
	v_cvt_pk_bf16_f32 v81, v82, v85
	v_cvt_pk_bf16_f32 v82, v77, v83
	v_cvt_pk_bf16_f32 v83, v76, v78
	v_cvt_pk_bf16_f32 v76, v73, v75
	v_cvt_pk_bf16_f32 v77, v71, v74
	v_cvt_pk_bf16_f32 v78, v69, v72
	v_cvt_pk_bf16_f32 v79, v68, v70
	v_cvt_pk_bf16_f32 v68, v101, v102
	v_cvt_pk_bf16_f32 v69, v87, v88
	v_cvt_pk_bf16_f32 v70, v89, v90
	v_cvt_pk_bf16_f32 v71, v91, v92
	v_cvt_pk_bf16_f32 v72, v93, v94
	v_cvt_pk_bf16_f32 v73, v95, v96
	v_cvt_pk_bf16_f32 v74, v97, v103
	v_cvt_pk_bf16_f32 v75, v104, v100
	s_nop 0
	v_permlane32_swap_b32_e32 v80, v82
	v_permlane32_swap_b32_e32 v81, v83
	v_permlane32_swap_b32_e32 v76, v78
	v_permlane32_swap_b32_e32 v77, v79
	v_permlane32_swap_b32_e32 v68, v70
	v_permlane32_swap_b32_e32 v69, v71
	v_permlane32_swap_b32_e32 v72, v74
	v_permlane32_swap_b32_e32 v73, v75
	ds_read_b64_tr_b16 v[84:85], v212 offset:0
	ds_read_b64_tr_b16 v[86:87], v212 offset:0x800
	ds_read_b64_tr_b16 v[88:89], v212 offset:0x1000
	ds_read_b64_tr_b16 v[90:91], v212 offset:0x1800
	ds_read_b64_tr_b16 v[92:93], v212 offset:0x2000
	ds_read_b64_tr_b16 v[94:95], v212 offset:0x2800
	ds_read_b64_tr_b16 v[100:101], v212 offset:0x3000
	ds_read_b64_tr_b16 v[102:103], v212 offset:0x3800
	s_waitcnt lgkmcnt(4)
	s_nop 0
	v_mfma_f32_32x32x16_bf16 v[2:17], v[80:83], v[84:87], v[2:17]
	ds_read_b64_tr_b16 v[84:85], v212 offset:0x200
	ds_read_b64_tr_b16 v[86:87], v212 offset:0xa00
	v_mfma_f32_32x32x16_bf16 v[2:17], v[76:79], v[88:91], v[2:17]
	ds_read_b64_tr_b16 v[88:89], v212 offset:0x1200
	ds_read_b64_tr_b16 v[90:91], v212 offset:0x1a00
	s_waitcnt lgkmcnt(4)
	v_mfma_f32_32x32x16_bf16 v[2:17], v[68:71], v[92:95], v[2:17]
	ds_read_b64_tr_b16 v[92:93], v212 offset:0x2200
	ds_read_b64_tr_b16 v[94:95], v212 offset:0x2a00
	v_mfma_f32_32x32x16_bf16 v[2:17], v[72:75], v[100:103], v[2:17]
	ds_read_b64_tr_b16 v[100:101], v212 offset:0x3200
	ds_read_b64_tr_b16 v[102:103], v212 offset:0x3a00
	s_waitcnt lgkmcnt(4)
	v_mfma_f32_32x32x16_bf16 v[50:65], v[80:83], v[84:87], v[50:65]
	ds_read_b64_tr_b16 v[84:85], v212 offset:0x400
	ds_read_b64_tr_b16 v[86:87], v212 offset:0xc00
	v_mfma_f32_32x32x16_bf16 v[50:65], v[76:79], v[88:91], v[50:65]
	ds_read_b64_tr_b16 v[88:89], v212 offset:0x1400
	ds_read_b64_tr_b16 v[90:91], v212 offset:0x1c00
	s_waitcnt lgkmcnt(4)
	v_mfma_f32_32x32x16_bf16 v[50:65], v[68:71], v[92:95], v[50:65]
	ds_read_b64_tr_b16 v[92:93], v212 offset:0x2400
	ds_read_b64_tr_b16 v[94:95], v212 offset:0x2c00
	v_mfma_f32_32x32x16_bf16 v[50:65], v[72:75], v[100:103], v[50:65]
	ds_read_b64_tr_b16 v[100:101], v212 offset:0x3400
	ds_read_b64_tr_b16 v[102:103], v212 offset:0x3c00
	s_waitcnt lgkmcnt(4)
	v_mfma_f32_32x32x16_bf16 v[34:49], v[80:83], v[84:87], v[34:49]
	ds_read_b64_tr_b16 v[84:85], v212 offset:0x600
	ds_read_b64_tr_b16 v[86:87], v212 offset:0xe00
	v_mfma_f32_32x32x16_bf16 v[34:49], v[76:79], v[88:91], v[34:49]
	ds_read_b64_tr_b16 v[88:89], v212 offset:0x1600
	ds_read_b64_tr_b16 v[90:91], v212 offset:0x1e00
	s_waitcnt lgkmcnt(4)
	v_mfma_f32_32x32x16_bf16 v[34:49], v[68:71], v[92:95], v[34:49]
	ds_read_b64_tr_b16 v[92:93], v212 offset:0x2600
	ds_read_b64_tr_b16 v[94:95], v212 offset:0x2e00
	v_mfma_f32_32x32x16_bf16 v[34:49], v[72:75], v[100:103], v[34:49]
	ds_read_b64_tr_b16 v[100:101], v212 offset:0x3600
	ds_read_b64_tr_b16 v[102:103], v212 offset:0x3e00
	s_waitcnt lgkmcnt(4)
	v_mfma_f32_32x32x16_bf16 v[18:33], v[80:83], v[84:87], v[18:33]
	v_mfma_f32_32x32x16_bf16 v[18:33], v[76:79], v[88:91], v[18:33]
	s_waitcnt lgkmcnt(0)
	v_mfma_f32_32x32x16_bf16 v[18:33], v[68:71], v[92:95], v[18:33]
	v_mfma_f32_32x32x16_bf16 v[18:33], v[72:75], v[100:103], v[18:33]
	s_and_saveexec_b64 s[2:3], s[6:7]
	s_cbranch_execz .LBB0_993
	v_add_f32_e32 v0, v0, v98
	v_fmac_f32_e32 v0, v211, v162
	v_add_f32_e32 v66, v66, v67
	v_fmac_f32_e32 v66, v0, v99
	ds_write_b32 v210, v66
	s_branch .LBB0_993

; __device__ __forceinline__ ItemPos item_load(const XItem* tab, int it, int lane, f32x4 (&v)[16], float (&gv)[16]) {
;     int e = 0;
; #pragma unroll 1
;     for (int q = 1; q < 20; ++q) if (it >= tab[q].start) e = q;
;     const XItem x = tab[e]; const int item = it - x.start;
;     const int nblk = x.N >> 6, kb = item / nblk, nb = item - kb * nblk, k0 = kb << 6, n0 = nb << 6;
;     const int lr = lane >> 4, lc = (lane & 15) * 4;
;     const float* W = x.src + (size_t)(k0 + lr) * x.N + n0 + lc; const size_t rstep = (size_t)4 * x.N;
; #pragma unroll
;     for (int i = 0; i < 16; ++i) v[i] = __builtin_nontemporal_load((const f32x4*)(W + i * rstep));
; #pragma unroll
;     for (int i = 0; i < 16; ++i) gv[i] = x.g ? x.g[k0 + 4 * i + lr] : 1.0f;
;     ItemPos p; p.scaled = (x.g != nullptr); p.WT = x.dst; p.K = x.K; p.k0 = k0; p.rb = (x.mode == 0) ? n0 : ((n0 >> 7) * 256 + (x.mode - 1) * 128 + (n0 & 127));
;     return p;
.LBB0_1373:
	v_mov_b32_e32 v3, s2
	ds_read_b32 v3, v3
	v_mov_b32_e32 v4, s3
	s_add_i32 s3, s3, 1
	s_add_i32 s2, s2, 40
	s_cmp_eq_u32 s3, 20
	s_waitcnt lgkmcnt(0)
	v_cmp_lt_i32_e32 vcc, s15, v3
	s_nop 1
	v_cndmask_b32_e32 v2, v4, v2, vcc
	s_cbranch_scc0 .LBB0_1373
	v_mul_lo_u32 v2, v2, 40
	v_add_u32_e32 v2, 0, v2
	v_add_u32_e32 v10, 0x20800, v2
	ds_read2_b64 v[2:5], v10 offset0:3 offset1:4
	v_mbcnt_lo_u32_b32 v0, -1, v0
	v_mbcnt_hi_u32_b32 v74, -1, v0
	ds_read2_b64 v[6:9], v10 offset1:1
	ds_read_b64 v[76:77], v10 offset:16
	s_waitcnt lgkmcnt(2)
	v_readfirstlane_b32 s4, v3
	s_ashr_i32 s2, s4, 6
	s_abs_i32 s3, s2
	v_cvt_f32_u32_e32 v3, s3
	s_sub_i32 s8, 0, s3
	v_readfirstlane_b32 s5, v5
	s_sub_i32 s5, s15, s5
	v_rcp_iflag_f32_e32 v0, v3
	s_abs_i32 s7, s5
	s_xor_b32 s6, s5, s2
	s_ashr_i32 s6, s6, 31
	v_mul_f32_e32 v0, 0x4f7ffffe, v0
	v_cvt_u32_f32_e32 v0, v0
	v_ashrrev_i32_e32 v3, 4, v74
	v_readfirstlane_b32 s9, v0
	s_mul_i32 s8, s8, s9
	s_mul_hi_u32 s8, s9, s8
	s_add_i32 s9, s9, s8
	s_mul_hi_u32 s8, s7, s9
	s_mul_i32 s9, s8, s3
	s_sub_i32 s7, s7, s9
	s_add_i32 s10, s8, 1
	s_sub_i32 s9, s7, s3
	s_cmp_ge_u32 s7, s3
	s_cselect_b32 s8, s10, s8
	s_cselect_b32 s7, s9, s7
	s_add_i32 s9, s8, 1
	s_cmp_ge_u32 s7, s3
	s_cselect_b32 s3, s9, s8
	s_xor_b32 s3, s3, s6
	s_sub_i32 s3, s3, s6
	s_mul_i32 s2, s3, s2
	s_lshl_b32 s8, s3, 6
	s_sub_i32 s9, s5, s2
	v_add_u32_e32 v78, s8, v3
	s_lshl_b32 s2, s9, 6
	v_lshlrev_b32_e32 v0, 2, v74
	v_mad_i64_i32 v[10:11], s[6:7], v78, s4, 0
	v_and_b32_e32 v5, 60, v0
	s_waitcnt lgkmcnt(1)
	v_lshl_add_u64 v[6:7], v[10:11], 2, v[6:7]
	s_ashr_i32 s3, s2, 31
	s_ashr_i32 s5, s4, 31
	v_lshl_add_u64 v[6:7], s[2:3], 2, v[6:7]
	v_lshlrev_b32_e32 v0, 2, v5
	v_lshl_add_u64 v[6:7], v[6:7], 0, v[0:1]
	s_lshl_b64 s[4:5], s[4:5], 4
	v_lshl_add_u64 v[18:19], v[6:7], 0, s[4:5]
	global_load_dwordx4 v[10:13], v[6:7], off nt
	global_load_dwordx4 v[14:17], v[18:19], off nt
	v_lshl_add_u64 v[6:7], v[18:19], 0, s[4:5]
	v_lshl_add_u64 v[26:27], v[6:7], 0, s[4:5]
	global_load_dwordx4 v[18:21], v[6:7], off nt
	global_load_dwordx4 v[22:25], v[26:27], off nt
	v_lshl_add_u64 v[6:7], v[26:27], 0, s[4:5]
	v_lshl_add_u64 v[34:35], v[6:7], 0, s[4:5]
	global_load_dwordx4 v[26:29], v[6:7], off nt
	global_load_dwordx4 v[30:33], v[34:35], off nt
	v_lshl_add_u64 v[6:7], v[34:35], 0, s[4:5]
	v_lshl_add_u64 v[42:43], v[6:7], 0, s[4:5]
	global_load_dwordx4 v[34:37], v[6:7], off nt
	global_load_dwordx4 v[38:41], v[42:43], off nt
	v_lshl_add_u64 v[6:7], v[42:43], 0, s[4:5]
	global_load_dwordx4 v[42:45], v[6:7], off nt
	v_lshl_add_u64 v[6:7], v[6:7], 0, s[4:5]
	global_load_dwordx4 v[46:49], v[6:7], off nt
	v_lshl_add_u64 v[6:7], v[6:7], 0, s[4:5]
	global_load_dwordx4 v[50:53], v[6:7], off nt
	v_lshl_add_u64 v[6:7], v[6:7], 0, s[4:5]
	global_load_dwordx4 v[54:57], v[6:7], off nt
	v_lshl_add_u64 v[6:7], v[6:7], 0, s[4:5]
	global_load_dwordx4 v[58:61], v[6:7], off nt
	v_lshl_add_u64 v[6:7], v[6:7], 0, s[4:5]
	global_load_dwordx4 v[62:65], v[6:7], off nt
	v_lshl_add_u64 v[6:7], v[6:7], 0, s[4:5]
	global_load_dwordx4 v[66:69], v[6:7], off nt
	v_lshl_add_u64 v[6:7], v[6:7], 0, s[4:5]
	global_load_dwordx4 v[70:73], v[6:7], off nt
	v_ashrrev_i32_e32 v79, 31, v78
	s_waitcnt lgkmcnt(0)
	v_cmp_ne_u64_e64 s[6:7], 0, v[76:77]
	s_and_b64 vcc, exec, s[6:7]
	v_lshl_add_u64 v[6:7], v[78:79], 2, v[76:77]
	s_cbranch_vccz .LBB0_1743
	global_load_dword v76, v[6:7], off
	global_load_dword v77, v[6:7], off offset:16
	v_cndmask_b32_e64 v75, 0, 1, s[6:7]
	v_cmp_ne_u32_e64 s[4:5], 1, v75
	s_andn2_b64 vcc, exec, s[6:7]
	s_cbranch_vccnz .LBB0_1744

; __device__ __forceinline__ ItemPos item_load(const XItem* tab, int it, int lane, f32x4 (&v)[16], float (&gv)[16]) {
;     ...
;     for (int i = 0; i < 16; ++i) gv[i] = x.g ? x.g[k0 + 4 * i + lr] : 1.0f;
.LBB0_1378:
	s_and_b64 vcc, exec, s[4:5]
	s_cbranch_vccnz .LBB0_1745
	global_load_dword v82, v[6:7], off offset:64
	global_load_dword v83, v[6:7], off offset:80
	s_cbranch_execnz .LBB0_1381

; __device__ __forceinline__ ItemPos item_load(const XItem* tab, int it, int lane, f32x4 (&v)[16], float (&gv)[16]) {
;     ...
;     for (int i = 0; i < 16; ++i) gv[i] = x.g ? x.g[k0 + 4 * i + lr] : 1.0f;
.LBB0_1381:
	s_and_b64 vcc, exec, s[4:5]
	s_cbranch_vccnz .LBB0_1746
	global_load_dword v84, v[6:7], off offset:96
	global_load_dword v85, v[6:7], off offset:112
	s_cbranch_execnz .LBB0_1384

; __device__ __forceinline__ ItemPos item_load(const XItem* tab, int it, int lane, f32x4 (&v)[16], float (&gv)[16]) {
;     ...
;     for (int i = 0; i < 16; ++i) gv[i] = x.g ? x.g[k0 + 4 * i + lr] : 1.0f;
.LBB0_1384:
	s_and_b64 vcc, exec, s[4:5]
	s_cbranch_vccnz .LBB0_1747
	global_load_dword v86, v[6:7], off offset:128
	global_load_dword v87, v[6:7], off offset:144
	s_cbranch_execnz .LBB0_1387

; __device__ __forceinline__ ItemPos item_load(const XItem* tab, int it, int lane, f32x4 (&v)[16], float (&gv)[16]) {
;     ...
;     for (int i = 0; i < 16; ++i) gv[i] = x.g ? x.g[k0 + 4 * i + lr] : 1.0f;
.LBB0_1387:
	s_and_b64 vcc, exec, s[4:5]
	s_cbranch_vccnz .LBB0_1748
	global_load_dword v88, v[6:7], off offset:160
	global_load_dword v89, v[6:7], off offset:176
	s_cbranch_execnz .LBB0_1390

; __device__ __forceinline__ ItemPos item_load(const XItem* tab, int it, int lane, f32x4 (&v)[16], float (&gv)[16]) {
;     ...
;     for (int i = 0; i < 16; ++i) gv[i] = x.g ? x.g[k0 + 4 * i + lr] : 1.0f;
.LBB0_1390:
	s_and_b64 vcc, exec, s[4:5]
	s_cbranch_vccnz .LBB0_1749
	global_load_dword v90, v[6:7], off offset:192
	global_load_dword v91, v[6:7], off offset:208
	s_cbranch_execnz .LBB0_1393

; __device__ __forceinline__ ItemPos item_load(const XItem* tab, int it, int lane, f32x4 (&v)[16], float (&gv)[16]) {
;     ...
;     for (int i = 0; i < 16; ++i) gv[i] = x.g ? x.g[k0 + 4 * i + lr] : 1.0f;
.LBB0_1393:
	s_and_b64 vcc, exec, s[4:5]
	s_cbranch_vccnz .LBB0_1750
	global_load_dword v92, v[6:7], off offset:224
	global_load_dword v93, v[6:7], off offset:240
	s_cbranch_execnz .LBB0_1396

; __device__ __forceinline__ ItemPos item_load(const XItem* tab, int it, int lane, f32x4 (&v)[16], float (&gv)[16]) {
;     ...
;     for (int q = 1; q < 20; ++q) if (it >= tab[q].start) e = q;
;     const XItem x = tab[e]; const int item = it - x.start;
;     const int nblk = x.N >> 6, kb = item / nblk, nb = item - kb * nblk, k0 = kb << 6, n0 = nb << 6;
;     const int lr = lane >> 4, lc = (lane & 15) * 4;
;     const float* W = x.src + (size_t)(k0 + lr) * x.N + n0 + lc; const size_t rstep = (size_t)4 * x.N;
; #pragma unroll
;     for (int i = 0; i < 16; ++i) v[i] = __builtin_nontemporal_load((const f32x4*)(W + i * rstep));
; #pragma unroll
;     for (int i = 0; i < 16; ++i) gv[i] = x.g ? x.g[k0 + 4 * i + lr] : 1.0f;
;     ItemPos p; p.scaled = (x.g != nullptr); p.WT = x.dst; p.K = x.K; p.k0 = k0; p.rb = (x.mode == 0) ? n0 : ((n0 >> 7) * 256 + (x.mode - 1) * 128 + (n0 & 127));
;     return p;
; __device__ __forceinline__ void convert_range(unsigned char* lds, int lo, int hi, int w, int nworkers, int wave, int lane) {
;     ...
;         if (more) pn = item_load(tab, nx, lane, v, gv);
.LBB0_1402:
	v_mov_b32_e32 v5, s2
	ds_read_b32 v5, v5
	v_mov_b32_e32 v6, s3
	s_add_i32 s3, s3, 1
	s_add_i32 s2, s2, 40
	s_cmp_eq_u32 s3, 20
	s_waitcnt lgkmcnt(0)
	v_cmp_lt_i32_e32 vcc, s1, v5
	s_nop 1
	v_cndmask_b32_e32 v4, v6, v4, vcc
	s_cbranch_scc0 .LBB0_1402
	v_mul_lo_u32 v4, v4, 40
	v_add_u32_e32 v4, 0, v4
	v_add_u32_e32 v10, 0x20800, v4
	ds_read2_b64 v[4:7], v10 offset0:3 offset1:4
	ds_read2_b64 v[72:75], v10 offset1:1
	ds_read_b64 v[76:77], v10 offset:16
	s_waitcnt lgkmcnt(2)
	v_readfirstlane_b32 s4, v5
	s_ashr_i32 s2, s4, 6
	s_abs_i32 s3, s2
	v_cvt_f32_u32_e32 v5, s3
	v_readfirstlane_b32 s5, v7
	s_sub_i32 s6, s1, s5
	s_xor_b32 s5, s6, s2
	v_rcp_iflag_f32_e32 v5, v5
	s_ashr_i32 s9, s5, 31
	s_sub_i32 s5, 0, s3
	s_abs_i32 s7, s6
	v_mul_f32_e32 v5, 0x4f7ffffe, v5
	v_cvt_u32_f32_e32 v5, v5
	s_nop 0
	v_readfirstlane_b32 s16, v5
	s_mul_i32 s5, s5, s16
	s_mul_hi_u32 s5, s16, s5
	s_add_i32 s16, s16, s5
	s_mul_hi_u32 s5, s7, s16
	s_mul_i32 s16, s5, s3
	s_sub_i32 s7, s7, s16
	s_add_i32 s18, s5, 1
	s_sub_i32 s16, s7, s3
	s_cmp_ge_u32 s7, s3
	s_cselect_b32 s5, s18, s5
	s_cselect_b32 s7, s16, s7
	s_add_i32 s16, s5, 1
	s_cmp_ge_u32 s7, s3
	s_cselect_b32 s3, s16, s5
	s_xor_b32 s3, s3, s9
	s_sub_i32 s3, s3, s9
	s_mul_i32 s2, s3, s2
	s_lshl_b32 s16, s3, 6
	s_sub_i32 s9, s6, s2
	v_add_u32_e32 v80, s16, v3
	s_lshl_b32 s2, s9, 6
	v_mad_i64_i32 v[10:11], s[6:7], v80, s4, 0
	s_waitcnt lgkmcnt(1)
	v_lshl_add_u64 v[10:11], v[10:11], 2, v[72:73]
	s_ashr_i32 s3, s2, 31
	s_ashr_i32 s5, s4, 31
	v_lshl_add_u64 v[10:11], s[2:3], 2, v[10:11]
	v_lshl_add_u64 v[10:11], v[10:11], 0, v[0:1]
	s_lshl_b64 s[4:5], s[4:5], 4
	v_lshl_add_u64 v[18:19], v[10:11], 0, s[4:5]
	global_load_dwordx4 v[10:13], v[10:11], off nt
	s_nop 0
	global_load_dwordx4 v[14:17], v[18:19], off nt
	v_lshl_add_u64 v[18:19], v[18:19], 0, s[4:5]
	v_lshl_add_u64 v[26:27], v[18:19], 0, s[4:5]
	global_load_dwordx4 v[18:21], v[18:19], off nt
	s_nop 0
	global_load_dwordx4 v[22:25], v[26:27], off nt
	v_lshl_add_u64 v[26:27], v[26:27], 0, s[4:5]
	v_lshl_add_u64 v[34:35], v[26:27], 0, s[4:5]
	global_load_dwordx4 v[26:29], v[26:27], off nt
	s_nop 0
	global_load_dwordx4 v[30:33], v[34:35], off nt
	v_lshl_add_u64 v[34:35], v[34:35], 0, s[4:5]
	v_lshl_add_u64 v[42:43], v[34:35], 0, s[4:5]
	v_lshl_add_u64 v[46:47], v[42:43], 0, s[4:5]
	v_lshl_add_u64 v[50:51], v[46:47], 0, s[4:5]
	v_lshl_add_u64 v[54:55], v[50:51], 0, s[4:5]
	v_lshl_add_u64 v[58:59], v[54:55], 0, s[4:5]
	v_lshl_add_u64 v[62:63], v[58:59], 0, s[4:5]
	v_lshl_add_u64 v[66:67], v[62:63], 0, s[4:5]
	v_lshl_add_u64 v[70:71], v[66:67], 0, s[4:5]
	global_load_dwordx4 v[34:37], v[34:35], off nt
	s_nop 0
	global_load_dwordx4 v[38:41], v[42:43], off nt
	v_ashrrev_i32_e32 v81, 31, v80
	global_load_dwordx4 v[42:45], v[46:47], off nt
	s_waitcnt lgkmcnt(0)
	v_cmp_ne_u64_e64 s[6:7], 0, v[76:77]
	global_load_dwordx4 v[46:49], v[50:51], off nt
	s_and_b64 vcc, exec, s[6:7]
	global_load_dwordx4 v[50:53], v[54:55], off nt
	v_lshl_add_u64 v[94:95], v[80:81], 2, v[76:77]
	global_load_dwordx4 v[54:57], v[58:59], off nt
	s_nop 0
	global_load_dwordx4 v[58:61], v[62:63], off nt
	s_nop 0
	global_load_dwordx4 v[62:65], v[66:67], off nt
	s_nop 0
	global_load_dwordx4 v[66:69], v[70:71], off nt
	v_lshl_add_u64 v[70:71], v[70:71], 0, s[4:5]
	global_load_dwordx4 v[70:73], v[70:71], off nt
	s_cbranch_vccz .LBB0_1430
	global_load_dword v76, v[94:95], off
	global_load_dword v77, v[94:95], off offset:16
	s_cbranch_execnz .LBB0_1406

; __device__ __forceinline__ ItemPos item_load(const XItem* tab, int it, int lane, f32x4 (&v)[16], float (&gv)[16]) {
;     ...
;     for (int i = 0; i < 16; ++i) gv[i] = x.g ? x.g[k0 + 4 * i + lr] : 1.0f;
;     ItemPos p; p.scaled = (x.g != nullptr); p.WT = x.dst; p.K = x.K; p.k0 = k0; p.rb = (x.mode == 0) ? n0 : ((n0 >> 7) * 256 + (x.mode - 1) * 128 + (n0 & 127));
.LBB0_1406:
	v_cndmask_b32_e64 v5, 0, 1, s[6:7]
	v_cmp_ne_u32_e64 s[4:5], 1, v5
	s_andn2_b64 vcc, exec, s[6:7]
	s_cbranch_vccnz .LBB0_1431
	global_load_dword v80, v[94:95], off offset:32
	global_load_dword v81, v[94:95], off offset:48
	s_cbranch_execnz .LBB0_1409

; __device__ __forceinline__ ItemPos item_load(const XItem* tab, int it, int lane, f32x4 (&v)[16], float (&gv)[16]) {
;     ...
;     for (int i = 0; i < 16; ++i) gv[i] = x.g ? x.g[k0 + 4 * i + lr] : 1.0f;
.LBB0_1409:
	s_and_b64 vcc, exec, s[4:5]
	s_cbranch_vccnz .LBB0_1432
	global_load_dword v82, v[94:95], off offset:64
	global_load_dword v83, v[94:95], off offset:80
	s_cbranch_execnz .LBB0_1412

; __device__ __forceinline__ ItemPos item_load(const XItem* tab, int it, int lane, f32x4 (&v)[16], float (&gv)[16]) {
;     ...
;     for (int i = 0; i < 16; ++i) gv[i] = x.g ? x.g[k0 + 4 * i + lr] : 1.0f;
.LBB0_1412:
	s_and_b64 vcc, exec, s[4:5]
	s_cbranch_vccnz .LBB0_1433
	global_load_dword v84, v[94:95], off offset:96
	global_load_dword v85, v[94:95], off offset:112
	s_cbranch_execnz .LBB0_1415

; __device__ __forceinline__ ItemPos item_load(const XItem* tab, int it, int lane, f32x4 (&v)[16], float (&gv)[16]) {
;     ...
;     for (int i = 0; i < 16; ++i) gv[i] = x.g ? x.g[k0 + 4 * i + lr] : 1.0f;
.LBB0_1415:
	s_and_b64 vcc, exec, s[4:5]
	s_cbranch_vccnz .LBB0_1434
	global_load_dword v86, v[94:95], off offset:128
	global_load_dword v87, v[94:95], off offset:144
	s_cbranch_execnz .LBB0_1418

; __device__ __forceinline__ ItemPos item_load(const XItem* tab, int it, int lane, f32x4 (&v)[16], float (&gv)[16]) {
;     ...
;     for (int i = 0; i < 16; ++i) gv[i] = x.g ? x.g[k0 + 4 * i + lr] : 1.0f;
.LBB0_1418:
	s_and_b64 vcc, exec, s[4:5]
	s_cbranch_vccnz .LBB0_1435
	global_load_dword v88, v[94:95], off offset:160
	global_load_dword v89, v[94:95], off offset:176
	s_cbranch_execnz .LBB0_1421

; __device__ __forceinline__ ItemPos item_load(const XItem* tab, int it, int lane, f32x4 (&v)[16], float (&gv)[16]) {
;     ...
;     for (int i = 0; i < 16; ++i) gv[i] = x.g ? x.g[k0 + 4 * i + lr] : 1.0f;
.LBB0_1421:
	s_and_b64 vcc, exec, s[4:5]
	s_cbranch_vccnz .LBB0_1436
	global_load_dword v90, v[94:95], off offset:192
	global_load_dword v91, v[94:95], off offset:208
	s_cbranch_execnz .LBB0_1424

; __device__ __forceinline__ ItemPos item_load(const XItem* tab, int it, int lane, f32x4 (&v)[16], float (&gv)[16]) {
;     ...
;     for (int i = 0; i < 16; ++i) gv[i] = x.g ? x.g[k0 + 4 * i + lr] : 1.0f;
.LBB0_1424:
	s_and_b64 vcc, exec, s[4:5]
	s_cbranch_vccnz .LBB0_1437
	global_load_dword v92, v[94:95], off offset:224
	global_load_dword v93, v[94:95], off offset:240
	s_cbranch_execnz .LBB0_1427

; #define LAS __attribute__((address_space(3)))
; __device__ __forceinline__ unsigned pk2(float lo, float hi) { return f2bf(lo) | (f2bf(hi) << 16); }
; __device__ __forceinline__ void item_store(const ItemPos p, LAS float* scr, int lane) {
;     const int c = lane & 7;
; #pragma unroll
;     for (int j = 0; j < 8; ++j) { const int n = (lane >> 3) + 8 * j; const LAS float* s = scr + (8 * c) * 65 + n;
;         u32x4 o; o.x = pk2(s[0 * 65], s[1 * 65]); o.y = pk2(s[2 * 65], s[3 * 65]); o.z = pk2(s[4 * 65], s[5 * 65]); o.w = pk2(s[6 * 65], s[7 * 65]);
;         __builtin_nontemporal_store(o, (u32x4*)(p.WT + (size_t)(p.rb + n) * p.K + p.k0 + 8 * c)); }
;     asm volatile("s_waitcnt lgkmcnt(0)" ::: "memory");
; }
.LBB0_1428:
	s_ashr_i32 s9, s8, 31
	s_lshl_b64 s[2:3], s[8:9], 1
	v_lshl_add_u64 v[6:7], v[8:9], 0, s[2:3]
	v_mov_b32_e32 v79, v1
	v_lshl_add_u64 v[6:7], v[6:7], 0, v[78:79]
	ds_read_b32 v79, v98
	ds_read_b32 v94, v98 offset:260
	ds_read_b32 v95, v98 offset:520
	ds_read_b32 v101, v98 offset:780
	ds_read_b32 v102, v98 offset:1040
	ds_read_b32 v103, v98 offset:1300
	ds_read_b32 v104, v98 offset:1560
	ds_read_b32 v105, v98 offset:1820
	s_waitcnt lgkmcnt(0)
	v_bfe_u32 v100, v79, 16, 1
	v_add3_u32 v79, v79, v100, s0
	v_bfe_u32 v100, v94, 16, 1
	v_lshrrev_b32_e32 v79, 16, v79
	v_add3_u32 v94, v94, v100, s0
	s_mov_b32 s4, 0xffff0000
	v_and_or_b32 v100, v94, s4, v79
	v_bfe_u32 v79, v95, 16, 1
	v_add3_u32 v79, v95, v79, s0
	v_bfe_u32 v94, v101, 16, 1
	v_lshrrev_b32_e32 v79, 16, v79
	v_add3_u32 v94, v101, v94, s0
	v_and_or_b32 v101, v94, s4, v79
	v_bfe_u32 v79, v102, 16, 1
	v_add3_u32 v79, v102, v79, s0
	v_bfe_u32 v94, v103, 16, 1
	v_lshrrev_b32_e32 v79, 16, v79
	v_add3_u32 v94, v103, v94, s0
	v_and_or_b32 v102, v94, s4, v79
	v_bfe_u32 v79, v104, 16, 1
	v_add3_u32 v79, v104, v79, s0
	v_bfe_u32 v94, v105, 16, 1
	v_lshrrev_b32_e32 v79, 16, v79
	v_add3_u32 v94, v105, v94, s0
	v_and_or_b32 v103, v94, s4, v79
	v_add_u32_e32 v79, v96, v97
	v_mad_i64_i32 v[94:95], s[2:3], v79, v2, 0
	v_lshl_add_u64 v[94:95], v[94:95], 1, v[6:7]
	global_store_dwordx4 v[94:95], v[100:103], off nt
	ds_read_b32 v94, v98 offset:32
	ds_read_b32 v95, v98 offset:292
	ds_read_b32 v101, v98 offset:552
	ds_read_b32 v102, v98 offset:812
	ds_read_b32 v103, v98 offset:1072
	ds_read_b32 v104, v98 offset:1332
	ds_read_b32 v105, v98 offset:1592
	ds_read_b32 v106, v98 offset:1852
	s_waitcnt lgkmcnt(0)
	v_bfe_u32 v100, v94, 16, 1
	v_add3_u32 v94, v94, v100, s0
	v_bfe_u32 v100, v95, 16, 1
	v_lshrrev_b32_e32 v94, 16, v94
	v_add3_u32 v95, v95, v100, s0
	v_and_or_b32 v100, v95, s4, v94
	v_bfe_u32 v94, v101, 16, 1
	v_add3_u32 v94, v101, v94, s0
	v_bfe_u32 v95, v102, 16, 1
	v_lshrrev_b32_e32 v94, 16, v94
	v_add3_u32 v95, v102, v95, s0
	v_and_or_b32 v101, v95, s4, v94
	v_bfe_u32 v94, v103, 16, 1
	v_add3_u32 v94, v103, v94, s0
	v_bfe_u32 v95, v104, 16, 1
	v_lshrrev_b32_e32 v94, 16, v94
	v_add3_u32 v95, v104, v95, s0
	v_and_or_b32 v102, v95, s4, v94
	v_bfe_u32 v94, v105, 16, 1
	v_add3_u32 v94, v105, v94, s0
	v_bfe_u32 v95, v106, 16, 1
	v_lshrrev_b32_e32 v94, 16, v94
	v_add3_u32 v95, v106, v95, s0
	v_and_or_b32 v103, v95, s4, v94
	v_add_u32_e32 v94, 8, v79
	v_mad_i64_i32 v[94:95], s[2:3], v94, v2, 0
	v_lshl_add_u64 v[94:95], v[94:95], 1, v[6:7]
	global_store_dwordx4 v[94:95], v[100:103], off nt
	ds_read_b32 v94, v98 offset:64
	ds_read_b32 v95, v98 offset:324
	ds_read_b32 v101, v98 offset:584
	ds_read_b32 v102, v98 offset:844
	ds_read_b32 v103, v98 offset:1104
	ds_read_b32 v104, v98 offset:1364
	ds_read_b32 v105, v98 offset:1624
	ds_read_b32 v106, v98 offset:1884
	s_waitcnt lgkmcnt(0)
	v_bfe_u32 v100, v94, 16, 1
	v_add3_u32 v94, v94, v100, s0
	v_bfe_u32 v100, v95, 16, 1
	v_lshrrev_b32_e32 v94, 16, v94
	v_add3_u32 v95, v95, v100, s0
	v_and_or_b32 v100, v95, s4, v94
	v_bfe_u32 v94, v101, 16, 1
	v_add3_u32 v94, v101, v94, s0
	v_bfe_u32 v95, v102, 16, 1
	v_lshrrev_b32_e32 v94, 16, v94
	v_add3_u32 v95, v102, v95, s0
	v_and_or_b32 v101, v95, s4, v94
	v_bfe_u32 v94, v103, 16, 1
	v_add3_u32 v94, v103, v94, s0
	v_bfe_u32 v95, v104, 16, 1
	v_lshrrev_b32_e32 v94, 16, v94
	v_add3_u32 v95, v104, v95, s0
	v_and_or_b32 v102, v95, s4, v94
	v_bfe_u32 v94, v105, 16, 1
	v_add3_u32 v94, v105, v94, s0
	v_bfe_u32 v95, v106, 16, 1
	v_lshrrev_b32_e32 v94, 16, v94
	v_add3_u32 v95, v106, v95, s0
	v_and_or_b32 v103, v95, s4, v94
	v_add_u32_e32 v94, 16, v79
	v_mad_i64_i32 v[94:95], s[2:3], v94, v2, 0
	v_lshl_add_u64 v[94:95], v[94:95], 1, v[6:7]
	global_store_dwordx4 v[94:95], v[100:103], off nt
	ds_read_b32 v94, v98 offset:96
	ds_read_b32 v95, v98 offset:356
	ds_read_b32 v101, v98 offset:616
	ds_read_b32 v102, v98 offset:876
	ds_read_b32 v103, v98 offset:1136
	ds_read_b32 v104, v98 offset:1396
	ds_read_b32 v105, v98 offset:1656
	ds_read_b32 v106, v98 offset:1916
	s_waitcnt lgkmcnt(0)
	v_bfe_u32 v100, v94, 16, 1
	v_add3_u32 v94, v94, v100, s0
	v_bfe_u32 v100, v95, 16, 1
	v_lshrrev_b32_e32 v94, 16, v94
	v_add3_u32 v95, v95, v100, s0
	v_and_or_b32 v100, v95, s4, v94
	v_bfe_u32 v94, v101, 16, 1
	v_add3_u32 v94, v101, v94, s0
	v_bfe_u32 v95, v102, 16, 1
	v_lshrrev_b32_e32 v94, 16, v94
	v_add3_u32 v95, v102, v95, s0
	v_and_or_b32 v101, v95, s4, v94
	v_bfe_u32 v94, v103, 16, 1
	v_add3_u32 v94, v103, v94, s0
	v_bfe_u32 v95, v104, 16, 1
	v_lshrrev_b32_e32 v94, 16, v94
	v_add3_u32 v95, v104, v95, s0
	v_and_or_b32 v102, v95, s4, v94
	v_bfe_u32 v94, v105, 16, 1
	v_add3_u32 v94, v105, v94, s0
	v_bfe_u32 v95, v106, 16, 1
	v_lshrrev_b32_e32 v94, 16, v94
	v_add3_u32 v95, v106, v95, s0
	v_and_or_b32 v103, v95, s4, v94
	v_add_u32_e32 v94, 24, v79
	v_mad_i64_i32 v[94:95], s[2:3], v94, v2, 0
	v_lshl_add_u64 v[94:95], v[94:95], 1, v[6:7]
	global_store_dwordx4 v[94:95], v[100:103], off nt
	ds_read_b32 v94, v98 offset:128
	ds_read_b32 v95, v98 offset:388
	ds_read_b32 v101, v98 offset:648
	ds_read_b32 v102, v98 offset:908
	ds_read_b32 v103, v98 offset:1168
	ds_read_b32 v104, v98 offset:1428
	ds_read_b32 v105, v98 offset:1688
	ds_read_b32 v106, v98 offset:1948
	s_waitcnt lgkmcnt(0)
; #define LAS __attribute__((address_space(3)))
; __device__ __forceinline__ unsigned pk2(float lo, float hi) { return f2bf(lo) | (f2bf(hi) << 16); }
; __device__ __forceinline__ void item_store(const ItemPos p, LAS float* scr, int lane) {
;     const int c = lane & 7;
; #pragma unroll
;     for (int j = 0; j < 8; ++j) { const int n = (lane >> 3) + 8 * j; const LAS float* s = scr + (8 * c) * 65 + n;
;         u32x4 o; o.x = pk2(s[0 * 65], s[1 * 65]); o.y = pk2(s[2 * 65], s[3 * 65]); o.z = pk2(s[4 * 65], s[5 * 65]); o.w = pk2(s[6 * 65], s[7 * 65]);
;         __builtin_nontemporal_store(o, (u32x4*)(p.WT + (size_t)(p.rb + n) * p.K + p.k0 + 8 * c)); }
;     asm volatile("s_waitcnt lgkmcnt(0)" ::: "memory");
; }
; __device__ __forceinline__ void convert_range(unsigned char* lds, int lo, int hi, int w, int nworkers, int wave, int lane) {
;     const XItem* tab = (const XItem*)(lds + 8 * 16640);
;     LAS float* scr = (LAS float*)((LAS unsigned char*)lds + wave * 16640);
;     int it = lo + w; if (it >= hi) return;
;     f32x4 v[16]; float gv[16]; ItemPos p = item_load(tab, it, lane, v, gv);
;     for (;;) {
;         item_to_lds(v, gv, p.scaled, scr, lane);
;         const int nx = it + nworkers; const bool more = nx < hi; ItemPos pn = p;
;         if (more) pn = item_load(tab, nx, lane, v, gv);
;         item_store(p, scr, lane);
;         if (!more) break;
;         it = nx; p = pn;
;     }
	v_bfe_u32 v100, v94, 16, 1
	v_add3_u32 v94, v94, v100, s0
	v_bfe_u32 v100, v95, 16, 1
	v_lshrrev_b32_e32 v94, 16, v94
	v_add3_u32 v95, v95, v100, s0
	v_and_or_b32 v100, v95, s4, v94
	v_bfe_u32 v94, v101, 16, 1
	v_add3_u32 v94, v101, v94, s0
	v_bfe_u32 v95, v102, 16, 1
	v_lshrrev_b32_e32 v94, 16, v94
	v_add3_u32 v95, v102, v95, s0
	v_and_or_b32 v101, v95, s4, v94
	v_bfe_u32 v94, v103, 16, 1
	v_add3_u32 v94, v103, v94, s0
	v_bfe_u32 v95, v104, 16, 1
	v_lshrrev_b32_e32 v94, 16, v94
	v_add3_u32 v95, v104, v95, s0
	v_and_or_b32 v102, v95, s4, v94
	v_bfe_u32 v94, v105, 16, 1
	v_add3_u32 v94, v105, v94, s0
	v_bfe_u32 v95, v106, 16, 1
	v_lshrrev_b32_e32 v94, 16, v94
	v_add3_u32 v95, v106, v95, s0
	v_and_or_b32 v103, v95, s4, v94
	v_add_u32_e32 v94, 32, v79
	v_mad_i64_i32 v[94:95], s[2:3], v94, v2, 0
	v_lshl_add_u64 v[94:95], v[94:95], 1, v[6:7]
	global_store_dwordx4 v[94:95], v[100:103], off nt
	ds_read_b32 v94, v98 offset:160
	ds_read_b32 v95, v98 offset:420
	ds_read_b32 v101, v98 offset:680
	ds_read_b32 v102, v98 offset:940
	ds_read_b32 v103, v98 offset:1200
	ds_read_b32 v104, v98 offset:1460
	ds_read_b32 v105, v98 offset:1720
	ds_read_b32 v106, v98 offset:1980
	s_waitcnt lgkmcnt(0)
	v_bfe_u32 v100, v94, 16, 1
	v_add3_u32 v94, v94, v100, s0
	v_bfe_u32 v100, v95, 16, 1
	v_lshrrev_b32_e32 v94, 16, v94
	v_add3_u32 v95, v95, v100, s0
	v_and_or_b32 v100, v95, s4, v94
	v_bfe_u32 v94, v101, 16, 1
	v_add3_u32 v94, v101, v94, s0
	v_bfe_u32 v95, v102, 16, 1
	v_lshrrev_b32_e32 v94, 16, v94
	v_add3_u32 v95, v102, v95, s0
	v_and_or_b32 v101, v95, s4, v94
	v_bfe_u32 v94, v103, 16, 1
	v_add3_u32 v94, v103, v94, s0
	v_bfe_u32 v95, v104, 16, 1
	v_lshrrev_b32_e32 v94, 16, v94
	v_add3_u32 v95, v104, v95, s0
	v_and_or_b32 v102, v95, s4, v94
	v_bfe_u32 v94, v105, 16, 1
	v_add3_u32 v94, v105, v94, s0
	v_bfe_u32 v95, v106, 16, 1
	v_lshrrev_b32_e32 v94, 16, v94
	v_add3_u32 v95, v106, v95, s0
	v_and_or_b32 v103, v95, s4, v94
	v_add_u32_e32 v94, 40, v79
	v_mad_i64_i32 v[94:95], s[2:3], v94, v2, 0
	v_lshl_add_u64 v[94:95], v[94:95], 1, v[6:7]
	global_store_dwordx4 v[94:95], v[100:103], off nt
	ds_read_b32 v94, v98 offset:192
	ds_read_b32 v95, v98 offset:452
	ds_read_b32 v101, v98 offset:712
	ds_read_b32 v102, v98 offset:972
	ds_read_b32 v103, v98 offset:1232
	ds_read_b32 v104, v98 offset:1492
	ds_read_b32 v105, v98 offset:1752
	ds_read_b32 v106, v98 offset:2012
	s_waitcnt lgkmcnt(0)
	v_bfe_u32 v100, v94, 16, 1
	v_add3_u32 v94, v94, v100, s0
	v_bfe_u32 v100, v95, 16, 1
	v_lshrrev_b32_e32 v94, 16, v94
	v_add3_u32 v95, v95, v100, s0
	v_and_or_b32 v100, v95, s4, v94
	v_bfe_u32 v94, v101, 16, 1
	v_add3_u32 v94, v101, v94, s0
	v_bfe_u32 v95, v102, 16, 1
	v_lshrrev_b32_e32 v94, 16, v94
	v_add3_u32 v95, v102, v95, s0
	v_and_or_b32 v101, v95, s4, v94
	v_bfe_u32 v94, v103, 16, 1
	v_add3_u32 v94, v103, v94, s0
	v_bfe_u32 v95, v104, 16, 1
	v_lshrrev_b32_e32 v94, 16, v94
	v_add3_u32 v95, v104, v95, s0
	v_and_or_b32 v102, v95, s4, v94
	v_bfe_u32 v94, v105, 16, 1
	v_add3_u32 v94, v105, v94, s0
	v_bfe_u32 v95, v106, 16, 1
	v_lshrrev_b32_e32 v94, 16, v94
	v_add3_u32 v95, v106, v95, s0
	v_and_or_b32 v103, v95, s4, v94
	v_add_u32_e32 v94, 48, v79
	v_mad_i64_i32 v[94:95], s[2:3], v94, v2, 0
	v_lshl_add_u64 v[94:95], v[94:95], 1, v[6:7]
	global_store_dwordx4 v[94:95], v[100:103], off nt
	ds_read_b32 v94, v98 offset:224
	ds_read_b32 v95, v98 offset:484
	ds_read_b32 v101, v98 offset:744
	ds_read_b32 v102, v98 offset:1004
	ds_read_b32 v103, v98 offset:1264
	ds_read_b32 v104, v98 offset:1524
	ds_read_b32 v105, v98 offset:1784
	ds_read_b32 v106, v98 offset:2044
	s_waitcnt lgkmcnt(0)
	v_bfe_u32 v100, v94, 16, 1
	v_add3_u32 v94, v94, v100, s0
	v_bfe_u32 v100, v95, 16, 1
	v_lshrrev_b32_e32 v94, 16, v94
	v_add3_u32 v95, v95, v100, s0
	v_and_or_b32 v100, v95, s4, v94
	v_bfe_u32 v94, v101, 16, 1
	v_add3_u32 v94, v101, v94, s0
	v_bfe_u32 v95, v102, 16, 1
	v_lshrrev_b32_e32 v94, 16, v94
	v_add3_u32 v95, v102, v95, s0
	v_and_or_b32 v101, v95, s4, v94
	v_bfe_u32 v94, v103, 16, 1
	v_add3_u32 v94, v103, v94, s0
	v_bfe_u32 v95, v104, 16, 1
	v_lshrrev_b32_e32 v94, 16, v94
	v_add3_u32 v95, v104, v95, s0
	v_and_or_b32 v102, v95, s4, v94
	v_bfe_u32 v94, v105, 16, 1
	v_add3_u32 v94, v105, v94, s0
	v_bfe_u32 v95, v106, 16, 1
	v_lshrrev_b32_e32 v94, 16, v94
	v_add3_u32 v95, v106, v95, s0
	v_add_u32_e32 v79, 56, v79
	v_and_or_b32 v103, v95, s4, v94
	v_mad_i64_i32 v[94:95], s[2:3], v79, v2, 0
	v_lshl_add_u64 v[6:7], v[94:95], 1, v[6:7]
	global_store_dwordx4 v[6:7], v[100:103], off nt
	s_waitcnt lgkmcnt(0)
	s_andn2_b64 vcc, exec, s[12:13]
	s_cbranch_vccnz .LBB0_1397
	v_mov_b64_e32 v[8:9], v[74:75]
	v_mov_b32_e32 v2, v4
	v_mov_b32_e32 v96, v5
	s_mov_b32 s8, s16
	s_mov_b32 s15, s1
	s_branch .LBB0_1397
